# all remaining xor-16 ds_swizzle reductions (GEMM epilogue row stats in P3/P5/P8, gMLP) via v_permlane16_swap
# speedup vs baseline: 1.0055x; 1.0005x over previous
.LBB0_346:
	s_lshl_b32 s8, s60, 8
	v_mbcnt_lo_u32_b32 v168, -1, 0
	v_mbcnt_hi_u32_b32 v168, -1, v168
	s_add_i32 s8, s8, s34
	v_ashrrev_i32_e32 v145, 1, v168
	v_and_or_b32 v144, v168, 15, s8
	v_and_b32_e32 v145, -8, v145
	s_lshl_b32 s62, s4, 8
	v_add_u32_e32 v146, s35, v145
	v_ashrrev_i32_e32 v145, 31, v144
	s_ashr_i32 s63, s62, 31
	v_lshlrev_b64 v[152:153], 10, v[144:145]
	v_lshl_add_u64 v[160:161], v[152:153], 0, s[62:63]
	v_ashrrev_i32_e32 v147, 31, v146
	v_lshl_add_u64 v[162:163], v[160:161], 0, v[146:147]
	v_lshl_add_u64 v[164:165], v[162:163], 2, s[52:53]
	global_load_dwordx4 v[152:155], v[164:165], off
	global_load_dwordx4 v[156:159], v[164:165], off offset:16
	v_lshl_add_u64 v[162:163], v[162:163], 1, s[72:73]
	s_lshl_b32 s60, s4, 2
	v_cmp_gt_u32_e32 vcc, 16, v168
	s_ashr_i32 s61, s60, 31
	s_waitcnt vmcnt(0)
	v_pk_fma_f32 v[126:127], v[154:155], s[42:43], v[126:127] op_sel_hi:[1,0,1]
	v_pk_fma_f32 v[166:167], v[152:153], s[42:43], v[124:125] op_sel_hi:[1,0,1]
	v_pk_fma_f32 v[158:159], v[158:159], s[42:43], v[122:123] op_sel_hi:[1,0,1]
	v_pk_fma_f32 v[156:157], v[156:157], s[42:43], v[120:121] op_sel_hi:[1,0,1]
	v_cvt_pk_bf16_f32 v120, v166, v167
	v_cvt_pk_bf16_f32 v121, v126, v127
	s_nop 0
	v_cvt_pk_bf16_f32 v122, v156, v157
	v_cvt_pk_bf16_f32 v123, v158, v159
	global_store_dwordx4 v[162:163], v[120:123], off
	global_load_dwordx4 v[122:125], v[164:165], off offset:512
	s_nop 0
	global_load_dwordx4 v[152:155], v[164:165], off offset:528
	v_add_f32_e32 v162, v166, v167
	v_add_f32_e32 v163, v126, v127
	v_add_f32_e32 v164, v156, v157
	v_add_f32_e32 v165, v158, v159
	v_mul_f32_e32 v167, v167, v167
	v_mul_f32_e32 v127, v127, v127
	v_mul_f32_e32 v157, v157, v157
	v_mul_f32_e32 v159, v159, v159
	v_add_f32_e32 v162, v162, v163
	v_add_f32_e32 v163, v164, v165
	v_fmac_f32_e32 v167, v166, v166
	v_fmac_f32_e32 v127, v126, v126
	v_fmac_f32_e32 v157, v156, v156
	v_fmac_f32_e32 v159, v158, v158
	v_add_f32_e32 v126, v162, v163
	v_add_f32_e32 v127, v167, v127
	v_add_f32_e32 v156, v157, v159
	v_add_f32_e32 v126, 0, v126
	v_add_f32_e32 v127, v127, v156
	v_add_u32_e32 v120, 0x80, v146
	v_ashrrev_i32_e32 v121, 31, v120
	v_lshl_add_u64 v[160:161], v[160:161], 0, v[120:121]
	v_lshl_add_u64 v[160:161], v[160:161], 1, s[72:73]
	s_waitcnt vmcnt(1)
	v_pk_fma_f32 v[118:119], v[124:125], s[42:43], v[118:119] op_sel_hi:[1,0,1]
	v_pk_fma_f32 v[116:117], v[122:123], s[42:43], v[116:117] op_sel_hi:[1,0,1]
	s_waitcnt vmcnt(0)
	v_pk_fma_f32 v[122:123], v[154:155], s[42:43], v[114:115] op_sel_hi:[1,0,1]
	v_pk_fma_f32 v[124:125], v[152:153], s[42:43], v[112:113] op_sel_hi:[1,0,1]
	v_cvt_pk_bf16_f32 v112, v116, v117
	v_cvt_pk_bf16_f32 v113, v118, v119
	v_add_f32_e32 v115, v116, v117
	v_cvt_pk_bf16_f32 v114, v124, v125
	v_add_f32_e32 v152, v118, v119
	v_add_f32_e32 v153, v124, v125
	v_add_f32_e32 v154, v122, v123
	v_mul_f32_e32 v117, v117, v117
	v_mul_f32_e32 v119, v119, v119
	v_mul_f32_e32 v125, v125, v125
	v_mul_f32_e32 v155, v123, v123
	v_add_f32_e32 v115, v115, v152
	v_add_f32_e32 v152, v153, v154
	v_fmac_f32_e32 v117, v116, v116
	v_fmac_f32_e32 v119, v118, v118
	v_fmac_f32_e32 v125, v124, v124
	v_fmac_f32_e32 v155, v122, v122
	v_add_f32_e32 v115, v115, v152
	v_add_f32_e32 v116, v117, v119
	v_add_f32_e32 v117, v125, v155
	v_add_f32_e32 v118, v126, v115
	v_add_f32_e32 v115, v116, v117
	v_add_f32_e32 v117, v127, v115
	v_cvt_pk_bf16_f32 v115, v122, v123
	global_store_dwordx4 v[160:161], v[112:115], off
	s_waitcnt lgkmcnt(1)
	s_nop 0
	v_mov_b32_e32 v116, v118
	s_nop 1
	v_permlane16_swap_b32_e32 v118, v116
	v_add_f32_e32 v112, v118, v116
	s_waitcnt lgkmcnt(0)
	v_mov_b32_e32 v119, v117
	s_nop 1
	v_permlane16_swap_b32_e32 v117, v119
	v_add_f32_e32 v113, v117, v119
	v_mov_b32_e32 v114, v112
	v_mov_b32_e32 v115, v113
	s_nop 0
	v_permlane32_swap_b32_e32 v112, v114
	v_permlane32_swap_b32_e32 v113, v115
	s_and_saveexec_b64 s[64:65], vcc
	s_cbranch_execz .LBB0_348
	v_pk_add_f32 v[112:113], v[112:113], v[114:115]
	v_lshlrev_b64 v[114:115], 7, v[144:145]
	v_lshl_add_u64 v[114:115], s[36:37], 0, v[114:115]
	v_lshl_add_u64 v[114:115], s[60:61], 3, v[114:115]
	s_lshl_b32 s4, s31, 3
	v_lshl_add_u64 v[114:115], v[114:115], 0, s[4:5]
	global_store_dwordx2 v[114:115], v[112:113], off
.LBB0_348:
	s_or_b64 exec, exec, s[64:65]
	v_or_b32_e32 v112, 16, v144
	v_ashrrev_i32_e32 v113, 31, v112
	v_lshlrev_b64 v[114:115], 10, v[112:113]
	v_lshl_add_u64 v[118:119], v[114:115], 0, s[62:63]
	v_lshl_add_u64 v[126:127], v[118:119], 0, v[146:147]
	v_lshl_add_u64 v[152:153], v[126:127], 2, s[52:53]
	global_load_dwordx4 v[114:117], v[152:153], off
	global_load_dwordx4 v[122:125], v[152:153], off offset:16
	v_lshl_add_u64 v[126:127], v[126:127], 1, s[72:73]
	v_lshl_add_u64 v[118:119], v[118:119], 0, v[120:121]
	v_lshl_add_u64 v[118:119], v[118:119], 1, s[72:73]
	s_waitcnt vmcnt(1)
	v_pk_fma_f32 v[116:117], v[116:117], s[42:43], v[110:111] op_sel_hi:[1,0,1]
	v_pk_fma_f32 v[114:115], v[114:115], s[42:43], v[108:109] op_sel_hi:[1,0,1]
	s_waitcnt vmcnt(0)
	v_pk_fma_f32 v[124:125], v[124:125], s[42:43], v[106:107] op_sel_hi:[1,0,1]
	v_pk_fma_f32 v[122:123], v[122:123], s[42:43], v[104:105] op_sel_hi:[1,0,1]
	v_cvt_pk_bf16_f32 v104, v114, v115
	v_cvt_pk_bf16_f32 v105, v116, v117
	s_nop 0
	v_cvt_pk_bf16_f32 v106, v122, v123
	v_cvt_pk_bf16_f32 v107, v124, v125
	global_store_dwordx4 v[126:127], v[104:107], off
	global_load_dwordx4 v[104:107], v[152:153], off offset:512
	s_nop 0
	global_load_dwordx4 v[108:111], v[152:153], off offset:528
	v_add_f32_e32 v126, v114, v115
	v_add_f32_e32 v127, v116, v117
	v_add_f32_e32 v145, v122, v123
	v_add_f32_e32 v152, v124, v125
	v_mul_f32_e32 v115, v115, v115
	v_mul_f32_e32 v117, v117, v117
	v_mul_f32_e32 v123, v123, v123
	v_mul_f32_e32 v125, v125, v125
	v_add_f32_e32 v126, v126, v127
	v_add_f32_e32 v127, v145, v152
	v_fmac_f32_e32 v115, v114, v114
	v_fmac_f32_e32 v117, v116, v116
	v_fmac_f32_e32 v123, v122, v122
	v_fmac_f32_e32 v125, v124, v124
	v_add_f32_e32 v114, v126, v127
	v_add_f32_e32 v115, v115, v117
	v_add_f32_e32 v116, v123, v125
	v_add_f32_e32 v114, 0, v114
	v_add_f32_e32 v115, v115, v116
	s_waitcnt vmcnt(1)
	v_pk_fma_f32 v[102:103], v[106:107], s[42:43], v[102:103] op_sel_hi:[1,0,1]
	v_pk_fma_f32 v[100:101], v[104:105], s[42:43], v[100:101] op_sel_hi:[1,0,1]
	s_waitcnt vmcnt(0)
	v_pk_fma_f32 v[104:105], v[110:111], s[42:43], v[98:99] op_sel_hi:[1,0,1]
	v_pk_fma_f32 v[106:107], v[108:109], s[42:43], v[96:97] op_sel_hi:[1,0,1]
	v_cvt_pk_bf16_f32 v96, v100, v101
	v_cvt_pk_bf16_f32 v97, v102, v103
	v_add_f32_e32 v99, v100, v101
	v_cvt_pk_bf16_f32 v98, v106, v107
	v_add_f32_e32 v108, v102, v103
	v_add_f32_e32 v109, v106, v107
	v_add_f32_e32 v110, v104, v105
	v_mul_f32_e32 v101, v101, v101
	v_mul_f32_e32 v103, v103, v103
	v_mul_f32_e32 v107, v107, v107
	v_mul_f32_e32 v111, v105, v105
	v_add_f32_e32 v99, v99, v108
	v_add_f32_e32 v108, v109, v110
	v_fmac_f32_e32 v101, v100, v100
	v_fmac_f32_e32 v103, v102, v102
	v_fmac_f32_e32 v107, v106, v106
	v_fmac_f32_e32 v111, v104, v104
	v_add_f32_e32 v99, v99, v108
	v_add_f32_e32 v100, v101, v103
	v_add_f32_e32 v101, v107, v111
	v_add_f32_e32 v102, v114, v99
	v_add_f32_e32 v99, v100, v101
	v_add_f32_e32 v101, v115, v99
	v_cvt_pk_bf16_f32 v99, v104, v105
	global_store_dwordx4 v[118:119], v[96:99], off
	s_waitcnt lgkmcnt(1)
	s_nop 0
	v_mov_b32_e32 v100, v102
	s_nop 1
	v_permlane16_swap_b32_e32 v102, v100
	v_add_f32_e32 v96, v102, v100
	s_waitcnt lgkmcnt(0)
	v_mov_b32_e32 v103, v101
	s_nop 1
	v_permlane16_swap_b32_e32 v101, v103
	v_add_f32_e32 v97, v101, v103
	v_mov_b32_e32 v98, v96
	v_mov_b32_e32 v99, v97
	s_nop 0
	v_permlane32_swap_b32_e32 v96, v98
	v_permlane32_swap_b32_e32 v97, v99
	s_and_saveexec_b64 s[64:65], vcc
	s_cbranch_execz .LBB0_350
	v_pk_add_f32 v[96:97], v[96:97], v[98:99]
	v_lshlrev_b64 v[98:99], 7, v[112:113]
	v_lshl_add_u64 v[98:99], s[36:37], 0, v[98:99]
	v_lshl_add_u64 v[98:99], s[60:61], 3, v[98:99]
	s_lshl_b32 s4, s31, 3
	v_lshl_add_u64 v[98:99], v[98:99], 0, s[4:5]
	global_store_dwordx2 v[98:99], v[96:97], off
.LBB0_350:
	s_or_b64 exec, exec, s[64:65]
	v_or_b32_e32 v96, 32, v144
	v_ashrrev_i32_e32 v97, 31, v96
	v_lshlrev_b64 v[98:99], 10, v[96:97]
	v_lshl_add_u64 v[106:107], v[98:99], 0, s[62:63]
	v_lshl_add_u64 v[108:109], v[106:107], 0, v[146:147]
	v_lshl_add_u64 v[110:111], v[108:109], 2, s[52:53]
	global_load_dwordx4 v[98:101], v[110:111], off
	global_load_dwordx4 v[102:105], v[110:111], off offset:16
	v_lshl_add_u64 v[108:109], v[108:109], 1, s[72:73]
	v_lshl_add_u64 v[106:107], v[106:107], 0, v[120:121]
	v_lshl_add_u64 v[106:107], v[106:107], 1, s[72:73]
	s_waitcnt vmcnt(1)
	v_pk_fma_f32 v[100:101], v[100:101], s[42:43], v[94:95] op_sel_hi:[1,0,1]
	v_pk_fma_f32 v[98:99], v[98:99], s[42:43], v[92:93] op_sel_hi:[1,0,1]
	s_waitcnt vmcnt(0)
	v_pk_fma_f32 v[104:105], v[104:105], s[42:43], v[90:91] op_sel_hi:[1,0,1]
	v_pk_fma_f32 v[102:103], v[102:103], s[42:43], v[88:89] op_sel_hi:[1,0,1]
	v_cvt_pk_bf16_f32 v88, v98, v99
	v_cvt_pk_bf16_f32 v89, v100, v101
	s_nop 0
	v_cvt_pk_bf16_f32 v90, v102, v103
	v_cvt_pk_bf16_f32 v91, v104, v105
	global_store_dwordx4 v[108:109], v[88:91], off
	global_load_dwordx4 v[88:91], v[110:111], off offset:512
	s_nop 0
	global_load_dwordx4 v[92:95], v[110:111], off offset:528
	v_add_f32_e32 v108, v98, v99
	v_add_f32_e32 v109, v100, v101
	v_add_f32_e32 v110, v102, v103
	v_add_f32_e32 v111, v104, v105
	v_mul_f32_e32 v99, v99, v99
	v_mul_f32_e32 v101, v101, v101
	v_mul_f32_e32 v103, v103, v103
	v_mul_f32_e32 v105, v105, v105
	v_add_f32_e32 v108, v108, v109
	v_add_f32_e32 v109, v110, v111
	v_fmac_f32_e32 v99, v98, v98
	v_fmac_f32_e32 v101, v100, v100
	v_fmac_f32_e32 v103, v102, v102
	v_fmac_f32_e32 v105, v104, v104
	v_add_f32_e32 v98, v108, v109
	v_add_f32_e32 v99, v99, v101
	v_add_f32_e32 v100, v103, v105
	v_add_f32_e32 v98, 0, v98
	v_add_f32_e32 v99, v99, v100
	s_waitcnt vmcnt(1)
	v_pk_fma_f32 v[86:87], v[90:91], s[42:43], v[86:87] op_sel_hi:[1,0,1]
	v_pk_fma_f32 v[84:85], v[88:89], s[42:43], v[84:85] op_sel_hi:[1,0,1]
	s_waitcnt vmcnt(0)
	v_pk_fma_f32 v[88:89], v[94:95], s[42:43], v[82:83] op_sel_hi:[1,0,1]
	v_pk_fma_f32 v[90:91], v[92:93], s[42:43], v[80:81] op_sel_hi:[1,0,1]
	v_cvt_pk_bf16_f32 v80, v84, v85
	v_cvt_pk_bf16_f32 v81, v86, v87
	v_add_f32_e32 v83, v84, v85
	v_cvt_pk_bf16_f32 v82, v90, v91
	v_add_f32_e32 v92, v86, v87
	v_add_f32_e32 v93, v90, v91
	v_add_f32_e32 v94, v88, v89
	v_mul_f32_e32 v85, v85, v85
	v_mul_f32_e32 v87, v87, v87
	v_mul_f32_e32 v91, v91, v91
	v_mul_f32_e32 v95, v89, v89
	v_add_f32_e32 v83, v83, v92
	v_add_f32_e32 v92, v93, v94
	v_fmac_f32_e32 v85, v84, v84
	v_fmac_f32_e32 v87, v86, v86
	v_fmac_f32_e32 v91, v90, v90
	v_fmac_f32_e32 v95, v88, v88
	v_add_f32_e32 v83, v83, v92
	v_add_f32_e32 v84, v85, v87
	v_add_f32_e32 v85, v91, v95
	v_add_f32_e32 v86, v98, v83
	v_add_f32_e32 v83, v84, v85
	v_add_f32_e32 v85, v99, v83
	v_cvt_pk_bf16_f32 v83, v88, v89
	global_store_dwordx4 v[106:107], v[80:83], off
	s_waitcnt lgkmcnt(1)
	s_nop 0
	v_mov_b32_e32 v84, v86
	s_nop 1
	v_permlane16_swap_b32_e32 v86, v84
	v_add_f32_e32 v80, v86, v84
	s_waitcnt lgkmcnt(0)
	v_mov_b32_e32 v87, v85
	s_nop 1
	v_permlane16_swap_b32_e32 v85, v87
	v_add_f32_e32 v81, v85, v87
	v_mov_b32_e32 v82, v80
	v_mov_b32_e32 v83, v81
	s_nop 0
	v_permlane32_swap_b32_e32 v80, v82
	v_permlane32_swap_b32_e32 v81, v83
	s_and_saveexec_b64 s[64:65], vcc
	s_cbranch_execz .LBB0_352
	v_pk_add_f32 v[80:81], v[80:81], v[82:83]
	v_lshlrev_b64 v[82:83], 7, v[96:97]
	v_lshl_add_u64 v[82:83], s[36:37], 0, v[82:83]
	v_lshl_add_u64 v[82:83], s[60:61], 3, v[82:83]
	s_lshl_b32 s4, s31, 3
	v_lshl_add_u64 v[82:83], v[82:83], 0, s[4:5]
	global_store_dwordx2 v[82:83], v[80:81], off
.LBB0_352:
	s_or_b64 exec, exec, s[64:65]
	v_or_b32_e32 v80, 48, v144
	v_ashrrev_i32_e32 v81, 31, v80
	v_lshlrev_b64 v[82:83], 10, v[80:81]
	v_lshl_add_u64 v[90:91], v[82:83], 0, s[62:63]
	v_lshl_add_u64 v[92:93], v[90:91], 0, v[146:147]
	v_lshl_add_u64 v[94:95], v[92:93], 2, s[52:53]
	global_load_dwordx4 v[82:85], v[94:95], off
	global_load_dwordx4 v[86:89], v[94:95], off offset:16
	v_lshl_add_u64 v[92:93], v[92:93], 1, s[72:73]
	v_lshl_add_u64 v[90:91], v[90:91], 0, v[120:121]
	v_lshl_add_u64 v[90:91], v[90:91], 1, s[72:73]
	s_waitcnt vmcnt(1)
	v_pk_fma_f32 v[84:85], v[84:85], s[42:43], v[78:79] op_sel_hi:[1,0,1]
	v_pk_fma_f32 v[82:83], v[82:83], s[42:43], v[76:77] op_sel_hi:[1,0,1]
	s_waitcnt vmcnt(0)
	v_pk_fma_f32 v[88:89], v[88:89], s[42:43], v[74:75] op_sel_hi:[1,0,1]
	v_pk_fma_f32 v[86:87], v[86:87], s[42:43], v[72:73] op_sel_hi:[1,0,1]
	v_cvt_pk_bf16_f32 v72, v82, v83
	v_cvt_pk_bf16_f32 v73, v84, v85
	s_nop 0
	v_cvt_pk_bf16_f32 v74, v86, v87
	v_cvt_pk_bf16_f32 v75, v88, v89
	global_store_dwordx4 v[92:93], v[72:75], off
	global_load_dwordx4 v[72:75], v[94:95], off offset:512
	s_nop 0
	global_load_dwordx4 v[76:79], v[94:95], off offset:528
	v_add_f32_e32 v92, v82, v83
	v_add_f32_e32 v93, v84, v85
	v_add_f32_e32 v94, v86, v87
	v_add_f32_e32 v95, v88, v89
	v_mul_f32_e32 v83, v83, v83
	v_mul_f32_e32 v85, v85, v85
	v_mul_f32_e32 v87, v87, v87
	v_mul_f32_e32 v89, v89, v89
	v_add_f32_e32 v92, v92, v93
	v_add_f32_e32 v93, v94, v95
	v_fmac_f32_e32 v83, v82, v82
	v_fmac_f32_e32 v85, v84, v84
	v_fmac_f32_e32 v87, v86, v86
	v_fmac_f32_e32 v89, v88, v88
	v_add_f32_e32 v82, v92, v93
	v_add_f32_e32 v83, v83, v85
	v_add_f32_e32 v84, v87, v89
	v_add_f32_e32 v82, 0, v82
	v_add_f32_e32 v83, v83, v84
	s_waitcnt vmcnt(1)
	v_pk_fma_f32 v[70:71], v[74:75], s[42:43], v[70:71] op_sel_hi:[1,0,1]
	v_pk_fma_f32 v[68:69], v[72:73], s[42:43], v[68:69] op_sel_hi:[1,0,1]
	s_waitcnt vmcnt(0)
	v_pk_fma_f32 v[72:73], v[78:79], s[42:43], v[66:67] op_sel_hi:[1,0,1]
	v_pk_fma_f32 v[74:75], v[76:77], s[42:43], v[64:65] op_sel_hi:[1,0,1]
	v_cvt_pk_bf16_f32 v64, v68, v69
	v_cvt_pk_bf16_f32 v65, v70, v71
	v_add_f32_e32 v67, v68, v69
	v_cvt_pk_bf16_f32 v66, v74, v75
	v_add_f32_e32 v76, v70, v71
	v_add_f32_e32 v77, v74, v75
	v_add_f32_e32 v78, v72, v73
	v_mul_f32_e32 v69, v69, v69
	v_mul_f32_e32 v71, v71, v71
	v_mul_f32_e32 v75, v75, v75
	v_mul_f32_e32 v79, v73, v73
	v_add_f32_e32 v67, v67, v76
	v_add_f32_e32 v76, v77, v78
	v_fmac_f32_e32 v69, v68, v68
	v_fmac_f32_e32 v71, v70, v70
	v_fmac_f32_e32 v75, v74, v74
	v_fmac_f32_e32 v79, v72, v72
	v_add_f32_e32 v67, v67, v76
	v_add_f32_e32 v68, v69, v71
	v_add_f32_e32 v69, v75, v79
	v_add_f32_e32 v70, v82, v67
	v_add_f32_e32 v67, v68, v69
	v_add_f32_e32 v69, v83, v67
	v_cvt_pk_bf16_f32 v67, v72, v73
	global_store_dwordx4 v[90:91], v[64:67], off
	s_waitcnt lgkmcnt(1)
	s_nop 0
	v_mov_b32_e32 v68, v70
	s_nop 1
	v_permlane16_swap_b32_e32 v70, v68
	v_add_f32_e32 v64, v70, v68
	s_waitcnt lgkmcnt(0)
	v_mov_b32_e32 v71, v69
	s_nop 1
	v_permlane16_swap_b32_e32 v69, v71
	v_add_f32_e32 v65, v69, v71
	v_mov_b32_e32 v66, v64
	v_mov_b32_e32 v67, v65
	s_nop 0
	v_permlane32_swap_b32_e32 v64, v66
	v_permlane32_swap_b32_e32 v65, v67
	s_and_saveexec_b64 s[64:65], vcc
	s_cbranch_execz .LBB0_354
	v_pk_add_f32 v[64:65], v[64:65], v[66:67]
	v_lshlrev_b64 v[66:67], 7, v[80:81]
	v_lshl_add_u64 v[66:67], s[36:37], 0, v[66:67]
	v_lshl_add_u64 v[66:67], s[60:61], 3, v[66:67]
	s_lshl_b32 s4, s31, 3
	v_lshl_add_u64 v[66:67], v[66:67], 0, s[4:5]
	global_store_dwordx2 v[66:67], v[64:65], off
.LBB0_354:
	s_or_b64 exec, exec, s[64:65]
	v_add_u32_e32 v64, 0x80, v144
	v_ashrrev_i32_e32 v65, 31, v64
	v_lshlrev_b64 v[66:67], 10, v[64:65]
	v_lshl_add_u64 v[74:75], v[66:67], 0, s[62:63]
	v_lshl_add_u64 v[76:77], v[74:75], 0, v[146:147]
	v_lshl_add_u64 v[78:79], v[76:77], 2, s[52:53]
	global_load_dwordx4 v[66:69], v[78:79], off
	global_load_dwordx4 v[70:73], v[78:79], off offset:16
	v_lshl_add_u64 v[76:77], v[76:77], 1, s[72:73]
	v_lshl_add_u64 v[74:75], v[74:75], 0, v[120:121]
	v_lshl_add_u64 v[74:75], v[74:75], 1, s[72:73]
	s_waitcnt vmcnt(1)
	v_pk_fma_f32 v[68:69], v[68:69], s[42:43], v[62:63] op_sel_hi:[1,0,1]
	v_pk_fma_f32 v[66:67], v[66:67], s[42:43], v[60:61] op_sel_hi:[1,0,1]
	s_waitcnt vmcnt(0)
	v_pk_fma_f32 v[72:73], v[72:73], s[42:43], v[58:59] op_sel_hi:[1,0,1]
	v_pk_fma_f32 v[70:71], v[70:71], s[42:43], v[56:57] op_sel_hi:[1,0,1]
	v_cvt_pk_bf16_f32 v56, v66, v67
	v_cvt_pk_bf16_f32 v57, v68, v69
	s_nop 0
	v_cvt_pk_bf16_f32 v58, v70, v71
	v_cvt_pk_bf16_f32 v59, v72, v73
	global_store_dwordx4 v[76:77], v[56:59], off
	global_load_dwordx4 v[56:59], v[78:79], off offset:512
	s_nop 0
	global_load_dwordx4 v[60:63], v[78:79], off offset:528
	v_add_f32_e32 v76, v66, v67
	v_add_f32_e32 v77, v68, v69
	v_add_f32_e32 v78, v70, v71
	v_add_f32_e32 v79, v72, v73
	v_mul_f32_e32 v67, v67, v67
	v_mul_f32_e32 v69, v69, v69
	v_mul_f32_e32 v71, v71, v71
	v_mul_f32_e32 v73, v73, v73
	v_add_f32_e32 v76, v76, v77
	v_add_f32_e32 v77, v78, v79
	v_fmac_f32_e32 v67, v66, v66
	v_fmac_f32_e32 v69, v68, v68
	v_fmac_f32_e32 v71, v70, v70
	v_fmac_f32_e32 v73, v72, v72
	v_add_f32_e32 v66, v76, v77
	v_add_f32_e32 v67, v67, v69
	v_add_f32_e32 v68, v71, v73
	v_add_f32_e32 v66, 0, v66
	v_add_f32_e32 v67, v67, v68
	s_waitcnt vmcnt(1)
	v_pk_fma_f32 v[54:55], v[58:59], s[42:43], v[54:55] op_sel_hi:[1,0,1]
	v_pk_fma_f32 v[52:53], v[56:57], s[42:43], v[52:53] op_sel_hi:[1,0,1]
	s_waitcnt vmcnt(0)
	v_pk_fma_f32 v[56:57], v[62:63], s[42:43], v[50:51] op_sel_hi:[1,0,1]
	v_pk_fma_f32 v[58:59], v[60:61], s[42:43], v[48:49] op_sel_hi:[1,0,1]
	v_cvt_pk_bf16_f32 v48, v52, v53
	v_cvt_pk_bf16_f32 v49, v54, v55
	v_add_f32_e32 v51, v52, v53
	v_cvt_pk_bf16_f32 v50, v58, v59
	v_add_f32_e32 v60, v54, v55
	v_add_f32_e32 v61, v58, v59
	v_add_f32_e32 v62, v56, v57
	v_mul_f32_e32 v53, v53, v53
	v_mul_f32_e32 v55, v55, v55
	v_mul_f32_e32 v59, v59, v59
	v_mul_f32_e32 v63, v57, v57
	v_add_f32_e32 v51, v51, v60
	v_add_f32_e32 v60, v61, v62
	v_fmac_f32_e32 v53, v52, v52
	v_fmac_f32_e32 v55, v54, v54
	v_fmac_f32_e32 v59, v58, v58
	v_fmac_f32_e32 v63, v56, v56
	v_add_f32_e32 v51, v51, v60
	v_add_f32_e32 v52, v53, v55
	v_add_f32_e32 v53, v59, v63
	v_add_f32_e32 v54, v66, v51
	v_add_f32_e32 v51, v52, v53
	v_add_f32_e32 v53, v67, v51
	v_cvt_pk_bf16_f32 v51, v56, v57
	global_store_dwordx4 v[74:75], v[48:51], off
	s_waitcnt lgkmcnt(1)
	s_nop 0
	v_mov_b32_e32 v52, v54
	s_nop 1
	v_permlane16_swap_b32_e32 v54, v52
	v_add_f32_e32 v48, v54, v52
	s_waitcnt lgkmcnt(0)
	v_mov_b32_e32 v55, v53
	s_nop 1
	v_permlane16_swap_b32_e32 v53, v55
	v_add_f32_e32 v49, v53, v55
	v_mov_b32_e32 v50, v48
	v_mov_b32_e32 v51, v49
	s_nop 0
	v_permlane32_swap_b32_e32 v48, v50
	v_permlane32_swap_b32_e32 v49, v51
	s_and_saveexec_b64 s[64:65], vcc
	s_cbranch_execz .LBB0_356
	v_pk_add_f32 v[48:49], v[48:49], v[50:51]
	v_lshlrev_b64 v[50:51], 7, v[64:65]
	v_lshl_add_u64 v[50:51], s[36:37], 0, v[50:51]
	v_lshl_add_u64 v[50:51], s[60:61], 3, v[50:51]
	s_lshl_b32 s4, s31, 3
	v_lshl_add_u64 v[50:51], v[50:51], 0, s[4:5]
	global_store_dwordx2 v[50:51], v[48:49], off
.LBB0_356:
	s_or_b64 exec, exec, s[64:65]
	v_add_u32_e32 v48, 0x90, v144
	v_ashrrev_i32_e32 v49, 31, v48
	v_lshlrev_b64 v[50:51], 10, v[48:49]
	v_lshl_add_u64 v[58:59], v[50:51], 0, s[62:63]
	v_lshl_add_u64 v[60:61], v[58:59], 0, v[146:147]
	v_lshl_add_u64 v[62:63], v[60:61], 2, s[52:53]
	global_load_dwordx4 v[50:53], v[62:63], off
	global_load_dwordx4 v[54:57], v[62:63], off offset:16
	v_lshl_add_u64 v[60:61], v[60:61], 1, s[72:73]
	v_lshl_add_u64 v[58:59], v[58:59], 0, v[120:121]
	v_lshl_add_u64 v[58:59], v[58:59], 1, s[72:73]
	s_waitcnt vmcnt(1)
	v_pk_fma_f32 v[52:53], v[52:53], s[42:43], v[46:47] op_sel_hi:[1,0,1]
	v_pk_fma_f32 v[50:51], v[50:51], s[42:43], v[44:45] op_sel_hi:[1,0,1]
	s_waitcnt vmcnt(0)
	v_pk_fma_f32 v[56:57], v[56:57], s[42:43], v[42:43] op_sel_hi:[1,0,1]
	v_pk_fma_f32 v[54:55], v[54:55], s[42:43], v[40:41] op_sel_hi:[1,0,1]
	v_cvt_pk_bf16_f32 v40, v50, v51
	v_cvt_pk_bf16_f32 v41, v52, v53
	s_nop 0
	v_cvt_pk_bf16_f32 v42, v54, v55
	v_cvt_pk_bf16_f32 v43, v56, v57
	global_store_dwordx4 v[60:61], v[40:43], off
	global_load_dwordx4 v[40:43], v[62:63], off offset:512
	s_nop 0
	global_load_dwordx4 v[44:47], v[62:63], off offset:528
	v_add_f32_e32 v60, v50, v51
	v_add_f32_e32 v61, v52, v53
	v_add_f32_e32 v62, v54, v55
	v_add_f32_e32 v63, v56, v57
	v_mul_f32_e32 v51, v51, v51
	v_mul_f32_e32 v53, v53, v53
	v_mul_f32_e32 v55, v55, v55
	v_mul_f32_e32 v57, v57, v57
	v_add_f32_e32 v60, v60, v61
	v_add_f32_e32 v61, v62, v63
	v_fmac_f32_e32 v51, v50, v50
	v_fmac_f32_e32 v53, v52, v52
	v_fmac_f32_e32 v55, v54, v54
	v_fmac_f32_e32 v57, v56, v56
	v_add_f32_e32 v50, v60, v61
	v_add_f32_e32 v51, v51, v53
	v_add_f32_e32 v52, v55, v57
	v_add_f32_e32 v50, 0, v50
	v_add_f32_e32 v51, v51, v52
	s_waitcnt vmcnt(1)
	v_pk_fma_f32 v[38:39], v[42:43], s[42:43], v[38:39] op_sel_hi:[1,0,1]
	v_pk_fma_f32 v[36:37], v[40:41], s[42:43], v[36:37] op_sel_hi:[1,0,1]
	s_waitcnt vmcnt(0)
	v_pk_fma_f32 v[40:41], v[46:47], s[42:43], v[34:35] op_sel_hi:[1,0,1]
	v_pk_fma_f32 v[42:43], v[44:45], s[42:43], v[32:33] op_sel_hi:[1,0,1]
	v_cvt_pk_bf16_f32 v32, v36, v37
	v_cvt_pk_bf16_f32 v33, v38, v39
	v_add_f32_e32 v35, v36, v37
	v_cvt_pk_bf16_f32 v34, v42, v43
	v_add_f32_e32 v44, v38, v39
	v_add_f32_e32 v45, v42, v43
	v_add_f32_e32 v46, v40, v41
	v_mul_f32_e32 v37, v37, v37
	v_mul_f32_e32 v39, v39, v39
	v_mul_f32_e32 v43, v43, v43
	v_mul_f32_e32 v47, v41, v41
	v_add_f32_e32 v35, v35, v44
	v_add_f32_e32 v44, v45, v46
	v_fmac_f32_e32 v37, v36, v36
	v_fmac_f32_e32 v39, v38, v38
	v_fmac_f32_e32 v43, v42, v42
	v_fmac_f32_e32 v47, v40, v40
	v_add_f32_e32 v35, v35, v44
	v_add_f32_e32 v36, v37, v39
	v_add_f32_e32 v37, v43, v47
	v_add_f32_e32 v38, v50, v35
	v_add_f32_e32 v35, v36, v37
	v_add_f32_e32 v37, v51, v35
	v_cvt_pk_bf16_f32 v35, v40, v41
	global_store_dwordx4 v[58:59], v[32:35], off
	s_waitcnt lgkmcnt(1)
	s_nop 0
	v_mov_b32_e32 v36, v38
	s_nop 1
	v_permlane16_swap_b32_e32 v38, v36
	v_add_f32_e32 v32, v38, v36
	s_waitcnt lgkmcnt(0)
	v_mov_b32_e32 v39, v37
	s_nop 1
	v_permlane16_swap_b32_e32 v37, v39
	v_add_f32_e32 v33, v37, v39
	v_mov_b32_e32 v34, v32
	v_mov_b32_e32 v35, v33
	s_nop 0
	v_permlane32_swap_b32_e32 v32, v34
	v_permlane32_swap_b32_e32 v33, v35
	s_and_saveexec_b64 s[64:65], vcc
	s_cbranch_execz .LBB0_358
	v_pk_add_f32 v[32:33], v[32:33], v[34:35]
	v_lshlrev_b64 v[34:35], 7, v[48:49]
	v_lshl_add_u64 v[34:35], s[36:37], 0, v[34:35]
	v_lshl_add_u64 v[34:35], s[60:61], 3, v[34:35]
	s_lshl_b32 s4, s31, 3
	v_lshl_add_u64 v[34:35], v[34:35], 0, s[4:5]
	global_store_dwordx2 v[34:35], v[32:33], off
.LBB0_358:
	s_or_b64 exec, exec, s[64:65]
	v_add_u32_e32 v32, 0xa0, v144
	v_ashrrev_i32_e32 v33, 31, v32
	v_lshlrev_b64 v[34:35], 10, v[32:33]
	v_lshl_add_u64 v[42:43], v[34:35], 0, s[62:63]
	v_lshl_add_u64 v[44:45], v[42:43], 0, v[146:147]
	v_lshl_add_u64 v[46:47], v[44:45], 2, s[52:53]
	global_load_dwordx4 v[34:37], v[46:47], off
	global_load_dwordx4 v[38:41], v[46:47], off offset:16
	v_lshl_add_u64 v[44:45], v[44:45], 1, s[72:73]
	v_lshl_add_u64 v[42:43], v[42:43], 0, v[120:121]
	v_lshl_add_u64 v[42:43], v[42:43], 1, s[72:73]
	s_waitcnt vmcnt(1)
	v_pk_fma_f32 v[36:37], v[36:37], s[42:43], v[30:31] op_sel_hi:[1,0,1]
	v_pk_fma_f32 v[34:35], v[34:35], s[42:43], v[28:29] op_sel_hi:[1,0,1]
	s_waitcnt vmcnt(0)
	v_pk_fma_f32 v[40:41], v[40:41], s[42:43], v[26:27] op_sel_hi:[1,0,1]
	v_pk_fma_f32 v[38:39], v[38:39], s[42:43], v[24:25] op_sel_hi:[1,0,1]
	v_cvt_pk_bf16_f32 v24, v34, v35
	v_cvt_pk_bf16_f32 v25, v36, v37
	s_nop 0
	v_cvt_pk_bf16_f32 v26, v38, v39
	v_cvt_pk_bf16_f32 v27, v40, v41
	global_store_dwordx4 v[44:45], v[24:27], off
	global_load_dwordx4 v[24:27], v[46:47], off offset:512
	s_nop 0
	global_load_dwordx4 v[28:31], v[46:47], off offset:528
	v_add_f32_e32 v44, v34, v35
	v_add_f32_e32 v45, v36, v37
	v_add_f32_e32 v46, v38, v39
	v_add_f32_e32 v47, v40, v41
	v_mul_f32_e32 v35, v35, v35
	v_mul_f32_e32 v37, v37, v37
	v_mul_f32_e32 v39, v39, v39
	v_mul_f32_e32 v41, v41, v41
	v_add_f32_e32 v44, v44, v45
	v_add_f32_e32 v45, v46, v47
	v_fmac_f32_e32 v35, v34, v34
	v_fmac_f32_e32 v37, v36, v36
	v_fmac_f32_e32 v39, v38, v38
	v_fmac_f32_e32 v41, v40, v40
	v_add_f32_e32 v34, v44, v45
	v_add_f32_e32 v35, v35, v37
	v_add_f32_e32 v36, v39, v41
	v_add_f32_e32 v34, 0, v34
	v_add_f32_e32 v35, v35, v36
	s_waitcnt vmcnt(1)
	v_pk_fma_f32 v[22:23], v[26:27], s[42:43], v[22:23] op_sel_hi:[1,0,1]
	v_pk_fma_f32 v[20:21], v[24:25], s[42:43], v[20:21] op_sel_hi:[1,0,1]
	s_waitcnt vmcnt(0)
	v_pk_fma_f32 v[24:25], v[30:31], s[42:43], v[18:19] op_sel_hi:[1,0,1]
	v_pk_fma_f32 v[26:27], v[28:29], s[42:43], v[16:17] op_sel_hi:[1,0,1]
	v_cvt_pk_bf16_f32 v16, v20, v21
	v_cvt_pk_bf16_f32 v17, v22, v23
	v_add_f32_e32 v19, v20, v21
	v_cvt_pk_bf16_f32 v18, v26, v27
	v_add_f32_e32 v28, v22, v23
	v_add_f32_e32 v29, v26, v27
	v_add_f32_e32 v30, v24, v25
	v_mul_f32_e32 v21, v21, v21
	v_mul_f32_e32 v23, v23, v23
	v_mul_f32_e32 v27, v27, v27
	v_mul_f32_e32 v31, v25, v25
	v_add_f32_e32 v19, v19, v28
	v_add_f32_e32 v28, v29, v30
	v_fmac_f32_e32 v21, v20, v20
	v_fmac_f32_e32 v23, v22, v22
	v_fmac_f32_e32 v27, v26, v26
	v_fmac_f32_e32 v31, v24, v24
	v_add_f32_e32 v19, v19, v28
	v_add_f32_e32 v20, v21, v23
	v_add_f32_e32 v21, v27, v31
	v_add_f32_e32 v22, v34, v19
	v_add_f32_e32 v19, v20, v21
	v_add_f32_e32 v21, v35, v19
	v_cvt_pk_bf16_f32 v19, v24, v25
	global_store_dwordx4 v[42:43], v[16:19], off
	s_waitcnt lgkmcnt(1)
	s_nop 0
	v_mov_b32_e32 v20, v22
	s_nop 1
	v_permlane16_swap_b32_e32 v22, v20
	v_add_f32_e32 v16, v22, v20
	s_waitcnt lgkmcnt(0)
	v_mov_b32_e32 v23, v21
	s_nop 1
	v_permlane16_swap_b32_e32 v21, v23
	v_add_f32_e32 v17, v21, v23
	v_mov_b32_e32 v18, v16
	v_mov_b32_e32 v19, v17
	s_nop 0
	v_permlane32_swap_b32_e32 v16, v18
	v_permlane32_swap_b32_e32 v17, v19
	s_and_saveexec_b64 s[64:65], vcc
	s_cbranch_execz .LBB0_360
	v_pk_add_f32 v[16:17], v[16:17], v[18:19]
	v_lshlrev_b64 v[18:19], 7, v[32:33]
	v_lshl_add_u64 v[18:19], s[36:37], 0, v[18:19]
	v_lshl_add_u64 v[18:19], s[60:61], 3, v[18:19]
	s_lshl_b32 s4, s31, 3
	v_lshl_add_u64 v[18:19], v[18:19], 0, s[4:5]
	global_store_dwordx2 v[18:19], v[16:17], off
.LBB0_360:
	s_or_b64 exec, exec, s[64:65]
	v_add_u32_e32 v16, 0xb0, v144
	v_ashrrev_i32_e32 v17, 31, v16
	v_lshlrev_b64 v[18:19], 10, v[16:17]
	v_lshl_add_u64 v[26:27], v[18:19], 0, s[62:63]
	v_lshl_add_u64 v[28:29], v[26:27], 0, v[146:147]
	v_lshl_add_u64 v[30:31], v[28:29], 2, s[52:53]
	global_load_dwordx4 v[18:21], v[30:31], off
	global_load_dwordx4 v[22:25], v[30:31], off offset:16
	v_lshl_add_u64 v[28:29], v[28:29], 1, s[72:73]
	v_lshl_add_u64 v[26:27], v[26:27], 0, v[120:121]
	v_lshl_add_u64 v[26:27], v[26:27], 1, s[72:73]
	s_waitcnt vmcnt(1)
	v_pk_fma_f32 v[20:21], v[20:21], s[42:43], v[14:15] op_sel_hi:[1,0,1]
	v_pk_fma_f32 v[18:19], v[18:19], s[42:43], v[12:13] op_sel_hi:[1,0,1]
	s_waitcnt vmcnt(0)
	v_pk_fma_f32 v[24:25], v[24:25], s[42:43], v[10:11] op_sel_hi:[1,0,1]
	v_pk_fma_f32 v[22:23], v[22:23], s[42:43], v[8:9] op_sel_hi:[1,0,1]
	v_cvt_pk_bf16_f32 v8, v18, v19
	v_cvt_pk_bf16_f32 v9, v20, v21
	s_nop 0
	v_cvt_pk_bf16_f32 v10, v22, v23
	v_cvt_pk_bf16_f32 v11, v24, v25
	global_store_dwordx4 v[28:29], v[8:11], off
	global_load_dwordx4 v[8:11], v[30:31], off offset:512
	s_nop 0
	global_load_dwordx4 v[12:15], v[30:31], off offset:528
	v_add_f32_e32 v28, v18, v19
	v_add_f32_e32 v29, v20, v21
	v_add_f32_e32 v30, v22, v23
	v_add_f32_e32 v31, v24, v25
	v_mul_f32_e32 v19, v19, v19
	v_mul_f32_e32 v21, v21, v21
	v_mul_f32_e32 v23, v23, v23
	v_mul_f32_e32 v25, v25, v25
	v_add_f32_e32 v28, v28, v29
	v_add_f32_e32 v29, v30, v31
	v_fmac_f32_e32 v19, v18, v18
	v_fmac_f32_e32 v21, v20, v20
	v_fmac_f32_e32 v23, v22, v22
	v_fmac_f32_e32 v25, v24, v24
	v_add_f32_e32 v18, v28, v29
	v_add_f32_e32 v19, v19, v21
	v_add_f32_e32 v20, v23, v25
	v_add_f32_e32 v18, 0, v18
	v_add_f32_e32 v19, v19, v20
	s_waitcnt vmcnt(1)
	v_pk_fma_f32 v[6:7], v[10:11], s[42:43], v[6:7] op_sel_hi:[1,0,1]
	v_pk_fma_f32 v[4:5], v[8:9], s[42:43], v[4:5] op_sel_hi:[1,0,1]
	s_waitcnt vmcnt(0)
	v_pk_fma_f32 v[8:9], v[14:15], s[42:43], v[2:3] op_sel_hi:[1,0,1]
	v_pk_fma_f32 v[10:11], v[12:13], s[42:43], v[0:1] op_sel_hi:[1,0,1]
	v_cvt_pk_bf16_f32 v0, v4, v5
	v_cvt_pk_bf16_f32 v1, v6, v7
	v_add_f32_e32 v3, v4, v5
	v_cvt_pk_bf16_f32 v2, v10, v11
	v_add_f32_e32 v12, v6, v7
	v_add_f32_e32 v13, v10, v11
	v_add_f32_e32 v14, v8, v9
	v_mul_f32_e32 v5, v5, v5
	v_mul_f32_e32 v7, v7, v7
	v_mul_f32_e32 v11, v11, v11
	v_mul_f32_e32 v15, v9, v9
	v_add_f32_e32 v3, v3, v12
	v_add_f32_e32 v12, v13, v14
	v_fmac_f32_e32 v5, v4, v4
	v_fmac_f32_e32 v7, v6, v6
	v_fmac_f32_e32 v11, v10, v10
	v_fmac_f32_e32 v15, v8, v8
	v_add_f32_e32 v3, v3, v12
	v_add_f32_e32 v4, v5, v7
	v_add_f32_e32 v5, v11, v15
	v_add_f32_e32 v6, v18, v3
	v_add_f32_e32 v3, v4, v5
	v_add_f32_e32 v5, v19, v3
	v_cvt_pk_bf16_f32 v3, v8, v9
	global_store_dwordx4 v[26:27], v[0:3], off
	s_waitcnt lgkmcnt(1)
	s_nop 0
	v_mov_b32_e32 v4, v6
	s_nop 1
	v_permlane16_swap_b32_e32 v6, v4
	v_add_f32_e32 v0, v6, v4
	s_waitcnt lgkmcnt(0)
	v_mov_b32_e32 v7, v5
	s_nop 1
	v_permlane16_swap_b32_e32 v5, v7
	v_add_f32_e32 v1, v5, v7
	v_mov_b32_e32 v2, v0
	v_mov_b32_e32 v3, v1
	s_nop 0
	v_permlane32_swap_b32_e32 v0, v2
	v_permlane32_swap_b32_e32 v1, v3
	s_and_saveexec_b64 s[62:63], vcc
	s_cbranch_execz .LBB0_362
	v_pk_add_f32 v[0:1], v[0:1], v[2:3]
	v_lshlrev_b64 v[2:3], 7, v[16:17]
	v_lshl_add_u64 v[2:3], s[36:37], 0, v[2:3]
	v_lshl_add_u64 v[2:3], s[60:61], 3, v[2:3]
	s_lshl_b32 s4, s31, 3
	v_lshl_add_u64 v[2:3], v[2:3], 0, s[4:5]
	global_store_dwordx2 v[2:3], v[0:1], off

.LBB0_525:
	s_lshl_b32 s27, s4, 8
	s_lshl_b32 s86, s82, 8
	s_add_i32 s27, s27, s55
	s_ashr_i32 s87, s86, 31
	s_cmp_gt_i32 s82, 5
	v_mbcnt_lo_u32_b32 v128, -1, 0
	v_mbcnt_hi_u32_b32 v128, -1, v128
	s_cselect_b64 s[6:7], -1, 0
	v_and_b32_e32 v167, 15, v128
	v_ashrrev_i32_e32 v129, 4, v128
	s_cmp_gt_i32 s82, 3
	v_lshlrev_b32_e32 v150, 3, v129
	v_cmp_gt_u32_e64 s[4:5], 16, v128
	v_lshlrev_b32_e32 v152, 2, v129
	s_cselect_b64 s[84:85], -1, 0
	v_or_b32_e32 v154, s27, v167
	s_ashr_i32 s69, s27, 9
	v_mov_b64_e32 v[128:129], s[72:73]
	v_add_u32_e32 v148, s42, v150
	s_and_b32 s88, s69, -8
	v_mad_i64_i32 v[128:129], s[8:9], v154, s35, v[128:129]
	v_ashrrev_i32_e32 v149, 31, v148
	v_ashrrev_i32_e32 v153, 31, v152
	v_ashrrev_i32_e32 v151, 31, v150
	v_ashrrev_i32_e32 v155, 31, v154
	v_lshl_add_u64 v[156:157], s[86:87], 1, v[128:129]
	s_mov_b64 s[94:95], -1
	s_mov_b64 s[90:91], 0
	s_cmp_lt_i32 s82, 1
	s_mov_b64 s[92:93], 0
	s_cbranch_scc1 .LBB0_533
	s_cmp_eq_u32 s82, 1
	s_mov_b64 s[92:93], -1
	s_cbranch_scc0 .LBB0_532
	v_cvt_pk_bf16_f32 v128, v124, v125
	v_cvt_pk_bf16_f32 v129, v126, v127
	v_lshl_add_u64 v[158:159], v[148:149], 1, v[156:157]
	v_cvt_pk_bf16_f32 v130, v120, v121
	v_cvt_pk_bf16_f32 v131, v122, v123
	global_store_dwordx4 v[158:159], v[128:131], off
	s_nop 1
	v_mul_f32_e32 v128, v125, v125
	v_mul_f32_e32 v129, v127, v127
	v_fmac_f32_e32 v128, v124, v124
	v_fmac_f32_e32 v129, v126, v126
	v_add_f32_e32 v128, v128, v129
	v_mul_f32_e32 v129, v121, v121
	v_mul_f32_e32 v130, v123, v123
	v_fmac_f32_e32 v129, v120, v120
	v_fmac_f32_e32 v130, v122, v122
	v_add_f32_e32 v129, v129, v130
	v_add_f32_e32 v128, v128, v129
	s_waitcnt lgkmcnt(0)
	v_mov_b32_e32 v129, v128
	s_nop 1
	v_permlane16_swap_b32_e32 v128, v129
	v_add_f32_e32 v128, v128, v129
	v_mov_b32_e32 v129, v128
	s_nop 1
	v_permlane32_swap_b32_e32 v128, v129
	s_and_saveexec_b64 s[92:93], s[4:5]
	s_cbranch_execz .LBB0_529
	v_lshl_add_u64 v[130:131], v[154:155], 4, s[64:65]
	v_add_f32_e32 v128, v128, v129
	global_store_dword v[130:131], v128, off

.LBB0_538:
	s_andn2_b64 vcc, exec, s[90:91]
	s_cbranch_vccnz .LBB0_543
	v_mul_f32_e32 v128, v124, v124
	v_mul_f32_e32 v129, v120, v120
	v_mul_f32_e32 v130, v125, v125
	v_mul_f32_e32 v131, v121, v121
	v_mul_f32_e32 v158, v126, v126
	v_mul_f32_e32 v159, v122, v122
	v_mul_f32_e32 v160, v127, v127
	v_mul_f32_e32 v161, v123, v123
	v_fmaak_f32 v128, v255, v128, 0xc0135761
	v_fmaak_f32 v129, v255, v129, 0xc0135761
	v_fmaak_f32 v130, v255, v130, 0xc0135761
	v_fmaak_f32 v131, v255, v131, 0xc0135761
	v_fmaak_f32 v158, v255, v158, 0xc0135761
	v_fmaak_f32 v159, v255, v159, 0xc0135761
	v_fmaak_f32 v160, v255, v160, 0xc0135761
	v_fmaak_f32 v161, v255, v161, 0xc0135761
	v_mul_f32_e32 v128, v124, v128
	v_mul_f32_e32 v129, v120, v129
	v_mul_f32_e32 v130, v125, v130
	v_mul_f32_e32 v131, v121, v131
	v_mul_f32_e32 v158, v126, v158
	v_mul_f32_e32 v159, v122, v159
	v_mul_f32_e32 v160, v127, v160
	v_mul_f32_e32 v161, v123, v161
	v_exp_f32_e32 v128, v128
	v_exp_f32_e32 v129, v129
	v_exp_f32_e32 v130, v130
	v_exp_f32_e32 v131, v131
	v_exp_f32_e32 v158, v158
	v_exp_f32_e32 v159, v159
	v_exp_f32_e32 v160, v160
	v_exp_f32_e32 v161, v161
	v_add_f32_e32 v128, 1.0, v128
	v_add_f32_e32 v129, 1.0, v129
	v_add_f32_e32 v130, 1.0, v130
	v_add_f32_e32 v131, 1.0, v131
	v_add_f32_e32 v158, 1.0, v158
	v_add_f32_e32 v159, 1.0, v159
	v_add_f32_e32 v160, 1.0, v160
	v_add_f32_e32 v161, 1.0, v161
	v_rcp_f32_e32 v128, v128
	v_rcp_f32_e32 v129, v129
	v_rcp_f32_e32 v130, v130
	v_rcp_f32_e32 v131, v131
	v_rcp_f32_e32 v158, v158
	v_rcp_f32_e32 v159, v159
	v_rcp_f32_e32 v160, v160
	v_rcp_f32_e32 v161, v161
	v_mul_f32_e32 v128, v124, v128
	v_mul_f32_e32 v129, v120, v129
	v_mul_f32_e32 v130, v125, v130
	v_mul_f32_e32 v131, v121, v131
	v_mul_f32_e32 v158, v126, v158
	v_mul_f32_e32 v159, v122, v159
	v_mul_f32_e32 v160, v127, v160
	v_mul_f32_e32 v161, v123, v161
	v_cvt_pk_bf16_f32 v168, v128, v130
	v_cvt_pk_bf16_f32 v169, v158, v160
	v_cvt_pk_bf16_f32 v170, v129, v131
	v_cvt_pk_bf16_f32 v171, v159, v161
	v_lshl_add_u64 v[180:181], v[148:149], 1, v[156:157]
	global_store_dwordx4 v[180:181], v[168:171], off
	v_mul_f32_e32 v172, v118, v118
	v_mul_f32_e32 v173, v114, v114
	v_mul_f32_e32 v168, v116, v116
	v_mul_f32_e32 v169, v112, v112
	v_mul_f32_e32 v170, v117, v117
	v_mul_f32_e32 v171, v113, v113
	v_mul_f32_e32 v174, v119, v119
	v_mul_f32_e32 v175, v115, v115
	v_fmaak_f32 v168, v255, v168, 0xc0135761
	v_fmaak_f32 v169, v255, v169, 0xc0135761
	v_fmaak_f32 v170, v255, v170, 0xc0135761
	v_fmaak_f32 v171, v255, v171, 0xc0135761
	v_fmaak_f32 v172, v255, v172, 0xc0135761
	v_fmaak_f32 v173, v255, v173, 0xc0135761
	v_fmaak_f32 v174, v255, v174, 0xc0135761
	v_fmaak_f32 v175, v255, v175, 0xc0135761
	v_mul_f32_e32 v168, v116, v168
	v_mul_f32_e32 v169, v112, v169
	v_mul_f32_e32 v170, v117, v170
	v_mul_f32_e32 v171, v113, v171
	v_mul_f32_e32 v172, v118, v172
	v_mul_f32_e32 v173, v114, v173
	v_mul_f32_e32 v174, v119, v174
	v_mul_f32_e32 v175, v115, v175
	v_exp_f32_e32 v168, v168
	v_exp_f32_e32 v169, v169
	v_exp_f32_e32 v170, v170
	v_exp_f32_e32 v171, v171
	v_exp_f32_e32 v172, v172
	v_exp_f32_e32 v173, v173
	v_exp_f32_e32 v174, v174
	v_exp_f32_e32 v175, v175
	v_add_f32_e32 v168, 1.0, v168
	v_add_f32_e32 v169, 1.0, v169
	v_add_f32_e32 v170, 1.0, v170
	v_add_f32_e32 v171, 1.0, v171
	v_add_f32_e32 v172, 1.0, v172
	v_add_f32_e32 v173, 1.0, v173
	v_add_f32_e32 v174, 1.0, v174
	v_add_f32_e32 v175, 1.0, v175
	v_rcp_f32_e32 v168, v168
	v_rcp_f32_e32 v169, v169
	v_rcp_f32_e32 v170, v170
	v_rcp_f32_e32 v171, v171
	v_rcp_f32_e32 v172, v172
	v_rcp_f32_e32 v173, v173
	v_rcp_f32_e32 v174, v174
	v_rcp_f32_e32 v175, v175
	v_mul_f32_e32 v168, v116, v168
	v_mul_f32_e32 v169, v112, v169
	v_mul_f32_e32 v170, v117, v170
	v_mul_f32_e32 v171, v113, v171
	v_mul_f32_e32 v172, v118, v172
	v_mul_f32_e32 v173, v114, v173
	v_mul_f32_e32 v174, v119, v174
	v_mul_f32_e32 v175, v115, v175
	s_andn2_b64 vcc, exec, s[84:85]
	v_cvt_pk_bf16_f32 v176, v168, v170
	v_cvt_pk_bf16_f32 v177, v172, v174
	v_cvt_pk_bf16_f32 v178, v169, v171
	v_cvt_pk_bf16_f32 v179, v173, v175
	global_store_dwordx4 v[180:181], v[176:179], off offset:256
	s_cbranch_vccnz .LBB0_543
	s_nop 0
	v_mul_f32_e32 v176, v130, v130
	v_mul_f32_e32 v177, v160, v160
	v_fmac_f32_e32 v176, v128, v128
	v_fmac_f32_e32 v177, v158, v158
	v_add_f32_e32 v176, v176, v177
	v_mul_f32_e32 v177, v131, v131
	v_mul_f32_e32 v178, v161, v161
	v_fmac_f32_e32 v177, v129, v129
	v_fmac_f32_e32 v178, v159, v159
	v_add_f32_e32 v128, v128, v130
	v_add_f32_e32 v130, v158, v160
	v_add_f32_e32 v177, v177, v178
	v_add_f32_e32 v128, v128, v130
	v_add_f32_e32 v129, v129, v131
	v_add_f32_e32 v130, v159, v161
	v_add_f32_e32 v176, v176, v177
	v_mul_f32_e32 v177, v170, v170
	v_mul_f32_e32 v178, v174, v174
	v_add_f32_e32 v129, v129, v130
	v_fmac_f32_e32 v177, v168, v168
	v_fmac_f32_e32 v178, v172, v172
	v_add_f32_e32 v128, v128, v129
	v_add_f32_e32 v129, v168, v170
	v_add_f32_e32 v130, v172, v174
	v_add_f32_e32 v177, v177, v178
	v_mul_f32_e32 v178, v171, v171
	v_mul_f32_e32 v179, v175, v175
	v_add_f32_e32 v129, v129, v130
	v_add_f32_e32 v130, v169, v171
	v_add_f32_e32 v131, v173, v175
	v_fmac_f32_e32 v178, v169, v169
	v_fmac_f32_e32 v179, v173, v173
	v_add_f32_e32 v130, v130, v131
	v_add_f32_e32 v129, v129, v130
	v_add_f32_e32 v130, v178, v179
	v_add_f32_e32 v128, 0, v128
	v_add_f32_e32 v130, v177, v130
	v_add_f32_e32 v128, v128, v129
	v_add_f32_e32 v131, v176, v130
	s_waitcnt lgkmcnt(0)
	v_mov_b32_e32 v129, v128
	s_nop 1
	v_permlane16_swap_b32_e32 v128, v129
	v_add_f32_e32 v128, v128, v129
	v_mov_b32_e32 v158, v131
	s_nop 1
	v_permlane16_swap_b32_e32 v131, v158
	v_add_f32_e32 v129, v131, v158
	v_mov_b32_e32 v130, v128
	v_mov_b32_e32 v131, v129
	s_nop 0
	v_permlane32_swap_b32_e32 v128, v130
	v_permlane32_swap_b32_e32 v129, v131
	s_and_saveexec_b64 s[90:91], s[4:5]
	s_cbranch_execz .LBB0_542
	v_pk_add_f32 v[128:129], v[128:129], v[130:131]
	v_lshlrev_b64 v[130:131], 6, v[154:155]
	v_lshl_add_u64 v[130:131], s[18:19], 0, v[130:131]
	v_lshl_add_u64 v[130:131], s[52:53], 3, v[130:131]
	s_lshl_b32 s8, s40, 3
	s_mov_b32 s9, s53
	v_lshl_add_u64 v[130:131], v[130:131], 0, s[8:9]
	global_store_dwordx2 v[130:131], v[128:129], off

.LBB0_544:
	s_andn2_b64 vcc, exec, s[90:91]
	s_cbranch_vccnz .LBB0_548
	v_cvt_pk_bf16_f32 v128, v124, v125
	v_cvt_pk_bf16_f32 v129, v126, v127
	v_cvt_pk_bf16_f32 v130, v120, v121
	v_mul_f32_e32 v125, v125, v125
	v_mul_f32_e32 v121, v121, v121
	v_fmac_f32_e32 v125, v124, v124
	v_mul_f32_e32 v124, v127, v127
	v_fmac_f32_e32 v121, v120, v120
	v_mul_f32_e32 v120, v123, v123
	v_fmac_f32_e32 v124, v126, v126
	v_fmac_f32_e32 v120, v122, v122
	v_lshl_add_u64 v[156:157], v[148:149], 1, v[156:157]
	v_add_f32_e32 v124, v125, v124
	v_add_f32_e32 v120, v121, v120
	v_cvt_pk_bf16_f32 v131, v122, v123
	global_store_dwordx4 v[156:157], v[128:131], off
	v_add_f32_e32 v121, v124, v120
	v_cvt_pk_bf16_f32 v120, v116, v117
	v_mul_f32_e32 v117, v117, v117
	v_fmac_f32_e32 v117, v116, v116
	v_mul_f32_e32 v116, v119, v119
	v_fmac_f32_e32 v116, v118, v118
	v_add_f32_e32 v116, v117, v116
	v_mul_f32_e32 v117, v113, v113
	v_mul_f32_e32 v122, v115, v115
	v_fmac_f32_e32 v117, v112, v112
	v_fmac_f32_e32 v122, v114, v114
	v_add_f32_e32 v117, v117, v122
	v_add_f32_e32 v116, v116, v117
	v_add_f32_e32 v116, v121, v116
	v_cvt_pk_bf16_f32 v121, v118, v119
	v_cvt_pk_bf16_f32 v122, v112, v113
	v_cvt_pk_bf16_f32 v123, v114, v115
	global_store_dwordx4 v[156:157], v[120:123], off offset:256
	s_waitcnt lgkmcnt(0)
	v_mov_b32_e32 v117, v116
	s_nop 1
	v_permlane16_swap_b32_e32 v116, v117
	v_add_f32_e32 v112, v116, v117
	v_mov_b32_e32 v113, v112
	s_nop 1
	v_permlane32_swap_b32_e32 v112, v113
	s_and_saveexec_b64 s[90:91], s[4:5]
	s_cbranch_execz .LBB0_547
	v_lshl_add_u64 v[114:115], v[154:155], 4, s[66:67]
	v_add_f32_e32 v112, v112, v113
	global_store_dword v[114:115], v112, off

.LBB0_548:
	v_or_b32_e32 v116, 16, v154
	v_mov_b64_e32 v[112:113], s[72:73]
	v_mad_i64_i32 v[112:113], s[8:9], v116, s35, v[112:113]
	v_ashrrev_i32_e32 v117, 31, v116
	v_lshl_add_u64 v[118:119], s[86:87], 1, v[112:113]
	s_mov_b64 s[94:95], -1
	s_mov_b64 s[90:91], 0
	s_cmp_lt_i32 s82, 1
	s_mov_b64 s[92:93], 0
	s_cbranch_scc1 .LBB0_565
	s_cmp_eq_u32 s82, 1
	s_mov_b64 s[92:93], -1
	s_cbranch_scc0 .LBB0_555
	v_cvt_pk_bf16_f32 v112, v108, v109
	v_cvt_pk_bf16_f32 v113, v110, v111
	v_lshl_add_u64 v[120:121], v[148:149], 1, v[118:119]
	v_cvt_pk_bf16_f32 v114, v104, v105
	v_cvt_pk_bf16_f32 v115, v106, v107
	global_store_dwordx4 v[120:121], v[112:115], off
	s_nop 1
	v_mul_f32_e32 v112, v109, v109
	v_mul_f32_e32 v113, v111, v111
	v_fmac_f32_e32 v112, v108, v108
	v_fmac_f32_e32 v113, v110, v110
	v_add_f32_e32 v112, v112, v113
	v_mul_f32_e32 v113, v105, v105
	v_mul_f32_e32 v114, v107, v107
	v_fmac_f32_e32 v113, v104, v104
	v_fmac_f32_e32 v114, v106, v106
	v_add_f32_e32 v113, v113, v114
	v_add_f32_e32 v112, v112, v113
	s_waitcnt lgkmcnt(0)
	v_mov_b32_e32 v113, v112
	s_nop 1
	v_permlane16_swap_b32_e32 v112, v113
	v_add_f32_e32 v112, v112, v113
	v_mov_b32_e32 v113, v112
	s_nop 1
	v_permlane32_swap_b32_e32 v112, v113
	s_and_saveexec_b64 s[92:93], s[4:5]
	s_cbranch_execz .LBB0_552
	v_lshl_add_u64 v[114:115], v[116:117], 4, s[64:65]
	v_add_f32_e32 v112, v112, v113
	global_store_dword v[114:115], v112, off

.LBB0_559:
	s_andn2_b64 vcc, exec, s[90:91]
	s_cbranch_vccnz .LBB0_564
	v_mul_f32_e32 v112, v108, v108
	v_mul_f32_e32 v113, v104, v104
	v_mul_f32_e32 v114, v109, v109
	v_mul_f32_e32 v115, v105, v105
	v_mul_f32_e32 v120, v110, v110
	v_mul_f32_e32 v121, v106, v106
	v_mul_f32_e32 v122, v111, v111
	v_mul_f32_e32 v123, v107, v107
	v_fmaak_f32 v112, v255, v112, 0xc0135761
	v_fmaak_f32 v113, v255, v113, 0xc0135761
	v_fmaak_f32 v114, v255, v114, 0xc0135761
	v_fmaak_f32 v115, v255, v115, 0xc0135761
	v_fmaak_f32 v120, v255, v120, 0xc0135761
	v_fmaak_f32 v121, v255, v121, 0xc0135761
	v_fmaak_f32 v122, v255, v122, 0xc0135761
	v_fmaak_f32 v123, v255, v123, 0xc0135761
	v_mul_f32_e32 v112, v108, v112
	v_mul_f32_e32 v113, v104, v113
	v_mul_f32_e32 v114, v109, v114
	v_mul_f32_e32 v115, v105, v115
	v_mul_f32_e32 v120, v110, v120
	v_mul_f32_e32 v121, v106, v121
	v_mul_f32_e32 v122, v111, v122
	v_mul_f32_e32 v123, v107, v123
	v_exp_f32_e32 v112, v112
	v_exp_f32_e32 v113, v113
	v_exp_f32_e32 v114, v114
	v_exp_f32_e32 v115, v115
	v_exp_f32_e32 v120, v120
	v_exp_f32_e32 v121, v121
	v_exp_f32_e32 v122, v122
	v_exp_f32_e32 v123, v123
	v_add_f32_e32 v112, 1.0, v112
	v_add_f32_e32 v113, 1.0, v113
	v_add_f32_e32 v114, 1.0, v114
	v_add_f32_e32 v115, 1.0, v115
	v_add_f32_e32 v120, 1.0, v120
	v_add_f32_e32 v121, 1.0, v121
	v_add_f32_e32 v122, 1.0, v122
	v_add_f32_e32 v123, 1.0, v123
	v_rcp_f32_e32 v112, v112
	v_rcp_f32_e32 v113, v113
	v_rcp_f32_e32 v114, v114
	v_rcp_f32_e32 v115, v115
	v_rcp_f32_e32 v120, v120
	v_rcp_f32_e32 v121, v121
	v_rcp_f32_e32 v122, v122
	v_rcp_f32_e32 v123, v123
	v_mul_f32_e32 v112, v108, v112
	v_mul_f32_e32 v113, v104, v113
	v_mul_f32_e32 v114, v109, v114
	v_mul_f32_e32 v115, v105, v115
	v_mul_f32_e32 v120, v110, v120
	v_mul_f32_e32 v121, v106, v121
	v_mul_f32_e32 v122, v111, v122
	v_mul_f32_e32 v123, v107, v123
	v_cvt_pk_bf16_f32 v124, v112, v114
	v_cvt_pk_bf16_f32 v125, v120, v122
	v_cvt_pk_bf16_f32 v126, v113, v115
	v_cvt_pk_bf16_f32 v127, v121, v123
	v_lshl_add_u64 v[160:161], v[148:149], 1, v[118:119]
	global_store_dwordx4 v[160:161], v[124:127], off
	v_mul_f32_e32 v128, v102, v102
	v_mul_f32_e32 v129, v98, v98
	v_mul_f32_e32 v124, v100, v100
	v_mul_f32_e32 v125, v96, v96
	v_mul_f32_e32 v126, v101, v101
	v_mul_f32_e32 v127, v97, v97
	v_mul_f32_e32 v130, v103, v103
	v_mul_f32_e32 v131, v99, v99
	v_fmaak_f32 v124, v255, v124, 0xc0135761
	v_fmaak_f32 v125, v255, v125, 0xc0135761
	v_fmaak_f32 v126, v255, v126, 0xc0135761
	v_fmaak_f32 v127, v255, v127, 0xc0135761
	v_fmaak_f32 v128, v255, v128, 0xc0135761
	v_fmaak_f32 v129, v255, v129, 0xc0135761
	v_fmaak_f32 v130, v255, v130, 0xc0135761
	v_fmaak_f32 v131, v255, v131, 0xc0135761
	v_mul_f32_e32 v124, v100, v124
	v_mul_f32_e32 v125, v96, v125
	v_mul_f32_e32 v126, v101, v126
	v_mul_f32_e32 v127, v97, v127
	v_mul_f32_e32 v128, v102, v128
	v_mul_f32_e32 v129, v98, v129
	v_mul_f32_e32 v130, v103, v130
	v_mul_f32_e32 v131, v99, v131
	v_exp_f32_e32 v124, v124
	v_exp_f32_e32 v125, v125
	v_exp_f32_e32 v126, v126
	v_exp_f32_e32 v127, v127
	v_exp_f32_e32 v128, v128
	v_exp_f32_e32 v129, v129
	v_exp_f32_e32 v130, v130
	v_exp_f32_e32 v131, v131
	v_add_f32_e32 v124, 1.0, v124
	v_add_f32_e32 v125, 1.0, v125
	v_add_f32_e32 v126, 1.0, v126
	v_add_f32_e32 v127, 1.0, v127
	v_add_f32_e32 v128, 1.0, v128
	v_add_f32_e32 v129, 1.0, v129
	v_add_f32_e32 v130, 1.0, v130
	v_add_f32_e32 v131, 1.0, v131
	v_rcp_f32_e32 v124, v124
	v_rcp_f32_e32 v125, v125
	v_rcp_f32_e32 v126, v126
	v_rcp_f32_e32 v127, v127
	v_rcp_f32_e32 v128, v128
	v_rcp_f32_e32 v129, v129
	v_rcp_f32_e32 v130, v130
	v_rcp_f32_e32 v131, v131
	v_mul_f32_e32 v124, v100, v124
	v_mul_f32_e32 v125, v96, v125
	v_mul_f32_e32 v126, v101, v126
	v_mul_f32_e32 v127, v97, v127
	v_mul_f32_e32 v128, v102, v128
	v_mul_f32_e32 v129, v98, v129
	v_mul_f32_e32 v130, v103, v130
	v_mul_f32_e32 v131, v99, v131
	s_andn2_b64 vcc, exec, s[84:85]
	v_cvt_pk_bf16_f32 v156, v124, v126
	v_cvt_pk_bf16_f32 v157, v128, v130
	v_cvt_pk_bf16_f32 v158, v125, v127
	v_cvt_pk_bf16_f32 v159, v129, v131
	global_store_dwordx4 v[160:161], v[156:159], off offset:256
	s_cbranch_vccnz .LBB0_564
	v_mul_f32_e32 v155, v114, v114
	v_mul_f32_e32 v156, v122, v122
	v_fmac_f32_e32 v155, v112, v112
	v_fmac_f32_e32 v156, v120, v120
	v_add_f32_e32 v155, v155, v156
	v_mul_f32_e32 v156, v115, v115
	v_mul_f32_e32 v157, v123, v123
	v_fmac_f32_e32 v156, v113, v113
	v_fmac_f32_e32 v157, v121, v121
	v_add_f32_e32 v112, v112, v114
	v_add_f32_e32 v114, v120, v122
	v_add_f32_e32 v156, v156, v157
	v_add_f32_e32 v112, v112, v114
	v_add_f32_e32 v113, v113, v115
	v_add_f32_e32 v114, v121, v123
	v_add_f32_e32 v155, v155, v156
	v_mul_f32_e32 v156, v126, v126
	v_mul_f32_e32 v157, v130, v130
	v_add_f32_e32 v113, v113, v114
	v_fmac_f32_e32 v156, v124, v124
	v_fmac_f32_e32 v157, v128, v128
	v_add_f32_e32 v112, v112, v113
	v_add_f32_e32 v113, v124, v126
	v_add_f32_e32 v114, v128, v130
	v_add_f32_e32 v156, v156, v157
	v_mul_f32_e32 v157, v127, v127
	v_mul_f32_e32 v158, v131, v131
	v_add_f32_e32 v113, v113, v114
	v_add_f32_e32 v114, v125, v127
	v_add_f32_e32 v115, v129, v131
	v_fmac_f32_e32 v157, v125, v125
	v_fmac_f32_e32 v158, v129, v129
	v_add_f32_e32 v114, v114, v115
	v_add_f32_e32 v113, v113, v114
	v_add_f32_e32 v114, v157, v158
	v_add_f32_e32 v112, 0, v112
	v_add_f32_e32 v114, v156, v114
	v_add_f32_e32 v112, v112, v113
	v_add_f32_e32 v115, v155, v114
	s_waitcnt lgkmcnt(0)
	v_mov_b32_e32 v113, v112
	s_nop 1
	v_permlane16_swap_b32_e32 v112, v113
	v_add_f32_e32 v112, v112, v113
	v_mov_b32_e32 v120, v115
	s_nop 1
	v_permlane16_swap_b32_e32 v115, v120
	v_add_f32_e32 v113, v115, v120
	v_mov_b32_e32 v114, v112
	v_mov_b32_e32 v115, v113
	s_nop 0
	v_permlane32_swap_b32_e32 v112, v114
	v_permlane32_swap_b32_e32 v113, v115
	s_and_saveexec_b64 s[90:91], s[4:5]
	s_cbranch_execz .LBB0_563
	v_pk_add_f32 v[112:113], v[112:113], v[114:115]
	v_lshlrev_b64 v[114:115], 6, v[116:117]
	v_lshl_add_u64 v[114:115], s[18:19], 0, v[114:115]
	v_lshl_add_u64 v[114:115], s[52:53], 3, v[114:115]
	s_lshl_b32 s8, s40, 3
	s_mov_b32 s9, s53
	v_lshl_add_u64 v[114:115], v[114:115], 0, s[8:9]
	global_store_dwordx2 v[114:115], v[112:113], off

.LBB0_568:
	v_cvt_pk_bf16_f32 v112, v108, v109
	v_cvt_pk_bf16_f32 v113, v110, v111
	v_cvt_pk_bf16_f32 v114, v104, v105
	v_mul_f32_e32 v109, v109, v109
	v_mul_f32_e32 v105, v105, v105
	v_fmac_f32_e32 v109, v108, v108
	v_mul_f32_e32 v108, v111, v111
	v_fmac_f32_e32 v105, v104, v104
	v_mul_f32_e32 v104, v107, v107
	v_fmac_f32_e32 v108, v110, v110
	v_fmac_f32_e32 v104, v106, v106
	v_lshl_add_u64 v[118:119], v[148:149], 1, v[118:119]
	v_add_f32_e32 v108, v109, v108
	v_add_f32_e32 v104, v105, v104
	v_cvt_pk_bf16_f32 v115, v106, v107
	global_store_dwordx4 v[118:119], v[112:115], off
	v_add_f32_e32 v105, v108, v104
	v_cvt_pk_bf16_f32 v104, v100, v101
	v_mul_f32_e32 v101, v101, v101
	v_fmac_f32_e32 v101, v100, v100
	v_mul_f32_e32 v100, v103, v103
	v_fmac_f32_e32 v100, v102, v102
	v_add_f32_e32 v100, v101, v100
	v_mul_f32_e32 v101, v97, v97
	v_mul_f32_e32 v106, v99, v99
	v_fmac_f32_e32 v101, v96, v96
	v_fmac_f32_e32 v106, v98, v98
	v_add_f32_e32 v101, v101, v106
	v_add_f32_e32 v100, v100, v101
	v_add_f32_e32 v100, v105, v100
	v_cvt_pk_bf16_f32 v105, v102, v103
	v_cvt_pk_bf16_f32 v106, v96, v97
	v_cvt_pk_bf16_f32 v107, v98, v99
	global_store_dwordx4 v[118:119], v[104:107], off offset:256
	s_waitcnt lgkmcnt(0)
	v_mov_b32_e32 v101, v100
	s_nop 1
	v_permlane16_swap_b32_e32 v100, v101
	v_add_f32_e32 v96, v100, v101
	v_mov_b32_e32 v97, v96
	s_nop 1
	v_permlane32_swap_b32_e32 v96, v97
	s_and_saveexec_b64 s[90:91], s[4:5]
	s_cbranch_execz .LBB0_570
	v_lshl_add_u64 v[98:99], v[116:117], 4, s[66:67]
	v_add_f32_e32 v96, v96, v97
	global_store_dword v[98:99], v96, off

.LBB0_571:
	v_or_b32_e32 v100, 32, v154
	v_mov_b64_e32 v[96:97], s[72:73]
	v_mad_i64_i32 v[96:97], s[8:9], v100, s35, v[96:97]
	v_ashrrev_i32_e32 v101, 31, v100
	v_lshl_add_u64 v[102:103], s[86:87], 1, v[96:97]
	s_mov_b64 s[94:95], -1
	s_mov_b64 s[90:91], 0
	s_cmp_lt_i32 s82, 1
	s_mov_b64 s[92:93], 0
	s_cbranch_scc1 .LBB0_588
	s_cmp_eq_u32 s82, 1
	s_mov_b64 s[92:93], -1
	s_cbranch_scc0 .LBB0_578
	v_cvt_pk_bf16_f32 v96, v92, v93
	v_cvt_pk_bf16_f32 v97, v94, v95
	v_lshl_add_u64 v[104:105], v[148:149], 1, v[102:103]
	v_cvt_pk_bf16_f32 v98, v88, v89
	v_cvt_pk_bf16_f32 v99, v90, v91
	global_store_dwordx4 v[104:105], v[96:99], off
	s_nop 1
	v_mul_f32_e32 v96, v93, v93
	v_mul_f32_e32 v97, v95, v95
	v_fmac_f32_e32 v96, v92, v92
	v_fmac_f32_e32 v97, v94, v94
	v_add_f32_e32 v96, v96, v97
	v_mul_f32_e32 v97, v89, v89
	v_mul_f32_e32 v98, v91, v91
	v_fmac_f32_e32 v97, v88, v88
	v_fmac_f32_e32 v98, v90, v90
	v_add_f32_e32 v97, v97, v98
	v_add_f32_e32 v96, v96, v97
	s_waitcnt lgkmcnt(0)
	v_mov_b32_e32 v97, v96
	s_nop 1
	v_permlane16_swap_b32_e32 v96, v97
	v_add_f32_e32 v96, v96, v97
	v_mov_b32_e32 v97, v96
	s_nop 1
	v_permlane32_swap_b32_e32 v96, v97
	s_and_saveexec_b64 s[92:93], s[4:5]
	s_cbranch_execz .LBB0_575
	v_lshl_add_u64 v[98:99], v[100:101], 4, s[64:65]
	v_add_f32_e32 v96, v96, v97
	global_store_dword v[98:99], v96, off

.LBB0_582:
	s_andn2_b64 vcc, exec, s[90:91]
	s_cbranch_vccnz .LBB0_587
	v_mul_f32_e32 v96, v92, v92
	v_mul_f32_e32 v97, v88, v88
	v_mul_f32_e32 v98, v93, v93
	v_mul_f32_e32 v99, v89, v89
	v_mul_f32_e32 v104, v94, v94
	v_mul_f32_e32 v105, v90, v90
	v_mul_f32_e32 v106, v95, v95
	v_mul_f32_e32 v107, v91, v91
	v_fmaak_f32 v96, v255, v96, 0xc0135761
	v_fmaak_f32 v97, v255, v97, 0xc0135761
	v_fmaak_f32 v98, v255, v98, 0xc0135761
	v_fmaak_f32 v99, v255, v99, 0xc0135761
	v_fmaak_f32 v104, v255, v104, 0xc0135761
	v_fmaak_f32 v105, v255, v105, 0xc0135761
	v_fmaak_f32 v106, v255, v106, 0xc0135761
	v_fmaak_f32 v107, v255, v107, 0xc0135761
	v_mul_f32_e32 v96, v92, v96
	v_mul_f32_e32 v97, v88, v97
	v_mul_f32_e32 v98, v93, v98
	v_mul_f32_e32 v99, v89, v99
	v_mul_f32_e32 v104, v94, v104
	v_mul_f32_e32 v105, v90, v105
	v_mul_f32_e32 v106, v95, v106
	v_mul_f32_e32 v107, v91, v107
	v_exp_f32_e32 v96, v96
	v_exp_f32_e32 v97, v97
	v_exp_f32_e32 v98, v98
	v_exp_f32_e32 v99, v99
	v_exp_f32_e32 v104, v104
	v_exp_f32_e32 v105, v105
	v_exp_f32_e32 v106, v106
	v_exp_f32_e32 v107, v107
	v_add_f32_e32 v96, 1.0, v96
	v_add_f32_e32 v97, 1.0, v97
	v_add_f32_e32 v98, 1.0, v98
	v_add_f32_e32 v99, 1.0, v99
	v_add_f32_e32 v104, 1.0, v104
	v_add_f32_e32 v105, 1.0, v105
	v_add_f32_e32 v106, 1.0, v106
	v_add_f32_e32 v107, 1.0, v107
	v_rcp_f32_e32 v96, v96
	v_rcp_f32_e32 v97, v97
	v_rcp_f32_e32 v98, v98
	v_rcp_f32_e32 v99, v99
	v_rcp_f32_e32 v104, v104
	v_rcp_f32_e32 v105, v105
	v_rcp_f32_e32 v106, v106
	v_rcp_f32_e32 v107, v107
	v_mul_f32_e32 v96, v92, v96
	v_mul_f32_e32 v97, v88, v97
	v_mul_f32_e32 v98, v93, v98
	v_mul_f32_e32 v99, v89, v99
	v_mul_f32_e32 v104, v94, v104
	v_mul_f32_e32 v105, v90, v105
	v_mul_f32_e32 v106, v95, v106
	v_mul_f32_e32 v107, v91, v107
	v_cvt_pk_bf16_f32 v108, v96, v98
	v_cvt_pk_bf16_f32 v109, v104, v106
	v_cvt_pk_bf16_f32 v110, v97, v99
	v_cvt_pk_bf16_f32 v111, v105, v107
	v_lshl_add_u64 v[120:121], v[148:149], 1, v[102:103]
	global_store_dwordx4 v[120:121], v[108:111], off
	v_mul_f32_e32 v112, v86, v86
	v_mul_f32_e32 v113, v82, v82
	v_mul_f32_e32 v108, v84, v84
	v_mul_f32_e32 v109, v80, v80
	v_mul_f32_e32 v110, v85, v85
	v_mul_f32_e32 v111, v81, v81
	v_mul_f32_e32 v114, v87, v87
	v_mul_f32_e32 v115, v83, v83
	v_fmaak_f32 v108, v255, v108, 0xc0135761
	v_fmaak_f32 v109, v255, v109, 0xc0135761
	v_fmaak_f32 v110, v255, v110, 0xc0135761
	v_fmaak_f32 v111, v255, v111, 0xc0135761
	v_fmaak_f32 v112, v255, v112, 0xc0135761
	v_fmaak_f32 v113, v255, v113, 0xc0135761
	v_fmaak_f32 v114, v255, v114, 0xc0135761
	v_fmaak_f32 v115, v255, v115, 0xc0135761
	v_mul_f32_e32 v108, v84, v108
	v_mul_f32_e32 v109, v80, v109
	v_mul_f32_e32 v110, v85, v110
	v_mul_f32_e32 v111, v81, v111
	v_mul_f32_e32 v112, v86, v112
	v_mul_f32_e32 v113, v82, v113
	v_mul_f32_e32 v114, v87, v114
	v_mul_f32_e32 v115, v83, v115
	v_exp_f32_e32 v108, v108
	v_exp_f32_e32 v109, v109
	v_exp_f32_e32 v110, v110
	v_exp_f32_e32 v111, v111
	v_exp_f32_e32 v112, v112
	v_exp_f32_e32 v113, v113
	v_exp_f32_e32 v114, v114
	v_exp_f32_e32 v115, v115
	v_add_f32_e32 v108, 1.0, v108
	v_add_f32_e32 v109, 1.0, v109
	v_add_f32_e32 v110, 1.0, v110
	v_add_f32_e32 v111, 1.0, v111
	v_add_f32_e32 v112, 1.0, v112
	v_add_f32_e32 v113, 1.0, v113
	v_add_f32_e32 v114, 1.0, v114
	v_add_f32_e32 v115, 1.0, v115
	v_rcp_f32_e32 v108, v108
	v_rcp_f32_e32 v109, v109
	v_rcp_f32_e32 v110, v110
	v_rcp_f32_e32 v111, v111
	v_rcp_f32_e32 v112, v112
	v_rcp_f32_e32 v113, v113
	v_rcp_f32_e32 v114, v114
	v_rcp_f32_e32 v115, v115
	v_mul_f32_e32 v108, v84, v108
	v_mul_f32_e32 v109, v80, v109
	v_mul_f32_e32 v110, v85, v110
	v_mul_f32_e32 v111, v81, v111
	v_mul_f32_e32 v112, v86, v112
	v_mul_f32_e32 v113, v82, v113
	v_mul_f32_e32 v114, v87, v114
	v_mul_f32_e32 v115, v83, v115
	s_andn2_b64 vcc, exec, s[84:85]
	v_cvt_pk_bf16_f32 v116, v108, v110
	v_cvt_pk_bf16_f32 v117, v112, v114
	v_cvt_pk_bf16_f32 v118, v109, v111
	v_cvt_pk_bf16_f32 v119, v113, v115
	global_store_dwordx4 v[120:121], v[116:119], off offset:256
	s_cbranch_vccnz .LBB0_587
	s_nop 0
	v_mul_f32_e32 v116, v98, v98
	v_mul_f32_e32 v117, v106, v106
	v_fmac_f32_e32 v116, v96, v96
	v_fmac_f32_e32 v117, v104, v104
	v_add_f32_e32 v116, v116, v117
	v_mul_f32_e32 v117, v99, v99
	v_mul_f32_e32 v118, v107, v107
	v_fmac_f32_e32 v117, v97, v97
	v_fmac_f32_e32 v118, v105, v105
	v_add_f32_e32 v96, v96, v98
	v_add_f32_e32 v98, v104, v106
	v_add_f32_e32 v117, v117, v118
	v_add_f32_e32 v96, v96, v98
	v_add_f32_e32 v97, v97, v99
	v_add_f32_e32 v98, v105, v107
	v_add_f32_e32 v116, v116, v117
	v_mul_f32_e32 v117, v110, v110
	v_mul_f32_e32 v118, v114, v114
	v_add_f32_e32 v97, v97, v98
	v_fmac_f32_e32 v117, v108, v108
	v_fmac_f32_e32 v118, v112, v112
	v_add_f32_e32 v96, v96, v97
	v_add_f32_e32 v97, v108, v110
	v_add_f32_e32 v98, v112, v114
	v_add_f32_e32 v117, v117, v118
	v_mul_f32_e32 v118, v111, v111
	v_mul_f32_e32 v119, v115, v115
	v_add_f32_e32 v97, v97, v98
	v_add_f32_e32 v98, v109, v111
	v_add_f32_e32 v99, v113, v115
	v_fmac_f32_e32 v118, v109, v109
	v_fmac_f32_e32 v119, v113, v113
	v_add_f32_e32 v98, v98, v99
	v_add_f32_e32 v97, v97, v98
	v_add_f32_e32 v98, v118, v119
	v_add_f32_e32 v96, 0, v96
	v_add_f32_e32 v98, v117, v98
	v_add_f32_e32 v96, v96, v97
	v_add_f32_e32 v99, v116, v98
	s_waitcnt lgkmcnt(0)
	v_mov_b32_e32 v97, v96
	s_nop 1
	v_permlane16_swap_b32_e32 v96, v97
	v_add_f32_e32 v96, v96, v97
	v_mov_b32_e32 v104, v99
	s_nop 1
	v_permlane16_swap_b32_e32 v99, v104
	v_add_f32_e32 v97, v99, v104
	v_mov_b32_e32 v98, v96
	v_mov_b32_e32 v99, v97
	s_nop 0
	v_permlane32_swap_b32_e32 v96, v98
	v_permlane32_swap_b32_e32 v97, v99
	s_and_saveexec_b64 s[90:91], s[4:5]
	s_cbranch_execz .LBB0_586
	v_pk_add_f32 v[96:97], v[96:97], v[98:99]
	v_lshlrev_b64 v[98:99], 6, v[100:101]
	v_lshl_add_u64 v[98:99], s[18:19], 0, v[98:99]
	v_lshl_add_u64 v[98:99], s[52:53], 3, v[98:99]
	s_lshl_b32 s8, s40, 3
	s_mov_b32 s9, s53
	v_lshl_add_u64 v[98:99], v[98:99], 0, s[8:9]
	global_store_dwordx2 v[98:99], v[96:97], off

.LBB0_591:
	v_cvt_pk_bf16_f32 v96, v92, v93
	v_cvt_pk_bf16_f32 v97, v94, v95
	v_cvt_pk_bf16_f32 v98, v88, v89
	v_mul_f32_e32 v93, v93, v93
	v_mul_f32_e32 v89, v89, v89
	v_fmac_f32_e32 v93, v92, v92
	v_mul_f32_e32 v92, v95, v95
	v_fmac_f32_e32 v89, v88, v88
	v_mul_f32_e32 v88, v91, v91
	v_fmac_f32_e32 v92, v94, v94
	v_fmac_f32_e32 v88, v90, v90
	v_lshl_add_u64 v[102:103], v[148:149], 1, v[102:103]
	v_add_f32_e32 v92, v93, v92
	v_add_f32_e32 v88, v89, v88
	v_cvt_pk_bf16_f32 v99, v90, v91
	global_store_dwordx4 v[102:103], v[96:99], off
	v_add_f32_e32 v89, v92, v88
	v_cvt_pk_bf16_f32 v88, v84, v85
	v_mul_f32_e32 v85, v85, v85
	v_fmac_f32_e32 v85, v84, v84
	v_mul_f32_e32 v84, v87, v87
	v_fmac_f32_e32 v84, v86, v86
	v_add_f32_e32 v84, v85, v84
	v_mul_f32_e32 v85, v81, v81
	v_mul_f32_e32 v90, v83, v83
	v_fmac_f32_e32 v85, v80, v80
	v_fmac_f32_e32 v90, v82, v82
	v_add_f32_e32 v85, v85, v90
	v_add_f32_e32 v84, v84, v85
	v_add_f32_e32 v84, v89, v84
	v_cvt_pk_bf16_f32 v89, v86, v87
	v_cvt_pk_bf16_f32 v90, v80, v81
	v_cvt_pk_bf16_f32 v91, v82, v83
	global_store_dwordx4 v[102:103], v[88:91], off offset:256
	s_waitcnt lgkmcnt(0)
	v_mov_b32_e32 v85, v84
	s_nop 1
	v_permlane16_swap_b32_e32 v84, v85
	v_add_f32_e32 v80, v84, v85
	v_mov_b32_e32 v81, v80
	s_nop 1
	v_permlane32_swap_b32_e32 v80, v81
	s_and_saveexec_b64 s[90:91], s[4:5]
	s_cbranch_execz .LBB0_593
	v_lshl_add_u64 v[82:83], v[100:101], 4, s[66:67]
	v_add_f32_e32 v80, v80, v81
	global_store_dword v[82:83], v80, off

.LBB0_594:
	v_or_b32_e32 v84, 48, v154
	v_mov_b64_e32 v[80:81], s[72:73]
	v_mad_i64_i32 v[80:81], s[8:9], v84, s35, v[80:81]
	v_ashrrev_i32_e32 v85, 31, v84
	v_lshl_add_u64 v[86:87], s[86:87], 1, v[80:81]
	s_mov_b64 s[94:95], -1
	s_mov_b64 s[90:91], 0
	s_cmp_lt_i32 s82, 1
	s_mov_b64 s[92:93], 0
	s_cbranch_scc1 .LBB0_611
	s_cmp_eq_u32 s82, 1
	s_mov_b64 s[92:93], -1
	s_cbranch_scc0 .LBB0_601
	v_cvt_pk_bf16_f32 v80, v76, v77
	v_cvt_pk_bf16_f32 v81, v78, v79
	v_lshl_add_u64 v[88:89], v[148:149], 1, v[86:87]
	v_cvt_pk_bf16_f32 v82, v72, v73
	v_cvt_pk_bf16_f32 v83, v74, v75
	global_store_dwordx4 v[88:89], v[80:83], off
	s_nop 1
	v_mul_f32_e32 v80, v77, v77
	v_mul_f32_e32 v81, v79, v79
	v_fmac_f32_e32 v80, v76, v76
	v_fmac_f32_e32 v81, v78, v78
	v_add_f32_e32 v80, v80, v81
	v_mul_f32_e32 v81, v73, v73
	v_mul_f32_e32 v82, v75, v75
	v_fmac_f32_e32 v81, v72, v72
	v_fmac_f32_e32 v82, v74, v74
	v_add_f32_e32 v81, v81, v82
	v_add_f32_e32 v80, v80, v81
	s_waitcnt lgkmcnt(0)
	v_mov_b32_e32 v81, v80
	s_nop 1
	v_permlane16_swap_b32_e32 v80, v81
	v_add_f32_e32 v80, v80, v81
	v_mov_b32_e32 v81, v80
	s_nop 1
	v_permlane32_swap_b32_e32 v80, v81
	s_and_saveexec_b64 s[92:93], s[4:5]
	s_cbranch_execz .LBB0_598
	v_lshl_add_u64 v[82:83], v[84:85], 4, s[64:65]
	v_add_f32_e32 v80, v80, v81
	global_store_dword v[82:83], v80, off

.LBB0_605:
	s_andn2_b64 vcc, exec, s[88:89]
	s_cbranch_vccnz .LBB0_610
	v_mul_f32_e32 v80, v76, v76
	v_mul_f32_e32 v81, v72, v72
	v_mul_f32_e32 v82, v77, v77
	v_mul_f32_e32 v83, v73, v73
	v_mul_f32_e32 v88, v78, v78
	v_mul_f32_e32 v89, v74, v74
	v_mul_f32_e32 v90, v79, v79
	v_mul_f32_e32 v91, v75, v75
	v_fmaak_f32 v80, v255, v80, 0xc0135761
	v_fmaak_f32 v81, v255, v81, 0xc0135761
	v_fmaak_f32 v82, v255, v82, 0xc0135761
	v_fmaak_f32 v83, v255, v83, 0xc0135761
	v_fmaak_f32 v88, v255, v88, 0xc0135761
	v_fmaak_f32 v89, v255, v89, 0xc0135761
	v_fmaak_f32 v90, v255, v90, 0xc0135761
	v_fmaak_f32 v91, v255, v91, 0xc0135761
	v_mul_f32_e32 v80, v76, v80
	v_mul_f32_e32 v81, v72, v81
	v_mul_f32_e32 v82, v77, v82
	v_mul_f32_e32 v83, v73, v83
	v_mul_f32_e32 v88, v78, v88
	v_mul_f32_e32 v89, v74, v89
	v_mul_f32_e32 v90, v79, v90
	v_mul_f32_e32 v91, v75, v91
	v_exp_f32_e32 v80, v80
	v_exp_f32_e32 v81, v81
	v_exp_f32_e32 v82, v82
	v_exp_f32_e32 v83, v83
	v_exp_f32_e32 v88, v88
	v_exp_f32_e32 v89, v89
	v_exp_f32_e32 v90, v90
	v_exp_f32_e32 v91, v91
	v_add_f32_e32 v80, 1.0, v80
	v_add_f32_e32 v81, 1.0, v81
	v_add_f32_e32 v82, 1.0, v82
	v_add_f32_e32 v83, 1.0, v83
	v_add_f32_e32 v88, 1.0, v88
	v_add_f32_e32 v89, 1.0, v89
	v_add_f32_e32 v90, 1.0, v90
	v_add_f32_e32 v91, 1.0, v91
	v_rcp_f32_e32 v80, v80
	v_rcp_f32_e32 v81, v81
	v_rcp_f32_e32 v82, v82
	v_rcp_f32_e32 v83, v83
	v_rcp_f32_e32 v88, v88
	v_rcp_f32_e32 v89, v89
	v_rcp_f32_e32 v90, v90
	v_rcp_f32_e32 v91, v91
	v_mul_f32_e32 v80, v76, v80
	v_mul_f32_e32 v81, v72, v81
	v_mul_f32_e32 v82, v77, v82
	v_mul_f32_e32 v83, v73, v83
	v_mul_f32_e32 v88, v78, v88
	v_mul_f32_e32 v89, v74, v89
	v_mul_f32_e32 v90, v79, v90
	v_mul_f32_e32 v91, v75, v91
	v_cvt_pk_bf16_f32 v92, v80, v82
	v_cvt_pk_bf16_f32 v93, v88, v90
	v_cvt_pk_bf16_f32 v94, v81, v83
	v_cvt_pk_bf16_f32 v95, v89, v91
	v_lshl_add_u64 v[104:105], v[148:149], 1, v[86:87]
	global_store_dwordx4 v[104:105], v[92:95], off
	v_mul_f32_e32 v96, v70, v70
	v_mul_f32_e32 v97, v66, v66
	v_mul_f32_e32 v92, v68, v68
	v_mul_f32_e32 v93, v64, v64
	v_mul_f32_e32 v94, v69, v69
	v_mul_f32_e32 v95, v65, v65
	v_mul_f32_e32 v98, v71, v71
	v_mul_f32_e32 v99, v67, v67
	v_fmaak_f32 v92, v255, v92, 0xc0135761
	v_fmaak_f32 v93, v255, v93, 0xc0135761
	v_fmaak_f32 v94, v255, v94, 0xc0135761
	v_fmaak_f32 v95, v255, v95, 0xc0135761
	v_fmaak_f32 v96, v255, v96, 0xc0135761
	v_fmaak_f32 v97, v255, v97, 0xc0135761
	v_fmaak_f32 v98, v255, v98, 0xc0135761
	v_fmaak_f32 v99, v255, v99, 0xc0135761
	v_mul_f32_e32 v92, v68, v92
	v_mul_f32_e32 v93, v64, v93
	v_mul_f32_e32 v94, v69, v94
	v_mul_f32_e32 v95, v65, v95
	v_mul_f32_e32 v96, v70, v96
	v_mul_f32_e32 v97, v66, v97
	v_mul_f32_e32 v98, v71, v98
	v_mul_f32_e32 v99, v67, v99
	v_exp_f32_e32 v92, v92
	v_exp_f32_e32 v93, v93
	v_exp_f32_e32 v94, v94
	v_exp_f32_e32 v95, v95
	v_exp_f32_e32 v96, v96
	v_exp_f32_e32 v97, v97
	v_exp_f32_e32 v98, v98
	v_exp_f32_e32 v99, v99
	v_add_f32_e32 v92, 1.0, v92
	v_add_f32_e32 v93, 1.0, v93
	v_add_f32_e32 v94, 1.0, v94
	v_add_f32_e32 v95, 1.0, v95
	v_add_f32_e32 v96, 1.0, v96
	v_add_f32_e32 v97, 1.0, v97
	v_add_f32_e32 v98, 1.0, v98
	v_add_f32_e32 v99, 1.0, v99
	v_rcp_f32_e32 v92, v92
	v_rcp_f32_e32 v93, v93
	v_rcp_f32_e32 v94, v94
	v_rcp_f32_e32 v95, v95
	v_rcp_f32_e32 v96, v96
	v_rcp_f32_e32 v97, v97
	v_rcp_f32_e32 v98, v98
	v_rcp_f32_e32 v99, v99
	v_mul_f32_e32 v92, v68, v92
	v_mul_f32_e32 v93, v64, v93
	v_mul_f32_e32 v94, v69, v94
	v_mul_f32_e32 v95, v65, v95
	v_mul_f32_e32 v96, v70, v96
	v_mul_f32_e32 v97, v66, v97
	v_mul_f32_e32 v98, v71, v98
	v_mul_f32_e32 v99, v67, v99
	s_andn2_b64 vcc, exec, s[84:85]
	v_cvt_pk_bf16_f32 v100, v92, v94
	v_cvt_pk_bf16_f32 v101, v96, v98
	v_cvt_pk_bf16_f32 v102, v93, v95
	v_cvt_pk_bf16_f32 v103, v97, v99
	global_store_dwordx4 v[104:105], v[100:103], off offset:256
	s_cbranch_vccnz .LBB0_610
	s_nop 0
	v_mul_f32_e32 v100, v82, v82
	v_mul_f32_e32 v101, v90, v90
	v_fmac_f32_e32 v100, v80, v80
	v_fmac_f32_e32 v101, v88, v88
	v_add_f32_e32 v100, v100, v101
	v_mul_f32_e32 v101, v83, v83
	v_mul_f32_e32 v102, v91, v91
	v_fmac_f32_e32 v101, v81, v81
	v_fmac_f32_e32 v102, v89, v89
	v_add_f32_e32 v80, v80, v82
	v_add_f32_e32 v82, v88, v90
	v_add_f32_e32 v101, v101, v102
	v_add_f32_e32 v80, v80, v82
	v_add_f32_e32 v81, v81, v83
	v_add_f32_e32 v82, v89, v91
	v_add_f32_e32 v100, v100, v101
	v_mul_f32_e32 v101, v94, v94
	v_mul_f32_e32 v102, v98, v98
	v_add_f32_e32 v81, v81, v82
	v_fmac_f32_e32 v101, v92, v92
	v_fmac_f32_e32 v102, v96, v96
	v_add_f32_e32 v80, v80, v81
	v_add_f32_e32 v81, v92, v94
	v_add_f32_e32 v82, v96, v98
	v_add_f32_e32 v101, v101, v102
	v_mul_f32_e32 v102, v95, v95
	v_mul_f32_e32 v103, v99, v99
	v_add_f32_e32 v81, v81, v82
	v_add_f32_e32 v82, v93, v95
	v_add_f32_e32 v83, v97, v99
	v_fmac_f32_e32 v102, v93, v93
	v_fmac_f32_e32 v103, v97, v97
	v_add_f32_e32 v82, v82, v83
	v_add_f32_e32 v81, v81, v82
	v_add_f32_e32 v82, v102, v103
	v_add_f32_e32 v80, 0, v80
	v_add_f32_e32 v82, v101, v82
	v_add_f32_e32 v80, v80, v81
	v_add_f32_e32 v83, v100, v82
	s_waitcnt lgkmcnt(0)
	v_mov_b32_e32 v81, v80
	s_nop 1
	v_permlane16_swap_b32_e32 v80, v81
	v_add_f32_e32 v80, v80, v81
	v_mov_b32_e32 v88, v83
	s_nop 1
	v_permlane16_swap_b32_e32 v83, v88
	v_add_f32_e32 v81, v83, v88
	v_mov_b32_e32 v82, v80
	v_mov_b32_e32 v83, v81
	s_nop 0
	v_permlane32_swap_b32_e32 v80, v82
	v_permlane32_swap_b32_e32 v81, v83
	s_and_saveexec_b64 s[88:89], s[4:5]
	s_cbranch_execz .LBB0_609
	v_pk_add_f32 v[80:81], v[80:81], v[82:83]
	v_lshlrev_b64 v[82:83], 6, v[84:85]
	v_lshl_add_u64 v[82:83], s[18:19], 0, v[82:83]
	v_lshl_add_u64 v[82:83], s[52:53], 3, v[82:83]
	s_lshl_b32 s8, s40, 3
	s_mov_b32 s9, s53
	v_lshl_add_u64 v[82:83], v[82:83], 0, s[8:9]
	global_store_dwordx2 v[82:83], v[80:81], off

.LBB0_614:
	v_cvt_pk_bf16_f32 v80, v76, v77
	v_cvt_pk_bf16_f32 v81, v78, v79
	v_cvt_pk_bf16_f32 v82, v72, v73
	v_mul_f32_e32 v77, v77, v77
	v_mul_f32_e32 v73, v73, v73
	v_fmac_f32_e32 v77, v76, v76
	v_mul_f32_e32 v76, v79, v79
	v_fmac_f32_e32 v73, v72, v72
	v_mul_f32_e32 v72, v75, v75
	v_fmac_f32_e32 v76, v78, v78
	v_fmac_f32_e32 v72, v74, v74
	v_lshl_add_u64 v[86:87], v[148:149], 1, v[86:87]
	v_add_f32_e32 v76, v77, v76
	v_add_f32_e32 v72, v73, v72
	v_cvt_pk_bf16_f32 v83, v74, v75
	global_store_dwordx4 v[86:87], v[80:83], off
	v_add_f32_e32 v73, v76, v72
	v_cvt_pk_bf16_f32 v72, v68, v69
	v_mul_f32_e32 v69, v69, v69
	v_fmac_f32_e32 v69, v68, v68
	v_mul_f32_e32 v68, v71, v71
	v_fmac_f32_e32 v68, v70, v70
	v_add_f32_e32 v68, v69, v68
	v_mul_f32_e32 v69, v65, v65
	v_mul_f32_e32 v74, v67, v67
	v_fmac_f32_e32 v69, v64, v64
	v_fmac_f32_e32 v74, v66, v66
	v_add_f32_e32 v69, v69, v74
	v_add_f32_e32 v68, v68, v69
	v_add_f32_e32 v68, v73, v68
	v_cvt_pk_bf16_f32 v73, v70, v71
	v_cvt_pk_bf16_f32 v74, v64, v65
	v_cvt_pk_bf16_f32 v75, v66, v67
	global_store_dwordx4 v[86:87], v[72:75], off offset:256
	s_waitcnt lgkmcnt(0)
	v_mov_b32_e32 v69, v68
	s_nop 1
	v_permlane16_swap_b32_e32 v68, v69
	v_add_f32_e32 v64, v68, v69
	v_mov_b32_e32 v65, v64
	s_nop 1
	v_permlane32_swap_b32_e32 v64, v65
	s_and_saveexec_b64 s[88:89], s[4:5]
	s_cbranch_execz .LBB0_616
	v_lshl_add_u64 v[66:67], v[84:85], 4, s[66:67]
	v_add_f32_e32 v64, v64, v65
	global_store_dword v[66:67], v64, off

.LBB0_617:
	s_addk_i32 s27, 0x80
	v_or_b32_e32 v68, s27, v167
	s_ashr_i32 s27, s27, 9
	v_mov_b64_e32 v[64:65], s[72:73]
	s_and_b32 s88, s27, -8
	v_mad_i64_i32 v[64:65], s[8:9], v68, s35, v[64:65]
	v_ashrrev_i32_e32 v69, 31, v68
	v_lshl_add_u64 v[70:71], s[86:87], 1, v[64:65]
	s_mov_b64 s[94:95], -1
	s_mov_b64 s[90:91], 0
	s_cmp_lt_i32 s82, 1
	s_mov_b64 s[92:93], 0
	s_cbranch_scc1 .LBB0_634
	s_cmp_eq_u32 s82, 1
	s_mov_b64 s[92:93], -1
	s_cbranch_scc0 .LBB0_624
	v_cvt_pk_bf16_f32 v64, v60, v61
	v_cvt_pk_bf16_f32 v65, v62, v63
	v_lshl_add_u64 v[72:73], v[148:149], 1, v[70:71]
	v_cvt_pk_bf16_f32 v66, v56, v57
	v_cvt_pk_bf16_f32 v67, v58, v59
	global_store_dwordx4 v[72:73], v[64:67], off
	s_nop 1
	v_mul_f32_e32 v64, v61, v61
	v_mul_f32_e32 v65, v63, v63
	v_fmac_f32_e32 v64, v60, v60
	v_fmac_f32_e32 v65, v62, v62
	v_add_f32_e32 v64, v64, v65
	v_mul_f32_e32 v65, v57, v57
	v_mul_f32_e32 v66, v59, v59
	v_fmac_f32_e32 v65, v56, v56
	v_fmac_f32_e32 v66, v58, v58
	v_add_f32_e32 v65, v65, v66
	v_add_f32_e32 v64, v64, v65
	s_waitcnt lgkmcnt(0)
	v_mov_b32_e32 v65, v64
	s_nop 1
	v_permlane16_swap_b32_e32 v64, v65
	v_add_f32_e32 v64, v64, v65
	v_mov_b32_e32 v65, v64
	s_nop 1
	v_permlane32_swap_b32_e32 v64, v65
	s_and_saveexec_b64 s[92:93], s[4:5]
	s_cbranch_execz .LBB0_621
	v_lshl_add_u64 v[66:67], v[68:69], 4, s[64:65]
	v_add_f32_e32 v64, v64, v65
	global_store_dword v[66:67], v64, off

.LBB0_628:
	s_andn2_b64 vcc, exec, s[90:91]
	s_cbranch_vccnz .LBB0_633
	v_mul_f32_e32 v64, v60, v60
	v_mul_f32_e32 v65, v56, v56
	v_mul_f32_e32 v66, v61, v61
	v_mul_f32_e32 v67, v57, v57
	v_mul_f32_e32 v72, v62, v62
	v_mul_f32_e32 v73, v58, v58
	v_mul_f32_e32 v74, v63, v63
	v_mul_f32_e32 v75, v59, v59
	v_fmaak_f32 v64, v255, v64, 0xc0135761
	v_fmaak_f32 v65, v255, v65, 0xc0135761
	v_fmaak_f32 v66, v255, v66, 0xc0135761
	v_fmaak_f32 v67, v255, v67, 0xc0135761
	v_fmaak_f32 v72, v255, v72, 0xc0135761
	v_fmaak_f32 v73, v255, v73, 0xc0135761
	v_fmaak_f32 v74, v255, v74, 0xc0135761
	v_fmaak_f32 v75, v255, v75, 0xc0135761
	v_mul_f32_e32 v64, v60, v64
	v_mul_f32_e32 v65, v56, v65
	v_mul_f32_e32 v66, v61, v66
	v_mul_f32_e32 v67, v57, v67
	v_mul_f32_e32 v72, v62, v72
	v_mul_f32_e32 v73, v58, v73
	v_mul_f32_e32 v74, v63, v74
	v_mul_f32_e32 v75, v59, v75
	v_exp_f32_e32 v64, v64
	v_exp_f32_e32 v65, v65
	v_exp_f32_e32 v66, v66
	v_exp_f32_e32 v67, v67
	v_exp_f32_e32 v72, v72
	v_exp_f32_e32 v73, v73
	v_exp_f32_e32 v74, v74
	v_exp_f32_e32 v75, v75
	v_add_f32_e32 v64, 1.0, v64
	v_add_f32_e32 v65, 1.0, v65
	v_add_f32_e32 v66, 1.0, v66
	v_add_f32_e32 v67, 1.0, v67
	v_add_f32_e32 v72, 1.0, v72
	v_add_f32_e32 v73, 1.0, v73
	v_add_f32_e32 v74, 1.0, v74
	v_add_f32_e32 v75, 1.0, v75
	v_rcp_f32_e32 v64, v64
	v_rcp_f32_e32 v65, v65
	v_rcp_f32_e32 v66, v66
	v_rcp_f32_e32 v67, v67
	v_rcp_f32_e32 v72, v72
	v_rcp_f32_e32 v73, v73
	v_rcp_f32_e32 v74, v74
	v_rcp_f32_e32 v75, v75
	v_mul_f32_e32 v64, v60, v64
	v_mul_f32_e32 v65, v56, v65
	v_mul_f32_e32 v66, v61, v66
	v_mul_f32_e32 v67, v57, v67
	v_mul_f32_e32 v72, v62, v72
	v_mul_f32_e32 v73, v58, v73
	v_mul_f32_e32 v74, v63, v74
	v_mul_f32_e32 v75, v59, v75
	v_cvt_pk_bf16_f32 v76, v64, v66
	v_cvt_pk_bf16_f32 v77, v72, v74
	v_cvt_pk_bf16_f32 v78, v65, v67
	v_cvt_pk_bf16_f32 v79, v73, v75
	v_lshl_add_u64 v[88:89], v[148:149], 1, v[70:71]
	global_store_dwordx4 v[88:89], v[76:79], off
	v_mul_f32_e32 v80, v54, v54
	v_mul_f32_e32 v81, v50, v50
	v_mul_f32_e32 v76, v52, v52
	v_mul_f32_e32 v77, v48, v48
	v_mul_f32_e32 v78, v53, v53
	v_mul_f32_e32 v79, v49, v49
	v_mul_f32_e32 v82, v55, v55
	v_mul_f32_e32 v83, v51, v51
	v_fmaak_f32 v76, v255, v76, 0xc0135761
	v_fmaak_f32 v77, v255, v77, 0xc0135761
	v_fmaak_f32 v78, v255, v78, 0xc0135761
	v_fmaak_f32 v79, v255, v79, 0xc0135761
	v_fmaak_f32 v80, v255, v80, 0xc0135761
	v_fmaak_f32 v81, v255, v81, 0xc0135761
	v_fmaak_f32 v82, v255, v82, 0xc0135761
	v_fmaak_f32 v83, v255, v83, 0xc0135761
	v_mul_f32_e32 v76, v52, v76
	v_mul_f32_e32 v77, v48, v77
	v_mul_f32_e32 v78, v53, v78
	v_mul_f32_e32 v79, v49, v79
	v_mul_f32_e32 v80, v54, v80
	v_mul_f32_e32 v81, v50, v81
	v_mul_f32_e32 v82, v55, v82
	v_mul_f32_e32 v83, v51, v83
	v_exp_f32_e32 v76, v76
	v_exp_f32_e32 v77, v77
	v_exp_f32_e32 v78, v78
	v_exp_f32_e32 v79, v79
	v_exp_f32_e32 v80, v80
	v_exp_f32_e32 v81, v81
	v_exp_f32_e32 v82, v82
	v_exp_f32_e32 v83, v83
	v_add_f32_e32 v76, 1.0, v76
	v_add_f32_e32 v77, 1.0, v77
	v_add_f32_e32 v78, 1.0, v78
	v_add_f32_e32 v79, 1.0, v79
	v_add_f32_e32 v80, 1.0, v80
	v_add_f32_e32 v81, 1.0, v81
	v_add_f32_e32 v82, 1.0, v82
	v_add_f32_e32 v83, 1.0, v83
	v_rcp_f32_e32 v76, v76
	v_rcp_f32_e32 v77, v77
	v_rcp_f32_e32 v78, v78
	v_rcp_f32_e32 v79, v79
	v_rcp_f32_e32 v80, v80
	v_rcp_f32_e32 v81, v81
	v_rcp_f32_e32 v82, v82
	v_rcp_f32_e32 v83, v83
	v_mul_f32_e32 v76, v52, v76
	v_mul_f32_e32 v77, v48, v77
	v_mul_f32_e32 v78, v53, v78
	v_mul_f32_e32 v79, v49, v79
	v_mul_f32_e32 v80, v54, v80
	v_mul_f32_e32 v81, v50, v81
	v_mul_f32_e32 v82, v55, v82
	v_mul_f32_e32 v83, v51, v83
	s_andn2_b64 vcc, exec, s[84:85]
	v_cvt_pk_bf16_f32 v84, v76, v78
	v_cvt_pk_bf16_f32 v85, v80, v82
	v_cvt_pk_bf16_f32 v86, v77, v79
	v_cvt_pk_bf16_f32 v87, v81, v83
	global_store_dwordx4 v[88:89], v[84:87], off offset:256
	s_cbranch_vccnz .LBB0_633
	s_nop 0
	v_mul_f32_e32 v84, v66, v66
	v_mul_f32_e32 v85, v74, v74
	v_fmac_f32_e32 v84, v64, v64
	v_fmac_f32_e32 v85, v72, v72
	v_add_f32_e32 v84, v84, v85
	v_mul_f32_e32 v85, v67, v67
	v_mul_f32_e32 v86, v75, v75
	v_fmac_f32_e32 v85, v65, v65
	v_fmac_f32_e32 v86, v73, v73
	v_add_f32_e32 v64, v64, v66
	v_add_f32_e32 v66, v72, v74
	v_add_f32_e32 v85, v85, v86
	v_add_f32_e32 v64, v64, v66
	v_add_f32_e32 v65, v65, v67
	v_add_f32_e32 v66, v73, v75
	v_add_f32_e32 v84, v84, v85
	v_mul_f32_e32 v85, v78, v78
	v_mul_f32_e32 v86, v82, v82
	v_add_f32_e32 v65, v65, v66
	v_fmac_f32_e32 v85, v76, v76
	v_fmac_f32_e32 v86, v80, v80
	v_add_f32_e32 v64, v64, v65
	v_add_f32_e32 v65, v76, v78
	v_add_f32_e32 v66, v80, v82
	v_add_f32_e32 v85, v85, v86
	v_mul_f32_e32 v86, v79, v79
	v_mul_f32_e32 v87, v83, v83
	v_add_f32_e32 v65, v65, v66
	v_add_f32_e32 v66, v77, v79
	v_add_f32_e32 v67, v81, v83
	v_fmac_f32_e32 v86, v77, v77
	v_fmac_f32_e32 v87, v81, v81
	v_add_f32_e32 v66, v66, v67
	v_add_f32_e32 v65, v65, v66
	v_add_f32_e32 v66, v86, v87
	v_add_f32_e32 v64, 0, v64
	v_add_f32_e32 v66, v85, v66
	v_add_f32_e32 v64, v64, v65
	v_add_f32_e32 v67, v84, v66
	s_waitcnt lgkmcnt(0)
	v_mov_b32_e32 v65, v64
	s_nop 1
	v_permlane16_swap_b32_e32 v64, v65
	v_add_f32_e32 v64, v64, v65
	v_mov_b32_e32 v72, v67
	s_nop 1
	v_permlane16_swap_b32_e32 v67, v72
	v_add_f32_e32 v65, v67, v72
	v_mov_b32_e32 v66, v64
	v_mov_b32_e32 v67, v65
	s_nop 0
	v_permlane32_swap_b32_e32 v64, v66
	v_permlane32_swap_b32_e32 v65, v67
	s_and_saveexec_b64 s[90:91], s[4:5]
	s_cbranch_execz .LBB0_632
	v_pk_add_f32 v[64:65], v[64:65], v[66:67]
	v_lshlrev_b64 v[66:67], 6, v[68:69]
	v_lshl_add_u64 v[66:67], s[18:19], 0, v[66:67]
	v_lshl_add_u64 v[66:67], s[52:53], 3, v[66:67]
	s_lshl_b32 s8, s40, 3
	s_mov_b32 s9, s53
	v_lshl_add_u64 v[66:67], v[66:67], 0, s[8:9]
	global_store_dwordx2 v[66:67], v[64:65], off

.LBB0_637:
	v_cvt_pk_bf16_f32 v64, v60, v61
	v_cvt_pk_bf16_f32 v65, v62, v63
	v_cvt_pk_bf16_f32 v66, v56, v57
	v_mul_f32_e32 v61, v61, v61
	v_mul_f32_e32 v57, v57, v57
	v_fmac_f32_e32 v61, v60, v60
	v_mul_f32_e32 v60, v63, v63
	v_fmac_f32_e32 v57, v56, v56
	v_mul_f32_e32 v56, v59, v59
	v_fmac_f32_e32 v60, v62, v62
	v_fmac_f32_e32 v56, v58, v58
	v_lshl_add_u64 v[70:71], v[148:149], 1, v[70:71]
	v_add_f32_e32 v60, v61, v60
	v_add_f32_e32 v56, v57, v56
	v_cvt_pk_bf16_f32 v67, v58, v59
	global_store_dwordx4 v[70:71], v[64:67], off
	v_add_f32_e32 v57, v60, v56
	v_cvt_pk_bf16_f32 v56, v52, v53
	v_mul_f32_e32 v53, v53, v53
	v_fmac_f32_e32 v53, v52, v52
	v_mul_f32_e32 v52, v55, v55
	v_fmac_f32_e32 v52, v54, v54
	v_add_f32_e32 v52, v53, v52
	v_mul_f32_e32 v53, v49, v49
	v_mul_f32_e32 v58, v51, v51
	v_fmac_f32_e32 v53, v48, v48
	v_fmac_f32_e32 v58, v50, v50
	v_add_f32_e32 v53, v53, v58
	v_add_f32_e32 v52, v52, v53
	v_add_f32_e32 v52, v57, v52
	v_cvt_pk_bf16_f32 v57, v54, v55
	v_cvt_pk_bf16_f32 v58, v48, v49
	v_cvt_pk_bf16_f32 v59, v50, v51
	global_store_dwordx4 v[70:71], v[56:59], off offset:256
	s_waitcnt lgkmcnt(0)
	v_mov_b32_e32 v53, v52
	s_nop 1
	v_permlane16_swap_b32_e32 v52, v53
	v_add_f32_e32 v48, v52, v53
	v_mov_b32_e32 v49, v48
	s_nop 1
	v_permlane32_swap_b32_e32 v48, v49
	s_and_saveexec_b64 s[90:91], s[4:5]
	s_cbranch_execz .LBB0_639
	v_lshl_add_u64 v[50:51], v[68:69], 4, s[66:67]
	v_add_f32_e32 v48, v48, v49
	global_store_dword v[50:51], v48, off

.LBB0_640:
	v_or_b32_e32 v52, 16, v68
	v_mov_b64_e32 v[48:49], s[72:73]
	v_mad_i64_i32 v[48:49], s[8:9], v52, s35, v[48:49]
	v_ashrrev_i32_e32 v53, 31, v52
	v_lshl_add_u64 v[54:55], s[86:87], 1, v[48:49]
	s_mov_b64 s[94:95], -1
	s_mov_b64 s[90:91], 0
	s_cmp_lt_i32 s82, 1
	s_mov_b64 s[92:93], 0
	s_cbranch_scc1 .LBB0_657
	s_cmp_eq_u32 s82, 1
	s_mov_b64 s[92:93], -1
	s_cbranch_scc0 .LBB0_647
	v_cvt_pk_bf16_f32 v48, v44, v45
	v_cvt_pk_bf16_f32 v49, v46, v47
	v_lshl_add_u64 v[56:57], v[148:149], 1, v[54:55]
	v_cvt_pk_bf16_f32 v50, v40, v41
	v_cvt_pk_bf16_f32 v51, v42, v43
	global_store_dwordx4 v[56:57], v[48:51], off
	s_nop 1
	v_mul_f32_e32 v48, v45, v45
	v_mul_f32_e32 v49, v47, v47
	v_fmac_f32_e32 v48, v44, v44
	v_fmac_f32_e32 v49, v46, v46
	v_add_f32_e32 v48, v48, v49
	v_mul_f32_e32 v49, v41, v41
	v_mul_f32_e32 v50, v43, v43
	v_fmac_f32_e32 v49, v40, v40
	v_fmac_f32_e32 v50, v42, v42
	v_add_f32_e32 v49, v49, v50
	v_add_f32_e32 v48, v48, v49
	s_waitcnt lgkmcnt(0)
	v_mov_b32_e32 v49, v48
	s_nop 1
	v_permlane16_swap_b32_e32 v48, v49
	v_add_f32_e32 v48, v48, v49
	v_mov_b32_e32 v49, v48
	s_nop 1
	v_permlane32_swap_b32_e32 v48, v49
	s_and_saveexec_b64 s[92:93], s[4:5]
	s_cbranch_execz .LBB0_644
	v_lshl_add_u64 v[50:51], v[52:53], 4, s[64:65]
	v_add_f32_e32 v48, v48, v49
	global_store_dword v[50:51], v48, off

.LBB0_651:
	s_andn2_b64 vcc, exec, s[90:91]
	s_cbranch_vccnz .LBB0_656
	v_mul_f32_e32 v48, v44, v44
	v_mul_f32_e32 v49, v40, v40
	v_mul_f32_e32 v50, v45, v45
	v_mul_f32_e32 v51, v41, v41
	v_mul_f32_e32 v56, v46, v46
	v_mul_f32_e32 v57, v42, v42
	v_mul_f32_e32 v58, v47, v47
	v_mul_f32_e32 v59, v43, v43
	v_fmaak_f32 v48, v255, v48, 0xc0135761
	v_fmaak_f32 v49, v255, v49, 0xc0135761
	v_fmaak_f32 v50, v255, v50, 0xc0135761
	v_fmaak_f32 v51, v255, v51, 0xc0135761
	v_fmaak_f32 v56, v255, v56, 0xc0135761
	v_fmaak_f32 v57, v255, v57, 0xc0135761
	v_fmaak_f32 v58, v255, v58, 0xc0135761
	v_fmaak_f32 v59, v255, v59, 0xc0135761
	v_mul_f32_e32 v48, v44, v48
	v_mul_f32_e32 v49, v40, v49
	v_mul_f32_e32 v50, v45, v50
	v_mul_f32_e32 v51, v41, v51
	v_mul_f32_e32 v56, v46, v56
	v_mul_f32_e32 v57, v42, v57
	v_mul_f32_e32 v58, v47, v58
	v_mul_f32_e32 v59, v43, v59
	v_exp_f32_e32 v48, v48
	v_exp_f32_e32 v49, v49
	v_exp_f32_e32 v50, v50
	v_exp_f32_e32 v51, v51
	v_exp_f32_e32 v56, v56
	v_exp_f32_e32 v57, v57
	v_exp_f32_e32 v58, v58
	v_exp_f32_e32 v59, v59
	v_add_f32_e32 v48, 1.0, v48
	v_add_f32_e32 v49, 1.0, v49
	v_add_f32_e32 v50, 1.0, v50
	v_add_f32_e32 v51, 1.0, v51
	v_add_f32_e32 v56, 1.0, v56
	v_add_f32_e32 v57, 1.0, v57
	v_add_f32_e32 v58, 1.0, v58
	v_add_f32_e32 v59, 1.0, v59
	v_rcp_f32_e32 v48, v48
	v_rcp_f32_e32 v49, v49
	v_rcp_f32_e32 v50, v50
	v_rcp_f32_e32 v51, v51
	v_rcp_f32_e32 v56, v56
	v_rcp_f32_e32 v57, v57
	v_rcp_f32_e32 v58, v58
	v_rcp_f32_e32 v59, v59
	v_mul_f32_e32 v48, v44, v48
	v_mul_f32_e32 v49, v40, v49
	v_mul_f32_e32 v50, v45, v50
	v_mul_f32_e32 v51, v41, v51
	v_mul_f32_e32 v56, v46, v56
	v_mul_f32_e32 v57, v42, v57
	v_mul_f32_e32 v58, v47, v58
	v_mul_f32_e32 v59, v43, v59
	v_cvt_pk_bf16_f32 v60, v48, v50
	v_cvt_pk_bf16_f32 v61, v56, v58
	v_cvt_pk_bf16_f32 v62, v49, v51
	v_cvt_pk_bf16_f32 v63, v57, v59
	v_lshl_add_u64 v[74:75], v[148:149], 1, v[54:55]
	global_store_dwordx4 v[74:75], v[60:63], off
	v_mul_f32_e32 v64, v38, v38
	v_mul_f32_e32 v65, v34, v34
	v_mul_f32_e32 v60, v36, v36
	v_mul_f32_e32 v61, v32, v32
	v_mul_f32_e32 v62, v37, v37
	v_mul_f32_e32 v63, v33, v33
	v_mul_f32_e32 v66, v39, v39
	v_mul_f32_e32 v67, v35, v35
	v_fmaak_f32 v60, v255, v60, 0xc0135761
	v_fmaak_f32 v61, v255, v61, 0xc0135761
	v_fmaak_f32 v62, v255, v62, 0xc0135761
	v_fmaak_f32 v63, v255, v63, 0xc0135761
	v_fmaak_f32 v64, v255, v64, 0xc0135761
	v_fmaak_f32 v65, v255, v65, 0xc0135761
	v_fmaak_f32 v66, v255, v66, 0xc0135761
	v_fmaak_f32 v67, v255, v67, 0xc0135761
	v_mul_f32_e32 v60, v36, v60
	v_mul_f32_e32 v61, v32, v61
	v_mul_f32_e32 v62, v37, v62
	v_mul_f32_e32 v63, v33, v63
	v_mul_f32_e32 v64, v38, v64
	v_mul_f32_e32 v65, v34, v65
	v_mul_f32_e32 v66, v39, v66
	v_mul_f32_e32 v67, v35, v67
	v_exp_f32_e32 v60, v60
	v_exp_f32_e32 v61, v61
	v_exp_f32_e32 v62, v62
	v_exp_f32_e32 v63, v63
	v_exp_f32_e32 v64, v64
	v_exp_f32_e32 v65, v65
	v_exp_f32_e32 v66, v66
	v_exp_f32_e32 v67, v67
	v_add_f32_e32 v60, 1.0, v60
	v_add_f32_e32 v61, 1.0, v61
	v_add_f32_e32 v62, 1.0, v62
	v_add_f32_e32 v63, 1.0, v63
	v_add_f32_e32 v64, 1.0, v64
	v_add_f32_e32 v65, 1.0, v65
	v_add_f32_e32 v66, 1.0, v66
	v_add_f32_e32 v67, 1.0, v67
	v_rcp_f32_e32 v60, v60
	v_rcp_f32_e32 v61, v61
	v_rcp_f32_e32 v62, v62
	v_rcp_f32_e32 v63, v63
	v_rcp_f32_e32 v64, v64
	v_rcp_f32_e32 v65, v65
	v_rcp_f32_e32 v66, v66
	v_rcp_f32_e32 v67, v67
	v_mul_f32_e32 v60, v36, v60
	v_mul_f32_e32 v61, v32, v61
	v_mul_f32_e32 v62, v37, v62
	v_mul_f32_e32 v63, v33, v63
	v_mul_f32_e32 v64, v38, v64
	v_mul_f32_e32 v65, v34, v65
	v_mul_f32_e32 v66, v39, v66
	v_mul_f32_e32 v67, v35, v67
	s_andn2_b64 vcc, exec, s[84:85]
	v_cvt_pk_bf16_f32 v70, v60, v62
	v_cvt_pk_bf16_f32 v71, v64, v66
	v_cvt_pk_bf16_f32 v72, v61, v63
	v_cvt_pk_bf16_f32 v73, v65, v67
	global_store_dwordx4 v[74:75], v[70:73], off offset:256
	s_cbranch_vccnz .LBB0_656
	v_mul_f32_e32 v69, v50, v50
	v_mul_f32_e32 v70, v58, v58
	v_fmac_f32_e32 v69, v48, v48
	v_fmac_f32_e32 v70, v56, v56
	v_add_f32_e32 v69, v69, v70
	v_mul_f32_e32 v70, v51, v51
	v_mul_f32_e32 v71, v59, v59
	v_fmac_f32_e32 v70, v49, v49
	v_fmac_f32_e32 v71, v57, v57
	v_add_f32_e32 v48, v48, v50
	v_add_f32_e32 v50, v56, v58
	v_add_f32_e32 v70, v70, v71
	v_add_f32_e32 v48, v48, v50
	v_add_f32_e32 v49, v49, v51
	v_add_f32_e32 v50, v57, v59
	v_add_f32_e32 v69, v69, v70
	v_mul_f32_e32 v70, v62, v62
	v_mul_f32_e32 v71, v66, v66
	v_add_f32_e32 v49, v49, v50
	v_fmac_f32_e32 v70, v60, v60
	v_fmac_f32_e32 v71, v64, v64
	v_add_f32_e32 v48, v48, v49
	v_add_f32_e32 v49, v60, v62
	v_add_f32_e32 v50, v64, v66
	v_add_f32_e32 v70, v70, v71
	v_mul_f32_e32 v71, v63, v63
	v_mul_f32_e32 v72, v67, v67
	v_add_f32_e32 v49, v49, v50
	v_add_f32_e32 v50, v61, v63
	v_add_f32_e32 v51, v65, v67
	v_fmac_f32_e32 v71, v61, v61
	v_fmac_f32_e32 v72, v65, v65
	v_add_f32_e32 v50, v50, v51
	v_add_f32_e32 v49, v49, v50
	v_add_f32_e32 v50, v71, v72
	v_add_f32_e32 v48, 0, v48
	v_add_f32_e32 v50, v70, v50
	v_add_f32_e32 v48, v48, v49
	v_add_f32_e32 v51, v69, v50
	s_waitcnt lgkmcnt(0)
	v_mov_b32_e32 v49, v48
	s_nop 1
	v_permlane16_swap_b32_e32 v48, v49
	v_add_f32_e32 v48, v48, v49
	v_mov_b32_e32 v56, v51
	s_nop 1
	v_permlane16_swap_b32_e32 v51, v56
	v_add_f32_e32 v49, v51, v56
	v_mov_b32_e32 v50, v48
	v_mov_b32_e32 v51, v49
	s_nop 0
	v_permlane32_swap_b32_e32 v48, v50
	v_permlane32_swap_b32_e32 v49, v51
	s_and_saveexec_b64 s[90:91], s[4:5]
	s_cbranch_execz .LBB0_655
	v_pk_add_f32 v[48:49], v[48:49], v[50:51]
	v_lshlrev_b64 v[50:51], 6, v[52:53]
	v_lshl_add_u64 v[50:51], s[18:19], 0, v[50:51]
	v_lshl_add_u64 v[50:51], s[52:53], 3, v[50:51]
	s_lshl_b32 s8, s40, 3
	s_mov_b32 s9, s53
	v_lshl_add_u64 v[50:51], v[50:51], 0, s[8:9]
	global_store_dwordx2 v[50:51], v[48:49], off

.LBB0_660:
	v_cvt_pk_bf16_f32 v48, v44, v45
	v_cvt_pk_bf16_f32 v49, v46, v47
	v_cvt_pk_bf16_f32 v50, v40, v41
	v_mul_f32_e32 v45, v45, v45
	v_mul_f32_e32 v41, v41, v41
	v_fmac_f32_e32 v45, v44, v44
	v_mul_f32_e32 v44, v47, v47
	v_fmac_f32_e32 v41, v40, v40
	v_mul_f32_e32 v40, v43, v43
	v_fmac_f32_e32 v44, v46, v46
	v_fmac_f32_e32 v40, v42, v42
	v_lshl_add_u64 v[54:55], v[148:149], 1, v[54:55]
	v_add_f32_e32 v44, v45, v44
	v_add_f32_e32 v40, v41, v40
	v_cvt_pk_bf16_f32 v51, v42, v43
	global_store_dwordx4 v[54:55], v[48:51], off
	v_add_f32_e32 v41, v44, v40
	v_cvt_pk_bf16_f32 v40, v36, v37
	v_mul_f32_e32 v37, v37, v37
	v_fmac_f32_e32 v37, v36, v36
	v_mul_f32_e32 v36, v39, v39
	v_fmac_f32_e32 v36, v38, v38
	v_add_f32_e32 v36, v37, v36
	v_mul_f32_e32 v37, v33, v33
	v_mul_f32_e32 v42, v35, v35
	v_fmac_f32_e32 v37, v32, v32
	v_fmac_f32_e32 v42, v34, v34
	v_add_f32_e32 v37, v37, v42
	v_add_f32_e32 v36, v36, v37
	v_add_f32_e32 v36, v41, v36
	v_cvt_pk_bf16_f32 v41, v38, v39
	v_cvt_pk_bf16_f32 v42, v32, v33
	v_cvt_pk_bf16_f32 v43, v34, v35
	global_store_dwordx4 v[54:55], v[40:43], off offset:256
	s_waitcnt lgkmcnt(0)
	v_mov_b32_e32 v37, v36
	s_nop 1
	v_permlane16_swap_b32_e32 v36, v37
	v_add_f32_e32 v32, v36, v37
	v_mov_b32_e32 v33, v32
	s_nop 1
	v_permlane32_swap_b32_e32 v32, v33
	s_and_saveexec_b64 s[90:91], s[4:5]
	s_cbranch_execz .LBB0_662
	v_lshl_add_u64 v[34:35], v[52:53], 4, s[66:67]
	v_add_f32_e32 v32, v32, v33
	global_store_dword v[34:35], v32, off

.LBB0_663:
	v_or_b32_e32 v36, 32, v68
	v_mov_b64_e32 v[32:33], s[72:73]
	v_mad_i64_i32 v[32:33], s[8:9], v36, s35, v[32:33]
	v_ashrrev_i32_e32 v37, 31, v36
	v_lshl_add_u64 v[38:39], s[86:87], 1, v[32:33]
	s_mov_b64 s[94:95], -1
	s_mov_b64 s[90:91], 0
	s_cmp_lt_i32 s82, 1
	s_mov_b64 s[92:93], 0
	s_cbranch_scc1 .LBB0_680
	s_cmp_eq_u32 s82, 1
	s_mov_b64 s[92:93], -1
	s_cbranch_scc0 .LBB0_670
	v_cvt_pk_bf16_f32 v32, v28, v29
	v_cvt_pk_bf16_f32 v33, v30, v31
	v_lshl_add_u64 v[40:41], v[148:149], 1, v[38:39]
	v_cvt_pk_bf16_f32 v34, v24, v25
	v_cvt_pk_bf16_f32 v35, v26, v27
	global_store_dwordx4 v[40:41], v[32:35], off
	s_nop 1
	v_mul_f32_e32 v32, v29, v29
	v_mul_f32_e32 v33, v31, v31
	v_fmac_f32_e32 v32, v28, v28
	v_fmac_f32_e32 v33, v30, v30
	v_add_f32_e32 v32, v32, v33
	v_mul_f32_e32 v33, v25, v25
	v_mul_f32_e32 v34, v27, v27
	v_fmac_f32_e32 v33, v24, v24
	v_fmac_f32_e32 v34, v26, v26
	v_add_f32_e32 v33, v33, v34
	v_add_f32_e32 v32, v32, v33
	s_waitcnt lgkmcnt(0)
	v_mov_b32_e32 v33, v32
	s_nop 1
	v_permlane16_swap_b32_e32 v32, v33
	v_add_f32_e32 v32, v32, v33
	v_mov_b32_e32 v33, v32
	s_nop 1
	v_permlane32_swap_b32_e32 v32, v33
	s_and_saveexec_b64 s[92:93], s[4:5]
	s_cbranch_execz .LBB0_667
	v_lshl_add_u64 v[34:35], v[36:37], 4, s[64:65]
	v_add_f32_e32 v32, v32, v33
	global_store_dword v[34:35], v32, off

.LBB0_674:
	s_andn2_b64 vcc, exec, s[90:91]
	s_cbranch_vccnz .LBB0_679
	v_mul_f32_e32 v32, v28, v28
	v_mul_f32_e32 v33, v24, v24
	v_mul_f32_e32 v34, v29, v29
	v_mul_f32_e32 v35, v25, v25
	v_mul_f32_e32 v40, v30, v30
	v_mul_f32_e32 v41, v26, v26
	v_mul_f32_e32 v42, v31, v31
	v_mul_f32_e32 v43, v27, v27
	v_fmaak_f32 v32, v255, v32, 0xc0135761
	v_fmaak_f32 v33, v255, v33, 0xc0135761
	v_fmaak_f32 v34, v255, v34, 0xc0135761
	v_fmaak_f32 v35, v255, v35, 0xc0135761
	v_fmaak_f32 v40, v255, v40, 0xc0135761
	v_fmaak_f32 v41, v255, v41, 0xc0135761
	v_fmaak_f32 v42, v255, v42, 0xc0135761
	v_fmaak_f32 v43, v255, v43, 0xc0135761
	v_mul_f32_e32 v32, v28, v32
	v_mul_f32_e32 v33, v24, v33
	v_mul_f32_e32 v34, v29, v34
	v_mul_f32_e32 v35, v25, v35
	v_mul_f32_e32 v40, v30, v40
	v_mul_f32_e32 v41, v26, v41
	v_mul_f32_e32 v42, v31, v42
	v_mul_f32_e32 v43, v27, v43
	v_exp_f32_e32 v32, v32
	v_exp_f32_e32 v33, v33
	v_exp_f32_e32 v34, v34
	v_exp_f32_e32 v35, v35
	v_exp_f32_e32 v40, v40
	v_exp_f32_e32 v41, v41
	v_exp_f32_e32 v42, v42
	v_exp_f32_e32 v43, v43
	v_add_f32_e32 v32, 1.0, v32
	v_add_f32_e32 v33, 1.0, v33
	v_add_f32_e32 v34, 1.0, v34
	v_add_f32_e32 v35, 1.0, v35
	v_add_f32_e32 v40, 1.0, v40
	v_add_f32_e32 v41, 1.0, v41
	v_add_f32_e32 v42, 1.0, v42
	v_add_f32_e32 v43, 1.0, v43
	v_rcp_f32_e32 v32, v32
	v_rcp_f32_e32 v33, v33
	v_rcp_f32_e32 v34, v34
	v_rcp_f32_e32 v35, v35
	v_rcp_f32_e32 v40, v40
	v_rcp_f32_e32 v41, v41
	v_rcp_f32_e32 v42, v42
	v_rcp_f32_e32 v43, v43
	v_mul_f32_e32 v32, v28, v32
	v_mul_f32_e32 v33, v24, v33
	v_mul_f32_e32 v34, v29, v34
	v_mul_f32_e32 v35, v25, v35
	v_mul_f32_e32 v40, v30, v40
	v_mul_f32_e32 v41, v26, v41
	v_mul_f32_e32 v42, v31, v42
	v_mul_f32_e32 v43, v27, v43
	v_cvt_pk_bf16_f32 v44, v32, v34
	v_cvt_pk_bf16_f32 v45, v40, v42
	v_cvt_pk_bf16_f32 v46, v33, v35
	v_cvt_pk_bf16_f32 v47, v41, v43
	v_lshl_add_u64 v[56:57], v[148:149], 1, v[38:39]
	global_store_dwordx4 v[56:57], v[44:47], off
	v_mul_f32_e32 v48, v22, v22
	v_mul_f32_e32 v49, v18, v18
	v_mul_f32_e32 v44, v20, v20
	v_mul_f32_e32 v45, v16, v16
	v_mul_f32_e32 v46, v21, v21
	v_mul_f32_e32 v47, v17, v17
	v_mul_f32_e32 v50, v23, v23
	v_mul_f32_e32 v51, v19, v19
	v_fmaak_f32 v44, v255, v44, 0xc0135761
	v_fmaak_f32 v45, v255, v45, 0xc0135761
	v_fmaak_f32 v46, v255, v46, 0xc0135761
	v_fmaak_f32 v47, v255, v47, 0xc0135761
	v_fmaak_f32 v48, v255, v48, 0xc0135761
	v_fmaak_f32 v49, v255, v49, 0xc0135761
	v_fmaak_f32 v50, v255, v50, 0xc0135761
	v_fmaak_f32 v51, v255, v51, 0xc0135761
	v_mul_f32_e32 v44, v20, v44
	v_mul_f32_e32 v45, v16, v45
	v_mul_f32_e32 v46, v21, v46
	v_mul_f32_e32 v47, v17, v47
	v_mul_f32_e32 v48, v22, v48
	v_mul_f32_e32 v49, v18, v49
	v_mul_f32_e32 v50, v23, v50
	v_mul_f32_e32 v51, v19, v51
	v_exp_f32_e32 v44, v44
	v_exp_f32_e32 v45, v45
	v_exp_f32_e32 v46, v46
	v_exp_f32_e32 v47, v47
	v_exp_f32_e32 v48, v48
	v_exp_f32_e32 v49, v49
	v_exp_f32_e32 v50, v50
	v_exp_f32_e32 v51, v51
	v_add_f32_e32 v44, 1.0, v44
	v_add_f32_e32 v45, 1.0, v45
	v_add_f32_e32 v46, 1.0, v46
	v_add_f32_e32 v47, 1.0, v47
	v_add_f32_e32 v48, 1.0, v48
	v_add_f32_e32 v49, 1.0, v49
	v_add_f32_e32 v50, 1.0, v50
	v_add_f32_e32 v51, 1.0, v51
	v_rcp_f32_e32 v44, v44
	v_rcp_f32_e32 v45, v45
	v_rcp_f32_e32 v46, v46
	v_rcp_f32_e32 v47, v47
	v_rcp_f32_e32 v48, v48
	v_rcp_f32_e32 v49, v49
	v_rcp_f32_e32 v50, v50
	v_rcp_f32_e32 v51, v51
	v_mul_f32_e32 v44, v20, v44
	v_mul_f32_e32 v45, v16, v45
	v_mul_f32_e32 v46, v21, v46
	v_mul_f32_e32 v47, v17, v47
	v_mul_f32_e32 v48, v22, v48
	v_mul_f32_e32 v49, v18, v49
	v_mul_f32_e32 v50, v23, v50
	v_mul_f32_e32 v51, v19, v51
	s_andn2_b64 vcc, exec, s[84:85]
	v_cvt_pk_bf16_f32 v52, v44, v46
	v_cvt_pk_bf16_f32 v53, v48, v50
	v_cvt_pk_bf16_f32 v54, v45, v47
	v_cvt_pk_bf16_f32 v55, v49, v51
	global_store_dwordx4 v[56:57], v[52:55], off offset:256
	s_cbranch_vccnz .LBB0_679
	s_nop 0
	v_mul_f32_e32 v52, v34, v34
	v_mul_f32_e32 v53, v42, v42
	v_fmac_f32_e32 v52, v32, v32
	v_fmac_f32_e32 v53, v40, v40
	v_add_f32_e32 v52, v52, v53
	v_mul_f32_e32 v53, v35, v35
	v_mul_f32_e32 v54, v43, v43
	v_fmac_f32_e32 v53, v33, v33
	v_fmac_f32_e32 v54, v41, v41
	v_add_f32_e32 v32, v32, v34
	v_add_f32_e32 v34, v40, v42
	v_add_f32_e32 v53, v53, v54
	v_add_f32_e32 v32, v32, v34
	v_add_f32_e32 v33, v33, v35
	v_add_f32_e32 v34, v41, v43
	v_add_f32_e32 v52, v52, v53
	v_mul_f32_e32 v53, v46, v46
	v_mul_f32_e32 v54, v50, v50
	v_add_f32_e32 v33, v33, v34
	v_fmac_f32_e32 v53, v44, v44
	v_fmac_f32_e32 v54, v48, v48
	v_add_f32_e32 v32, v32, v33
	v_add_f32_e32 v33, v44, v46
	v_add_f32_e32 v34, v48, v50
	v_add_f32_e32 v53, v53, v54
	v_mul_f32_e32 v54, v47, v47
	v_mul_f32_e32 v55, v51, v51
	v_add_f32_e32 v33, v33, v34
	v_add_f32_e32 v34, v45, v47
	v_add_f32_e32 v35, v49, v51
	v_fmac_f32_e32 v54, v45, v45
	v_fmac_f32_e32 v55, v49, v49
	v_add_f32_e32 v34, v34, v35
	v_add_f32_e32 v33, v33, v34
	v_add_f32_e32 v34, v54, v55
	v_add_f32_e32 v32, 0, v32
	v_add_f32_e32 v34, v53, v34
	v_add_f32_e32 v32, v32, v33
	v_add_f32_e32 v35, v52, v34
	s_waitcnt lgkmcnt(0)
	v_mov_b32_e32 v33, v32
	s_nop 1
	v_permlane16_swap_b32_e32 v32, v33
	v_add_f32_e32 v32, v32, v33
	v_mov_b32_e32 v40, v35
	s_nop 1
	v_permlane16_swap_b32_e32 v35, v40
	v_add_f32_e32 v33, v35, v40
	v_mov_b32_e32 v34, v32
	v_mov_b32_e32 v35, v33
	s_nop 0
	v_permlane32_swap_b32_e32 v32, v34
	v_permlane32_swap_b32_e32 v33, v35
	s_and_saveexec_b64 s[90:91], s[4:5]
	s_cbranch_execz .LBB0_678
	v_pk_add_f32 v[32:33], v[32:33], v[34:35]
	v_lshlrev_b64 v[34:35], 6, v[36:37]
	v_lshl_add_u64 v[34:35], s[18:19], 0, v[34:35]
	v_lshl_add_u64 v[34:35], s[52:53], 3, v[34:35]
	s_lshl_b32 s8, s40, 3
	s_mov_b32 s9, s53
	v_lshl_add_u64 v[34:35], v[34:35], 0, s[8:9]
	global_store_dwordx2 v[34:35], v[32:33], off

.LBB0_683:
	v_cvt_pk_bf16_f32 v32, v28, v29
	v_cvt_pk_bf16_f32 v33, v30, v31
	v_cvt_pk_bf16_f32 v34, v24, v25
	v_mul_f32_e32 v29, v29, v29
	v_mul_f32_e32 v25, v25, v25
	v_fmac_f32_e32 v29, v28, v28
	v_mul_f32_e32 v28, v31, v31
	v_fmac_f32_e32 v25, v24, v24
	v_mul_f32_e32 v24, v27, v27
	v_fmac_f32_e32 v28, v30, v30
	v_fmac_f32_e32 v24, v26, v26
	v_lshl_add_u64 v[38:39], v[148:149], 1, v[38:39]
	v_add_f32_e32 v28, v29, v28
	v_add_f32_e32 v24, v25, v24
	v_cvt_pk_bf16_f32 v35, v26, v27
	global_store_dwordx4 v[38:39], v[32:35], off
	v_add_f32_e32 v25, v28, v24
	v_cvt_pk_bf16_f32 v24, v20, v21
	v_mul_f32_e32 v21, v21, v21
	v_fmac_f32_e32 v21, v20, v20
	v_mul_f32_e32 v20, v23, v23
	v_fmac_f32_e32 v20, v22, v22
	v_add_f32_e32 v20, v21, v20
	v_mul_f32_e32 v21, v17, v17
	v_mul_f32_e32 v26, v19, v19
	v_fmac_f32_e32 v21, v16, v16
	v_fmac_f32_e32 v26, v18, v18
	v_add_f32_e32 v21, v21, v26
	v_add_f32_e32 v20, v20, v21
	v_add_f32_e32 v20, v25, v20
	v_cvt_pk_bf16_f32 v25, v22, v23
	v_cvt_pk_bf16_f32 v26, v16, v17
	v_cvt_pk_bf16_f32 v27, v18, v19
	global_store_dwordx4 v[38:39], v[24:27], off offset:256
	s_waitcnt lgkmcnt(0)
	v_mov_b32_e32 v21, v20
	s_nop 1
	v_permlane16_swap_b32_e32 v20, v21
	v_add_f32_e32 v16, v20, v21
	v_mov_b32_e32 v17, v16
	s_nop 1
	v_permlane32_swap_b32_e32 v16, v17
	s_and_saveexec_b64 s[90:91], s[4:5]
	s_cbranch_execz .LBB0_685
	v_lshl_add_u64 v[18:19], v[36:37], 4, s[66:67]
	v_add_f32_e32 v16, v16, v17
	global_store_dword v[18:19], v16, off

.LBB0_686:
	v_or_b32_e32 v20, 48, v68
	v_mov_b64_e32 v[16:17], s[72:73]
	v_mad_i64_i32 v[16:17], s[8:9], v20, s35, v[16:17]
	v_ashrrev_i32_e32 v21, 31, v20
	v_lshl_add_u64 v[22:23], s[86:87], 1, v[16:17]
	s_mov_b64 s[92:93], -1
	s_mov_b64 s[86:87], 0
	s_cmp_lt_i32 s82, 1
	s_mov_b64 s[90:91], 0
	s_cbranch_scc1 .LBB0_703
	s_cmp_eq_u32 s82, 1
	s_mov_b64 s[90:91], -1
	s_cbranch_scc0 .LBB0_693
	v_cvt_pk_bf16_f32 v16, v12, v13
	v_cvt_pk_bf16_f32 v17, v14, v15
	v_lshl_add_u64 v[24:25], v[148:149], 1, v[22:23]
	v_cvt_pk_bf16_f32 v18, v8, v9
	v_cvt_pk_bf16_f32 v19, v10, v11
	global_store_dwordx4 v[24:25], v[16:19], off
	s_nop 1
	v_mul_f32_e32 v16, v13, v13
	v_mul_f32_e32 v17, v15, v15
	v_fmac_f32_e32 v16, v12, v12
	v_fmac_f32_e32 v17, v14, v14
	v_add_f32_e32 v16, v16, v17
	v_mul_f32_e32 v17, v9, v9
	v_mul_f32_e32 v18, v11, v11
	v_fmac_f32_e32 v17, v8, v8
	v_fmac_f32_e32 v18, v10, v10
	v_add_f32_e32 v17, v17, v18
	v_add_f32_e32 v16, v16, v17
	s_waitcnt lgkmcnt(0)
	v_mov_b32_e32 v17, v16
	s_nop 1
	v_permlane16_swap_b32_e32 v16, v17
	v_add_f32_e32 v16, v16, v17
	v_mov_b32_e32 v17, v16
	s_nop 1
	v_permlane32_swap_b32_e32 v16, v17
	s_and_saveexec_b64 s[90:91], s[4:5]
	s_cbranch_execz .LBB0_690
	v_lshl_add_u64 v[18:19], v[20:21], 4, s[64:65]
	v_add_f32_e32 v16, v16, v17
	global_store_dword v[18:19], v16, off

.LBB0_697:
	s_andn2_b64 vcc, exec, s[6:7]
	s_cbranch_vccnz .LBB0_702
	v_mul_f32_e32 v17, v8, v8
	v_fmaak_f32 v17, v255, v17, 0xc0135761
	v_mul_f32_e32 v18, v13, v13
	v_mul_f32_e32 v17, v8, v17
	v_fmaak_f32 v18, v255, v18, 0xc0135761
	v_mul_f32_e32 v18, v13, v18
	v_exp_f32_e32 v17, v17
	v_mul_f32_e32 v16, v12, v12
	v_exp_f32_e32 v18, v18
	v_fmaak_f32 v16, v255, v16, 0xc0135761
	v_mul_f32_e32 v16, v12, v16
	v_add_f32_e32 v17, 1.0, v17
	v_rcp_f32_e32 v19, v17
	v_add_f32_e32 v17, 1.0, v18
	v_exp_f32_e32 v16, v16
	v_rcp_f32_e32 v18, v17
	v_mul_f32_e32 v17, v9, v9
	v_fmaak_f32 v17, v255, v17, 0xc0135761
	v_mul_f32_e32 v17, v9, v17
	v_add_f32_e32 v16, 1.0, v16
	v_rcp_f32_e32 v16, v16
	v_exp_f32_e32 v24, v17
	v_mul_f32_e32 v25, v10, v10
	v_fmaak_f32 v25, v255, v25, 0xc0135761
	v_mul_f32_e32 v26, v15, v15
	v_mul_f32_e32 v17, v12, v16
	v_mul_f32_e32 v16, v8, v19
	v_add_f32_e32 v19, 1.0, v24
	v_mul_f32_e32 v24, v14, v14
	v_mul_f32_e32 v25, v10, v25
	v_fmaak_f32 v26, v255, v26, 0xc0135761
	v_mul_f32_e32 v27, v11, v11
	v_fmaak_f32 v24, v255, v24, 0xc0135761
	v_mul_f32_e32 v26, v15, v26
	v_fmaak_f32 v27, v255, v27, 0xc0135761
	v_mul_f32_e32 v24, v14, v24
	v_mul_f32_e32 v27, v11, v27
	v_exp_f32_e32 v25, v25
	v_exp_f32_e32 v26, v26
	v_exp_f32_e32 v24, v24
	v_exp_f32_e32 v27, v27
	v_add_f32_e32 v25, 1.0, v25
	v_rcp_f32_e32 v28, v25
	v_add_f32_e32 v25, 1.0, v26
	v_add_f32_e32 v24, 1.0, v24
	v_rcp_f32_e32 v26, v25
	v_add_f32_e32 v25, 1.0, v27
	v_rcp_f32_e32 v24, v24
	v_rcp_f32_e32 v29, v25
	v_mul_f32_e32 v31, v4, v4
	v_rcp_f32_e32 v19, v19
	v_fmaak_f32 v31, v255, v31, 0xc0135761
	v_mul_f32_e32 v31, v4, v31
	v_mul_f32_e32 v18, v13, v18
	v_mul_f32_e32 v25, v14, v24
	v_mul_f32_e32 v24, v10, v28
	v_mul_f32_e32 v27, v15, v26
	v_mul_f32_e32 v26, v11, v29
	v_cvt_pk_bf16_f32 v28, v17, v18
	v_cvt_pk_bf16_f32 v29, v25, v27
	v_lshl_add_u64 v[40:41], v[148:149], 1, v[22:23]
	v_mul_f32_e32 v19, v9, v19
	v_cvt_pk_bf16_f32 v30, v16, v19
	v_exp_f32_e32 v32, v31
	v_cvt_pk_bf16_f32 v31, v24, v26
	global_store_dwordx4 v[40:41], v[28:31], off
	v_mul_f32_e32 v33, v2, v2
	v_fmaak_f32 v33, v255, v33, 0xc0135761
	v_mul_f32_e32 v29, v0, v0
	v_fmaak_f32 v29, v255, v29, 0xc0135761
	v_mul_f32_e32 v30, v5, v5
	v_mul_f32_e32 v29, v0, v29
	v_fmaak_f32 v30, v255, v30, 0xc0135761
	v_mul_f32_e32 v30, v5, v30
	v_exp_f32_e32 v29, v29
	v_exp_f32_e32 v30, v30
	v_add_f32_e32 v28, 1.0, v32
	v_add_f32_e32 v29, 1.0, v29
	v_rcp_f32_e32 v31, v29
	v_add_f32_e32 v29, 1.0, v30
	v_rcp_f32_e32 v30, v29
	v_mul_f32_e32 v29, v1, v1
	v_fmaak_f32 v29, v255, v29, 0xc0135761
	v_mul_f32_e32 v29, v1, v29
	v_rcp_f32_e32 v28, v28
	v_exp_f32_e32 v32, v29
	v_mul_f32_e32 v34, v7, v7
	v_mul_f32_e32 v33, v2, v33
	v_mul_f32_e32 v29, v4, v28
	v_mul_f32_e32 v28, v0, v31
	v_add_f32_e32 v31, 1.0, v32
	v_mul_f32_e32 v32, v6, v6
	v_fmaak_f32 v34, v255, v34, 0xc0135761
	v_mul_f32_e32 v35, v3, v3
	v_fmaak_f32 v32, v255, v32, 0xc0135761
	v_mul_f32_e32 v34, v7, v34
	v_fmaak_f32 v35, v255, v35, 0xc0135761
	v_mul_f32_e32 v32, v6, v32
	v_mul_f32_e32 v35, v3, v35
	v_exp_f32_e32 v33, v33
	v_exp_f32_e32 v34, v34
	v_exp_f32_e32 v32, v32
	v_exp_f32_e32 v35, v35
	v_add_f32_e32 v33, 1.0, v33
	v_rcp_f32_e32 v36, v33
	v_add_f32_e32 v33, 1.0, v34
	v_add_f32_e32 v32, 1.0, v32
	v_rcp_f32_e32 v34, v33
	v_add_f32_e32 v33, 1.0, v35
	v_rcp_f32_e32 v31, v31
	v_rcp_f32_e32 v32, v32
	v_rcp_f32_e32 v37, v33
	v_mul_f32_e32 v30, v5, v30
	v_mul_f32_e32 v31, v1, v31
	v_mul_f32_e32 v33, v6, v32
	v_mul_f32_e32 v32, v2, v36
	v_mul_f32_e32 v35, v7, v34
	v_mul_f32_e32 v34, v3, v37
	s_andn2_b64 vcc, exec, s[84:85]
	v_cvt_pk_bf16_f32 v36, v29, v30
	v_cvt_pk_bf16_f32 v37, v33, v35
	v_cvt_pk_bf16_f32 v38, v28, v31
	v_cvt_pk_bf16_f32 v39, v32, v34
	global_store_dwordx4 v[40:41], v[36:39], off offset:256
	s_cbranch_vccnz .LBB0_702
	s_nop 0
	v_mul_f32_e32 v36, v18, v18
	v_mul_f32_e32 v37, v27, v27
	v_fmac_f32_e32 v36, v17, v17
	v_fmac_f32_e32 v37, v25, v25
	v_add_f32_e32 v36, v36, v37
	v_mul_f32_e32 v37, v19, v19
	v_mul_f32_e32 v38, v26, v26
	v_fmac_f32_e32 v37, v16, v16
	v_fmac_f32_e32 v38, v24, v24
	v_add_f32_e32 v17, v17, v18
	v_add_f32_e32 v18, v25, v27
	v_add_f32_e32 v37, v37, v38
	v_add_f32_e32 v17, v17, v18
	v_add_f32_e32 v16, v16, v19
	v_add_f32_e32 v18, v24, v26
	v_add_f32_e32 v36, v36, v37
	v_mul_f32_e32 v37, v30, v30
	v_mul_f32_e32 v38, v35, v35
	v_add_f32_e32 v16, v16, v18
	v_fmac_f32_e32 v37, v29, v29
	v_fmac_f32_e32 v38, v33, v33
	v_add_f32_e32 v16, v17, v16
	v_add_f32_e32 v17, v29, v30
	v_add_f32_e32 v18, v33, v35
	v_add_f32_e32 v37, v37, v38
	v_mul_f32_e32 v38, v31, v31
	v_mul_f32_e32 v39, v34, v34
	v_add_f32_e32 v17, v17, v18
	v_add_f32_e32 v18, v28, v31
	v_add_f32_e32 v19, v32, v34
	v_fmac_f32_e32 v38, v28, v28
	v_fmac_f32_e32 v39, v32, v32
	v_add_f32_e32 v18, v18, v19
	v_add_f32_e32 v17, v17, v18
	v_add_f32_e32 v18, v38, v39
	v_add_f32_e32 v16, 0, v16
	v_add_f32_e32 v18, v37, v18
	v_add_f32_e32 v16, v16, v17
	v_add_f32_e32 v19, v36, v18
	s_waitcnt lgkmcnt(0)
	v_mov_b32_e32 v17, v16
	s_nop 1
	v_permlane16_swap_b32_e32 v16, v17
	v_add_f32_e32 v16, v16, v17
	v_mov_b32_e32 v24, v19
	s_nop 1
	v_permlane16_swap_b32_e32 v19, v24
	v_add_f32_e32 v17, v19, v24
	v_mov_b32_e32 v18, v16
	v_mov_b32_e32 v19, v17
	s_nop 0
	v_permlane32_swap_b32_e32 v16, v18
	v_permlane32_swap_b32_e32 v17, v19
	s_and_saveexec_b64 s[6:7], s[4:5]
	s_cbranch_execz .LBB0_701
	v_pk_add_f32 v[16:17], v[16:17], v[18:19]
	v_lshlrev_b64 v[18:19], 6, v[20:21]
	v_lshl_add_u64 v[18:19], s[18:19], 0, v[18:19]
	v_lshl_add_u64 v[18:19], s[52:53], 3, v[18:19]
	s_lshl_b32 s52, s40, 3
	v_lshl_add_u64 v[18:19], v[18:19], 0, s[52:53]
	global_store_dwordx2 v[18:19], v[16:17], off

.LBB0_706:
	v_cvt_pk_bf16_f32 v16, v12, v13
	v_cvt_pk_bf16_f32 v17, v14, v15
	v_cvt_pk_bf16_f32 v18, v8, v9
	v_mul_f32_e32 v13, v13, v13
	v_mul_f32_e32 v9, v9, v9
	v_fmac_f32_e32 v13, v12, v12
	v_mul_f32_e32 v12, v15, v15
	v_fmac_f32_e32 v9, v8, v8
	v_mul_f32_e32 v8, v11, v11
	v_fmac_f32_e32 v12, v14, v14
	v_fmac_f32_e32 v8, v10, v10
	v_lshl_add_u64 v[22:23], v[148:149], 1, v[22:23]
	v_add_f32_e32 v12, v13, v12
	v_add_f32_e32 v8, v9, v8
	v_cvt_pk_bf16_f32 v19, v10, v11
	global_store_dwordx4 v[22:23], v[16:19], off
	v_add_f32_e32 v9, v12, v8
	v_cvt_pk_bf16_f32 v8, v4, v5
	v_mul_f32_e32 v5, v5, v5
	v_fmac_f32_e32 v5, v4, v4
	v_mul_f32_e32 v4, v7, v7
	v_fmac_f32_e32 v4, v6, v6
	v_add_f32_e32 v4, v5, v4
	v_mul_f32_e32 v5, v1, v1
	v_mul_f32_e32 v10, v3, v3
	v_fmac_f32_e32 v5, v0, v0
	v_fmac_f32_e32 v10, v2, v2
	v_add_f32_e32 v5, v5, v10
	v_add_f32_e32 v4, v4, v5
	v_add_f32_e32 v4, v9, v4
	v_cvt_pk_bf16_f32 v9, v6, v7
	v_cvt_pk_bf16_f32 v10, v0, v1
	v_cvt_pk_bf16_f32 v11, v2, v3
	global_store_dwordx4 v[22:23], v[8:11], off offset:256
	s_waitcnt lgkmcnt(0)
	v_mov_b32_e32 v5, v4
	s_nop 1
	v_permlane16_swap_b32_e32 v4, v5
	v_add_f32_e32 v0, v4, v5
	v_mov_b32_e32 v1, v0
	s_nop 1
	v_permlane32_swap_b32_e32 v0, v1
	s_and_saveexec_b64 s[6:7], s[4:5]
	s_cbranch_execz .LBB0_708
	v_lshl_add_u64 v[2:3], v[20:21], 4, s[66:67]
	v_add_f32_e32 v0, v0, v1
	global_store_dword v[2:3], v0, off

.LBB0_897:
	s_or_b64 exec, exec, s[12:13]
	v_bfe_u32 v32, v4, 2, 7
	v_lshl_add_u64 v[0:1], s[4:5], 0, v[32:33]
	v_mad_u64_u32 v[2:3], s[12:13], v0, s9, v[34:35]
	v_mov_b32_e32 v0, v3
	v_mad_u64_u32 v[0:1], s[12:13], v1, s9, v[0:1]
	v_mov_b32_e32 v3, v0
	v_lshlrev_b32_e32 v0, 3, v4
	v_and_b32_e32 v5, 24, v0
	v_lshlrev_b32_e32 v0, 1, v5
	v_mov_b32_e32 v1, v33
	v_lshl_add_u64 v[46:47], v[2:3], 0, v[0:1]
	global_load_dwordx4 v[8:11], v[46:47], off offset:2048
	v_lshlrev_b32_e32 v157, 2, v5
	global_load_dwordx4 v[12:15], v[46:47], off offset:2112
	global_load_dwordx4 v[16:19], v[46:47], off offset:2176
	global_load_dwordx4 v[0:3], v[46:47], off offset:2240
	s_waitcnt lgkmcnt(0)
	s_barrier
	global_load_dwordx4 v[20:23], v157, s[48:49]
	global_load_dwordx4 v[24:27], v157, s[50:51]
	global_load_dwordx4 v[28:31], v157, s[48:49] offset:16
	global_load_dwordx4 v[36:39], v157, s[50:51] offset:16
	v_lshl_add_u32 v6, v32, 3, 0
	v_lshlrev_b32_e32 v7, 1, v32
	v_add_u32_e32 v160, 0x11000, v6
	v_mul_u32_u24_e32 v5, 0x110, v5
	v_add3_u32 v155, 0, v7, v5
	ds_read_b64 v[6:7], v160
	v_ashrrev_i32_e32 v44, 2, v4
	v_and_b32_e32 v50, 15, v4
	v_mov_b32_e32 v49, v33
	v_readlane_b32 s56, v254, 12
	v_readlane_b32 s58, v254, 14
	v_readlane_b32 s59, v254, 15
	v_readlane_b32 s57, v254, 13
	v_readlane_b32 s60, v254, 16
	v_readlane_b32 s61, v254, 17
	v_readlane_b32 s62, v254, 18
	v_readlane_b32 s63, v254, 19
	v_readlane_b32 s64, v254, 20
	v_readlane_b32 s65, v254, 21
	v_readlane_b32 s66, v254, 22
	v_readlane_b32 s67, v254, 23
	v_readlane_b32 s68, v254, 24
	v_readlane_b32 s69, v254, 25
	v_readlane_b32 s70, v254, 26
	v_readlane_b32 s71, v254, 27
	s_waitcnt vmcnt(7)
	v_lshlrev_b32_e32 v5, 16, v8
	s_waitcnt lgkmcnt(0)
	v_sub_f32_e32 v5, v5, v6
	v_and_b32_e32 v8, 0xffff0000, v8
	v_mul_f32_e32 v5, v7, v5
	v_lshlrev_b32_e32 v32, 16, v9
	v_sub_f32_e32 v8, v8, v6
	s_waitcnt vmcnt(2)
	v_fma_f32 v5, v20, v5, v24
	v_and_b32_e32 v9, 0xffff0000, v9
	v_sub_f32_e32 v32, v32, v6
	v_mul_f32_e32 v8, v7, v8
	v_cvt_pk_bf16_f32 v5, v5, v33
	v_lshlrev_b32_e32 v40, 16, v10
	v_sub_f32_e32 v9, v9, v6
	v_mul_f32_e32 v32, v7, v32
	v_fma_f32 v8, v21, v8, v25
	ds_write_b16 v155, v5
	v_cvt_pk_bf16_f32 v5, v8, v33
	v_and_b32_e32 v10, 0xffff0000, v10
	v_sub_f32_e32 v40, v40, v6
	v_mul_f32_e32 v9, v7, v9
	v_fma_f32 v20, v22, v32, v26
	ds_write_b16 v155, v5 offset:272
	v_cvt_pk_bf16_f32 v5, v20, v33
	v_lshlrev_b32_e32 v41, 16, v11
	v_sub_f32_e32 v10, v10, v6
	v_mul_f32_e32 v40, v7, v40
	v_fmac_f32_e32 v27, v23, v9
	ds_write_b16 v155, v5 offset:544
	v_cvt_pk_bf16_f32 v5, v27, v33
	v_and_b32_e32 v11, 0xffff0000, v11
	v_sub_f32_e32 v41, v41, v6
	v_mul_f32_e32 v10, v7, v10
	s_waitcnt vmcnt(0)
	v_fma_f32 v9, v40, v28, v36
	ds_write_b16 v155, v5 offset:816
	v_cvt_pk_bf16_f32 v5, v9, v33
	v_sub_f32_e32 v11, v11, v6
	v_mul_f32_e32 v41, v7, v41
	v_fma_f32 v10, v10, v29, v37
	ds_write_b16 v155, v5 offset:1088
	v_cvt_pk_bf16_f32 v5, v10, v33
	v_mul_f32_e32 v11, v7, v11
	v_fma_f32 v21, v41, v30, v38
	ds_write_b16 v155, v5 offset:1360
	v_cvt_pk_bf16_f32 v5, v21, v33
	v_fmac_f32_e32 v39, v11, v31
	ds_write_b16 v155, v5 offset:1632
	v_cvt_pk_bf16_f32 v5, v39, v33
	global_load_dwordx4 v[8:11], v157, s[48:49] offset:128
	global_load_dwordx4 v[20:23], v157, s[50:51] offset:128
	global_load_dwordx4 v[24:27], v157, s[48:49] offset:144
	global_load_dwordx4 v[28:31], v157, s[50:51] offset:144
	v_lshlrev_b32_e32 v32, 16, v12
	v_sub_f32_e32 v32, v32, v6
	v_and_b32_e32 v12, 0xffff0000, v12
	v_mul_f32_e32 v32, v7, v32
	v_lshlrev_b32_e32 v36, 16, v13
	v_sub_f32_e32 v12, v12, v6
	ds_write_b16 v155, v5 offset:1904
	v_and_b32_e32 v13, 0xffff0000, v13
	v_sub_f32_e32 v36, v36, v6
	v_mul_f32_e32 v12, v7, v12
	v_lshlrev_b32_e32 v37, 16, v14
	v_sub_f32_e32 v13, v13, v6
	v_mul_f32_e32 v36, v7, v36
	v_and_b32_e32 v14, 0xffff0000, v14
	v_sub_f32_e32 v37, v37, v6
	v_mul_f32_e32 v13, v7, v13
	v_lshlrev_b32_e32 v38, 16, v15
	v_sub_f32_e32 v14, v14, v6
	v_mul_f32_e32 v37, v7, v37
	v_and_b32_e32 v15, 0xffff0000, v15
	v_sub_f32_e32 v38, v38, v6
	v_mul_f32_e32 v14, v7, v14
	v_sub_f32_e32 v15, v15, v6
	v_mul_f32_e32 v38, v7, v38
	v_mul_f32_e32 v15, v7, v15
	s_waitcnt vmcnt(2)
	v_fma_f32 v5, v32, v8, v20
	v_cvt_pk_bf16_f32 v5, v5, v33
	v_fma_f32 v8, v12, v9, v21
	ds_write_b16 v155, v5 offset:8704
	v_cvt_pk_bf16_f32 v5, v8, v33
	v_fma_f32 v9, v36, v10, v22
	ds_write_b16 v155, v5 offset:8976
	v_cvt_pk_bf16_f32 v5, v9, v33
	v_fmac_f32_e32 v23, v13, v11
	ds_write_b16 v155, v5 offset:9248
	v_cvt_pk_bf16_f32 v5, v23, v33
	s_waitcnt vmcnt(0)
	v_fma_f32 v10, v37, v24, v28
	ds_write_b16 v155, v5 offset:9520
	v_cvt_pk_bf16_f32 v5, v10, v33
	v_fma_f32 v11, v14, v25, v29
	ds_write_b16 v155, v5 offset:9792
	v_cvt_pk_bf16_f32 v5, v11, v33
	v_fma_f32 v12, v38, v26, v30
	ds_write_b16 v155, v5 offset:10064
	v_cvt_pk_bf16_f32 v5, v12, v33
	v_fmac_f32_e32 v31, v15, v27
	ds_write_b16 v155, v5 offset:10336
	v_cvt_pk_bf16_f32 v5, v31, v33
	global_load_dwordx4 v[8:11], v157, s[48:49] offset:256
	global_load_dwordx4 v[12:15], v157, s[50:51] offset:256
	global_load_dwordx4 v[20:23], v157, s[48:49] offset:272
	global_load_dwordx4 v[24:27], v157, s[50:51] offset:272
	v_lshlrev_b32_e32 v28, 16, v16
	v_sub_f32_e32 v28, v28, v6
	v_and_b32_e32 v16, 0xffff0000, v16
	v_mul_f32_e32 v28, v7, v28
	v_lshlrev_b32_e32 v29, 16, v17
	v_sub_f32_e32 v16, v16, v6
	ds_write_b16 v155, v5 offset:10608
	v_and_b32_e32 v17, 0xffff0000, v17
	v_sub_f32_e32 v29, v29, v6
	v_mul_f32_e32 v16, v7, v16
	v_lshlrev_b32_e32 v30, 16, v18
	v_sub_f32_e32 v17, v17, v6
	v_mul_f32_e32 v29, v7, v29
	v_and_b32_e32 v18, 0xffff0000, v18
	v_sub_f32_e32 v30, v30, v6
	v_mul_f32_e32 v17, v7, v17
	v_lshlrev_b32_e32 v31, 16, v19
	v_sub_f32_e32 v18, v18, v6
	v_mul_f32_e32 v30, v7, v30
	v_and_b32_e32 v19, 0xffff0000, v19
	v_sub_f32_e32 v31, v31, v6
	v_mul_f32_e32 v18, v7, v18
	v_sub_f32_e32 v19, v19, v6
	v_mul_f32_e32 v31, v7, v31
	v_mul_f32_e32 v19, v7, v19
	s_waitcnt vmcnt(2)
	v_fma_f32 v5, v28, v8, v12
	v_cvt_pk_bf16_f32 v5, v5, v33
	v_fma_f32 v8, v16, v9, v13
	ds_write_b16 v155, v5 offset:17408
	v_cvt_pk_bf16_f32 v5, v8, v33
	v_fma_f32 v9, v29, v10, v14
	ds_write_b16 v155, v5 offset:17680
	v_cvt_pk_bf16_f32 v5, v9, v33
	v_fmac_f32_e32 v15, v17, v11
	ds_write_b16 v155, v5 offset:17952
	v_cvt_pk_bf16_f32 v5, v15, v33
	s_waitcnt vmcnt(0)
	v_fma_f32 v10, v30, v20, v24
	ds_write_b16 v155, v5 offset:18224
	v_cvt_pk_bf16_f32 v5, v10, v33
	v_fma_f32 v11, v18, v21, v25
	ds_write_b16 v155, v5 offset:18496
	v_cvt_pk_bf16_f32 v5, v11, v33
	v_fma_f32 v12, v31, v22, v26
	ds_write_b16 v155, v5 offset:18768
	v_cvt_pk_bf16_f32 v5, v12, v33
	v_fmac_f32_e32 v27, v19, v23
	ds_write_b16 v155, v5 offset:19040
	v_cvt_pk_bf16_f32 v5, v27, v33
	global_load_dwordx4 v[8:11], v157, s[48:49] offset:384
	global_load_dwordx4 v[12:15], v157, s[50:51] offset:384
	global_load_dwordx4 v[16:19], v157, s[48:49] offset:400
	global_load_dwordx4 v[20:23], v157, s[50:51] offset:400
	v_bfe_u32 v24, v4, 4, 2
	v_and_b32_e32 v26, -16, v44
	v_lshlrev_b32_e32 v32, 3, v24
	v_lshlrev_b32_e32 v48, 4, v24
	v_ashrrev_i32_e32 v25, 31, v26
	v_or_b32_e32 v24, v26, v50
	v_lshl_add_u64 v[26:27], s[0:1], 0, v[48:49]
	v_lshl_add_u64 v[36:37], s[4:5], 0, v[24:25]
	v_lshlrev_b64 v[24:25], 8, v[24:25]
	v_lshl_add_u64 v[42:43], v[26:27], 0, v[24:25]
	v_lshlrev_b32_e32 v24, 16, v0
	v_and_b32_e32 v0, 0xffff0000, v0
	v_lshlrev_b32_e32 v27, 16, v3
	v_and_b32_e32 v3, 0xffff0000, v3
	v_sub_f32_e32 v0, v0, v6
	v_lshlrev_b32_e32 v25, 16, v1
	v_and_b32_e32 v1, 0xffff0000, v1
	v_lshlrev_b32_e32 v26, 16, v2
	v_and_b32_e32 v2, 0xffff0000, v2
	v_sub_f32_e32 v24, v24, v6
	v_sub_f32_e32 v3, v3, v6
	v_mul_f32_e32 v0, v7, v0
	v_sub_f32_e32 v25, v25, v6
	v_sub_f32_e32 v1, v1, v6
	v_sub_f32_e32 v26, v26, v6
	v_sub_f32_e32 v2, v2, v6
	v_sub_f32_e32 v27, v27, v6
	v_mul_f32_e32 v6, v7, v24
	v_mul_f32_e32 v3, v7, v3
	v_mul_f32_e32 v24, v7, v25
	ds_write_b16 v155, v5 offset:19312
	v_mul_f32_e32 v1, v7, v1
	v_mul_f32_e32 v25, v7, v26
	v_mul_f32_e32 v2, v7, v2
	v_mul_f32_e32 v26, v7, v27
	v_mad_u64_u32 v[38:39], s[12:13], v36, s9, v[34:35]
	s_waitcnt vmcnt(2)
	v_fma_f32 v0, v0, v9, v13
	v_fma_f32 v5, v6, v8, v12
	s_waitcnt vmcnt(0)
	v_fmac_f32_e32 v23, v3, v19
	v_cvt_pk_bf16_f32 v3, v5, v33
	ds_write_b16 v155, v3 offset:26112
	v_cvt_pk_bf16_f32 v0, v0, v33
	v_fma_f32 v6, v24, v10, v14
	ds_write_b16 v155, v0 offset:26384
	v_cvt_pk_bf16_f32 v0, v6, v33
	v_fmac_f32_e32 v15, v1, v11
	ds_write_b16 v155, v0 offset:26656
	v_cvt_pk_bf16_f32 v0, v15, v33
	v_fma_f32 v1, v25, v16, v20
	ds_write_b16 v155, v0 offset:26928
	v_cvt_pk_bf16_f32 v0, v1, v33
	v_fma_f32 v2, v2, v17, v21
	ds_write_b16 v155, v0 offset:27200
	v_cvt_pk_bf16_f32 v0, v2, v33
	v_fma_f32 v7, v26, v18, v22
	ds_write_b16 v155, v0 offset:27472
	v_cvt_pk_bf16_f32 v0, v7, v33
	ds_write_b16 v155, v0 offset:27744
	v_cvt_pk_bf16_f32 v0, v23, v33
	ds_write_b16 v155, v0 offset:28016
	s_waitcnt lgkmcnt(0)
	s_barrier
	global_load_dwordx4 v[20:23], v[42:43], off
	global_load_dwordx4 v[24:27], v[42:43], off offset:64
	v_mov_b32_e32 v0, v39
	v_mad_u64_u32 v[0:1], s[12:13], v37, s9, v[0:1]
	v_mov_b32_e32 v39, v0
	v_lshl_add_u64 v[40:41], v[38:39], 0, v[32:33]
	global_load_dwordx2 v[52:53], v[40:41], off offset:1024
	global_load_dwordx4 v[28:31], v[42:43], off offset:128
	global_load_dwordx4 v[16:19], v[42:43], off offset:192
	v_bfi_b32 v0, -16, v44, v4
	v_ashrrev_i32_e32 v1, 31, v0
	v_lshl_add_u64 v[44:45], v[0:1], 2, s[58:59]
	global_load_dword v54, v[44:45], off
	v_mul_u32_u24_e32 v0, 0x110, v50
	v_add3_u32 v152, 0, v48, v0
	ds_read_b128 v[0:3], v152
	ds_read_b128 v[4:7], v152 offset:64
	ds_read_b128 v[48:51], v152 offset:128
	s_waitcnt vmcnt(5) lgkmcnt(2)
	v_mfma_f32_16x16x32_bf16 v[0:3], v[0:3], v[20:23], 0
	global_load_dwordx4 v[12:15], v[46:47], off offset:2304
	global_load_dwordx4 v[8:11], v[46:47], off offset:2368
	ds_read_b128 v[56:59], v152 offset:192
	s_waitcnt vmcnt(5)
	v_lshlrev_b32_e32 v64, 16, v52
	s_waitcnt lgkmcnt(2)
	v_mfma_f32_16x16x32_bf16 v[60:63], v[4:7], v[24:27], v[0:3]
	v_and_b32_e32 v65, 0xffff0000, v52
	v_lshlrev_b32_e32 v52, 16, v53
	v_and_b32_e32 v53, 0xffff0000, v53
	s_waitcnt vmcnt(4) lgkmcnt(1)
	v_mfma_f32_16x16x32_bf16 v[48:51], v[48:51], v[28:31], v[60:63]
	global_load_dwordx4 v[4:7], v[46:47], off offset:2432
	global_load_dwordx4 v[0:3], v[46:47], off offset:2496
	s_waitcnt vmcnt(0)
	v_lshlrev_b32_e32 v101, 16, v2
	s_waitcnt lgkmcnt(0)
	v_mfma_f32_16x16x32_bf16 v[48:51], v[56:59], v[16:19], v[48:51]
	v_and_b32_e32 v102, 0xffff0000, v2
	v_and_b32_e32 v100, 0xffff0000, v1
	v_lshlrev_b32_e32 v103, 16, v3
	v_and_b32_e32 v104, 0xffff0000, v3
	s_nop 3
	v_pk_add_f32 v[48:49], v[54:55], v[48:49] op_sel_hi:[0,1]
	v_pk_add_f32 v[50:51], v[54:55], v[50:51] op_sel_hi:[0,1]
	v_pk_mul_f32 v[48:49], v[48:49], v[64:65]
	v_pk_mul_f32 v[50:51], v[50:51], v[52:53]
	v_cvt_pk_bf16_f32 v150, v48, v49
	v_mul_f32_e32 v2, v49, v49
	v_cvt_pk_bf16_f32 v148, v50, v51
	ds_read_b128 v[56:59], v152 offset:4352
	ds_read_b128 v[60:63], v152 offset:4416
	s_waitcnt lgkmcnt(1)
	v_mfma_f32_16x16x32_bf16 v[56:59], v[56:59], v[20:23], 0
	v_pk_fma_f32 v[2:3], v[48:49], v[48:49], v[2:3] op_sel_hi:[1,1,0]
	s_nop 0
	v_mov_b32_e32 v84, v2
	s_waitcnt lgkmcnt(0)
	v_mfma_f32_16x16x32_bf16 v[56:59], v[60:63], v[24:27], v[56:59]
	ds_read_b128 v[60:63], v152 offset:4480
	ds_read_b128 v[64:67], v152 offset:4544
	global_load_dwordx2 v[52:53], v[40:41], off offset:1056
	s_waitcnt lgkmcnt(1)
	v_mfma_f32_16x16x32_bf16 v[56:59], v[60:63], v[28:31], v[56:59]
	s_waitcnt vmcnt(0)
	v_lshlrev_b32_e32 v60, 16, v52
	s_waitcnt lgkmcnt(0)
	v_mfma_f32_16x16x32_bf16 v[56:59], v[64:67], v[16:19], v[56:59]
	v_and_b32_e32 v61, 0xffff0000, v52
	v_lshlrev_b32_e32 v62, 16, v53
	v_and_b32_e32 v63, 0xffff0000, v53
	s_nop 4
	v_pk_add_f32 v[56:57], v[54:55], v[56:57] op_sel_hi:[0,1]
	v_pk_add_f32 v[58:59], v[54:55], v[58:59] op_sel_hi:[0,1]
	v_pk_mul_f32 v[52:53], v[56:57], v[60:61]
	v_pk_mul_f32 v[60:61], v[58:59], v[62:63]
	v_cvt_pk_bf16_f32 v145, v52, v53
	s_nop 0
	v_cvt_pk_bf16_f32 v142, v60, v61
	ds_read_b128 v[56:59], v152 offset:8704
	ds_read_b128 v[62:65], v152 offset:8768
	s_waitcnt lgkmcnt(1)
	v_mfma_f32_16x16x32_bf16 v[56:59], v[56:59], v[20:23], 0
	s_waitcnt lgkmcnt(0)
	v_mfma_f32_16x16x32_bf16 v[56:59], v[62:65], v[24:27], v[56:59]
	ds_read_b128 v[62:65], v152 offset:8832
	ds_read_b128 v[66:69], v152 offset:8896
	s_waitcnt lgkmcnt(1)
	v_mfma_f32_16x16x32_bf16 v[56:59], v[62:65], v[28:31], v[56:59]
	global_load_dwordx2 v[62:63], v[40:41], off offset:1088
	s_waitcnt vmcnt(0)
	v_lshlrev_b32_e32 v65, 16, v63
	s_waitcnt lgkmcnt(0)
	v_mfma_f32_16x16x32_bf16 v[56:59], v[66:69], v[16:19], v[56:59]
	v_and_b32_e32 v63, 0xffff0000, v63
	s_nop 6
	v_add_f32_e32 v55, v54, v56
	v_add_f32_e32 v56, v54, v57
	v_add_f32_e32 v57, v54, v58
	v_add_f32_e32 v58, v54, v59
	v_lshlrev_b32_e32 v59, 16, v62
	v_and_b32_e32 v62, 0xffff0000, v62
	v_mul_f32_e32 v64, v55, v59
	v_mul_f32_e32 v68, v56, v62
	v_mul_f32_e32 v66, v57, v65
	v_mul_f32_e32 v62, v58, v63
	v_cvt_pk_bf16_f32 v139, v64, v68
	v_cvt_pk_bf16_f32 v137, v66, v62
	ds_read_b128 v[56:59], v152 offset:13056
	ds_read_b128 v[70:73], v152 offset:13120
	s_waitcnt lgkmcnt(1)
	v_mfma_f32_16x16x32_bf16 v[56:59], v[56:59], v[20:23], 0
	s_waitcnt lgkmcnt(0)
	v_mfma_f32_16x16x32_bf16 v[56:59], v[70:73], v[24:27], v[56:59]
	ds_read_b128 v[70:73], v152 offset:13184
	ds_read_b128 v[74:77], v152 offset:13248
	global_load_dwordx2 v[78:79], v[40:41], off offset:1120
	s_waitcnt lgkmcnt(1)
	v_mfma_f32_16x16x32_bf16 v[56:59], v[70:73], v[28:31], v[56:59]
	v_mov_b32_e32 v70, v64
	v_mov_b32_e32 v72, v66
	s_waitcnt vmcnt(0)
	v_lshlrev_b32_e32 v71, 16, v79
	s_waitcnt lgkmcnt(0)
	v_mfma_f32_16x16x32_bf16 v[56:59], v[74:77], v[16:19], v[56:59]
	v_and_b32_e32 v73, 0xffff0000, v79
	s_nop 6
	v_add_f32_e32 v55, v54, v56
	v_add_f32_e32 v56, v54, v57
	v_add_f32_e32 v65, v54, v58
	v_add_f32_e32 v67, v54, v59
	v_lshlrev_b32_e32 v57, 16, v78
	v_and_b32_e32 v58, 0xffff0000, v78
	v_mul_f32_e32 v85, v55, v57
	v_mul_f32_e32 v75, v56, v58
	v_pk_mul_f32 v[86:87], v[64:65], v[70:71]
	v_pk_mul_f32 v[88:89], v[66:67], v[72:73]
	v_cvt_pk_bf16_f32 v136, v85, v75
	v_lshlrev_b32_e32 v72, 16, v15
	v_cvt_pk_bf16_f32 v133, v87, v89
	ds_read_b128 v[56:59], v152 offset:17408
	ds_read_b128 v[76:79], v152 offset:17472
	s_waitcnt lgkmcnt(1)
	v_mfma_f32_16x16x32_bf16 v[56:59], v[56:59], v[20:23], 0
	v_and_b32_e32 v15, 0xffff0000, v15
	v_pk_mul_f32 v[48:49], v[88:89], v[88:89]
	s_waitcnt lgkmcnt(0)
	v_mfma_f32_16x16x32_bf16 v[56:59], v[76:79], v[24:27], v[56:59]
	ds_read_b128 v[76:79], v152 offset:17536
	ds_read_b128 v[80:83], v152 offset:17600
	s_waitcnt lgkmcnt(1)
	v_mfma_f32_16x16x32_bf16 v[56:59], v[76:79], v[28:31], v[56:59]
	global_load_dwordx2 v[76:77], v[40:41], off offset:1152
	s_waitcnt lgkmcnt(0)
	v_mfma_f32_16x16x32_bf16 v[56:59], v[80:83], v[16:19], v[56:59]
	s_nop 7
	v_mov_b32_e32 v78, v56
	v_mov_b32_e32 v79, v58
	v_mov_b32_e32 v58, v57
	v_pk_add_f32 v[56:57], v[54:55], v[78:79] op_sel_hi:[0,1]
	v_pk_add_f32 v[58:59], v[54:55], v[58:59] op_sel_hi:[0,1]
	s_waitcnt vmcnt(0)
	v_lshlrev_b32_e32 v79, 16, v77
	v_lshlrev_b32_e32 v78, 16, v76
	v_and_b32_e32 v77, 0xffff0000, v77
	v_and_b32_e32 v76, 0xffff0000, v76
	v_pk_mul_f32 v[90:91], v[56:57], v[78:79]
	v_pk_mul_f32 v[92:93], v[58:59], v[76:77]
	s_nop 0
	v_cvt_pk_bf16_f32 v134, v90, v92
	v_cvt_pk_bf16_f32 v132, v91, v93
	ds_read_b128 v[56:59], v152 offset:21760
	ds_read_b128 v[76:79], v152 offset:21824
	s_waitcnt lgkmcnt(1)
	v_mfma_f32_16x16x32_bf16 v[56:59], v[56:59], v[20:23], 0
	s_waitcnt lgkmcnt(0)
	v_mfma_f32_16x16x32_bf16 v[56:59], v[76:79], v[24:27], v[56:59]
	ds_read_b128 v[76:79], v152 offset:21888
	ds_read_b128 v[80:83], v152 offset:21952
	s_waitcnt lgkmcnt(1)
	v_mfma_f32_16x16x32_bf16 v[56:59], v[76:79], v[28:31], v[56:59]
	global_load_dwordx2 v[76:77], v[40:41], off offset:1184
	s_waitcnt lgkmcnt(0)
	v_mfma_f32_16x16x32_bf16 v[56:59], v[80:83], v[16:19], v[56:59]
	s_nop 7
	v_pk_add_f32 v[56:57], v[54:55], v[56:57] op_sel_hi:[0,1]
	v_pk_add_f32 v[78:79], v[54:55], v[58:59] op_sel_hi:[0,1]
	s_waitcnt vmcnt(0)
	v_lshlrev_b32_e32 v58, 16, v76
	v_and_b32_e32 v59, 0xffff0000, v76
	v_lshlrev_b32_e32 v76, 16, v77
	v_and_b32_e32 v77, 0xffff0000, v77
	v_pk_mul_f32 v[58:59], v[56:57], v[58:59]
	v_pk_mul_f32 v[94:95], v[78:79], v[76:77]
	v_cvt_pk_bf16_f32 v130, v58, v59
	s_nop 0
	v_cvt_pk_bf16_f32 v129, v94, v95
	ds_read_b128 v[76:79], v152 offset:26112
	ds_read_b128 v[80:83], v152 offset:26176
	s_waitcnt lgkmcnt(1)
	v_mfma_f32_16x16x32_bf16 v[76:79], v[76:79], v[20:23], 0
	s_waitcnt lgkmcnt(0)
	v_mfma_f32_16x16x32_bf16 v[76:79], v[80:83], v[24:27], v[76:79]
	ds_read_b128 v[80:83], v152 offset:26240
	ds_read_b128 v[96:99], v152 offset:26304
	global_load_dwordx2 v[56:57], v[40:41], off offset:1216
	s_waitcnt vmcnt(0)
	v_lshlrev_b32_e32 v66, 16, v56
	s_waitcnt lgkmcnt(1)
	v_mfma_f32_16x16x32_bf16 v[76:79], v[80:83], v[28:31], v[76:79]
	v_and_b32_e32 v56, 0xffff0000, v56
	v_lshlrev_b32_e32 v70, 16, v57
	v_and_b32_e32 v57, 0xffff0000, v57
	s_waitcnt lgkmcnt(0)
	v_mfma_f32_16x16x32_bf16 v[76:79], v[96:99], v[16:19], v[76:79]
	s_nop 7
	v_add_f32_e32 v55, v54, v76
	v_add_f32_e32 v63, v54, v77
	v_add_f32_e32 v64, v54, v78
	v_add_f32_e32 v69, v54, v79
	v_mul_f32_e32 v96, v55, v66
	v_mul_f32_e32 v66, v63, v56
	v_mul_f32_e32 v98, v64, v70
	v_mul_f32_e32 v64, v69, v57
	v_cvt_pk_bf16_f32 v128, v96, v66
	v_cvt_pk_bf16_f32 v127, v98, v64
	ds_read_b128 v[76:79], v152 offset:30464
	ds_read_b128 v[80:83], v152 offset:30528
	s_waitcnt lgkmcnt(1)
	v_mfma_f32_16x16x32_bf16 v[20:23], v[76:79], v[20:23], 0
	v_mov_b32_e32 v76, v96
	v_mov_b32_e32 v78, v98
	v_and_b32_e32 v56, 0xffff0000, v12
	s_waitcnt lgkmcnt(0)
	v_mfma_f32_16x16x32_bf16 v[20:23], v[80:83], v[24:27], v[20:23]
	ds_read_b128 v[24:27], v152 offset:30592
	ds_read_b128 v[80:83], v152 offset:30656
	v_lshlrev_b32_e32 v63, 16, v13
	v_and_b32_e32 v69, 0xffff0000, v13
	s_waitcnt lgkmcnt(1)
	v_mfma_f32_16x16x32_bf16 v[20:23], v[24:27], v[28:31], v[20:23]
	global_load_dwordx2 v[24:25], v[40:41], off offset:1248
	v_lshlrev_b32_e32 v70, 16, v14
	v_and_b32_e32 v14, 0xffff0000, v14
	s_waitcnt lgkmcnt(0)
	v_mfma_f32_16x16x32_bf16 v[16:19], v[80:83], v[16:19], v[20:23]
	s_waitcnt vmcnt(0)
	v_lshlrev_b32_e32 v77, 16, v25
	s_nop 5
	v_add_f32_e32 v16, v54, v16
	v_add_f32_e32 v17, v54, v17
	v_add_f32_e32 v97, v54, v18
	v_add_f32_e32 v99, v54, v19
	v_lshlrev_b32_e32 v18, 16, v24
	v_and_b32_e32 v19, 0xffff0000, v24
	v_and_b32_e32 v79, 0xffff0000, v25
	v_mul_f32_e32 v57, v16, v18
	v_mul_f32_e32 v55, v17, v19
	v_pk_mul_f32 v[80:81], v[96:97], v[76:77]
	v_pk_mul_f32 v[82:83], v[98:99], v[78:79]
	v_cvt_pk_bf16_f32 v126, v57, v55
	v_lshlrev_b32_e32 v54, 16, v12
	v_cvt_pk_bf16_f32 v125, v81, v83
	global_load_dwordx4 v[16:19], v157, s[48:49] offset:512
	global_load_dwordx4 v[20:23], v157, s[50:51] offset:512
	global_load_dwordx4 v[24:27], v157, s[48:49] offset:528
	global_load_dwordx4 v[28:31], v157, s[50:51] offset:528
	ds_read_b64 v[12:13], v160
	v_and_b32_e32 v96, 0xffff0000, v0
	v_lshlrev_b32_e32 v98, 16, v1
	v_mov_b32_e32 v76, v66
	v_mov_b32_e32 v78, v64
	s_waitcnt lgkmcnt(0)
	v_sub_f32_e32 v54, v54, v12
	v_sub_f32_e32 v15, v15, v12
	v_sub_f32_e32 v56, v56, v12
	v_mul_f32_e32 v54, v13, v54
	v_mul_f32_e32 v15, v13, v15
	v_sub_f32_e32 v63, v63, v12
	v_mul_f32_e32 v56, v13, v56
	v_sub_f32_e32 v69, v69, v12
	v_sub_f32_e32 v14, v14, v12
	v_mul_f32_e32 v63, v13, v63
	v_sub_f32_e32 v70, v70, v12
	v_mul_f32_e32 v69, v13, v69
	v_mul_f32_e32 v14, v13, v14
	v_sub_f32_e32 v72, v72, v12
	v_mul_f32_e32 v70, v13, v70
	v_mul_f32_e32 v72, v13, v72
	s_waitcnt vmcnt(2)
	v_fma_f32 v16, v16, v54, v20
	v_fma_f32 v17, v17, v56, v21
	s_waitcnt vmcnt(0)
	v_fmac_f32_e32 v31, v27, v15
	v_cvt_pk_bf16_f32 v15, v16, v33
	ds_write_b16 v155, v15 offset:34816
	v_cvt_pk_bf16_f32 v15, v17, v33
	v_fma_f32 v18, v18, v63, v22
	ds_write_b16 v155, v15 offset:35088
	v_cvt_pk_bf16_f32 v15, v18, v33
	v_fmac_f32_e32 v23, v19, v69
	v_fma_f32 v14, v25, v14, v29
	ds_write_b16 v155, v15 offset:35360
	v_cvt_pk_bf16_f32 v15, v23, v33
	v_fma_f32 v19, v24, v70, v28
	ds_write_b16 v155, v15 offset:35632
	v_cvt_pk_bf16_f32 v15, v19, v33
	ds_write_b16 v155, v15 offset:35904
	v_cvt_pk_bf16_f32 v14, v14, v33
	v_fma_f32 v20, v26, v72, v30
	ds_write_b16 v155, v14 offset:36176
	v_cvt_pk_bf16_f32 v14, v20, v33
	ds_write_b16 v155, v14 offset:36448
	v_cvt_pk_bf16_f32 v30, v31, v33
	global_load_dwordx4 v[14:17], v157, s[48:49] offset:640
	global_load_dwordx4 v[18:21], v157, s[50:51] offset:640
	global_load_dwordx4 v[22:25], v157, s[48:49] offset:656
	global_load_dwordx4 v[26:29], v157, s[50:51] offset:656
	v_lshlrev_b32_e32 v31, 16, v8
	v_and_b32_e32 v8, 0xffff0000, v8
	v_lshlrev_b32_e32 v63, 16, v11
	v_and_b32_e32 v11, 0xffff0000, v11
	v_sub_f32_e32 v8, v8, v12
	v_lshlrev_b32_e32 v54, 16, v9
	v_sub_f32_e32 v31, v31, v12
	v_sub_f32_e32 v11, v11, v12
	v_mul_f32_e32 v8, v13, v8
	v_and_b32_e32 v9, 0xffff0000, v9
	v_sub_f32_e32 v54, v54, v12
	v_mul_f32_e32 v31, v13, v31
	v_mul_f32_e32 v11, v13, v11
	v_lshlrev_b32_e32 v56, 16, v10
	v_sub_f32_e32 v9, v9, v12
	v_mul_f32_e32 v54, v13, v54
	ds_write_b16 v155, v30 offset:36720
	v_and_b32_e32 v10, 0xffff0000, v10
	v_sub_f32_e32 v56, v56, v12
	v_mul_f32_e32 v9, v13, v9
	v_sub_f32_e32 v10, v10, v12
	v_mul_f32_e32 v56, v13, v56
	v_sub_f32_e32 v63, v63, v12
	v_mul_f32_e32 v10, v13, v10
	v_mul_f32_e32 v63, v13, v63
	v_lshlrev_b32_e32 v30, 16, v7
	v_and_b32_e32 v7, 0xffff0000, v7
	v_sub_f32_e32 v7, v7, v12
	v_mul_f32_e32 v7, v13, v7
	v_sub_f32_e32 v30, v30, v12
	v_mul_f32_e32 v30, v13, v30
	v_mov_b32_e32 v69, v65
	v_mov_b32_e32 v70, v68
	v_mov_b32_e32 v72, v62
	v_mov_b32_e32 v65, v99
	s_waitcnt vmcnt(2)
	v_fma_f32 v8, v8, v15, v19
	v_fma_f32 v14, v31, v14, v18
	s_waitcnt vmcnt(0)
	v_fmac_f32_e32 v29, v11, v25
	v_cvt_pk_bf16_f32 v11, v14, v33
	ds_write_b16 v155, v11 offset:43520
	v_cvt_pk_bf16_f32 v8, v8, v33
	v_fma_f32 v15, v54, v16, v20
	ds_write_b16 v155, v8 offset:43792
	v_cvt_pk_bf16_f32 v8, v15, v33
	v_fmac_f32_e32 v21, v9, v17
	ds_write_b16 v155, v8 offset:44064
	v_cvt_pk_bf16_f32 v8, v21, v33
	v_fma_f32 v9, v56, v22, v26
	ds_write_b16 v155, v8 offset:44336
	v_cvt_pk_bf16_f32 v8, v9, v33
	v_fma_f32 v10, v10, v23, v27
	ds_write_b16 v155, v8 offset:44608
	v_cvt_pk_bf16_f32 v8, v10, v33
	v_fma_f32 v16, v63, v24, v28
	ds_write_b16 v155, v8 offset:44880
	v_cvt_pk_bf16_f32 v8, v16, v33
	ds_write_b16 v155, v8 offset:45152
	v_cvt_pk_bf16_f32 v26, v29, v33
	global_load_dwordx4 v[8:11], v157, s[48:49] offset:768
	global_load_dwordx4 v[14:17], v157, s[50:51] offset:768
	global_load_dwordx4 v[18:21], v157, s[48:49] offset:784
	global_load_dwordx4 v[22:25], v157, s[50:51] offset:784
	v_lshlrev_b32_e32 v27, 16, v4
	v_and_b32_e32 v4, 0xffff0000, v4
	v_sub_f32_e32 v4, v4, v12
	v_lshlrev_b32_e32 v28, 16, v5
	v_sub_f32_e32 v27, v27, v12
	v_mul_f32_e32 v4, v13, v4
	v_and_b32_e32 v5, 0xffff0000, v5
	v_sub_f32_e32 v28, v28, v12
	v_mul_f32_e32 v27, v13, v27
	v_lshlrev_b32_e32 v29, 16, v6
	v_sub_f32_e32 v5, v5, v12
	v_mul_f32_e32 v28, v13, v28
	ds_write_b16 v155, v26 offset:45424
	v_and_b32_e32 v6, 0xffff0000, v6
	v_sub_f32_e32 v29, v29, v12
	v_mul_f32_e32 v5, v13, v5
	v_sub_f32_e32 v6, v6, v12
	v_mul_f32_e32 v29, v13, v29
	v_mul_f32_e32 v6, v13, v6
	v_lshlrev_b32_e32 v56, 16, v0
	v_mul_f32_e32 v0, v51, v51
	v_pk_fma_f32 v[0:1], v[50:51], v[50:51], v[0:1] op_sel_hi:[1,1,0]
	v_mov_b32_e32 v63, v67
	v_mov_b32_e32 v67, v97
	s_waitcnt vmcnt(2)
	v_fma_f32 v4, v4, v9, v15
	v_fma_f32 v8, v27, v8, v14
	s_waitcnt vmcnt(0)
	v_fmac_f32_e32 v25, v7, v21
	v_cvt_pk_bf16_f32 v7, v8, v33
	ds_write_b16 v155, v7 offset:52224
	v_cvt_pk_bf16_f32 v4, v4, v33
	v_fma_f32 v9, v28, v10, v16
	ds_write_b16 v155, v4 offset:52496
	v_cvt_pk_bf16_f32 v4, v9, v33
	v_fmac_f32_e32 v17, v5, v11
	ds_write_b16 v155, v4 offset:52768
	v_cvt_pk_bf16_f32 v4, v17, v33
	v_fma_f32 v5, v29, v18, v22
	ds_write_b16 v155, v4 offset:53040
	v_cvt_pk_bf16_f32 v4, v5, v33
	v_fma_f32 v6, v6, v19, v23
	ds_write_b16 v155, v4 offset:53312
	v_cvt_pk_bf16_f32 v4, v6, v33
	v_fma_f32 v10, v30, v20, v24
	ds_write_b16 v155, v4 offset:53584
	v_cvt_pk_bf16_f32 v4, v10, v33
	ds_write_b16 v155, v4 offset:53856
	v_cvt_pk_bf16_f32 v54, v25, v33
	global_load_dwordx4 v[4:7], v157, s[48:49] offset:896
	global_load_dwordx4 v[8:11], v157, s[50:51] offset:896
	global_load_dwordx4 v[14:17], v157, s[48:49] offset:912
	global_load_dwordx4 v[18:21], v157, s[50:51] offset:912
	v_mov_b32_e32 v22, v0
	v_pk_add_f32 v[0:1], v[2:3], v[0:1]
	v_mul_f32_e32 v2, v61, v61
	v_mul_f32_e32 v24, v53, v53
	v_pk_fma_f32 v[2:3], v[60:61], v[60:61], v[2:3] op_sel_hi:[1,1,0]
	v_pk_fma_f32 v[24:25], v[52:53], v[52:53], v[24:25] op_sel_hi:[1,1,0]
	v_mov_b32_e32 v26, v2
	v_mov_b32_e32 v74, v24
	v_mov_b32_e32 v23, v85
	v_mov_b32_e32 v27, v75
	v_pk_add_f32 v[2:3], v[24:25], v[2:3]
	v_pk_fma_f32 v[24:25], v[68:69], v[70:71], v[86:87]
	v_pk_mul_f32 v[28:29], v[86:87], v[86:87]
	v_pk_fma_f32 v[30:31], v[62:63], v[72:73], v[88:89]
	v_pk_mul_f32 v[22:23], v[84:85], v[22:23]
	v_pk_mul_f32 v[26:27], v[74:75], v[26:27]
	v_mov_b32_e32 v25, v29
	v_mov_b32_e32 v31, v49
	v_mov_b32_e32 v1, v23
	v_mov_b32_e32 v3, v27
	v_pk_add_f32 v[22:23], v[24:25], v[30:31]
	v_pk_add_f32 v[0:1], v[0:1], v[2:3]
	v_sub_f32_e32 v2, v98, v12
	v_pk_add_f32 v[88:89], v[0:1], v[22:23]
	v_pk_mul_f32 v[0:1], v[92:93], v[92:93]
	ds_write_b16 v155, v54 offset:54128
	v_pk_fma_f32 v[0:1], v[90:91], v[90:91], v[0:1]
	v_sub_f32_e32 v3, v100, v12
	v_pk_add_f32 v[86:87], v[0:1], v[0:1] op_sel:[0,1] op_sel_hi:[1,0]
	v_mul_f32_e32 v0, v95, v95
	v_pk_fma_f32 v[84:85], v[94:95], v[94:95], v[0:1] op_sel_hi:[1,1,0]
	v_sub_f32_e32 v0, v56, v12
	v_mul_f32_e32 v0, v13, v0
	v_sub_f32_e32 v1, v96, v12
	v_mul_f32_e32 v1, v13, v1
	v_mul_f32_e32 v2, v13, v2
	v_sub_f32_e32 v22, v101, v12
	v_mul_f32_e32 v3, v13, v3
	v_sub_f32_e32 v23, v102, v12
	v_mul_f32_e32 v22, v13, v22
	v_sub_f32_e32 v24, v103, v12
	v_mul_f32_e32 v23, v13, v23
	v_sub_f32_e32 v12, v104, v12
	v_mul_f32_e32 v24, v13, v24
	v_mul_f32_e32 v12, v13, v12
	s_waitcnt vmcnt(2)
	v_fma_f32 v0, v0, v4, v8
	v_cvt_pk_bf16_f32 v0, v0, v33
	v_fma_f32 v1, v1, v5, v9
	ds_write_b16 v155, v0 offset:60928
	v_cvt_pk_bf16_f32 v0, v1, v33
	v_fma_f32 v2, v2, v6, v10
	ds_write_b16 v155, v0 offset:61200
	v_cvt_pk_bf16_f32 v0, v2, v33
	v_fmac_f32_e32 v11, v3, v7
	ds_write_b16 v155, v0 offset:61472
	v_cvt_pk_bf16_f32 v0, v11, v33
	s_waitcnt vmcnt(0)
	v_fma_f32 v3, v22, v14, v18
	ds_write_b16 v155, v0 offset:61744
	v_cvt_pk_bf16_f32 v0, v3, v33
	v_fma_f32 v4, v23, v15, v19
	ds_write_b16 v155, v0 offset:62016
	v_cvt_pk_bf16_f32 v0, v4, v33
	v_fma_f32 v5, v24, v16, v20
	ds_write_b16 v155, v0 offset:62288
	v_cvt_pk_bf16_f32 v0, v5, v33
	v_fmac_f32_e32 v21, v12, v17
	ds_write_b16 v155, v0 offset:62560
	v_cvt_pk_bf16_f32 v0, v21, v33
	ds_write_b16 v155, v0 offset:62832
	s_waitcnt lgkmcnt(0)
	s_barrier
	v_add_co_u32_e32 v0, vcc, s26, v42
	v_pk_fma_f32 v[66:67], v[66:67], v[76:77], v[80:81]
	s_nop 0
	v_addc_co_u32_e32 v1, vcc, 0, v43, vcc
	global_load_dwordx4 v[20:23], v[0:1], off
	global_load_dwordx4 v[24:27], v[0:1], off offset:64
	global_load_dwordx2 v[72:73], v[40:41], off offset:1280
	global_load_dwordx4 v[28:31], v[0:1], off offset:128
	global_load_dwordx4 v[16:19], v[0:1], off offset:192
	global_load_dword v48, v[44:45], off offset:512
	ds_read_b128 v[0:3], v152 offset:34816
	ds_read_b128 v[4:7], v152 offset:34880
	ds_read_b128 v[50:53], v152 offset:34944
	global_load_dwordx4 v[12:15], v[46:47], off offset:2560
	global_load_dwordx4 v[8:11], v[46:47], off offset:2624
	ds_read_b128 v[60:63], v152 offset:35008
	v_pk_mul_f32 v[76:77], v[80:81], v[80:81]
	v_pk_fma_f32 v[64:65], v[64:65], v[78:79], v[82:83]
	v_pk_mul_f32 v[78:79], v[82:83], v[82:83]
	v_mov_b32_e32 v67, v77
	v_mov_b32_e32 v65, v79
	s_waitcnt vmcnt(7) lgkmcnt(3)
	v_mfma_f32_16x16x32_bf16 v[0:3], v[0:3], v[20:23], 0
	s_waitcnt vmcnt(5)
	v_lshlrev_b32_e32 v75, 16, v73
	v_lshlrev_b32_e32 v74, 16, v72
	s_waitcnt lgkmcnt(2)
	v_mfma_f32_16x16x32_bf16 v[68:71], v[4:7], v[24:27], v[0:3]
	global_load_dwordx4 v[4:7], v[46:47], off offset:2688
	s_nop 1
	global_load_dwordx4 v[0:3], v[46:47], off offset:2752
	s_waitcnt vmcnt(0)
	v_and_b32_e32 v76, 0xffff0000, v1
	s_waitcnt lgkmcnt(1)
	v_mfma_f32_16x16x32_bf16 v[50:53], v[50:53], v[28:31], v[68:71]
	v_lshlrev_b32_e32 v77, 16, v2
	v_and_b32_e32 v78, 0xffff0000, v2
	v_lshlrev_b32_e32 v79, 16, v3
	s_waitcnt lgkmcnt(0)
	v_mfma_f32_16x16x32_bf16 v[50:53], v[60:63], v[16:19], v[50:53]
	v_and_b32_e32 v69, 0xffff0000, v73
	v_and_b32_e32 v68, 0xffff0000, v72
	v_and_b32_e32 v80, 0xffff0000, v3
	s_nop 4
	v_mov_b32_e32 v60, v50
	v_mov_b32_e32 v61, v52
	v_mov_b32_e32 v52, v51
	v_pk_add_f32 v[50:51], v[48:49], v[60:61] op_sel_hi:[0,1]
	v_pk_add_f32 v[52:53], v[48:49], v[52:53] op_sel_hi:[0,1]
	v_pk_mul_f32 v[90:91], v[50:51], v[74:75]
	v_pk_mul_f32 v[92:93], v[52:53], v[68:69]
	s_nop 0
	v_cvt_pk_bf16_f32 v156, v90, v92
	v_cvt_pk_bf16_f32 v154, v91, v93
	ds_read_b128 v[50:53], v152 offset:39168
	ds_read_b128 v[60:63], v152 offset:39232
	s_waitcnt lgkmcnt(1)
	v_mfma_f32_16x16x32_bf16 v[50:53], v[50:53], v[20:23], 0
	s_waitcnt lgkmcnt(0)
	v_mfma_f32_16x16x32_bf16 v[50:53], v[60:63], v[24:27], v[50:53]
	ds_read_b128 v[60:63], v152 offset:39296
	ds_read_b128 v[68:71], v152 offset:39360
	s_waitcnt lgkmcnt(1)
	v_mfma_f32_16x16x32_bf16 v[50:53], v[60:63], v[28:31], v[50:53]
	global_load_dwordx2 v[60:61], v[40:41], off offset:1312
	s_waitcnt vmcnt(0)
	v_lshlrev_b32_e32 v62, 16, v60
	s_waitcnt lgkmcnt(0)
	v_mfma_f32_16x16x32_bf16 v[50:53], v[68:71], v[16:19], v[50:53]
	v_and_b32_e32 v63, 0xffff0000, v60
	v_lshlrev_b32_e32 v60, 16, v61
	v_and_b32_e32 v61, 0xffff0000, v61
	s_nop 4
	v_pk_add_f32 v[50:51], v[48:49], v[50:51] op_sel_hi:[0,1]
	v_pk_add_f32 v[52:53], v[48:49], v[52:53] op_sel_hi:[0,1]
	v_pk_mul_f32 v[94:95], v[50:51], v[62:63]
	v_pk_mul_f32 v[96:97], v[52:53], v[60:61]
	v_cvt_pk_bf16_f32 v153, v94, v95
	s_nop 0
	v_cvt_pk_bf16_f32 v151, v96, v97
	ds_read_b128 v[50:53], v152 offset:43520
	ds_read_b128 v[60:63], v152 offset:43584
	s_waitcnt lgkmcnt(1)
	v_mfma_f32_16x16x32_bf16 v[50:53], v[50:53], v[20:23], 0
	s_waitcnt lgkmcnt(0)
	v_mfma_f32_16x16x32_bf16 v[50:53], v[60:63], v[24:27], v[50:53]
	ds_read_b128 v[60:63], v152 offset:43648
	ds_read_b128 v[68:71], v152 offset:43712
	s_waitcnt lgkmcnt(1)
	v_mfma_f32_16x16x32_bf16 v[50:53], v[60:63], v[28:31], v[50:53]
	global_load_dwordx2 v[60:61], v[40:41], off offset:1344
	s_waitcnt vmcnt(0)
	v_and_b32_e32 v54, 0xffff0000, v60
	s_waitcnt lgkmcnt(0)
	v_mfma_f32_16x16x32_bf16 v[50:53], v[68:71], v[16:19], v[50:53]
	v_lshlrev_b32_e32 v56, 16, v61
	v_and_b32_e32 v61, 0xffff0000, v61
	s_nop 5
	v_add_f32_e32 v49, v48, v50
	v_add_f32_e32 v50, v48, v51
	v_add_f32_e32 v51, v48, v52
	v_add_f32_e32 v52, v48, v53
	v_lshlrev_b32_e32 v53, 16, v60
	v_mul_f32_e32 v60, v49, v53
	v_mul_f32_e32 v100, v50, v54
	v_mul_f32_e32 v62, v51, v56
	v_mul_f32_e32 v98, v52, v61
	v_cvt_pk_bf16_f32 v149, v60, v100
	v_cvt_pk_bf16_f32 v147, v62, v98
	ds_read_b128 v[50:53], v152 offset:47872
	ds_read_b128 v[68:71], v152 offset:47936
	s_waitcnt lgkmcnt(1)
	v_mfma_f32_16x16x32_bf16 v[50:53], v[50:53], v[20:23], 0
	v_mov_b32_e32 v102, v60
	v_mov_b32_e32 v104, v62
	s_waitcnt lgkmcnt(0)
	v_mfma_f32_16x16x32_bf16 v[50:53], v[68:71], v[24:27], v[50:53]
	ds_read_b128 v[68:71], v152 offset:48000
	ds_read_b128 v[72:75], v152 offset:48064
	s_waitcnt lgkmcnt(1)
	v_mfma_f32_16x16x32_bf16 v[50:53], v[68:71], v[28:31], v[50:53]
	global_load_dwordx2 v[68:69], v[40:41], off offset:1376
	s_waitcnt vmcnt(0)
	v_lshlrev_b32_e32 v103, 16, v69
	s_waitcnt lgkmcnt(0)
	v_mfma_f32_16x16x32_bf16 v[50:53], v[72:75], v[16:19], v[50:53]
	v_and_b32_e32 v105, 0xffff0000, v69
	s_nop 6
	v_add_f32_e32 v49, v48, v50
	v_add_f32_e32 v50, v48, v51
	v_add_f32_e32 v61, v48, v52
	v_add_f32_e32 v63, v48, v53
	v_lshlrev_b32_e32 v51, 16, v68
	v_and_b32_e32 v52, 0xffff0000, v68
	v_mul_f32_e32 v109, v49, v51
	v_mul_f32_e32 v107, v50, v52
	v_pk_mul_f32 v[110:111], v[60:61], v[102:103]
	v_pk_mul_f32 v[112:113], v[62:63], v[104:105]
	v_cvt_pk_bf16_f32 v146, v109, v107
	v_mov_b32_e32 v101, v61
	v_cvt_pk_bf16_f32 v143, v111, v113
	ds_read_b128 v[50:53], v152 offset:52224
	ds_read_b128 v[68:71], v152 offset:52288
	s_waitcnt lgkmcnt(1)
	v_mfma_f32_16x16x32_bf16 v[50:53], v[50:53], v[20:23], 0
	v_mov_b32_e32 v99, v63
	v_mov_b32_e32 v102, v100
	v_mov_b32_e32 v104, v98
	s_waitcnt lgkmcnt(0)
	v_mfma_f32_16x16x32_bf16 v[50:53], v[68:71], v[24:27], v[50:53]
	ds_read_b128 v[68:71], v152 offset:52352
	ds_read_b128 v[72:75], v152 offset:52416
	v_mov_b32_e32 v3, v109
	s_waitcnt lgkmcnt(1)
	v_mfma_f32_16x16x32_bf16 v[50:53], v[68:71], v[28:31], v[50:53]
	global_load_dwordx2 v[68:69], v[40:41], off offset:1408
	s_waitcnt lgkmcnt(0)
	v_mfma_f32_16x16x32_bf16 v[50:53], v[72:75], v[16:19], v[50:53]
	s_nop 7
	v_mov_b32_e32 v70, v50
	v_mov_b32_e32 v71, v52
	v_mov_b32_e32 v52, v51
	v_pk_add_f32 v[50:51], v[48:49], v[70:71] op_sel_hi:[0,1]
	v_pk_add_f32 v[52:53], v[48:49], v[52:53] op_sel_hi:[0,1]
	s_waitcnt vmcnt(0)
	v_lshlrev_b32_e32 v71, 16, v69
	v_lshlrev_b32_e32 v70, 16, v68
	v_and_b32_e32 v69, 0xffff0000, v69
	v_and_b32_e32 v68, 0xffff0000, v68
	v_pk_mul_f32 v[114:115], v[50:51], v[70:71]
	v_pk_mul_f32 v[116:117], v[52:53], v[68:69]
	s_nop 0
	v_cvt_pk_bf16_f32 v144, v114, v116
	v_cvt_pk_bf16_f32 v141, v115, v117
	ds_read_b128 v[50:53], v152 offset:56576
	ds_read_b128 v[68:71], v152 offset:56640
	s_waitcnt lgkmcnt(1)
	v_mfma_f32_16x16x32_bf16 v[50:53], v[50:53], v[20:23], 0
	s_waitcnt lgkmcnt(0)
	v_mfma_f32_16x16x32_bf16 v[50:53], v[68:71], v[24:27], v[50:53]
	ds_read_b128 v[68:71], v152 offset:56704
	ds_read_b128 v[72:75], v152 offset:56768
	s_waitcnt lgkmcnt(1)
	v_mfma_f32_16x16x32_bf16 v[50:53], v[68:71], v[28:31], v[50:53]
	global_load_dwordx2 v[68:69], v[40:41], off offset:1440
	s_waitcnt lgkmcnt(0)
	v_mfma_f32_16x16x32_bf16 v[50:53], v[72:75], v[16:19], v[50:53]
	s_nop 7
	v_pk_add_f32 v[50:51], v[48:49], v[50:51] op_sel_hi:[0,1]
	v_pk_add_f32 v[70:71], v[48:49], v[52:53] op_sel_hi:[0,1]
	s_waitcnt vmcnt(0)
	v_lshlrev_b32_e32 v52, 16, v68
	v_and_b32_e32 v53, 0xffff0000, v68
	v_lshlrev_b32_e32 v68, 16, v69
	v_and_b32_e32 v69, 0xffff0000, v69
	v_pk_mul_f32 v[52:53], v[50:51], v[52:53]
	v_pk_mul_f32 v[118:119], v[70:71], v[68:69]
	v_cvt_pk_bf16_f32 v140, v52, v53
	s_nop 0
	v_cvt_pk_bf16_f32 v138, v118, v119
	ds_read_b128 v[68:71], v152 offset:60928
	ds_read_b128 v[72:75], v152 offset:60992
	s_waitcnt lgkmcnt(1)
	v_mfma_f32_16x16x32_bf16 v[68:71], v[68:71], v[20:23], 0
	s_waitcnt lgkmcnt(0)
	v_mfma_f32_16x16x32_bf16 v[68:71], v[72:75], v[24:27], v[68:71]
	ds_read_b128 v[72:75], v152 offset:61056
	ds_read_b128 v[120:123], v152 offset:61120
	global_load_dwordx2 v[50:51], v[40:41], off offset:1472
	s_waitcnt vmcnt(0)
	v_lshlrev_b32_e32 v62, 16, v50
	s_waitcnt lgkmcnt(1)
	v_mfma_f32_16x16x32_bf16 v[68:71], v[72:75], v[28:31], v[68:71]
	v_and_b32_e32 v50, 0xffff0000, v50
	s_waitcnt lgkmcnt(0)
	v_mfma_f32_16x16x32_bf16 v[68:71], v[120:123], v[16:19], v[68:71]
	s_nop 7
	v_add_f32_e32 v49, v48, v68
	v_add_f32_e32 v54, v48, v69
	v_add_f32_e32 v56, v48, v70
	v_add_f32_e32 v60, v48, v71
	v_lshlrev_b32_e32 v68, 16, v51
	v_and_b32_e32 v51, 0xffff0000, v51
	v_mul_f32_e32 v120, v49, v62
	v_mul_f32_e32 v62, v54, v50
	v_mul_f32_e32 v122, v56, v68
	v_mul_f32_e32 v60, v60, v51
	v_cvt_pk_bf16_f32 v135, v120, v62
	v_cvt_pk_bf16_f32 v131, v122, v60
	ds_read_b128 v[68:71], v152 offset:65280
	ds_read_b128 v[72:75], v152 offset:65344
	s_waitcnt lgkmcnt(1)
	v_mfma_f32_16x16x32_bf16 v[20:23], v[68:71], v[20:23], 0
	v_mov_b32_e32 v68, v120
	v_mov_b32_e32 v70, v122
	v_and_b32_e32 v50, 0xffff0000, v12
	s_waitcnt lgkmcnt(0)
	v_mfma_f32_16x16x32_bf16 v[20:23], v[72:75], v[24:27], v[20:23]
	ds_read_b128 v[24:27], v152 offset:65408
	ds_read_b128 v[72:75], v152 offset:65472
	v_lshlrev_b32_e32 v54, 16, v13
	v_and_b32_e32 v56, 0xffff0000, v13
	s_waitcnt lgkmcnt(1)
	v_mfma_f32_16x16x32_bf16 v[20:23], v[24:27], v[28:31], v[20:23]
	global_load_dwordx2 v[24:25], v[40:41], off offset:1504
	s_waitcnt vmcnt(0)
	v_lshlrev_b32_e32 v69, 16, v25
	s_waitcnt lgkmcnt(0)
	v_mfma_f32_16x16x32_bf16 v[16:19], v[72:75], v[16:19], v[20:23]
	v_and_b32_e32 v71, 0xffff0000, v25
	s_nop 6
	v_add_f32_e32 v16, v48, v16
	v_add_f32_e32 v17, v48, v17
	v_add_f32_e32 v121, v48, v18
	v_add_f32_e32 v123, v48, v19
	v_lshlrev_b32_e32 v18, 16, v24
	v_and_b32_e32 v19, 0xffff0000, v24
	v_mul_f32_e32 v51, v16, v18
	v_mul_f32_e32 v49, v17, v19
	v_pk_mul_f32 v[72:73], v[120:121], v[68:69]
	v_pk_mul_f32 v[74:75], v[122:123], v[70:71]
	v_cvt_pk_bf16_f32 v122, v51, v49
	v_lshlrev_b32_e32 v48, 16, v12
	v_cvt_pk_bf16_f32 v120, v73, v75
	global_load_dwordx4 v[16:19], v157, s[48:49] offset:1024
	global_load_dwordx4 v[20:23], v157, s[50:51] offset:1024
	global_load_dwordx4 v[24:27], v157, s[48:49] offset:1040
	global_load_dwordx4 v[28:31], v157, s[50:51] offset:1040
	ds_read_b64 v[12:13], v160
	v_lshlrev_b32_e32 v70, 16, v15
	v_and_b32_e32 v15, 0xffff0000, v15
	v_lshlrev_b32_e32 v68, 16, v14
	v_and_b32_e32 v14, 0xffff0000, v14
	s_waitcnt lgkmcnt(0)
	v_sub_f32_e32 v48, v48, v12
	v_sub_f32_e32 v15, v15, v12
	v_sub_f32_e32 v50, v50, v12
	v_mul_f32_e32 v48, v13, v48
	v_mul_f32_e32 v15, v13, v15
	v_sub_f32_e32 v54, v54, v12
	v_mul_f32_e32 v50, v13, v50
	v_sub_f32_e32 v56, v56, v12
	v_sub_f32_e32 v14, v14, v12
	v_mul_f32_e32 v54, v13, v54
	v_sub_f32_e32 v68, v68, v12
	v_mul_f32_e32 v56, v13, v56
	v_mul_f32_e32 v14, v13, v14
	v_sub_f32_e32 v70, v70, v12
	v_mul_f32_e32 v68, v13, v68
	v_mul_f32_e32 v70, v13, v70
	v_mov_b32_e32 v63, v121
	v_mov_b32_e32 v61, v123
	s_waitcnt vmcnt(2)
	v_fma_f32 v16, v16, v48, v20
	v_fma_f32 v17, v17, v50, v21
	s_waitcnt vmcnt(0)
	v_fmac_f32_e32 v31, v27, v15
	v_cvt_pk_bf16_f32 v15, v16, v33
	ds_write_b16 v155, v15
	v_cvt_pk_bf16_f32 v15, v17, v33
	v_fma_f32 v18, v18, v54, v22
	ds_write_b16 v155, v15 offset:272
	v_cvt_pk_bf16_f32 v15, v18, v33
	v_fmac_f32_e32 v23, v19, v56
	v_fma_f32 v14, v25, v14, v29
	ds_write_b16 v155, v15 offset:544
	v_cvt_pk_bf16_f32 v15, v23, v33
	v_fma_f32 v19, v24, v68, v28
	ds_write_b16 v155, v15 offset:816
	v_cvt_pk_bf16_f32 v15, v19, v33
	ds_write_b16 v155, v15 offset:1088
	v_cvt_pk_bf16_f32 v14, v14, v33
	v_fma_f32 v20, v26, v70, v30
	ds_write_b16 v155, v14 offset:1360
	v_cvt_pk_bf16_f32 v14, v20, v33
	ds_write_b16 v155, v14 offset:1632
	v_cvt_pk_bf16_f32 v30, v31, v33
	global_load_dwordx4 v[14:17], v157, s[48:49] offset:1152
	global_load_dwordx4 v[18:21], v157, s[50:51] offset:1152
	global_load_dwordx4 v[22:25], v157, s[48:49] offset:1168
	global_load_dwordx4 v[26:29], v157, s[50:51] offset:1168
	v_lshlrev_b32_e32 v31, 16, v8
	v_and_b32_e32 v8, 0xffff0000, v8
	v_lshlrev_b32_e32 v54, 16, v11
	v_and_b32_e32 v11, 0xffff0000, v11
	v_sub_f32_e32 v8, v8, v12
	v_lshlrev_b32_e32 v48, 16, v9
	v_sub_f32_e32 v31, v31, v12
	v_sub_f32_e32 v11, v11, v12
	v_mul_f32_e32 v8, v13, v8
	v_and_b32_e32 v9, 0xffff0000, v9
	v_sub_f32_e32 v48, v48, v12
	v_mul_f32_e32 v31, v13, v31
	v_mul_f32_e32 v11, v13, v11
	v_lshlrev_b32_e32 v50, 16, v10
	v_sub_f32_e32 v9, v9, v12
	v_mul_f32_e32 v48, v13, v48
	ds_write_b16 v155, v30 offset:1904
	v_and_b32_e32 v10, 0xffff0000, v10
	v_sub_f32_e32 v50, v50, v12
	v_mul_f32_e32 v9, v13, v9
	v_sub_f32_e32 v10, v10, v12
	v_mul_f32_e32 v50, v13, v50
	v_sub_f32_e32 v54, v54, v12
	v_mul_f32_e32 v10, v13, v10
	v_mul_f32_e32 v54, v13, v54
	v_mul_f32_e32 v30, v59, v59
	v_mov_b32_e32 v68, v62
	v_mov_b32_e32 v70, v60
	s_waitcnt vmcnt(2)
	v_fma_f32 v8, v8, v15, v19
	v_fma_f32 v14, v31, v14, v18
	s_waitcnt vmcnt(0)
	v_fmac_f32_e32 v29, v11, v25
	v_cvt_pk_bf16_f32 v11, v14, v33
	ds_write_b16 v155, v11 offset:8704
	v_cvt_pk_bf16_f32 v8, v8, v33
	v_fma_f32 v15, v48, v16, v20
	ds_write_b16 v155, v8 offset:8976
	v_cvt_pk_bf16_f32 v8, v15, v33
	v_fmac_f32_e32 v21, v9, v17
	ds_write_b16 v155, v8 offset:9248
	v_cvt_pk_bf16_f32 v8, v21, v33
	v_fma_f32 v9, v50, v22, v26
	ds_write_b16 v155, v8 offset:9520
	v_cvt_pk_bf16_f32 v8, v9, v33
	v_fma_f32 v10, v10, v23, v27
	ds_write_b16 v155, v8 offset:9792
	v_cvt_pk_bf16_f32 v8, v10, v33
	v_fma_f32 v16, v54, v24, v28
	ds_write_b16 v155, v8 offset:10064
	v_cvt_pk_bf16_f32 v8, v16, v33
	ds_write_b16 v155, v8 offset:10336
	v_cvt_pk_bf16_f32 v48, v29, v33
	global_load_dwordx4 v[8:11], v157, s[48:49] offset:1280
	global_load_dwordx4 v[14:17], v157, s[50:51] offset:1280
	global_load_dwordx4 v[18:21], v157, s[48:49] offset:1296
	global_load_dwordx4 v[22:25], v157, s[50:51] offset:1296
	v_pk_add_f32 v[26:27], v[88:89], v[88:89] op_sel:[0,1] op_sel_hi:[1,0]
	v_pk_fma_f32 v[30:31], v[58:59], v[58:59], v[30:31] op_sel_hi:[1,1,0]
	v_mov_b32_e32 v56, v26
	v_pk_add_f32 v[26:27], v[26:27], v[86:87]
	v_lshlrev_b32_e32 v58, 16, v7
	v_lshlrev_b32_e32 v27, 16, v4
	v_and_b32_e32 v4, 0xffff0000, v4
	v_and_b32_e32 v7, 0xffff0000, v7
	v_sub_f32_e32 v4, v4, v12
	v_lshlrev_b32_e32 v50, 16, v5
	v_sub_f32_e32 v27, v27, v12
	v_sub_f32_e32 v7, v7, v12
	v_mul_f32_e32 v4, v13, v4
	v_and_b32_e32 v5, 0xffff0000, v5
	v_sub_f32_e32 v50, v50, v12
	v_mul_f32_e32 v27, v13, v27
	v_mul_f32_e32 v7, v13, v7
	v_lshlrev_b32_e32 v54, 16, v6
	v_sub_f32_e32 v5, v5, v12
	v_mul_f32_e32 v50, v13, v50
	ds_write_b16 v155, v48 offset:10608
	v_and_b32_e32 v6, 0xffff0000, v6
	v_sub_f32_e32 v54, v54, v12
	v_mul_f32_e32 v5, v13, v5
	v_sub_f32_e32 v6, v6, v12
	v_mul_f32_e32 v54, v13, v54
	v_sub_f32_e32 v58, v58, v12
	v_mul_f32_e32 v6, v13, v6
	v_mul_f32_e32 v58, v13, v58
	v_mov_b32_e32 v28, v86
	v_mov_b32_e32 v29, v57
	v_mov_b32_e32 v88, v84
	v_mov_b32_e32 v89, v55
	s_waitcnt vmcnt(2)
	v_fma_f32 v4, v4, v9, v15
	v_fma_f32 v8, v27, v8, v14
	s_waitcnt vmcnt(0)
	v_fmac_f32_e32 v25, v7, v21
	v_cvt_pk_bf16_f32 v7, v8, v33
	ds_write_b16 v155, v7 offset:17408
	v_cvt_pk_bf16_f32 v4, v4, v33
	v_fma_f32 v9, v50, v10, v16
	ds_write_b16 v155, v4 offset:17680
	v_cvt_pk_bf16_f32 v4, v9, v33
	v_fmac_f32_e32 v17, v5, v11
	ds_write_b16 v155, v4 offset:17952
	v_cvt_pk_bf16_f32 v4, v17, v33
	v_fma_f32 v5, v54, v18, v22
	ds_write_b16 v155, v4 offset:18224
	v_cvt_pk_bf16_f32 v4, v5, v33
	v_fma_f32 v6, v6, v19, v23
	ds_write_b16 v155, v4 offset:18496
	v_cvt_pk_bf16_f32 v4, v6, v33
	v_fma_f32 v10, v58, v20, v24
	ds_write_b16 v155, v4 offset:18768
	v_cvt_pk_bf16_f32 v4, v10, v33
	ds_write_b16 v155, v4 offset:19040
	v_cvt_pk_bf16_f32 v48, v25, v33
	global_load_dwordx4 v[4:7], v157, s[48:49] offset:1408
	global_load_dwordx4 v[8:11], v157, s[50:51] offset:1408
	global_load_dwordx4 v[14:17], v157, s[48:49] offset:1424
	global_load_dwordx4 v[18:21], v157, s[50:51] offset:1424
	v_pk_mul_f32 v[22:23], v[56:57], v[28:29]
	v_mov_b32_e32 v54, v30
	v_pk_add_f32 v[24:25], v[30:31], v[84:85]
	v_mov_b32_e32 v27, v23
	v_pk_mul_f32 v[22:23], v[54:55], v[88:89]
	v_pk_add_f32 v[28:29], v[66:67], v[64:65]
	v_mov_b32_e32 v25, v23
	v_pk_add_f32 v[22:23], v[26:27], v[24:25]
	v_lshlrev_b32_e32 v50, 16, v0
	v_and_b32_e32 v56, 0xffff0000, v0
	v_lshlrev_b32_e32 v57, 16, v1
	v_pk_mul_f32 v[0:1], v[92:93], v[92:93]
	v_pk_add_f32 v[22:23], v[22:23], v[28:29]
	v_pk_fma_f32 v[0:1], v[90:91], v[90:91], v[0:1]
	v_pk_add_f32 v[22:23], v[22:23], v[22:23] op_sel:[0,1] op_sel_hi:[1,0]
	v_pk_add_f32 v[0:1], v[0:1], v[0:1] op_sel:[0,1] op_sel_hi:[1,0]
	v_mov_b32_e32 v108, v22
	v_mov_b32_e32 v2, v0
	v_pk_add_f32 v[0:1], v[22:23], v[0:1]
	v_mul_f32_e32 v22, v97, v97
	v_mul_f32_e32 v24, v95, v95
	v_pk_fma_f32 v[22:23], v[96:97], v[96:97], v[22:23] op_sel_hi:[1,1,0]
	v_pk_fma_f32 v[24:25], v[94:95], v[94:95], v[24:25] op_sel_hi:[1,1,0]
	v_mov_b32_e32 v26, v22
	v_mov_b32_e32 v106, v24
	v_mov_b32_e32 v27, v107
	v_pk_add_f32 v[22:23], v[24:25], v[22:23]
	v_pk_fma_f32 v[24:25], v[100:101], v[102:103], v[110:111]
	v_pk_mul_f32 v[28:29], v[110:111], v[110:111]
	v_pk_fma_f32 v[30:31], v[98:99], v[104:105], v[112:113]
	v_pk_mul_f32 v[54:55], v[112:113], v[112:113]
	v_pk_mul_f32 v[2:3], v[108:109], v[2:3]
	v_pk_mul_f32 v[26:27], v[106:107], v[26:27]
	v_mov_b32_e32 v25, v29
	v_mov_b32_e32 v31, v55
	v_mov_b32_e32 v1, v3
	v_mov_b32_e32 v23, v27
	v_pk_add_f32 v[2:3], v[24:25], v[30:31]
	v_pk_add_f32 v[0:1], v[0:1], v[22:23]
	ds_write_b16 v155, v48 offset:19312
	v_pk_add_f32 v[66:67], v[0:1], v[2:3]
	v_pk_mul_f32 v[0:1], v[116:117], v[116:117]
	v_sub_f32_e32 v2, v57, v12
	v_pk_fma_f32 v[0:1], v[114:115], v[114:115], v[0:1]
	v_sub_f32_e32 v3, v76, v12
	v_pk_add_f32 v[64:65], v[0:1], v[0:1] op_sel:[0,1] op_sel_hi:[1,0]
	v_mul_f32_e32 v0, v119, v119
	v_pk_fma_f32 v[58:59], v[118:119], v[118:119], v[0:1] op_sel_hi:[1,1,0]
	v_sub_f32_e32 v0, v50, v12
	v_mul_f32_e32 v0, v13, v0
	v_sub_f32_e32 v1, v56, v12
	v_mul_f32_e32 v1, v13, v1
	v_mul_f32_e32 v2, v13, v2
	v_sub_f32_e32 v22, v77, v12
	v_mul_f32_e32 v3, v13, v3
	v_sub_f32_e32 v23, v78, v12
	v_mul_f32_e32 v22, v13, v22
	v_sub_f32_e32 v24, v79, v12
	v_mul_f32_e32 v23, v13, v23
	v_sub_f32_e32 v12, v80, v12
	v_mul_f32_e32 v24, v13, v24
	v_mul_f32_e32 v12, v13, v12
	s_waitcnt vmcnt(2)
	v_fma_f32 v0, v0, v4, v8
	v_cvt_pk_bf16_f32 v0, v0, v33
	v_fma_f32 v1, v1, v5, v9
	ds_write_b16 v155, v0 offset:26112
	v_cvt_pk_bf16_f32 v0, v1, v33
	v_fma_f32 v2, v2, v6, v10
	ds_write_b16 v155, v0 offset:26384
	v_cvt_pk_bf16_f32 v0, v2, v33
	v_fmac_f32_e32 v11, v3, v7
	ds_write_b16 v155, v0 offset:26656
	v_cvt_pk_bf16_f32 v0, v11, v33
	s_waitcnt vmcnt(0)
	v_fma_f32 v3, v22, v14, v18
	ds_write_b16 v155, v0 offset:26928
	v_cvt_pk_bf16_f32 v0, v3, v33
	v_fma_f32 v4, v23, v15, v19
	ds_write_b16 v155, v0 offset:27200
	v_cvt_pk_bf16_f32 v0, v4, v33
	v_fma_f32 v5, v24, v16, v20
	ds_write_b16 v155, v0 offset:27472
	v_cvt_pk_bf16_f32 v0, v5, v33
	v_fmac_f32_e32 v21, v12, v17
	ds_write_b16 v155, v0 offset:27744
	v_cvt_pk_bf16_f32 v0, v21, v33
	ds_write_b16 v155, v0 offset:28016
	s_waitcnt lgkmcnt(0)
	s_barrier
	v_add_co_u32_e32 v0, vcc, s27, v42
	v_pk_fma_f32 v[68:69], v[62:63], v[68:69], v[72:73]
	s_nop 0
	v_addc_co_u32_e32 v1, vcc, 0, v43, vcc
	global_load_dwordx4 v[20:23], v[0:1], off
	global_load_dwordx4 v[24:27], v[0:1], off offset:64
	global_load_dwordx2 v[84:85], v[40:41], off offset:1536
	global_load_dwordx4 v[28:31], v[0:1], off offset:128
	global_load_dwordx4 v[16:19], v[0:1], off offset:192
	global_load_dword v48, v[44:45], off offset:1024
	ds_read_b128 v[0:3], v152
	ds_read_b128 v[4:7], v152 offset:64
	ds_read_b128 v[54:57], v152 offset:128
	global_load_dwordx4 v[12:15], v[46:47], off offset:2816
	global_load_dwordx4 v[8:11], v[46:47], off offset:2880
	ds_read_b128 v[76:79], v152 offset:192
	v_pk_mul_f32 v[62:63], v[72:73], v[72:73]
	v_pk_fma_f32 v[70:71], v[60:61], v[70:71], v[74:75]
	v_pk_mul_f32 v[60:61], v[74:75], v[74:75]
	v_mov_b32_e32 v69, v63
	v_mov_b32_e32 v71, v61
	s_waitcnt vmcnt(7) lgkmcnt(3)
	v_mfma_f32_16x16x32_bf16 v[0:3], v[0:3], v[20:23], 0
	s_waitcnt vmcnt(6) lgkmcnt(2)
	v_mfma_f32_16x16x32_bf16 v[80:83], v[4:7], v[24:27], v[0:3]
	global_load_dwordx4 v[4:7], v[46:47], off offset:2944
	s_nop 4
	global_load_dwordx4 v[0:3], v[46:47], off offset:3008
	s_waitcnt vmcnt(7)
	v_lshlrev_b32_e32 v47, 16, v85
	v_lshlrev_b32_e32 v46, 16, v84
	s_waitcnt vmcnt(6) lgkmcnt(1)
	v_mfma_f32_16x16x32_bf16 v[54:57], v[54:57], v[28:31], v[80:83]
	s_waitcnt vmcnt(0)
	v_and_b32_e32 v72, 0xffff0000, v2
	s_waitcnt lgkmcnt(0)
	v_mfma_f32_16x16x32_bf16 v[54:57], v[76:79], v[16:19], v[54:57]
	v_and_b32_e32 v81, 0xffff0000, v85
	v_and_b32_e32 v80, 0xffff0000, v84
	v_lshlrev_b32_e32 v73, 16, v3
	v_and_b32_e32 v74, 0xffff0000, v3
	s_nop 3
	v_mov_b32_e32 v76, v54
	v_mov_b32_e32 v77, v56
	v_mov_b32_e32 v56, v55
	v_pk_add_f32 v[54:55], v[48:49], v[76:77] op_sel_hi:[0,1]
	v_pk_add_f32 v[56:57], v[48:49], v[56:57] op_sel_hi:[0,1]
	v_pk_mul_f32 v[76:77], v[54:55], v[46:47]
	v_pk_mul_f32 v[78:79], v[56:57], v[80:81]
	s_nop 0
	v_cvt_pk_bf16_f32 v159, v76, v78
	v_cvt_pk_bf16_f32 v158, v77, v79
	ds_read_b128 v[54:57], v152 offset:4352
	ds_read_b128 v[80:83], v152 offset:4416
	s_waitcnt lgkmcnt(1)
	v_mfma_f32_16x16x32_bf16 v[54:57], v[54:57], v[20:23], 0
	s_waitcnt lgkmcnt(0)
	v_mfma_f32_16x16x32_bf16 v[54:57], v[80:83], v[24:27], v[54:57]
	ds_read_b128 v[80:83], v152 offset:4480
	ds_read_b128 v[84:87], v152 offset:4544
	global_load_dwordx2 v[46:47], v[40:41], off offset:1568
	s_waitcnt lgkmcnt(1)
	v_mfma_f32_16x16x32_bf16 v[54:57], v[80:83], v[28:31], v[54:57]
	s_waitcnt vmcnt(0)
	v_lshlrev_b32_e32 v80, 16, v46
	s_waitcnt lgkmcnt(0)
	v_mfma_f32_16x16x32_bf16 v[54:57], v[84:87], v[16:19], v[54:57]
	v_and_b32_e32 v81, 0xffff0000, v46
	v_lshlrev_b32_e32 v46, 16, v47
	v_and_b32_e32 v47, 0xffff0000, v47
	s_nop 4
	v_pk_add_f32 v[54:55], v[48:49], v[54:55] op_sel_hi:[0,1]
	v_pk_add_f32 v[56:57], v[48:49], v[56:57] op_sel_hi:[0,1]
	v_pk_mul_f32 v[80:81], v[54:55], v[80:81]
	v_pk_mul_f32 v[82:83], v[56:57], v[46:47]
	v_cvt_pk_bf16_f32 v123, v80, v81
	s_nop 0
	v_cvt_pk_bf16_f32 v121, v82, v83
	ds_read_b128 v[54:57], v152 offset:8704
	ds_read_b128 v[84:87], v152 offset:8768
	s_waitcnt lgkmcnt(1)
	v_mfma_f32_16x16x32_bf16 v[54:57], v[54:57], v[20:23], 0
	s_waitcnt lgkmcnt(0)
	v_mfma_f32_16x16x32_bf16 v[54:57], v[84:87], v[24:27], v[54:57]
	ds_read_b128 v[84:87], v152 offset:8832
	ds_read_b128 v[88:91], v152 offset:8896
	global_load_dwordx2 v[46:47], v[40:41], off offset:1600
	s_waitcnt lgkmcnt(1)
	v_mfma_f32_16x16x32_bf16 v[54:57], v[84:87], v[28:31], v[54:57]
	s_waitcnt vmcnt(0)
	v_lshlrev_b32_e32 v84, 16, v47
	s_waitcnt lgkmcnt(0)
	v_mfma_f32_16x16x32_bf16 v[54:57], v[88:91], v[16:19], v[54:57]
	v_and_b32_e32 v47, 0xffff0000, v47
	s_nop 6
	v_add_f32_e32 v50, v48, v54
	v_add_f32_e32 v55, v48, v55
	v_add_f32_e32 v56, v48, v56
	v_add_f32_e32 v57, v48, v57
	v_lshlrev_b32_e32 v54, 16, v46
	v_and_b32_e32 v46, 0xffff0000, v46
	v_mul_f32_e32 v54, v50, v54
	v_mul_f32_e32 v86, v55, v46
	v_mul_f32_e32 v56, v56, v84
	v_mul_f32_e32 v84, v57, v47
	v_cvt_pk_bf16_f32 v119, v54, v86
	v_cvt_pk_bf16_f32 v118, v56, v84
	ds_read_b128 v[88:91], v152 offset:13056
	ds_read_b128 v[92:95], v152 offset:13120
	s_waitcnt lgkmcnt(1)
	v_mfma_f32_16x16x32_bf16 v[88:91], v[88:91], v[20:23], 0
	s_waitcnt lgkmcnt(0)
	v_mfma_f32_16x16x32_bf16 v[88:91], v[92:95], v[24:27], v[88:91]
	ds_read_b128 v[92:95], v152 offset:13184
	ds_read_b128 v[96:99], v152 offset:13248
	global_load_dwordx2 v[46:47], v[40:41], off offset:1632
	s_waitcnt vmcnt(0)
	v_lshlrev_b32_e32 v87, 16, v46
	s_waitcnt lgkmcnt(1)
	v_mfma_f32_16x16x32_bf16 v[92:95], v[92:95], v[28:31], v[88:91]
	v_and_b32_e32 v46, 0xffff0000, v46
	s_waitcnt lgkmcnt(0)
	v_mfma_f32_16x16x32_bf16 v[92:95], v[96:99], v[16:19], v[92:95]
	v_mov_b32_e32 v88, v54
	v_mov_b32_e32 v90, v56
	v_lshlrev_b32_e32 v89, 16, v47
	v_and_b32_e32 v91, 0xffff0000, v47
	s_nop 3
	v_add_f32_e32 v50, v48, v92
	v_add_f32_e32 v85, v48, v93
	v_add_f32_e32 v55, v48, v94
	v_add_f32_e32 v57, v48, v95
	v_mul_f32_e32 v95, v50, v87
	v_mul_f32_e32 v93, v85, v46
	v_pk_mul_f32 v[96:97], v[54:55], v[88:89]
	v_pk_mul_f32 v[98:99], v[56:57], v[90:91]
	v_cvt_pk_bf16_f32 v117, v95, v93
	v_mov_b32_e32 v3, v95
	v_cvt_pk_bf16_f32 v115, v97, v99
	ds_read_b128 v[100:103], v152 offset:17408
	ds_read_b128 v[104:107], v152 offset:17472
	s_waitcnt lgkmcnt(1)
	v_mfma_f32_16x16x32_bf16 v[100:103], v[100:103], v[20:23], 0
	s_waitcnt lgkmcnt(0)
	v_mfma_f32_16x16x32_bf16 v[100:103], v[104:107], v[24:27], v[100:103]
	ds_read_b128 v[104:107], v152 offset:17536
	ds_read_b128 v[108:111], v152 offset:17600
	global_load_dwordx2 v[46:47], v[40:41], off offset:1664
	s_waitcnt lgkmcnt(1)
	v_mfma_f32_16x16x32_bf16 v[100:103], v[104:107], v[28:31], v[100:103]
	s_waitcnt lgkmcnt(0)
	v_mfma_f32_16x16x32_bf16 v[100:103], v[108:111], v[16:19], v[100:103]
	s_nop 7
	v_mov_b32_e32 v104, v100
	v_mov_b32_e32 v105, v102
	v_mov_b32_e32 v102, v101
	v_pk_add_f32 v[100:101], v[48:49], v[104:105] op_sel_hi:[0,1]
	v_pk_add_f32 v[102:103], v[48:49], v[102:103] op_sel_hi:[0,1]
	s_waitcnt vmcnt(0)
	v_lshlrev_b32_e32 v105, 16, v47
	v_lshlrev_b32_e32 v104, 16, v46
	v_and_b32_e32 v47, 0xffff0000, v47
	v_and_b32_e32 v46, 0xffff0000, v46
	v_pk_mul_f32 v[100:101], v[100:101], v[104:105]
	v_pk_mul_f32 v[102:103], v[102:103], v[46:47]
	s_nop 0
	v_cvt_pk_bf16_f32 v116, v100, v102
	v_cvt_pk_bf16_f32 v114, v101, v103
	ds_read_b128 v[104:107], v152 offset:21760
	ds_read_b128 v[108:111], v152 offset:21824
	s_waitcnt lgkmcnt(1)
	v_mfma_f32_16x16x32_bf16 v[104:107], v[104:107], v[20:23], 0
	s_waitcnt lgkmcnt(0)
	v_mfma_f32_16x16x32_bf16 v[104:107], v[108:111], v[24:27], v[104:107]
	ds_read_b128 v[108:111], v152 offset:21888
	ds_read_b128 v[162:165], v152 offset:21952
	global_load_dwordx2 v[46:47], v[40:41], off offset:1696
	s_waitcnt lgkmcnt(1)
	v_mfma_f32_16x16x32_bf16 v[104:107], v[108:111], v[28:31], v[104:107]
	s_waitcnt vmcnt(0)
	v_lshlrev_b32_e32 v108, 16, v46
	s_waitcnt lgkmcnt(0)
	v_mfma_f32_16x16x32_bf16 v[104:107], v[162:165], v[16:19], v[104:107]
	v_and_b32_e32 v109, 0xffff0000, v46
	v_lshlrev_b32_e32 v110, 16, v47
	v_and_b32_e32 v111, 0xffff0000, v47
	s_nop 4
	v_pk_add_f32 v[104:105], v[48:49], v[104:105] op_sel_hi:[0,1]
	v_pk_add_f32 v[106:107], v[48:49], v[106:107] op_sel_hi:[0,1]
	v_pk_mul_f32 v[46:47], v[104:105], v[108:109]
	v_pk_mul_f32 v[104:105], v[106:107], v[110:111]
	v_cvt_pk_bf16_f32 v113, v46, v47
	s_nop 0
	v_cvt_pk_bf16_f32 v112, v104, v105
	ds_read_b128 v[106:109], v152 offset:26112
	ds_read_b128 v[162:165], v152 offset:26176
	s_waitcnt lgkmcnt(1)
	v_mfma_f32_16x16x32_bf16 v[106:109], v[106:109], v[20:23], 0
	s_waitcnt lgkmcnt(0)
	v_mfma_f32_16x16x32_bf16 v[106:109], v[162:165], v[24:27], v[106:109]
	ds_read_b128 v[162:165], v152 offset:26240
	ds_read_b128 v[166:169], v152 offset:26304
	global_load_dwordx2 v[110:111], v[40:41], off offset:1728
	s_waitcnt vmcnt(0)
	v_lshlrev_b32_e32 v56, 16, v110
	s_waitcnt lgkmcnt(1)
	v_mfma_f32_16x16x32_bf16 v[106:109], v[162:165], v[28:31], v[106:109]
	v_and_b32_e32 v88, 0xffff0000, v110
	v_lshlrev_b32_e32 v90, 16, v111
	v_and_b32_e32 v92, 0xffff0000, v111
	s_waitcnt lgkmcnt(0)
	v_mfma_f32_16x16x32_bf16 v[106:109], v[166:169], v[16:19], v[106:109]
	s_nop 7
	v_add_f32_e32 v50, v48, v106
	v_add_f32_e32 v54, v48, v107
	v_add_f32_e32 v85, v48, v108
	v_add_f32_e32 v87, v48, v109
	v_mul_f32_e32 v106, v50, v56
	v_mul_f32_e32 v56, v54, v88
	v_mul_f32_e32 v108, v85, v90
	v_mul_f32_e32 v54, v87, v92
	v_cvt_pk_bf16_f32 v111, v106, v56
	v_cvt_pk_bf16_f32 v110, v108, v54
	ds_read_b128 v[162:165], v152 offset:30464
	ds_read_b128 v[166:169], v152 offset:30528
	s_waitcnt lgkmcnt(1)
	v_mfma_f32_16x16x32_bf16 v[20:23], v[162:165], v[20:23], 0
	v_mov_b32_e32 v87, v55
	v_mov_b32_e32 v85, v57
	v_mov_b32_e32 v88, v86
	s_waitcnt lgkmcnt(0)
	v_mfma_f32_16x16x32_bf16 v[20:23], v[166:169], v[24:27], v[20:23]
	ds_read_b128 v[24:27], v152 offset:30592
	ds_read_b128 v[162:165], v152 offset:30656
	v_mov_b32_e32 v90, v84
	s_waitcnt lgkmcnt(1)
	v_mfma_f32_16x16x32_bf16 v[24:27], v[24:27], v[28:31], v[20:23]
	global_load_dwordx2 v[28:29], v[40:41], off offset:1760
	v_lshlrev_b32_e32 v30, 16, v15
	s_nop 0
	v_mov_b32_e32 v20, v106
	s_waitcnt lgkmcnt(0)
	v_mfma_f32_16x16x32_bf16 v[16:19], v[162:165], v[16:19], v[24:27]
	v_mov_b32_e32 v22, v108
	v_and_b32_e32 v15, 0xffff0000, v15
	v_mov_b32_e32 v31, v51
	s_waitcnt vmcnt(0)
	v_and_b32_e32 v24, 0xffff0000, v28
	s_nop 2
	v_add_f32_e32 v16, v48, v16
	v_add_f32_e32 v17, v48, v17
	v_add_f32_e32 v107, v48, v18
	v_add_f32_e32 v109, v48, v19
	v_lshlrev_b32_e32 v18, 16, v28
	v_lshlrev_b32_e32 v21, 16, v29
	v_and_b32_e32 v23, 0xffff0000, v29
	v_mul_f32_e32 v19, v16, v18
	v_mul_f32_e32 v17, v17, v24
	v_pk_mul_f32 v[26:27], v[106:107], v[20:21]
	v_pk_mul_f32 v[24:25], v[108:109], v[22:23]
	v_cvt_pk_bf16_f32 v106, v19, v17
	v_lshlrev_b32_e32 v16, 16, v12
	v_cvt_pk_bf16_f32 v29, v27, v25
	global_load_dwordx4 v[162:165], v157, s[48:49] offset:1536
	global_load_dwordx4 v[166:169], v157, s[50:51] offset:1536
	global_load_dwordx4 v[170:173], v157, s[48:49] offset:1552
	global_load_dwordx4 v[174:177], v157, s[50:51] offset:1552
	v_and_b32_e32 v18, 0xffff0000, v12
	v_lshlrev_b32_e32 v20, 16, v13
	v_and_b32_e32 v22, 0xffff0000, v13
	ds_read_b64 v[12:13], v160
	v_lshlrev_b32_e32 v28, 16, v14
	v_and_b32_e32 v14, 0xffff0000, v14
	v_mov_b32_e32 v57, v107
	v_mov_b32_e32 v55, v109
	s_waitcnt lgkmcnt(0)
	v_sub_f32_e32 v16, v16, v12
	v_sub_f32_e32 v15, v15, v12
	v_sub_f32_e32 v18, v18, v12
	v_mul_f32_e32 v16, v13, v16
	v_mul_f32_e32 v15, v13, v15
	v_sub_f32_e32 v20, v20, v12
	v_mul_f32_e32 v18, v13, v18
	v_sub_f32_e32 v22, v22, v12
	v_sub_f32_e32 v14, v14, v12
	v_mul_f32_e32 v20, v13, v20
	v_sub_f32_e32 v28, v28, v12
	v_mul_f32_e32 v22, v13, v22
	v_mul_f32_e32 v14, v13, v14
	v_sub_f32_e32 v30, v30, v12
	v_mul_f32_e32 v28, v13, v28
	v_mul_f32_e32 v30, v13, v30
	s_waitcnt vmcnt(2)
	v_fma_f32 v16, v162, v16, v166
	v_fma_f32 v18, v163, v18, v167
	s_waitcnt vmcnt(0)
	v_fmac_f32_e32 v177, v173, v15
	v_cvt_pk_bf16_f32 v15, v16, v33
	ds_write_b16 v155, v15 offset:34816
	v_cvt_pk_bf16_f32 v15, v18, v33
	v_fma_f32 v20, v164, v20, v168
	ds_write_b16 v155, v15 offset:35088
	v_cvt_pk_bf16_f32 v15, v20, v33
	v_fmac_f32_e32 v169, v165, v22
	v_fma_f32 v14, v171, v14, v175
	ds_write_b16 v155, v15 offset:35360
	v_cvt_pk_bf16_f32 v15, v169, v33
	v_fma_f32 v22, v170, v28, v174
	ds_write_b16 v155, v15 offset:35632
	v_cvt_pk_bf16_f32 v15, v22, v33
	ds_write_b16 v155, v15 offset:35904
	v_cvt_pk_bf16_f32 v14, v14, v33
	v_fma_f32 v28, v172, v30, v176
	ds_write_b16 v155, v14 offset:36176
	v_cvt_pk_bf16_f32 v14, v28, v33
	ds_write_b16 v155, v14 offset:36448
	v_cvt_pk_bf16_f32 v14, v177, v33
	global_load_dwordx4 v[160:163], v157, s[48:49] offset:1664
	global_load_dwordx4 v[164:167], v157, s[50:51] offset:1664
	global_load_dwordx4 v[168:171], v157, s[48:49] offset:1680
	global_load_dwordx4 v[172:175], v157, s[50:51] offset:1680
	v_lshlrev_b32_e32 v15, 16, v8
	v_and_b32_e32 v8, 0xffff0000, v8
	v_lshlrev_b32_e32 v20, 16, v11
	v_and_b32_e32 v11, 0xffff0000, v11
	v_sub_f32_e32 v8, v8, v12
	v_lshlrev_b32_e32 v16, 16, v9
	v_sub_f32_e32 v15, v15, v12
	v_sub_f32_e32 v11, v11, v12
	v_mul_f32_e32 v8, v13, v8
	v_and_b32_e32 v9, 0xffff0000, v9
	v_sub_f32_e32 v16, v16, v12
	v_mul_f32_e32 v15, v13, v15
	v_mul_f32_e32 v11, v13, v11
	v_lshlrev_b32_e32 v18, 16, v10
	v_sub_f32_e32 v9, v9, v12
	v_mul_f32_e32 v16, v13, v16
	ds_write_b16 v155, v14 offset:36720
	v_and_b32_e32 v10, 0xffff0000, v10
	v_sub_f32_e32 v18, v18, v12
	v_mul_f32_e32 v9, v13, v9
	v_sub_f32_e32 v10, v10, v12
	v_mul_f32_e32 v18, v13, v18
	v_sub_f32_e32 v20, v20, v12
	v_mul_f32_e32 v10, v13, v10
	v_mul_f32_e32 v20, v13, v20
	v_lshlrev_b32_e32 v22, 16, v7
	v_and_b32_e32 v7, 0xffff0000, v7
	v_sub_f32_e32 v7, v7, v12
	v_mul_f32_e32 v7, v13, v7
	v_sub_f32_e32 v22, v22, v12
	v_mul_f32_e32 v22, v13, v22
	v_mov_b32_e32 v30, v64
	v_lshlrev_b32_e32 v28, 16, v0
	s_waitcnt vmcnt(2)
	v_fma_f32 v8, v8, v161, v165
	v_fma_f32 v14, v15, v160, v164
	s_waitcnt vmcnt(0)
	v_fmac_f32_e32 v175, v11, v171
	v_cvt_pk_bf16_f32 v11, v14, v33
	ds_write_b16 v155, v11 offset:43520
	v_cvt_pk_bf16_f32 v8, v8, v33
	v_fma_f32 v15, v16, v162, v166
	ds_write_b16 v155, v8 offset:43792
	v_cvt_pk_bf16_f32 v8, v15, v33
	v_fmac_f32_e32 v167, v9, v163
	ds_write_b16 v155, v8 offset:44064
	v_cvt_pk_bf16_f32 v8, v167, v33
	v_fma_f32 v9, v18, v168, v172
	ds_write_b16 v155, v8 offset:44336
	v_cvt_pk_bf16_f32 v8, v9, v33
	v_fma_f32 v10, v10, v169, v173
	ds_write_b16 v155, v8 offset:44608
	v_cvt_pk_bf16_f32 v8, v10, v33
	v_fma_f32 v16, v20, v170, v174
	ds_write_b16 v155, v8 offset:44880
	v_cvt_pk_bf16_f32 v8, v16, v33
	ds_write_b16 v155, v8 offset:45152
	v_cvt_pk_bf16_f32 v18, v175, v33
	global_load_dwordx4 v[8:11], v157, s[48:49] offset:1792
	global_load_dwordx4 v[160:163], v157, s[50:51] offset:1792
	global_load_dwordx4 v[164:167], v157, s[48:49] offset:1808
	global_load_dwordx4 v[168:171], v157, s[50:51] offset:1808
	v_pk_add_f32 v[14:15], v[66:67], v[66:67] op_sel:[0,1] op_sel_hi:[1,0]
	v_mul_f32_e32 v16, v53, v53
	v_mov_b32_e32 v50, v14
	v_pk_add_f32 v[14:15], v[14:15], v[64:65]
	v_pk_fma_f32 v[52:53], v[52:53], v[52:53], v[16:17] op_sel_hi:[1,1,0]
	v_lshlrev_b32_e32 v15, 16, v4
	v_and_b32_e32 v4, 0xffff0000, v4
	v_sub_f32_e32 v4, v4, v12
	v_lshlrev_b32_e32 v16, 16, v5
	v_sub_f32_e32 v15, v15, v12
	v_mul_f32_e32 v4, v13, v4
	v_and_b32_e32 v5, 0xffff0000, v5
	v_sub_f32_e32 v16, v16, v12
	v_mul_f32_e32 v15, v13, v15
	v_lshlrev_b32_e32 v20, 16, v6
	v_sub_f32_e32 v5, v5, v12
	v_mul_f32_e32 v16, v13, v16
	ds_write_b16 v155, v18 offset:45424
	v_and_b32_e32 v6, 0xffff0000, v6
	v_sub_f32_e32 v20, v20, v12
	v_mul_f32_e32 v5, v13, v5
	v_sub_f32_e32 v6, v6, v12
	v_mul_f32_e32 v20, v13, v20
	v_mul_f32_e32 v6, v13, v6
	v_mov_b32_e32 v172, v58
	v_mov_b32_e32 v173, v49
	v_pk_mul_f32 v[30:31], v[50:51], v[30:31]
	v_mov_b32_e32 v48, v52
	v_pk_add_f32 v[50:51], v[52:53], v[58:59]
	v_pk_add_f32 v[52:53], v[68:69], v[70:71]
	v_and_b32_e32 v68, 0xffff0000, v0
	v_lshlrev_b32_e32 v69, 16, v1
	v_and_b32_e32 v70, 0xffff0000, v1
	v_pk_mul_f32 v[0:1], v[78:79], v[78:79]
	v_lshlrev_b32_e32 v71, 16, v2
	v_pk_fma_f32 v[0:1], v[76:77], v[76:77], v[0:1]
	v_pk_mul_f32 v[58:59], v[98:99], v[98:99]
	v_pk_add_f32 v[0:1], v[0:1], v[0:1] op_sel:[0,1] op_sel_hi:[1,0]
	s_waitcnt vmcnt(2)
	v_fma_f32 v4, v4, v9, v161
	v_fma_f32 v8, v15, v8, v160
	s_waitcnt vmcnt(0)
	v_fmac_f32_e32 v171, v7, v167
	v_cvt_pk_bf16_f32 v7, v8, v33
	ds_write_b16 v155, v7 offset:52224
	v_cvt_pk_bf16_f32 v4, v4, v33
	v_fma_f32 v9, v16, v10, v162
	ds_write_b16 v155, v4 offset:52496
	v_cvt_pk_bf16_f32 v4, v9, v33
	v_fmac_f32_e32 v163, v5, v11
	ds_write_b16 v155, v4 offset:52768
	v_cvt_pk_bf16_f32 v4, v163, v33
	v_fma_f32 v5, v20, v164, v168
	ds_write_b16 v155, v4 offset:53040
	v_cvt_pk_bf16_f32 v4, v5, v33
	v_fma_f32 v6, v6, v165, v169
	ds_write_b16 v155, v4 offset:53312
	v_cvt_pk_bf16_f32 v4, v6, v33
	v_fma_f32 v10, v22, v166, v170
	ds_write_b16 v155, v4 offset:53584
	v_cvt_pk_bf16_f32 v4, v10, v33
	ds_write_b16 v155, v4 offset:53856
	v_cvt_pk_bf16_f32 v18, v171, v33
	global_load_dwordx4 v[4:7], v157, s[48:49] offset:1920
	global_load_dwordx4 v[8:11], v157, s[50:51] offset:1920
	global_load_dwordx4 v[60:63], v157, s[48:49] offset:1936
	global_load_dwordx4 v[64:67], v157, s[50:51] offset:1936
	v_mov_b32_e32 v15, v31
	v_pk_mul_f32 v[30:31], v[48:49], v[172:173]
	v_mov_b32_e32 v2, v0
	v_mov_b32_e32 v51, v31
	v_pk_add_f32 v[14:15], v[14:15], v[50:51]
	v_mul_f32_e32 v16, v81, v81
	v_pk_add_f32 v[14:15], v[14:15], v[52:53]
	v_pk_fma_f32 v[30:31], v[80:81], v[80:81], v[16:17] op_sel_hi:[1,1,0]
	v_pk_add_f32 v[14:15], v[14:15], v[14:15] op_sel:[0,1] op_sel_hi:[1,0]
	v_mov_b32_e32 v92, v30
	v_mov_b32_e32 v94, v14
	v_pk_add_f32 v[0:1], v[14:15], v[0:1]
	v_mul_f32_e32 v14, v83, v83
	v_pk_fma_f32 v[14:15], v[82:83], v[82:83], v[14:15] op_sel_hi:[1,1,0]
	v_mov_b32_e32 v49, v93
	v_mov_b32_e32 v48, v14
	v_pk_add_f32 v[14:15], v[30:31], v[14:15]
	v_pk_fma_f32 v[30:31], v[86:87], v[88:89], v[96:97]
	v_pk_mul_f32 v[50:51], v[96:97], v[96:97]
	v_pk_fma_f32 v[52:53], v[84:85], v[90:91], v[98:99]
	v_pk_mul_f32 v[2:3], v[94:95], v[2:3]
	v_pk_mul_f32 v[48:49], v[92:93], v[48:49]
	v_mov_b32_e32 v31, v51
	v_mov_b32_e32 v53, v59
	v_mov_b32_e32 v1, v3
	v_mov_b32_e32 v15, v49
	v_pk_add_f32 v[2:3], v[30:31], v[52:53]
	v_pk_add_f32 v[0:1], v[0:1], v[14:15]
	ds_write_b16 v155, v18 offset:54128
	v_pk_add_f32 v[50:51], v[0:1], v[2:3]
	v_pk_mul_f32 v[0:1], v[102:103], v[102:103]
	v_sub_f32_e32 v2, v69, v12
	v_pk_fma_f32 v[0:1], v[100:101], v[100:101], v[0:1]
	v_sub_f32_e32 v3, v70, v12
	v_pk_add_f32 v[48:49], v[0:1], v[0:1] op_sel:[0,1] op_sel_hi:[1,0]
	v_mul_f32_e32 v0, v105, v105
	v_pk_fma_f32 v[30:31], v[104:105], v[104:105], v[0:1] op_sel_hi:[1,1,0]
	v_sub_f32_e32 v0, v28, v12
	v_mul_f32_e32 v0, v13, v0
	v_sub_f32_e32 v1, v68, v12
	v_mul_f32_e32 v1, v13, v1
	v_mul_f32_e32 v2, v13, v2
	v_sub_f32_e32 v14, v71, v12
	v_mul_f32_e32 v3, v13, v3
	v_sub_f32_e32 v15, v72, v12
	v_mul_f32_e32 v14, v13, v14
	v_sub_f32_e32 v16, v73, v12
	v_mul_f32_e32 v15, v13, v15
	v_sub_f32_e32 v12, v74, v12
	v_mul_f32_e32 v16, v13, v16
	v_mul_f32_e32 v12, v13, v12
	v_mov_b32_e32 v20, v56
	v_mov_b32_e32 v22, v54
	s_waitcnt vmcnt(2)
	v_fma_f32 v0, v0, v4, v8
	v_cvt_pk_bf16_f32 v0, v0, v33
	v_fma_f32 v1, v1, v5, v9
	ds_write_b16 v155, v0 offset:60928
	v_cvt_pk_bf16_f32 v0, v1, v33
	v_fma_f32 v2, v2, v6, v10
	ds_write_b16 v155, v0 offset:61200
	v_cvt_pk_bf16_f32 v0, v2, v33
	v_fmac_f32_e32 v11, v3, v7
	ds_write_b16 v155, v0 offset:61472
	v_cvt_pk_bf16_f32 v0, v11, v33
	s_waitcnt vmcnt(0)
	v_fma_f32 v3, v14, v60, v64
	ds_write_b16 v155, v0 offset:61744
	v_cvt_pk_bf16_f32 v0, v3, v33
	v_fma_f32 v4, v15, v61, v65
	ds_write_b16 v155, v0 offset:62016
	v_cvt_pk_bf16_f32 v0, v4, v33
	v_fma_f32 v5, v16, v62, v66
	ds_write_b16 v155, v0 offset:62288
	v_cvt_pk_bf16_f32 v0, v5, v33
	v_fmac_f32_e32 v67, v12, v63
	ds_write_b16 v155, v0 offset:62560
	v_cvt_pk_bf16_f32 v0, v67, v33
	ds_write_b16 v155, v0 offset:62832
	s_waitcnt lgkmcnt(0)
	s_barrier
	v_add_co_u32_e32 v4, vcc, s28, v42
	v_pk_fma_f32 v[56:57], v[56:57], v[20:21], v[26:27]
	s_nop 0
	v_addc_co_u32_e32 v5, vcc, 0, v43, vcc
	global_load_dwordx4 v[8:11], v[4:5], off
	global_load_dwordx4 v[0:3], v[4:5], off offset:64
	global_load_dwordx2 v[52:53], v[40:41], off offset:1792
	global_load_dwordx4 v[12:15], v[4:5], off offset:128
	s_nop 0
	global_load_dwordx4 v[4:7], v[4:5], off offset:192
	s_nop 0
	global_load_dword v28, v[44:45], off offset:1536
	ds_read_b128 v[42:45], v152 offset:34816
	ds_read_b128 v[58:61], v152 offset:34880
	ds_read_b128 v[62:65], v152 offset:34944
	v_pk_fma_f32 v[54:55], v[54:55], v[22:23], v[24:25]
	v_pk_mul_f32 v[24:25], v[24:25], v[24:25]
	v_pk_mul_f32 v[26:27], v[26:27], v[26:27]
	v_pk_add_f32 v[50:51], v[50:51], v[50:51] op_sel:[0,1] op_sel_hi:[1,0]
	v_mov_b32_e32 v168, v48
	v_mov_b32_e32 v169, v19
	v_mov_b32_e32 v170, v30
	v_mov_b32_e32 v171, v17
	s_waitcnt vmcnt(5) lgkmcnt(2)
	v_mfma_f32_16x16x32_bf16 v[42:45], v[42:45], v[8:11], 0
	s_waitcnt vmcnt(3)
	v_lshlrev_b32_e32 v67, 16, v53
	v_lshlrev_b32_e32 v66, 16, v52
	s_waitcnt lgkmcnt(1)
	v_mfma_f32_16x16x32_bf16 v[42:45], v[58:61], v[0:3], v[42:45]
	ds_read_b128 v[58:61], v152 offset:35008
	v_and_b32_e32 v53, 0xffff0000, v53
	v_and_b32_e32 v52, 0xffff0000, v52
	s_waitcnt vmcnt(2) lgkmcnt(1)
	v_mfma_f32_16x16x32_bf16 v[42:45], v[62:65], v[12:15], v[42:45]
	s_waitcnt vmcnt(1) lgkmcnt(0)
	v_mfma_f32_16x16x32_bf16 v[42:45], v[58:61], v[4:7], v[42:45]
	s_nop 7
	v_mov_b32_e32 v58, v42
	v_mov_b32_e32 v59, v44
	v_mov_b32_e32 v44, v43
	s_waitcnt vmcnt(0)
	v_pk_add_f32 v[42:43], v[28:29], v[58:59] op_sel_hi:[0,1]
	v_pk_add_f32 v[44:45], v[28:29], v[44:45] op_sel_hi:[0,1]
	v_pk_mul_f32 v[42:43], v[42:43], v[66:67]
	v_pk_mul_f32 v[44:45], v[44:45], v[52:53]
	s_nop 0
	v_cvt_pk_bf16_f32 v77, v42, v44
	v_cvt_pk_bf16_f32 v76, v43, v45
	ds_read_b128 v[58:61], v152 offset:39168
	ds_read_b128 v[62:65], v152 offset:39232
	s_waitcnt lgkmcnt(1)
	v_mfma_f32_16x16x32_bf16 v[58:61], v[58:61], v[8:11], 0
	s_waitcnt lgkmcnt(0)
	v_mfma_f32_16x16x32_bf16 v[58:61], v[62:65], v[0:3], v[58:61]
	ds_read_b128 v[62:65], v152 offset:39296
	ds_read_b128 v[66:69], v152 offset:39360
	global_load_dwordx2 v[52:53], v[40:41], off offset:1824
	s_waitcnt lgkmcnt(1)
	v_mfma_f32_16x16x32_bf16 v[58:61], v[62:65], v[12:15], v[58:61]
	s_waitcnt vmcnt(0)
	v_lshlrev_b32_e32 v62, 16, v52
	s_waitcnt lgkmcnt(0)
	v_mfma_f32_16x16x32_bf16 v[58:61], v[66:69], v[4:7], v[58:61]
	v_and_b32_e32 v63, 0xffff0000, v52
	v_lshlrev_b32_e32 v64, 16, v53
	v_and_b32_e32 v65, 0xffff0000, v53
	s_nop 4
	v_pk_add_f32 v[58:59], v[28:29], v[58:59] op_sel_hi:[0,1]
	v_pk_add_f32 v[60:61], v[28:29], v[60:61] op_sel_hi:[0,1]
	v_pk_mul_f32 v[52:53], v[58:59], v[62:63]
	v_pk_mul_f32 v[58:59], v[60:61], v[64:65]
	v_cvt_pk_bf16_f32 v75, v52, v53
	s_nop 0
	v_cvt_pk_bf16_f32 v74, v58, v59
	ds_read_b128 v[60:63], v152 offset:43520
	ds_read_b128 v[64:67], v152 offset:43584
	s_waitcnt lgkmcnt(1)
	v_mfma_f32_16x16x32_bf16 v[60:63], v[60:63], v[8:11], 0
	s_waitcnt lgkmcnt(0)
	v_mfma_f32_16x16x32_bf16 v[60:63], v[64:67], v[0:3], v[60:63]
	ds_read_b128 v[64:67], v152 offset:43648
	ds_read_b128 v[68:71], v152 offset:43712
	s_waitcnt lgkmcnt(1)
	v_mfma_f32_16x16x32_bf16 v[60:63], v[64:67], v[12:15], v[60:63]
	global_load_dwordx2 v[64:65], v[40:41], off offset:1856
	s_waitcnt vmcnt(0)
	v_lshlrev_b32_e32 v66, 16, v65
	s_waitcnt lgkmcnt(0)
	v_mfma_f32_16x16x32_bf16 v[60:63], v[68:71], v[4:7], v[60:63]
	v_and_b32_e32 v65, 0xffff0000, v65
	s_nop 6
	v_add_f32_e32 v16, v28, v60
	v_add_f32_e32 v18, v28, v61
	v_add_f32_e32 v60, v28, v62
	v_add_f32_e32 v61, v28, v63
	v_lshlrev_b32_e32 v62, 16, v64
	v_and_b32_e32 v63, 0xffff0000, v64
	v_mul_f32_e32 v64, v16, v62
	v_mul_f32_e32 v62, v18, v63
	v_mul_f32_e32 v66, v60, v66
	v_mul_f32_e32 v60, v61, v65
	v_cvt_pk_bf16_f32 v73, v64, v62
	v_cvt_pk_bf16_f32 v72, v66, v60
	ds_read_b128 v[68:71], v152 offset:47872
	ds_read_b128 v[78:81], v152 offset:47936
	s_waitcnt lgkmcnt(1)
	v_mfma_f32_16x16x32_bf16 v[68:71], v[68:71], v[8:11], 0
	v_mov_b32_e32 v94, v64
	v_mov_b32_e32 v96, v66
	s_waitcnt lgkmcnt(0)
	v_mfma_f32_16x16x32_bf16 v[68:71], v[78:81], v[0:3], v[68:71]
	ds_read_b128 v[78:81], v152 offset:48000
	ds_read_b128 v[82:85], v152 offset:48064
	s_waitcnt lgkmcnt(1)
	v_mfma_f32_16x16x32_bf16 v[68:71], v[78:81], v[12:15], v[68:71]
	global_load_dwordx2 v[78:79], v[40:41], off offset:1888
	s_waitcnt vmcnt(0)
	v_lshlrev_b32_e32 v61, 16, v78
	s_waitcnt lgkmcnt(0)
	v_mfma_f32_16x16x32_bf16 v[68:71], v[82:85], v[4:7], v[68:71]
	v_and_b32_e32 v63, 0xffff0000, v78
	v_lshlrev_b32_e32 v95, 16, v79
	v_and_b32_e32 v97, 0xffff0000, v79
	s_nop 4
	v_add_f32_e32 v16, v28, v68
	v_add_f32_e32 v18, v28, v69
	v_add_f32_e32 v65, v28, v70
	v_add_f32_e32 v67, v28, v71
	v_mul_f32_e32 v99, v16, v61
	v_mul_f32_e32 v101, v18, v63
	v_pk_mul_f32 v[102:103], v[64:65], v[94:95]
	v_pk_mul_f32 v[104:105], v[66:67], v[96:97]
	v_cvt_pk_bf16_f32 v71, v99, v101
	v_mul_f32_e32 v16, v47, v47
	v_cvt_pk_bf16_f32 v69, v103, v105
	ds_read_b128 v[78:81], v152 offset:52224
	ds_read_b128 v[82:85], v152 offset:52288
	s_waitcnt lgkmcnt(1)
	v_mfma_f32_16x16x32_bf16 v[78:81], v[78:81], v[8:11], 0
	v_mov_b32_e32 v18, v50
	v_pk_mul_f32 v[18:19], v[18:19], v[168:169]
	v_mov_b32_e32 v63, v65
	s_waitcnt lgkmcnt(0)
	v_mfma_f32_16x16x32_bf16 v[78:81], v[82:85], v[0:3], v[78:81]
	ds_read_b128 v[82:85], v152 offset:52352
	ds_read_b128 v[86:89], v152 offset:52416
	v_mov_b32_e32 v94, v62
	v_mov_b32_e32 v96, v60
	s_waitcnt lgkmcnt(1)
	v_mfma_f32_16x16x32_bf16 v[78:81], v[82:85], v[12:15], v[78:81]
	global_load_dwordx2 v[82:83], v[40:41], off offset:1920
	s_waitcnt lgkmcnt(0)
	v_mfma_f32_16x16x32_bf16 v[78:81], v[86:89], v[4:7], v[78:81]
	s_nop 7
	v_mov_b32_e32 v84, v78
	v_mov_b32_e32 v85, v80
	v_mov_b32_e32 v80, v79
	v_pk_add_f32 v[78:79], v[28:29], v[84:85] op_sel_hi:[0,1]
	v_pk_add_f32 v[80:81], v[28:29], v[80:81] op_sel_hi:[0,1]
	s_waitcnt vmcnt(0)
	v_lshlrev_b32_e32 v85, 16, v83
	v_lshlrev_b32_e32 v84, 16, v82
	v_and_b32_e32 v83, 0xffff0000, v83
	v_and_b32_e32 v82, 0xffff0000, v82
	v_pk_mul_f32 v[108:109], v[78:79], v[84:85]
	v_pk_mul_f32 v[160:161], v[80:81], v[82:83]
	s_nop 0
	v_cvt_pk_bf16_f32 v70, v108, v160
	v_cvt_pk_bf16_f32 v68, v109, v161
	ds_read_b128 v[78:81], v152 offset:56576
	ds_read_b128 v[82:85], v152 offset:56640
	s_waitcnt lgkmcnt(1)
	v_mfma_f32_16x16x32_bf16 v[78:81], v[78:81], v[8:11], 0
	s_waitcnt lgkmcnt(0)
	v_mfma_f32_16x16x32_bf16 v[78:81], v[82:85], v[0:3], v[78:81]
	ds_read_b128 v[82:85], v152 offset:56704
	ds_read_b128 v[86:89], v152 offset:56768
	s_waitcnt lgkmcnt(1)
	v_mfma_f32_16x16x32_bf16 v[78:81], v[82:85], v[12:15], v[78:81]
	global_load_dwordx2 v[82:83], v[40:41], off offset:1952
	s_waitcnt vmcnt(0)
	v_lshlrev_b32_e32 v84, 16, v82
	s_waitcnt lgkmcnt(0)
	v_mfma_f32_16x16x32_bf16 v[78:81], v[86:89], v[4:7], v[78:81]
	v_and_b32_e32 v85, 0xffff0000, v82
	v_lshlrev_b32_e32 v82, 16, v83
	v_and_b32_e32 v83, 0xffff0000, v83
	s_nop 4
	v_pk_add_f32 v[78:79], v[28:29], v[78:79] op_sel_hi:[0,1]
	v_pk_add_f32 v[80:81], v[28:29], v[80:81] op_sel_hi:[0,1]
	v_pk_mul_f32 v[162:163], v[78:79], v[84:85]
	v_pk_mul_f32 v[164:165], v[80:81], v[82:83]
	v_cvt_pk_bf16_f32 v66, v162, v163
	s_nop 0
	v_cvt_pk_bf16_f32 v64, v164, v165
	global_load_dwordx2 v[166:167], v[40:41], off offset:1984
	ds_read_b128 v[78:81], v152 offset:60928
	ds_read_b128 v[82:85], v152 offset:60992
	ds_read_b128 v[86:89], v152 offset:61056
	ds_read_b128 v[90:93], v152 offset:61120
	s_waitcnt lgkmcnt(3)
	v_mfma_f32_16x16x32_bf16 v[78:81], v[78:81], v[8:11], 0
	s_waitcnt vmcnt(0)
	v_lshlrev_b32_e32 v24, 16, v166
	s_waitcnt lgkmcnt(2)
	v_mfma_f32_16x16x32_bf16 v[78:81], v[82:85], v[0:3], v[78:81]
	v_and_b32_e32 v55, 0xffff0000, v166
	v_lshlrev_b32_e32 v57, 16, v167
	v_and_b32_e32 v61, 0xffff0000, v167
	s_waitcnt lgkmcnt(1)
	v_mfma_f32_16x16x32_bf16 v[78:81], v[86:89], v[12:15], v[78:81]
	s_waitcnt lgkmcnt(0)
	v_mfma_f32_16x16x32_bf16 v[20:23], v[90:93], v[4:7], v[78:81]
	s_nop 7
	v_add_f32_e32 v20, v28, v20
	v_add_f32_e32 v21, v28, v21
	v_add_f32_e32 v22, v28, v22
	v_add_f32_e32 v23, v28, v23
	v_mul_f32_e32 v26, v20, v24
	v_mul_f32_e32 v78, v21, v55
	v_mul_f32_e32 v80, v22, v57
	v_mul_f32_e32 v82, v23, v61
	v_cvt_pk_bf16_f32 v21, v26, v78
	v_cvt_pk_bf16_f32 v20, v80, v82
	global_load_dwordx2 v[84:85], v[40:41], off offset:2016
	v_pk_fma_f32 v[40:41], v[46:47], v[46:47], v[16:17] op_sel_hi:[1,1,0]
	v_pk_add_f32 v[22:23], v[50:51], v[48:49]
	v_mov_b32_e32 v16, v40
	v_mov_b32_e32 v55, v25
	v_pk_add_f32 v[24:25], v[40:41], v[30:31]
	v_pk_mul_f32 v[16:17], v[16:17], v[170:171]
	v_mov_b32_e32 v57, v27
	v_mov_b32_e32 v23, v19
	v_mov_b32_e32 v25, v17
	v_pk_add_f32 v[30:31], v[56:57], v[54:55]
	v_pk_add_f32 v[16:17], v[22:23], v[24:25]
	v_pk_mul_f32 v[18:19], v[44:45], v[44:45]
	v_pk_add_f32 v[16:17], v[16:17], v[30:31]
	v_pk_fma_f32 v[18:19], v[42:43], v[42:43], v[18:19]
	v_pk_add_f32 v[16:17], v[16:17], v[16:17] op_sel:[0,1] op_sel_hi:[1,0]
	v_pk_add_f32 v[18:19], v[18:19], v[18:19] op_sel:[0,1] op_sel_hi:[1,0]
	v_mov_b32_e32 v98, v16
	v_mov_b32_e32 v22, v18
	v_pk_add_f32 v[16:17], v[16:17], v[18:19]
	v_mul_f32_e32 v18, v59, v59
	v_mul_f32_e32 v24, v53, v53
	v_pk_fma_f32 v[18:19], v[58:59], v[58:59], v[18:19] op_sel_hi:[1,1,0]
	v_pk_fma_f32 v[24:25], v[52:53], v[52:53], v[24:25] op_sel_hi:[1,1,0]
	v_mov_b32_e32 v30, v18
	v_mov_b32_e32 v100, v24
	v_mov_b32_e32 v61, v67
	v_mov_b32_e32 v23, v99
	v_mov_b32_e32 v31, v101
	v_pk_add_f32 v[18:19], v[24:25], v[18:19]
	v_pk_fma_f32 v[24:25], v[62:63], v[94:95], v[102:103]
	v_pk_mul_f32 v[40:41], v[102:103], v[102:103]
	v_pk_fma_f32 v[42:43], v[60:61], v[96:97], v[104:105]
	v_pk_mul_f32 v[44:45], v[104:105], v[104:105]
	v_pk_mul_f32 v[22:23], v[98:99], v[22:23]
	v_pk_mul_f32 v[30:31], v[100:101], v[30:31]
	v_mov_b32_e32 v25, v41
	v_mov_b32_e32 v43, v45
	v_mov_b32_e32 v17, v23
	v_mov_b32_e32 v19, v31
	v_pk_add_f32 v[22:23], v[24:25], v[42:43]
	v_pk_add_f32 v[16:17], v[16:17], v[18:19]
	v_mul_f32_e32 v48, v165, v165
	v_pk_add_f32 v[16:17], v[16:17], v[22:23]
	v_pk_mul_f32 v[22:23], v[160:161], v[160:161]
	v_pk_add_f32 v[30:31], v[16:17], v[16:17] op_sel:[0,1] op_sel_hi:[1,0]
	ds_read_b128 v[16:19], v152 offset:65280
	v_pk_fma_f32 v[22:23], v[108:109], v[108:109], v[22:23]
	v_mov_b32_e32 v44, v30
	v_pk_add_f32 v[40:41], v[22:23], v[22:23] op_sel:[0,1] op_sel_hi:[1,0]
	ds_read_b128 v[22:25], v152 offset:65344
	v_mov_b32_e32 v46, v40
	v_pk_add_f32 v[30:31], v[30:31], v[40:41]
	ds_read_b128 v[40:43], v152 offset:65408
	s_waitcnt lgkmcnt(2)
	v_mfma_f32_16x16x32_bf16 v[8:11], v[16:19], v[8:11], 0
	ds_read_b128 v[16:19], v152 offset:65472
	v_mul_f32_e32 v50, v163, v163
	v_pk_fma_f32 v[48:49], v[164:165], v[164:165], v[48:49] op_sel_hi:[1,1,0]
	s_waitcnt lgkmcnt(2)
	v_mfma_f32_16x16x32_bf16 v[0:3], v[22:25], v[0:3], v[8:11]
	v_mov_b32_e32 v22, v48
	s_waitcnt lgkmcnt(1)
	v_mfma_f32_16x16x32_bf16 v[0:3], v[40:43], v[12:15], v[0:3]
	v_fma_f32 v8, v162, v162, v50
	v_fma_f32 v9, v163, v163, v50
	v_mov_b32_e32 v12, v26
	v_mov_b32_e32 v14, v80
	s_waitcnt lgkmcnt(0)
	v_mfma_f32_16x16x32_bf16 v[0:3], v[16:19], v[4:7], v[0:3]
	v_mov_b32_e32 v10, v8
	v_pk_add_f32 v[8:9], v[8:9], v[48:49]
	s_waitcnt vmcnt(0)
	v_lshlrev_b32_e32 v13, 16, v85
	s_nop 3
	v_add_f32_e32 v0, v28, v0
	v_add_f32_e32 v1, v28, v1
	v_add_f32_e32 v27, v28, v2
	v_add_f32_e32 v81, v28, v3
	v_lshlrev_b32_e32 v2, 16, v84
	v_and_b32_e32 v3, 0xffff0000, v84
	v_and_b32_e32 v15, 0xffff0000, v85
	v_mul_f32_e32 v45, v0, v2
	v_mul_f32_e32 v11, v1, v3
	v_mov_b32_e32 v79, v27
	v_mov_b32_e32 v83, v81
	v_pk_mul_f32 v[0:1], v[26:27], v[12:13]
	v_mov_b32_e32 v12, v78
	v_pk_mul_f32 v[2:3], v[80:81], v[14:15]
	v_mov_b32_e32 v14, v82
	v_mov_b32_e32 v47, v45
	v_mov_b32_e32 v23, v11
	v_cvt_pk_bf16_f32 v7, v45, v11
	v_cvt_pk_bf16_f32 v6, v1, v3
	v_pk_fma_f32 v[4:5], v[78:79], v[12:13], v[0:1]
	v_pk_mul_f32 v[0:1], v[0:1], v[0:1]
	v_pk_fma_f32 v[12:13], v[82:83], v[14:15], v[2:3]
	v_pk_mul_f32 v[2:3], v[2:3], v[2:3]
	v_pk_mul_f32 v[14:15], v[44:45], v[46:47]
	v_pk_mul_f32 v[10:11], v[10:11], v[22:23]
	v_mov_b32_e32 v5, v1
	v_mov_b32_e32 v13, v3
	v_mov_b32_e32 v31, v15
	v_mov_b32_e32 v9, v11
	v_pk_add_f32 v[0:1], v[4:5], v[12:13]
	v_pk_add_f32 v[2:3], v[30:31], v[8:9]
	s_nop 0
	v_pk_add_f32 v[0:1], v[2:3], v[0:1]
	s_barrier
	v_add_f32_e32 v8, v0, v1
	v_lshl_add_u64 v[4:5], v[38:39], 0, s[10:11]
	v_lshl_add_u64 v[0:1], v[4:5], 0, v[32:33]
	global_load_dwordx2 v[0:1], v[0:1], off
	v_lshlrev_b64 v[2:3], 11, v[36:37]
	v_lshl_add_u64 v[18:19], s[86:87], 0, v[2:3]
	v_lshlrev_b32_e32 v9, 16, v150
	v_and_b32_e32 v11, 0xffff0000, v150
	s_waitcnt lgkmcnt(0)
	v_mov_b32_e32 v10, v8
	s_nop 1
	v_permlane16_swap_b32_e32 v8, v10
	v_add_f32_e32 v8, v8, v10
	v_mov_b32_e32 v10, v8
	s_nop 1
	v_permlane32_swap_b32_e32 v8, v10
	v_add_f32_e32 v8, v8, v10
	v_fmamk_f32 v8, v8, 0x3b000000, v124
	v_mul_f32_e32 v10, 0x4b800000, v8
	v_cmp_gt_f32_e32 vcc, s3, v8
	v_lshlrev_b32_e32 v13, 16, v148
	v_and_b32_e32 v15, 0xffff0000, v148
	v_cndmask_b32_e32 v8, v8, v10, vcc
	v_rsq_f32_e32 v8, v8
	v_or_b32_e32 v16, 32, v32
	v_mov_b32_e32 v17, v33
	v_lshl_add_u64 v[16:17], v[4:5], 0, v[16:17]
	v_mul_f32_e32 v2, 0x45800000, v8
	v_cndmask_b32_e32 v3, v8, v2, vcc
	v_mov_b32_e32 v24, v3
	v_mov_b32_e32 v26, v3
	v_mov_b32_e32 v30, v3
	s_add_i32 s54, s54, s52
	s_add_u32 s4, s4, s6
	s_addc_u32 s5, s5, s7
	s_cmpk_gt_i32 s54, 0xff
	s_waitcnt vmcnt(0)
	v_lshlrev_b32_e32 v8, 16, v0
	v_and_b32_e32 v10, 0xffff0000, v0
	v_mul_f32_e32 v0, 0xbfb8aa3b, v8
	v_exp_f32_e32 v0, v0
	v_lshlrev_b32_e32 v12, 16, v1
	v_and_b32_e32 v14, 0xffff0000, v1
	v_mul_f32_e32 v1, 0xbfb8aa3b, v10
	v_exp_f32_e32 v1, v1
	v_add_f32_e32 v0, 1.0, v0
	v_rcp_f32_e32 v2, v0
	v_mul_f32_e32 v0, 0xbfb8aa3b, v12
	v_exp_f32_e32 v0, v0
	v_add_f32_e32 v1, 1.0, v1
	v_pk_mul_f32 v[8:9], v[2:3], v[8:9]
	v_rcp_f32_e32 v2, v1
	v_mul_f32_e32 v1, 0xbfb8aa3b, v14
	v_exp_f32_e32 v22, v1
	v_add_f32_e32 v0, 1.0, v0
	v_pk_mul_f32 v[10:11], v[2:3], v[10:11]
	v_rcp_f32_e32 v2, v0
	v_lshl_add_u64 v[0:1], v[18:19], 0, v[32:33]
	v_add_f32_e32 v18, 1.0, v22
	v_mul_f32_e32 v19, v8, v9
	v_pk_mul_f32 v[8:9], v[2:3], v[12:13]
	v_rcp_f32_e32 v2, v18
	v_mul_f32_e32 v10, v10, v11
	v_mul_f32_e32 v11, v8, v9
	v_cvt_pk_bf16_f32 v10, v19, v10
	v_pk_mul_f32 v[8:9], v[2:3], v[14:15]
	v_and_b32_e32 v12, 0xffff0000, v145
	v_mul_f32_e32 v2, v8, v9
	v_cvt_pk_bf16_f32 v11, v11, v2
	global_store_dwordx2 v[0:1], v[10:11], off offset:1024
	global_load_dwordx2 v[8:9], v[16:17], off
	v_lshlrev_b32_e32 v10, 16, v145
	v_lshlrev_b32_e32 v14, 16, v142
	v_mov_b32_e32 v22, v3
	v_and_b32_e32 v16, 0xffff0000, v142
	v_or_b32_e32 v18, 64, v32
	v_mov_b32_e32 v19, v33
	v_lshl_add_u64 v[18:19], v[4:5], 0, v[18:19]
	s_waitcnt vmcnt(0)
	v_lshlrev_b32_e32 v11, 16, v8
	v_and_b32_e32 v13, 0xffff0000, v8
	v_lshlrev_b32_e32 v15, 16, v9
	v_and_b32_e32 v17, 0xffff0000, v9
	v_mul_f32_e32 v2, 0xbfb8aa3b, v11
	v_mul_f32_e32 v8, 0xbfb8aa3b, v13
	v_mul_f32_e32 v9, 0xbfb8aa3b, v15
	v_mul_f32_e32 v23, 0xbfb8aa3b, v17
	v_exp_f32_e32 v2, v2
	v_exp_f32_e32 v8, v8
	v_exp_f32_e32 v9, v9
	v_exp_f32_e32 v23, v23
	v_add_f32_e32 v2, 1.0, v2
	v_add_f32_e32 v8, 1.0, v8
	v_add_f32_e32 v9, 1.0, v9
	v_add_f32_e32 v28, 1.0, v23
	v_rcp_f32_e32 v23, v2
	v_rcp_f32_e32 v25, v8
	v_rcp_f32_e32 v27, v9
	v_rcp_f32_e32 v31, v28
	v_pk_mul_f32 v[8:9], v[22:23], v[10:11]
	v_pk_mul_f32 v[10:11], v[24:25], v[12:13]
	v_pk_mul_f32 v[12:13], v[26:27], v[14:15]
	v_pk_mul_f32 v[14:15], v[30:31], v[16:17]
	v_mul_f32_e32 v2, v8, v9
	v_mul_f32_e32 v8, v10, v11
	v_mul_f32_e32 v9, v12, v13
	v_mul_f32_e32 v10, v14, v15
	v_cvt_pk_bf16_f32 v8, v2, v8
	v_cvt_pk_bf16_f32 v9, v9, v10
	global_store_dwordx2 v[0:1], v[8:9], off offset:1056
	global_load_dwordx2 v[8:9], v[18:19], off
	v_lshlrev_b32_e32 v10, 16, v139
	v_and_b32_e32 v12, 0xffff0000, v139
	v_lshlrev_b32_e32 v14, 16, v137
	v_and_b32_e32 v16, 0xffff0000, v137
	v_or_b32_e32 v18, 0x60, v32
	v_mov_b32_e32 v19, v33
	v_lshl_add_u64 v[18:19], v[4:5], 0, v[18:19]
	s_waitcnt vmcnt(0)
	v_lshlrev_b32_e32 v11, 16, v8
	v_and_b32_e32 v13, 0xffff0000, v8
	v_lshlrev_b32_e32 v15, 16, v9
	v_and_b32_e32 v17, 0xffff0000, v9
	v_mul_f32_e32 v2, 0xbfb8aa3b, v11
	v_mul_f32_e32 v8, 0xbfb8aa3b, v13
	v_mul_f32_e32 v9, 0xbfb8aa3b, v15
	v_mul_f32_e32 v23, 0xbfb8aa3b, v17
	v_exp_f32_e32 v2, v2
	v_exp_f32_e32 v8, v8
	v_exp_f32_e32 v9, v9
	v_exp_f32_e32 v23, v23
	v_add_f32_e32 v2, 1.0, v2
	v_add_f32_e32 v8, 1.0, v8
	v_add_f32_e32 v9, 1.0, v9
	v_add_f32_e32 v28, 1.0, v23
	v_rcp_f32_e32 v23, v2
	v_rcp_f32_e32 v25, v8
	v_rcp_f32_e32 v27, v9
	v_rcp_f32_e32 v31, v28
	v_pk_mul_f32 v[8:9], v[22:23], v[10:11]
	v_pk_mul_f32 v[10:11], v[24:25], v[12:13]
	v_pk_mul_f32 v[12:13], v[26:27], v[14:15]
	v_pk_mul_f32 v[14:15], v[30:31], v[16:17]
	v_mul_f32_e32 v2, v8, v9
	v_mul_f32_e32 v8, v10, v11
	v_mul_f32_e32 v9, v12, v13
	v_mul_f32_e32 v10, v14, v15
	v_cvt_pk_bf16_f32 v8, v2, v8
	v_cvt_pk_bf16_f32 v9, v9, v10
	global_store_dwordx2 v[0:1], v[8:9], off offset:1088
	global_load_dwordx2 v[8:9], v[18:19], off
	v_lshlrev_b32_e32 v10, 16, v136
	v_and_b32_e32 v12, 0xffff0000, v136
	v_lshlrev_b32_e32 v14, 16, v133
	v_and_b32_e32 v16, 0xffff0000, v133
	v_or_b32_e32 v18, 0x80, v32
	v_mov_b32_e32 v19, v33
	v_lshl_add_u64 v[18:19], v[4:5], 0, v[18:19]
	s_waitcnt vmcnt(0)
	v_lshlrev_b32_e32 v11, 16, v8
	v_and_b32_e32 v13, 0xffff0000, v8
	v_lshlrev_b32_e32 v15, 16, v9
	v_and_b32_e32 v17, 0xffff0000, v9
	v_mul_f32_e32 v2, 0xbfb8aa3b, v11
	v_mul_f32_e32 v8, 0xbfb8aa3b, v13
	v_mul_f32_e32 v9, 0xbfb8aa3b, v15
	v_mul_f32_e32 v23, 0xbfb8aa3b, v17
	v_exp_f32_e32 v2, v2
	v_exp_f32_e32 v8, v8
	v_exp_f32_e32 v9, v9
	v_exp_f32_e32 v23, v23
	v_add_f32_e32 v2, 1.0, v2
	v_add_f32_e32 v8, 1.0, v8
	v_add_f32_e32 v9, 1.0, v9
	v_add_f32_e32 v28, 1.0, v23
	v_rcp_f32_e32 v23, v2
	v_rcp_f32_e32 v25, v8
	v_rcp_f32_e32 v27, v9
	v_rcp_f32_e32 v31, v28
	v_pk_mul_f32 v[8:9], v[22:23], v[10:11]
	v_pk_mul_f32 v[10:11], v[24:25], v[12:13]
	v_pk_mul_f32 v[12:13], v[26:27], v[14:15]
	v_pk_mul_f32 v[14:15], v[30:31], v[16:17]
	v_mul_f32_e32 v2, v8, v9
	v_mul_f32_e32 v8, v10, v11
	v_mul_f32_e32 v9, v12, v13
	v_mul_f32_e32 v10, v14, v15
	v_cvt_pk_bf16_f32 v8, v2, v8
	v_cvt_pk_bf16_f32 v9, v9, v10
	global_store_dwordx2 v[0:1], v[8:9], off offset:1120
	global_load_dwordx2 v[8:9], v[18:19], off
	v_lshlrev_b32_e32 v10, 16, v134
	v_and_b32_e32 v12, 0xffff0000, v134
	v_lshlrev_b32_e32 v14, 16, v132
	v_and_b32_e32 v16, 0xffff0000, v132
	v_or_b32_e32 v18, 0xa0, v32
	v_mov_b32_e32 v19, v33
	v_lshl_add_u64 v[18:19], v[4:5], 0, v[18:19]
	s_waitcnt vmcnt(0)
	v_lshlrev_b32_e32 v11, 16, v8
	v_and_b32_e32 v13, 0xffff0000, v8
	v_lshlrev_b32_e32 v15, 16, v9
	v_and_b32_e32 v17, 0xffff0000, v9
	v_mul_f32_e32 v2, 0xbfb8aa3b, v11
	v_mul_f32_e32 v8, 0xbfb8aa3b, v13
	v_mul_f32_e32 v9, 0xbfb8aa3b, v15
	v_mul_f32_e32 v23, 0xbfb8aa3b, v17
	v_exp_f32_e32 v2, v2
	v_exp_f32_e32 v8, v8
	v_exp_f32_e32 v9, v9
	v_exp_f32_e32 v23, v23
	v_add_f32_e32 v2, 1.0, v2
	v_add_f32_e32 v8, 1.0, v8
	v_add_f32_e32 v9, 1.0, v9
	v_add_f32_e32 v28, 1.0, v23
	v_rcp_f32_e32 v23, v2
	v_rcp_f32_e32 v25, v8
	v_rcp_f32_e32 v27, v9
	v_rcp_f32_e32 v31, v28
	v_pk_mul_f32 v[8:9], v[22:23], v[10:11]
	v_pk_mul_f32 v[10:11], v[24:25], v[12:13]
	v_pk_mul_f32 v[12:13], v[26:27], v[14:15]
	v_pk_mul_f32 v[14:15], v[30:31], v[16:17]
	v_mul_f32_e32 v2, v8, v9
	v_mul_f32_e32 v8, v10, v11
	v_mul_f32_e32 v9, v12, v13
	v_mul_f32_e32 v10, v14, v15
	v_cvt_pk_bf16_f32 v8, v2, v8
	v_cvt_pk_bf16_f32 v9, v9, v10
	global_store_dwordx2 v[0:1], v[8:9], off offset:1152
	global_load_dwordx2 v[8:9], v[18:19], off
	v_lshlrev_b32_e32 v10, 16, v130
	v_and_b32_e32 v12, 0xffff0000, v130
	v_lshlrev_b32_e32 v14, 16, v129
	v_and_b32_e32 v16, 0xffff0000, v129
	v_or_b32_e32 v18, 0xc0, v32
	v_mov_b32_e32 v19, v33
	v_lshl_add_u64 v[18:19], v[4:5], 0, v[18:19]
	s_waitcnt vmcnt(0)
	v_lshlrev_b32_e32 v11, 16, v8
	v_and_b32_e32 v13, 0xffff0000, v8
	v_lshlrev_b32_e32 v15, 16, v9
	v_and_b32_e32 v17, 0xffff0000, v9
	v_mul_f32_e32 v2, 0xbfb8aa3b, v11
	v_mul_f32_e32 v8, 0xbfb8aa3b, v13
	v_mul_f32_e32 v9, 0xbfb8aa3b, v15
	v_mul_f32_e32 v23, 0xbfb8aa3b, v17
	v_exp_f32_e32 v2, v2
	v_exp_f32_e32 v8, v8
	v_exp_f32_e32 v9, v9
	v_exp_f32_e32 v23, v23
	v_add_f32_e32 v2, 1.0, v2
	v_add_f32_e32 v8, 1.0, v8
	v_add_f32_e32 v9, 1.0, v9
	v_add_f32_e32 v28, 1.0, v23
	v_rcp_f32_e32 v23, v2
	v_rcp_f32_e32 v25, v8
	v_rcp_f32_e32 v27, v9
	v_rcp_f32_e32 v31, v28
	v_pk_mul_f32 v[8:9], v[22:23], v[10:11]
	v_pk_mul_f32 v[10:11], v[24:25], v[12:13]
	v_pk_mul_f32 v[12:13], v[26:27], v[14:15]
	v_pk_mul_f32 v[14:15], v[30:31], v[16:17]
	v_mul_f32_e32 v2, v8, v9
	v_mul_f32_e32 v8, v10, v11
	v_mul_f32_e32 v9, v12, v13
	v_mul_f32_e32 v10, v14, v15
	v_cvt_pk_bf16_f32 v8, v2, v8
	v_cvt_pk_bf16_f32 v9, v9, v10
	global_store_dwordx2 v[0:1], v[8:9], off offset:1184
	global_load_dwordx2 v[8:9], v[18:19], off
	v_lshlrev_b32_e32 v10, 16, v128
	v_and_b32_e32 v12, 0xffff0000, v128
	v_lshlrev_b32_e32 v14, 16, v127
	v_and_b32_e32 v16, 0xffff0000, v127
	v_or_b32_e32 v18, 0xe0, v32
	v_mov_b32_e32 v19, v33
	v_lshl_add_u64 v[18:19], v[4:5], 0, v[18:19]
	s_waitcnt vmcnt(0)
	v_lshlrev_b32_e32 v11, 16, v8
	v_and_b32_e32 v13, 0xffff0000, v8
	v_lshlrev_b32_e32 v15, 16, v9
	v_and_b32_e32 v17, 0xffff0000, v9
	v_mul_f32_e32 v2, 0xbfb8aa3b, v11
	v_mul_f32_e32 v8, 0xbfb8aa3b, v13
	v_mul_f32_e32 v9, 0xbfb8aa3b, v15
	v_mul_f32_e32 v23, 0xbfb8aa3b, v17
	v_exp_f32_e32 v2, v2
	v_exp_f32_e32 v8, v8
	v_exp_f32_e32 v9, v9
	v_exp_f32_e32 v23, v23
	v_add_f32_e32 v2, 1.0, v2
	v_add_f32_e32 v8, 1.0, v8
	v_add_f32_e32 v9, 1.0, v9
	v_add_f32_e32 v28, 1.0, v23
	v_rcp_f32_e32 v23, v2
	v_rcp_f32_e32 v25, v8
	v_rcp_f32_e32 v27, v9
	v_rcp_f32_e32 v31, v28
	v_pk_mul_f32 v[8:9], v[22:23], v[10:11]
	v_pk_mul_f32 v[10:11], v[24:25], v[12:13]
	v_pk_mul_f32 v[12:13], v[26:27], v[14:15]
	v_pk_mul_f32 v[14:15], v[30:31], v[16:17]
	v_mul_f32_e32 v2, v8, v9
	v_mul_f32_e32 v8, v10, v11
	v_mul_f32_e32 v9, v12, v13
	v_mul_f32_e32 v10, v14, v15
	v_cvt_pk_bf16_f32 v8, v2, v8
	v_cvt_pk_bf16_f32 v9, v9, v10
	global_store_dwordx2 v[0:1], v[8:9], off offset:1216
	global_load_dwordx2 v[8:9], v[18:19], off
	v_lshlrev_b32_e32 v10, 16, v126
	v_and_b32_e32 v12, 0xffff0000, v126
	v_lshlrev_b32_e32 v14, 16, v125
	v_and_b32_e32 v16, 0xffff0000, v125
	v_or_b32_e32 v18, 0x100, v32
	v_mov_b32_e32 v19, v33
	v_lshl_add_u64 v[18:19], v[4:5], 0, v[18:19]
	s_waitcnt vmcnt(0)
	v_lshlrev_b32_e32 v11, 16, v8
	v_and_b32_e32 v13, 0xffff0000, v8
	v_lshlrev_b32_e32 v15, 16, v9
	v_and_b32_e32 v17, 0xffff0000, v9
	v_mul_f32_e32 v2, 0xbfb8aa3b, v11
	v_mul_f32_e32 v8, 0xbfb8aa3b, v13
	v_mul_f32_e32 v9, 0xbfb8aa3b, v15
	v_mul_f32_e32 v23, 0xbfb8aa3b, v17
	v_exp_f32_e32 v2, v2
	v_exp_f32_e32 v8, v8
	v_exp_f32_e32 v9, v9
	v_exp_f32_e32 v23, v23
	v_add_f32_e32 v2, 1.0, v2
	v_add_f32_e32 v8, 1.0, v8
	v_add_f32_e32 v9, 1.0, v9
	v_add_f32_e32 v28, 1.0, v23
	v_rcp_f32_e32 v23, v2
	v_rcp_f32_e32 v25, v8
	v_rcp_f32_e32 v27, v9
	v_rcp_f32_e32 v31, v28
	v_pk_mul_f32 v[8:9], v[22:23], v[10:11]
	v_pk_mul_f32 v[10:11], v[24:25], v[12:13]
	v_pk_mul_f32 v[12:13], v[26:27], v[14:15]
	v_pk_mul_f32 v[14:15], v[30:31], v[16:17]
	v_mul_f32_e32 v2, v8, v9
	v_mul_f32_e32 v8, v10, v11
	v_mul_f32_e32 v9, v12, v13
	v_mul_f32_e32 v10, v14, v15
	v_cvt_pk_bf16_f32 v8, v2, v8
	v_cvt_pk_bf16_f32 v9, v9, v10
	global_store_dwordx2 v[0:1], v[8:9], off offset:1248
	global_load_dwordx2 v[8:9], v[18:19], off
	v_lshlrev_b32_e32 v10, 16, v156
	v_and_b32_e32 v12, 0xffff0000, v156
	v_lshlrev_b32_e32 v14, 16, v154
	v_and_b32_e32 v16, 0xffff0000, v154
	v_or_b32_e32 v18, 0x120, v32
	v_mov_b32_e32 v19, v33
	v_lshl_add_u64 v[18:19], v[4:5], 0, v[18:19]
	s_waitcnt vmcnt(0)
	v_lshlrev_b32_e32 v11, 16, v8
	v_and_b32_e32 v13, 0xffff0000, v8
	v_lshlrev_b32_e32 v15, 16, v9
	v_and_b32_e32 v17, 0xffff0000, v9
	v_mul_f32_e32 v2, 0xbfb8aa3b, v11
	v_mul_f32_e32 v8, 0xbfb8aa3b, v13
	v_mul_f32_e32 v9, 0xbfb8aa3b, v15
	v_mul_f32_e32 v23, 0xbfb8aa3b, v17
	v_exp_f32_e32 v2, v2
	v_exp_f32_e32 v8, v8
	v_exp_f32_e32 v9, v9
	v_exp_f32_e32 v23, v23
	v_add_f32_e32 v2, 1.0, v2
	v_add_f32_e32 v8, 1.0, v8
	v_add_f32_e32 v9, 1.0, v9
	v_add_f32_e32 v28, 1.0, v23
	v_rcp_f32_e32 v23, v2
	v_rcp_f32_e32 v25, v8
	v_rcp_f32_e32 v27, v9
	v_rcp_f32_e32 v31, v28
	v_pk_mul_f32 v[8:9], v[22:23], v[10:11]
	v_pk_mul_f32 v[10:11], v[24:25], v[12:13]
	v_pk_mul_f32 v[12:13], v[26:27], v[14:15]
	v_pk_mul_f32 v[14:15], v[30:31], v[16:17]
	v_mul_f32_e32 v2, v8, v9
	v_mul_f32_e32 v8, v10, v11
	v_mul_f32_e32 v9, v12, v13
	v_mul_f32_e32 v10, v14, v15
	v_cvt_pk_bf16_f32 v8, v2, v8
	v_cvt_pk_bf16_f32 v9, v9, v10
	global_store_dwordx2 v[0:1], v[8:9], off offset:1280
	global_load_dwordx2 v[8:9], v[18:19], off
	v_lshlrev_b32_e32 v10, 16, v153
	v_and_b32_e32 v12, 0xffff0000, v153
	v_lshlrev_b32_e32 v14, 16, v151
	v_and_b32_e32 v16, 0xffff0000, v151
	v_or_b32_e32 v18, 0x140, v32
	v_mov_b32_e32 v19, v33
	v_lshl_add_u64 v[18:19], v[4:5], 0, v[18:19]
	s_waitcnt vmcnt(0)
	v_lshlrev_b32_e32 v11, 16, v8
	v_and_b32_e32 v13, 0xffff0000, v8
	v_lshlrev_b32_e32 v15, 16, v9
	v_and_b32_e32 v17, 0xffff0000, v9
	v_mul_f32_e32 v2, 0xbfb8aa3b, v11
	v_mul_f32_e32 v8, 0xbfb8aa3b, v13
	v_mul_f32_e32 v9, 0xbfb8aa3b, v15
	v_mul_f32_e32 v23, 0xbfb8aa3b, v17
	v_exp_f32_e32 v2, v2
	v_exp_f32_e32 v8, v8
	v_exp_f32_e32 v9, v9
	v_exp_f32_e32 v23, v23
	v_add_f32_e32 v2, 1.0, v2
	v_add_f32_e32 v8, 1.0, v8
	v_add_f32_e32 v9, 1.0, v9
	v_add_f32_e32 v28, 1.0, v23
	v_rcp_f32_e32 v23, v2
	v_rcp_f32_e32 v25, v8
	v_rcp_f32_e32 v27, v9
	v_rcp_f32_e32 v31, v28
	v_pk_mul_f32 v[8:9], v[22:23], v[10:11]
	v_pk_mul_f32 v[10:11], v[24:25], v[12:13]
	v_pk_mul_f32 v[12:13], v[26:27], v[14:15]
	v_pk_mul_f32 v[14:15], v[30:31], v[16:17]
	v_mul_f32_e32 v2, v8, v9
	v_mul_f32_e32 v8, v10, v11
	v_mul_f32_e32 v9, v12, v13
	v_mul_f32_e32 v10, v14, v15
	v_cvt_pk_bf16_f32 v8, v2, v8
	v_cvt_pk_bf16_f32 v9, v9, v10
	global_store_dwordx2 v[0:1], v[8:9], off offset:1312
	global_load_dwordx2 v[8:9], v[18:19], off
	v_lshlrev_b32_e32 v10, 16, v149
	v_and_b32_e32 v12, 0xffff0000, v149
	v_lshlrev_b32_e32 v14, 16, v147
	v_and_b32_e32 v16, 0xffff0000, v147
	v_or_b32_e32 v18, 0x160, v32
	v_mov_b32_e32 v19, v33
	v_lshl_add_u64 v[18:19], v[4:5], 0, v[18:19]
	s_waitcnt vmcnt(0)
	v_lshlrev_b32_e32 v11, 16, v8
	v_and_b32_e32 v13, 0xffff0000, v8
	v_lshlrev_b32_e32 v15, 16, v9
	v_and_b32_e32 v17, 0xffff0000, v9
	v_mul_f32_e32 v2, 0xbfb8aa3b, v11
	v_mul_f32_e32 v8, 0xbfb8aa3b, v13
	v_mul_f32_e32 v9, 0xbfb8aa3b, v15
	v_mul_f32_e32 v23, 0xbfb8aa3b, v17
	v_exp_f32_e32 v2, v2
	v_exp_f32_e32 v8, v8
	v_exp_f32_e32 v9, v9
	v_exp_f32_e32 v23, v23
	v_add_f32_e32 v2, 1.0, v2
	v_add_f32_e32 v8, 1.0, v8
	v_add_f32_e32 v9, 1.0, v9
	v_add_f32_e32 v28, 1.0, v23
	v_rcp_f32_e32 v23, v2
	v_rcp_f32_e32 v25, v8
	v_rcp_f32_e32 v27, v9
	v_rcp_f32_e32 v31, v28
	v_pk_mul_f32 v[8:9], v[22:23], v[10:11]
	v_pk_mul_f32 v[10:11], v[24:25], v[12:13]
	v_pk_mul_f32 v[12:13], v[26:27], v[14:15]
	v_pk_mul_f32 v[14:15], v[30:31], v[16:17]
	v_mul_f32_e32 v2, v8, v9
	v_mul_f32_e32 v8, v10, v11
	v_mul_f32_e32 v9, v12, v13
	v_mul_f32_e32 v10, v14, v15
	v_cvt_pk_bf16_f32 v8, v2, v8
	v_cvt_pk_bf16_f32 v9, v9, v10
	global_store_dwordx2 v[0:1], v[8:9], off offset:1344
	global_load_dwordx2 v[8:9], v[18:19], off
	v_lshlrev_b32_e32 v10, 16, v146
	v_and_b32_e32 v12, 0xffff0000, v146
	v_lshlrev_b32_e32 v14, 16, v143
	v_and_b32_e32 v16, 0xffff0000, v143
	v_or_b32_e32 v18, 0x180, v32
	v_mov_b32_e32 v19, v33
	v_lshl_add_u64 v[18:19], v[4:5], 0, v[18:19]
	s_waitcnt vmcnt(0)
	v_lshlrev_b32_e32 v11, 16, v8
	v_and_b32_e32 v13, 0xffff0000, v8
	v_lshlrev_b32_e32 v15, 16, v9
	v_and_b32_e32 v17, 0xffff0000, v9
	v_mul_f32_e32 v2, 0xbfb8aa3b, v11
	v_mul_f32_e32 v8, 0xbfb8aa3b, v13
	v_mul_f32_e32 v9, 0xbfb8aa3b, v15
	v_mul_f32_e32 v23, 0xbfb8aa3b, v17
	v_exp_f32_e32 v2, v2
	v_exp_f32_e32 v8, v8
	v_exp_f32_e32 v9, v9
	v_exp_f32_e32 v23, v23
	v_add_f32_e32 v2, 1.0, v2
	v_add_f32_e32 v8, 1.0, v8
	v_add_f32_e32 v9, 1.0, v9
	v_add_f32_e32 v28, 1.0, v23
	v_rcp_f32_e32 v23, v2
	v_rcp_f32_e32 v25, v8
	v_rcp_f32_e32 v27, v9
	v_rcp_f32_e32 v31, v28
	v_pk_mul_f32 v[8:9], v[22:23], v[10:11]
	v_pk_mul_f32 v[10:11], v[24:25], v[12:13]
	v_pk_mul_f32 v[12:13], v[26:27], v[14:15]
	v_pk_mul_f32 v[14:15], v[30:31], v[16:17]
	v_mul_f32_e32 v2, v8, v9
	v_mul_f32_e32 v8, v10, v11
	v_mul_f32_e32 v9, v12, v13
	v_mul_f32_e32 v10, v14, v15
	v_cvt_pk_bf16_f32 v8, v2, v8
	v_cvt_pk_bf16_f32 v9, v9, v10
	global_store_dwordx2 v[0:1], v[8:9], off offset:1376
	global_load_dwordx2 v[8:9], v[18:19], off
	v_lshlrev_b32_e32 v10, 16, v144
	v_and_b32_e32 v12, 0xffff0000, v144
	v_lshlrev_b32_e32 v14, 16, v141
	v_and_b32_e32 v16, 0xffff0000, v141
	v_or_b32_e32 v18, 0x1a0, v32
	v_mov_b32_e32 v19, v33
	v_lshl_add_u64 v[18:19], v[4:5], 0, v[18:19]
	s_waitcnt vmcnt(0)
	v_lshlrev_b32_e32 v11, 16, v8
	v_and_b32_e32 v13, 0xffff0000, v8
	v_lshlrev_b32_e32 v15, 16, v9
	v_and_b32_e32 v17, 0xffff0000, v9
	v_mul_f32_e32 v2, 0xbfb8aa3b, v11
	v_mul_f32_e32 v8, 0xbfb8aa3b, v13
	v_mul_f32_e32 v9, 0xbfb8aa3b, v15
	v_mul_f32_e32 v23, 0xbfb8aa3b, v17
	v_exp_f32_e32 v2, v2
	v_exp_f32_e32 v8, v8
	v_exp_f32_e32 v9, v9
	v_exp_f32_e32 v23, v23
	v_add_f32_e32 v2, 1.0, v2
	v_add_f32_e32 v8, 1.0, v8
	v_add_f32_e32 v9, 1.0, v9
	v_add_f32_e32 v28, 1.0, v23
	v_rcp_f32_e32 v23, v2
	v_rcp_f32_e32 v25, v8
	v_rcp_f32_e32 v27, v9
	v_rcp_f32_e32 v31, v28
	v_pk_mul_f32 v[8:9], v[22:23], v[10:11]
	v_pk_mul_f32 v[10:11], v[24:25], v[12:13]
	v_pk_mul_f32 v[12:13], v[26:27], v[14:15]
	v_pk_mul_f32 v[14:15], v[30:31], v[16:17]
	v_mul_f32_e32 v2, v8, v9
	v_mul_f32_e32 v8, v10, v11
	v_mul_f32_e32 v9, v12, v13
	v_mul_f32_e32 v10, v14, v15
	v_cvt_pk_bf16_f32 v8, v2, v8
	v_cvt_pk_bf16_f32 v9, v9, v10
	global_store_dwordx2 v[0:1], v[8:9], off offset:1408
	global_load_dwordx2 v[8:9], v[18:19], off
	v_lshlrev_b32_e32 v10, 16, v140
	v_and_b32_e32 v12, 0xffff0000, v140
	v_lshlrev_b32_e32 v14, 16, v138
	v_and_b32_e32 v16, 0xffff0000, v138
	v_or_b32_e32 v18, 0x1c0, v32
	v_mov_b32_e32 v19, v33
	v_lshl_add_u64 v[18:19], v[4:5], 0, v[18:19]
	s_waitcnt vmcnt(0)
	v_lshlrev_b32_e32 v11, 16, v8
	v_and_b32_e32 v13, 0xffff0000, v8
	v_lshlrev_b32_e32 v15, 16, v9
	v_and_b32_e32 v17, 0xffff0000, v9
	v_mul_f32_e32 v2, 0xbfb8aa3b, v11
	v_mul_f32_e32 v8, 0xbfb8aa3b, v13
	v_mul_f32_e32 v9, 0xbfb8aa3b, v15
	v_mul_f32_e32 v23, 0xbfb8aa3b, v17
	v_exp_f32_e32 v2, v2
	v_exp_f32_e32 v8, v8
	v_exp_f32_e32 v9, v9
	v_exp_f32_e32 v23, v23
	v_add_f32_e32 v2, 1.0, v2
	v_add_f32_e32 v8, 1.0, v8
	v_add_f32_e32 v9, 1.0, v9
	v_add_f32_e32 v28, 1.0, v23
	v_rcp_f32_e32 v23, v2
	v_rcp_f32_e32 v25, v8
	v_rcp_f32_e32 v27, v9
	v_rcp_f32_e32 v31, v28
	v_pk_mul_f32 v[8:9], v[22:23], v[10:11]
	v_pk_mul_f32 v[10:11], v[24:25], v[12:13]
	v_pk_mul_f32 v[12:13], v[26:27], v[14:15]
	v_pk_mul_f32 v[14:15], v[30:31], v[16:17]
	v_mul_f32_e32 v2, v8, v9
	v_mul_f32_e32 v8, v10, v11
	v_mul_f32_e32 v9, v12, v13
	v_mul_f32_e32 v10, v14, v15
	v_cvt_pk_bf16_f32 v8, v2, v8
	v_cvt_pk_bf16_f32 v9, v9, v10
	global_store_dwordx2 v[0:1], v[8:9], off offset:1440
	global_load_dwordx2 v[8:9], v[18:19], off
	v_lshlrev_b32_e32 v10, 16, v135
	v_and_b32_e32 v12, 0xffff0000, v135
	v_lshlrev_b32_e32 v14, 16, v131
	v_and_b32_e32 v16, 0xffff0000, v131
	v_or_b32_e32 v18, 0x1e0, v32
	v_mov_b32_e32 v19, v33
	v_lshl_add_u64 v[18:19], v[4:5], 0, v[18:19]
	s_waitcnt vmcnt(0)
	v_lshlrev_b32_e32 v11, 16, v8
	v_and_b32_e32 v13, 0xffff0000, v8
	v_lshlrev_b32_e32 v15, 16, v9
	v_and_b32_e32 v17, 0xffff0000, v9
	v_mul_f32_e32 v2, 0xbfb8aa3b, v11
	v_mul_f32_e32 v8, 0xbfb8aa3b, v13
	v_mul_f32_e32 v9, 0xbfb8aa3b, v15
	v_mul_f32_e32 v23, 0xbfb8aa3b, v17
	v_exp_f32_e32 v2, v2
	v_exp_f32_e32 v8, v8
	v_exp_f32_e32 v9, v9
	v_exp_f32_e32 v23, v23
	v_add_f32_e32 v2, 1.0, v2
	v_add_f32_e32 v8, 1.0, v8
	v_add_f32_e32 v9, 1.0, v9
	v_add_f32_e32 v28, 1.0, v23
	v_rcp_f32_e32 v23, v2
	v_rcp_f32_e32 v25, v8
	v_rcp_f32_e32 v27, v9
	v_rcp_f32_e32 v31, v28
	v_pk_mul_f32 v[8:9], v[22:23], v[10:11]
	v_pk_mul_f32 v[10:11], v[24:25], v[12:13]
	v_pk_mul_f32 v[12:13], v[26:27], v[14:15]
	v_pk_mul_f32 v[14:15], v[30:31], v[16:17]
	v_mul_f32_e32 v2, v8, v9
	v_mul_f32_e32 v8, v10, v11
	v_mul_f32_e32 v9, v12, v13
	v_mul_f32_e32 v10, v14, v15
	v_cvt_pk_bf16_f32 v8, v2, v8
	v_cvt_pk_bf16_f32 v9, v9, v10
	global_store_dwordx2 v[0:1], v[8:9], off offset:1472
	global_load_dwordx2 v[8:9], v[18:19], off
	v_lshlrev_b32_e32 v10, 16, v122
	v_and_b32_e32 v12, 0xffff0000, v122
	v_lshlrev_b32_e32 v14, 16, v120
	v_and_b32_e32 v16, 0xffff0000, v120
	v_or_b32_e32 v18, 0x200, v32
	v_mov_b32_e32 v19, v33
	v_lshl_add_u64 v[18:19], v[4:5], 0, v[18:19]
	s_waitcnt vmcnt(0)
	v_lshlrev_b32_e32 v11, 16, v8
	v_and_b32_e32 v13, 0xffff0000, v8
	v_lshlrev_b32_e32 v15, 16, v9
	v_and_b32_e32 v17, 0xffff0000, v9
	v_mul_f32_e32 v2, 0xbfb8aa3b, v11
	v_mul_f32_e32 v8, 0xbfb8aa3b, v13
	v_mul_f32_e32 v9, 0xbfb8aa3b, v15
	v_mul_f32_e32 v23, 0xbfb8aa3b, v17
	v_exp_f32_e32 v2, v2
	v_exp_f32_e32 v8, v8
	v_exp_f32_e32 v9, v9
	v_exp_f32_e32 v23, v23
	v_add_f32_e32 v2, 1.0, v2
	v_add_f32_e32 v8, 1.0, v8
	v_add_f32_e32 v9, 1.0, v9
	v_add_f32_e32 v28, 1.0, v23
	v_rcp_f32_e32 v23, v2
	v_rcp_f32_e32 v25, v8
	v_rcp_f32_e32 v27, v9
	v_rcp_f32_e32 v31, v28
	v_pk_mul_f32 v[8:9], v[22:23], v[10:11]
	v_pk_mul_f32 v[10:11], v[24:25], v[12:13]
	v_pk_mul_f32 v[12:13], v[26:27], v[14:15]
	v_pk_mul_f32 v[14:15], v[30:31], v[16:17]
	v_mul_f32_e32 v2, v8, v9
	v_mul_f32_e32 v8, v10, v11
	v_mul_f32_e32 v9, v12, v13
	v_mul_f32_e32 v10, v14, v15
	v_cvt_pk_bf16_f32 v8, v2, v8
	v_cvt_pk_bf16_f32 v9, v9, v10
	global_store_dwordx2 v[0:1], v[8:9], off offset:1504
	global_load_dwordx2 v[8:9], v[18:19], off
	v_lshlrev_b32_e32 v10, 16, v159
	v_and_b32_e32 v12, 0xffff0000, v159
	v_lshlrev_b32_e32 v14, 16, v158
	v_and_b32_e32 v16, 0xffff0000, v158
	v_or_b32_e32 v18, 0x220, v32
	v_mov_b32_e32 v19, v33
	v_lshl_add_u64 v[18:19], v[4:5], 0, v[18:19]
	s_waitcnt vmcnt(0)
	v_lshlrev_b32_e32 v11, 16, v8
	v_and_b32_e32 v13, 0xffff0000, v8
	v_lshlrev_b32_e32 v15, 16, v9
	v_and_b32_e32 v17, 0xffff0000, v9
	v_mul_f32_e32 v2, 0xbfb8aa3b, v11
	v_mul_f32_e32 v8, 0xbfb8aa3b, v13
	v_mul_f32_e32 v9, 0xbfb8aa3b, v15
	v_mul_f32_e32 v23, 0xbfb8aa3b, v17
	v_exp_f32_e32 v2, v2
	v_exp_f32_e32 v8, v8
	v_exp_f32_e32 v9, v9
	v_exp_f32_e32 v23, v23
	v_add_f32_e32 v2, 1.0, v2
	v_add_f32_e32 v8, 1.0, v8
	v_add_f32_e32 v9, 1.0, v9
	v_add_f32_e32 v28, 1.0, v23
	v_rcp_f32_e32 v23, v2
	v_rcp_f32_e32 v25, v8
	v_rcp_f32_e32 v27, v9
	v_rcp_f32_e32 v31, v28
	v_pk_mul_f32 v[8:9], v[22:23], v[10:11]
	v_pk_mul_f32 v[10:11], v[24:25], v[12:13]
	v_pk_mul_f32 v[12:13], v[26:27], v[14:15]
	v_pk_mul_f32 v[14:15], v[30:31], v[16:17]
	v_mul_f32_e32 v2, v8, v9
	v_mul_f32_e32 v8, v10, v11
	v_mul_f32_e32 v9, v12, v13
	v_mul_f32_e32 v10, v14, v15
	v_cvt_pk_bf16_f32 v8, v2, v8
	v_cvt_pk_bf16_f32 v9, v9, v10
	global_store_dwordx2 v[0:1], v[8:9], off offset:1536
	global_load_dwordx2 v[8:9], v[18:19], off
	v_lshlrev_b32_e32 v10, 16, v123
	v_and_b32_e32 v12, 0xffff0000, v123
	v_lshlrev_b32_e32 v14, 16, v121
	v_and_b32_e32 v16, 0xffff0000, v121
	v_or_b32_e32 v18, 0x240, v32
	v_mov_b32_e32 v19, v33
	v_lshl_add_u64 v[18:19], v[4:5], 0, v[18:19]
	s_waitcnt vmcnt(0)
	v_lshlrev_b32_e32 v11, 16, v8
	v_and_b32_e32 v13, 0xffff0000, v8
	v_lshlrev_b32_e32 v15, 16, v9
	v_and_b32_e32 v17, 0xffff0000, v9
	v_mul_f32_e32 v2, 0xbfb8aa3b, v11
	v_mul_f32_e32 v8, 0xbfb8aa3b, v13
	v_mul_f32_e32 v9, 0xbfb8aa3b, v15
	v_mul_f32_e32 v23, 0xbfb8aa3b, v17
	v_exp_f32_e32 v2, v2
	v_exp_f32_e32 v8, v8
	v_exp_f32_e32 v9, v9
	v_exp_f32_e32 v23, v23
	v_add_f32_e32 v2, 1.0, v2
	v_add_f32_e32 v8, 1.0, v8
	v_add_f32_e32 v9, 1.0, v9
	v_add_f32_e32 v28, 1.0, v23
	v_rcp_f32_e32 v23, v2
	v_rcp_f32_e32 v25, v8
	v_rcp_f32_e32 v27, v9
	v_rcp_f32_e32 v31, v28
	v_pk_mul_f32 v[8:9], v[22:23], v[10:11]
	v_pk_mul_f32 v[10:11], v[24:25], v[12:13]
	v_pk_mul_f32 v[12:13], v[26:27], v[14:15]
	v_pk_mul_f32 v[14:15], v[30:31], v[16:17]
	v_mul_f32_e32 v2, v8, v9
	v_mul_f32_e32 v8, v10, v11
	v_mul_f32_e32 v9, v12, v13
	v_mul_f32_e32 v10, v14, v15
	v_cvt_pk_bf16_f32 v8, v2, v8
	v_cvt_pk_bf16_f32 v9, v9, v10
	global_store_dwordx2 v[0:1], v[8:9], off offset:1568
	global_load_dwordx2 v[8:9], v[18:19], off
	v_lshlrev_b32_e32 v10, 16, v119
	v_and_b32_e32 v12, 0xffff0000, v119
	v_lshlrev_b32_e32 v14, 16, v118
	v_and_b32_e32 v16, 0xffff0000, v118
	v_or_b32_e32 v18, 0x260, v32
	v_mov_b32_e32 v19, v33
	v_lshl_add_u64 v[18:19], v[4:5], 0, v[18:19]
	s_waitcnt vmcnt(0)
	v_lshlrev_b32_e32 v11, 16, v8
	v_and_b32_e32 v13, 0xffff0000, v8
	v_lshlrev_b32_e32 v15, 16, v9
	v_and_b32_e32 v17, 0xffff0000, v9
	v_mul_f32_e32 v2, 0xbfb8aa3b, v11
	v_mul_f32_e32 v8, 0xbfb8aa3b, v13
	v_mul_f32_e32 v9, 0xbfb8aa3b, v15
	v_mul_f32_e32 v23, 0xbfb8aa3b, v17
	v_exp_f32_e32 v2, v2
	v_exp_f32_e32 v8, v8
	v_exp_f32_e32 v9, v9
	v_exp_f32_e32 v23, v23
	v_add_f32_e32 v2, 1.0, v2
	v_add_f32_e32 v8, 1.0, v8
	v_add_f32_e32 v9, 1.0, v9
	v_add_f32_e32 v28, 1.0, v23
	v_rcp_f32_e32 v23, v2
	v_rcp_f32_e32 v25, v8
	v_rcp_f32_e32 v27, v9
	v_rcp_f32_e32 v31, v28
	v_pk_mul_f32 v[8:9], v[22:23], v[10:11]
	v_pk_mul_f32 v[10:11], v[24:25], v[12:13]
	v_pk_mul_f32 v[12:13], v[26:27], v[14:15]
	v_pk_mul_f32 v[14:15], v[30:31], v[16:17]
	v_mul_f32_e32 v2, v8, v9
	v_mul_f32_e32 v8, v10, v11
	v_mul_f32_e32 v9, v12, v13
	v_mul_f32_e32 v10, v14, v15
	v_cvt_pk_bf16_f32 v8, v2, v8
	v_cvt_pk_bf16_f32 v9, v9, v10
	global_store_dwordx2 v[0:1], v[8:9], off offset:1600
	global_load_dwordx2 v[8:9], v[18:19], off
	v_lshlrev_b32_e32 v10, 16, v117
	v_and_b32_e32 v12, 0xffff0000, v117
	v_lshlrev_b32_e32 v14, 16, v115
	v_and_b32_e32 v16, 0xffff0000, v115
	v_or_b32_e32 v18, 0x280, v32
	v_mov_b32_e32 v19, v33
	v_lshl_add_u64 v[18:19], v[4:5], 0, v[18:19]
	s_waitcnt vmcnt(0)
	v_lshlrev_b32_e32 v11, 16, v8
	v_and_b32_e32 v13, 0xffff0000, v8
	v_lshlrev_b32_e32 v15, 16, v9
	v_and_b32_e32 v17, 0xffff0000, v9
	v_mul_f32_e32 v2, 0xbfb8aa3b, v11
	v_mul_f32_e32 v8, 0xbfb8aa3b, v13
	v_mul_f32_e32 v9, 0xbfb8aa3b, v15
	v_mul_f32_e32 v23, 0xbfb8aa3b, v17
	v_exp_f32_e32 v2, v2
	v_exp_f32_e32 v8, v8
	v_exp_f32_e32 v9, v9
	v_exp_f32_e32 v23, v23
	v_add_f32_e32 v2, 1.0, v2
	v_add_f32_e32 v8, 1.0, v8
	v_add_f32_e32 v9, 1.0, v9
	v_add_f32_e32 v28, 1.0, v23
	v_rcp_f32_e32 v23, v2
	v_rcp_f32_e32 v25, v8
	v_rcp_f32_e32 v27, v9
	v_rcp_f32_e32 v31, v28
	v_pk_mul_f32 v[8:9], v[22:23], v[10:11]
	v_pk_mul_f32 v[10:11], v[24:25], v[12:13]
	v_pk_mul_f32 v[12:13], v[26:27], v[14:15]
	v_pk_mul_f32 v[14:15], v[30:31], v[16:17]
	v_mul_f32_e32 v2, v8, v9
	v_mul_f32_e32 v8, v10, v11
	v_mul_f32_e32 v9, v12, v13
	v_mul_f32_e32 v10, v14, v15
	v_cvt_pk_bf16_f32 v8, v2, v8
	v_cvt_pk_bf16_f32 v9, v9, v10
	global_store_dwordx2 v[0:1], v[8:9], off offset:1632
	global_load_dwordx2 v[8:9], v[18:19], off
	v_lshlrev_b32_e32 v10, 16, v116
	v_and_b32_e32 v12, 0xffff0000, v116
	v_lshlrev_b32_e32 v14, 16, v114
	v_and_b32_e32 v16, 0xffff0000, v114
	v_or_b32_e32 v18, 0x2a0, v32
	v_mov_b32_e32 v19, v33
	v_lshl_add_u64 v[18:19], v[4:5], 0, v[18:19]
	s_waitcnt vmcnt(0)
	v_lshlrev_b32_e32 v11, 16, v8
	v_and_b32_e32 v13, 0xffff0000, v8
	v_lshlrev_b32_e32 v15, 16, v9
	v_and_b32_e32 v17, 0xffff0000, v9
	v_mul_f32_e32 v2, 0xbfb8aa3b, v11
	v_mul_f32_e32 v8, 0xbfb8aa3b, v13
	v_mul_f32_e32 v9, 0xbfb8aa3b, v15
	v_mul_f32_e32 v23, 0xbfb8aa3b, v17
	v_exp_f32_e32 v2, v2
	v_exp_f32_e32 v8, v8
	v_exp_f32_e32 v9, v9
	v_exp_f32_e32 v23, v23
	v_add_f32_e32 v2, 1.0, v2
	v_add_f32_e32 v8, 1.0, v8
	v_add_f32_e32 v9, 1.0, v9
	v_add_f32_e32 v28, 1.0, v23
	v_rcp_f32_e32 v23, v2
	v_rcp_f32_e32 v25, v8
	v_rcp_f32_e32 v27, v9
	v_rcp_f32_e32 v31, v28
	v_pk_mul_f32 v[8:9], v[22:23], v[10:11]
	v_pk_mul_f32 v[10:11], v[24:25], v[12:13]
	v_pk_mul_f32 v[12:13], v[26:27], v[14:15]
	v_pk_mul_f32 v[14:15], v[30:31], v[16:17]
	v_mul_f32_e32 v2, v8, v9
	v_mul_f32_e32 v8, v10, v11
	v_mul_f32_e32 v9, v12, v13
	v_mul_f32_e32 v10, v14, v15
	v_cvt_pk_bf16_f32 v8, v2, v8
	v_cvt_pk_bf16_f32 v9, v9, v10
	global_store_dwordx2 v[0:1], v[8:9], off offset:1664
	global_load_dwordx2 v[8:9], v[18:19], off
	v_lshlrev_b32_e32 v10, 16, v113
	v_and_b32_e32 v12, 0xffff0000, v113
	v_lshlrev_b32_e32 v14, 16, v112
	v_and_b32_e32 v16, 0xffff0000, v112
	v_or_b32_e32 v18, 0x2c0, v32
	v_mov_b32_e32 v19, v33
	v_lshl_add_u64 v[18:19], v[4:5], 0, v[18:19]
	s_waitcnt vmcnt(0)
	v_lshlrev_b32_e32 v11, 16, v8
	v_and_b32_e32 v13, 0xffff0000, v8
	v_lshlrev_b32_e32 v15, 16, v9
	v_and_b32_e32 v17, 0xffff0000, v9
	v_mul_f32_e32 v2, 0xbfb8aa3b, v11
	v_mul_f32_e32 v8, 0xbfb8aa3b, v13
	v_mul_f32_e32 v9, 0xbfb8aa3b, v15
	v_mul_f32_e32 v23, 0xbfb8aa3b, v17
	v_exp_f32_e32 v2, v2
	v_exp_f32_e32 v8, v8
	v_exp_f32_e32 v9, v9
	v_exp_f32_e32 v23, v23
	v_add_f32_e32 v2, 1.0, v2
	v_add_f32_e32 v8, 1.0, v8
	v_add_f32_e32 v9, 1.0, v9
	v_add_f32_e32 v28, 1.0, v23
	v_rcp_f32_e32 v23, v2
	v_rcp_f32_e32 v25, v8
	v_rcp_f32_e32 v27, v9
	v_rcp_f32_e32 v31, v28
	v_pk_mul_f32 v[8:9], v[22:23], v[10:11]
	v_pk_mul_f32 v[10:11], v[24:25], v[12:13]
	v_pk_mul_f32 v[12:13], v[26:27], v[14:15]
	v_pk_mul_f32 v[14:15], v[30:31], v[16:17]
	v_mul_f32_e32 v2, v8, v9
	v_mul_f32_e32 v8, v10, v11
	v_mul_f32_e32 v9, v12, v13
	v_mul_f32_e32 v10, v14, v15
	v_cvt_pk_bf16_f32 v8, v2, v8
	v_cvt_pk_bf16_f32 v9, v9, v10
	global_store_dwordx2 v[0:1], v[8:9], off offset:1696
	global_load_dwordx2 v[8:9], v[18:19], off
	v_lshlrev_b32_e32 v10, 16, v111
	v_and_b32_e32 v12, 0xffff0000, v111
	v_lshlrev_b32_e32 v14, 16, v110
	v_and_b32_e32 v16, 0xffff0000, v110
	v_or_b32_e32 v18, 0x2e0, v32
	v_mov_b32_e32 v19, v33
	v_lshl_add_u64 v[18:19], v[4:5], 0, v[18:19]
	s_waitcnt vmcnt(0)
	v_lshlrev_b32_e32 v11, 16, v8
	v_and_b32_e32 v13, 0xffff0000, v8
	v_lshlrev_b32_e32 v15, 16, v9
	v_and_b32_e32 v17, 0xffff0000, v9
	v_mul_f32_e32 v2, 0xbfb8aa3b, v11
	v_mul_f32_e32 v8, 0xbfb8aa3b, v13
	v_mul_f32_e32 v9, 0xbfb8aa3b, v15
	v_mul_f32_e32 v23, 0xbfb8aa3b, v17
	v_exp_f32_e32 v2, v2
	v_exp_f32_e32 v8, v8
	v_exp_f32_e32 v9, v9
	v_exp_f32_e32 v23, v23
	v_add_f32_e32 v2, 1.0, v2
	v_add_f32_e32 v8, 1.0, v8
	v_add_f32_e32 v9, 1.0, v9
	v_add_f32_e32 v28, 1.0, v23
	v_rcp_f32_e32 v23, v2
	v_rcp_f32_e32 v25, v8
	v_rcp_f32_e32 v27, v9
	v_rcp_f32_e32 v31, v28
	v_pk_mul_f32 v[8:9], v[22:23], v[10:11]
	v_pk_mul_f32 v[10:11], v[24:25], v[12:13]
	v_pk_mul_f32 v[12:13], v[26:27], v[14:15]
	v_pk_mul_f32 v[14:15], v[30:31], v[16:17]
	v_mul_f32_e32 v2, v8, v9
	v_mul_f32_e32 v8, v10, v11
	v_mul_f32_e32 v9, v12, v13
	v_mul_f32_e32 v10, v14, v15
	v_cvt_pk_bf16_f32 v8, v2, v8
	v_cvt_pk_bf16_f32 v9, v9, v10
	global_store_dwordx2 v[0:1], v[8:9], off offset:1728
	global_load_dwordx2 v[8:9], v[18:19], off
	v_lshlrev_b32_e32 v14, 16, v29
	v_and_b32_e32 v16, 0xffff0000, v29
	v_lshlrev_b32_e32 v10, 16, v106
	v_and_b32_e32 v12, 0xffff0000, v106
	v_mov_b32_e32 v28, v3
	v_or_b32_e32 v18, 0x300, v32
	v_mov_b32_e32 v19, v33
	v_lshl_add_u64 v[18:19], v[4:5], 0, v[18:19]
	s_waitcnt vmcnt(0)
	v_lshlrev_b32_e32 v11, 16, v8
	v_and_b32_e32 v13, 0xffff0000, v8
	v_lshlrev_b32_e32 v15, 16, v9
	v_and_b32_e32 v17, 0xffff0000, v9
	v_mul_f32_e32 v2, 0xbfb8aa3b, v11
	v_mul_f32_e32 v8, 0xbfb8aa3b, v13
	v_mul_f32_e32 v9, 0xbfb8aa3b, v15
	v_mul_f32_e32 v23, 0xbfb8aa3b, v17
	v_exp_f32_e32 v2, v2
	v_exp_f32_e32 v8, v8
	v_exp_f32_e32 v9, v9
	v_exp_f32_e32 v23, v23
	v_add_f32_e32 v2, 1.0, v2
	v_add_f32_e32 v8, 1.0, v8
	v_add_f32_e32 v9, 1.0, v9
	v_add_f32_e32 v29, 1.0, v23
	v_rcp_f32_e32 v23, v2
	v_rcp_f32_e32 v25, v8
	v_rcp_f32_e32 v27, v9
	v_rcp_f32_e32 v29, v29
	v_pk_mul_f32 v[8:9], v[22:23], v[10:11]
	v_pk_mul_f32 v[10:11], v[24:25], v[12:13]
	v_pk_mul_f32 v[12:13], v[26:27], v[14:15]
	v_pk_mul_f32 v[14:15], v[28:29], v[16:17]
	v_mul_f32_e32 v2, v8, v9
	v_mul_f32_e32 v8, v10, v11
	v_mul_f32_e32 v9, v12, v13
	v_mul_f32_e32 v10, v14, v15
	v_cvt_pk_bf16_f32 v8, v2, v8
	v_cvt_pk_bf16_f32 v9, v9, v10
	global_store_dwordx2 v[0:1], v[8:9], off offset:1760
	global_load_dwordx2 v[8:9], v[18:19], off
	v_lshlrev_b32_e32 v10, 16, v77
	v_and_b32_e32 v12, 0xffff0000, v77
	v_lshlrev_b32_e32 v14, 16, v76
	v_and_b32_e32 v16, 0xffff0000, v76
	v_or_b32_e32 v18, 0x320, v32
	v_mov_b32_e32 v19, v33
	v_lshl_add_u64 v[18:19], v[4:5], 0, v[18:19]
	s_waitcnt vmcnt(0)
	v_lshlrev_b32_e32 v11, 16, v8
	v_and_b32_e32 v13, 0xffff0000, v8
	v_lshlrev_b32_e32 v15, 16, v9
	v_and_b32_e32 v17, 0xffff0000, v9
	v_mul_f32_e32 v2, 0xbfb8aa3b, v11
	v_mul_f32_e32 v8, 0xbfb8aa3b, v13
	v_mul_f32_e32 v9, 0xbfb8aa3b, v15
	v_mul_f32_e32 v23, 0xbfb8aa3b, v17
	v_exp_f32_e32 v2, v2
	v_exp_f32_e32 v8, v8
	v_exp_f32_e32 v9, v9
	v_exp_f32_e32 v23, v23
	v_add_f32_e32 v2, 1.0, v2
	v_add_f32_e32 v8, 1.0, v8
	v_add_f32_e32 v9, 1.0, v9
	v_add_f32_e32 v29, 1.0, v23
	v_rcp_f32_e32 v23, v2
	v_rcp_f32_e32 v25, v8
	v_rcp_f32_e32 v27, v9
	v_rcp_f32_e32 v29, v29
	v_pk_mul_f32 v[8:9], v[22:23], v[10:11]
	v_pk_mul_f32 v[10:11], v[24:25], v[12:13]
	v_pk_mul_f32 v[12:13], v[26:27], v[14:15]
	v_pk_mul_f32 v[14:15], v[28:29], v[16:17]
	v_mul_f32_e32 v2, v8, v9
	v_mul_f32_e32 v8, v10, v11
	v_mul_f32_e32 v9, v12, v13
	v_mul_f32_e32 v10, v14, v15
	v_cvt_pk_bf16_f32 v8, v2, v8
	v_cvt_pk_bf16_f32 v9, v9, v10
	global_store_dwordx2 v[0:1], v[8:9], off offset:1792
	global_load_dwordx2 v[8:9], v[18:19], off
	v_lshlrev_b32_e32 v10, 16, v75
	v_and_b32_e32 v12, 0xffff0000, v75
	v_lshlrev_b32_e32 v14, 16, v74
	v_and_b32_e32 v16, 0xffff0000, v74
	v_or_b32_e32 v18, 0x340, v32
	v_mov_b32_e32 v19, v33
	v_lshl_add_u64 v[18:19], v[4:5], 0, v[18:19]
	s_waitcnt vmcnt(0)
	v_lshlrev_b32_e32 v11, 16, v8
	v_and_b32_e32 v13, 0xffff0000, v8
	v_lshlrev_b32_e32 v15, 16, v9
	v_and_b32_e32 v17, 0xffff0000, v9
	v_mul_f32_e32 v2, 0xbfb8aa3b, v11
	v_mul_f32_e32 v8, 0xbfb8aa3b, v13
	v_mul_f32_e32 v9, 0xbfb8aa3b, v15
	v_mul_f32_e32 v23, 0xbfb8aa3b, v17
	v_exp_f32_e32 v2, v2
	v_exp_f32_e32 v8, v8
	v_exp_f32_e32 v9, v9
	v_exp_f32_e32 v23, v23
	v_add_f32_e32 v2, 1.0, v2
	v_add_f32_e32 v8, 1.0, v8
	v_add_f32_e32 v9, 1.0, v9
	v_add_f32_e32 v29, 1.0, v23
	v_rcp_f32_e32 v23, v2
	v_rcp_f32_e32 v25, v8
	v_rcp_f32_e32 v27, v9
	v_rcp_f32_e32 v29, v29
	v_pk_mul_f32 v[8:9], v[22:23], v[10:11]
	v_pk_mul_f32 v[10:11], v[24:25], v[12:13]
	v_pk_mul_f32 v[12:13], v[26:27], v[14:15]
	v_pk_mul_f32 v[14:15], v[28:29], v[16:17]
	v_mul_f32_e32 v2, v8, v9
	v_mul_f32_e32 v8, v10, v11
	v_mul_f32_e32 v9, v12, v13
	v_mul_f32_e32 v10, v14, v15
	v_cvt_pk_bf16_f32 v8, v2, v8
	v_cvt_pk_bf16_f32 v9, v9, v10
	global_store_dwordx2 v[0:1], v[8:9], off offset:1824
	global_load_dwordx2 v[8:9], v[18:19], off
	v_lshlrev_b32_e32 v10, 16, v73
	v_and_b32_e32 v12, 0xffff0000, v73
	v_lshlrev_b32_e32 v14, 16, v72
	v_and_b32_e32 v16, 0xffff0000, v72
	v_or_b32_e32 v18, 0x360, v32
	v_mov_b32_e32 v19, v33
	v_lshl_add_u64 v[18:19], v[4:5], 0, v[18:19]
	s_waitcnt vmcnt(0)
	v_lshlrev_b32_e32 v11, 16, v8
	v_and_b32_e32 v13, 0xffff0000, v8
	v_lshlrev_b32_e32 v15, 16, v9
	v_and_b32_e32 v17, 0xffff0000, v9
	v_mul_f32_e32 v2, 0xbfb8aa3b, v11
	v_mul_f32_e32 v8, 0xbfb8aa3b, v13
	v_mul_f32_e32 v9, 0xbfb8aa3b, v15
	v_mul_f32_e32 v23, 0xbfb8aa3b, v17
	v_exp_f32_e32 v2, v2
	v_exp_f32_e32 v8, v8
	v_exp_f32_e32 v9, v9
	v_exp_f32_e32 v23, v23
	v_add_f32_e32 v2, 1.0, v2
	v_add_f32_e32 v8, 1.0, v8
	v_add_f32_e32 v9, 1.0, v9
	v_add_f32_e32 v29, 1.0, v23
	v_rcp_f32_e32 v23, v2
	v_rcp_f32_e32 v25, v8
	v_rcp_f32_e32 v27, v9
	v_rcp_f32_e32 v29, v29
	v_pk_mul_f32 v[8:9], v[22:23], v[10:11]
	v_pk_mul_f32 v[10:11], v[24:25], v[12:13]
	v_pk_mul_f32 v[12:13], v[26:27], v[14:15]
	v_pk_mul_f32 v[14:15], v[28:29], v[16:17]
	v_mul_f32_e32 v2, v8, v9
	v_mul_f32_e32 v8, v10, v11
	v_mul_f32_e32 v9, v12, v13
	v_mul_f32_e32 v10, v14, v15
	v_cvt_pk_bf16_f32 v8, v2, v8
	v_cvt_pk_bf16_f32 v9, v9, v10
	global_store_dwordx2 v[0:1], v[8:9], off offset:1856
	global_load_dwordx2 v[8:9], v[18:19], off
	v_lshlrev_b32_e32 v10, 16, v71
	v_and_b32_e32 v12, 0xffff0000, v71
	v_lshlrev_b32_e32 v14, 16, v69
	v_and_b32_e32 v16, 0xffff0000, v69
	v_or_b32_e32 v18, 0x380, v32
	v_mov_b32_e32 v19, v33
	v_lshl_add_u64 v[18:19], v[4:5], 0, v[18:19]
	s_waitcnt vmcnt(0)
	v_lshlrev_b32_e32 v11, 16, v8
	v_and_b32_e32 v13, 0xffff0000, v8
	v_lshlrev_b32_e32 v15, 16, v9
	v_and_b32_e32 v17, 0xffff0000, v9
	v_mul_f32_e32 v2, 0xbfb8aa3b, v11
	v_mul_f32_e32 v8, 0xbfb8aa3b, v13
	v_mul_f32_e32 v9, 0xbfb8aa3b, v15
	v_mul_f32_e32 v23, 0xbfb8aa3b, v17
	v_exp_f32_e32 v2, v2
	v_exp_f32_e32 v8, v8
	v_exp_f32_e32 v9, v9
	v_exp_f32_e32 v23, v23
	v_add_f32_e32 v2, 1.0, v2
	v_add_f32_e32 v8, 1.0, v8
	v_add_f32_e32 v9, 1.0, v9
	v_add_f32_e32 v29, 1.0, v23
	v_rcp_f32_e32 v23, v2
	v_rcp_f32_e32 v25, v8
	v_rcp_f32_e32 v27, v9
	v_rcp_f32_e32 v29, v29
	v_pk_mul_f32 v[8:9], v[22:23], v[10:11]
	v_pk_mul_f32 v[10:11], v[24:25], v[12:13]
	v_pk_mul_f32 v[12:13], v[26:27], v[14:15]
	v_pk_mul_f32 v[14:15], v[28:29], v[16:17]
	v_mul_f32_e32 v2, v8, v9
	v_mul_f32_e32 v8, v10, v11
	v_mul_f32_e32 v9, v12, v13
	v_mul_f32_e32 v10, v14, v15
	v_cvt_pk_bf16_f32 v8, v2, v8
	v_cvt_pk_bf16_f32 v9, v9, v10
	global_store_dwordx2 v[0:1], v[8:9], off offset:1888
	global_load_dwordx2 v[8:9], v[18:19], off
	v_lshlrev_b32_e32 v10, 16, v70
	v_and_b32_e32 v12, 0xffff0000, v70
	v_lshlrev_b32_e32 v14, 16, v68
	v_and_b32_e32 v16, 0xffff0000, v68
	v_or_b32_e32 v18, 0x3a0, v32
	v_mov_b32_e32 v19, v33
	v_lshl_add_u64 v[18:19], v[4:5], 0, v[18:19]
	s_waitcnt vmcnt(0)
	v_lshlrev_b32_e32 v11, 16, v8
	v_and_b32_e32 v13, 0xffff0000, v8
	v_lshlrev_b32_e32 v15, 16, v9
	v_and_b32_e32 v17, 0xffff0000, v9
	v_mul_f32_e32 v2, 0xbfb8aa3b, v11
	v_mul_f32_e32 v8, 0xbfb8aa3b, v13
	v_mul_f32_e32 v9, 0xbfb8aa3b, v15
	v_mul_f32_e32 v23, 0xbfb8aa3b, v17
	v_exp_f32_e32 v2, v2
	v_exp_f32_e32 v8, v8
	v_exp_f32_e32 v9, v9
	v_exp_f32_e32 v23, v23
	v_add_f32_e32 v2, 1.0, v2
	v_add_f32_e32 v8, 1.0, v8
	v_add_f32_e32 v9, 1.0, v9
	v_add_f32_e32 v29, 1.0, v23
	v_rcp_f32_e32 v23, v2
	v_rcp_f32_e32 v25, v8
	v_rcp_f32_e32 v27, v9
	v_rcp_f32_e32 v29, v29
	v_pk_mul_f32 v[8:9], v[22:23], v[10:11]
	v_pk_mul_f32 v[10:11], v[24:25], v[12:13]
	v_pk_mul_f32 v[12:13], v[26:27], v[14:15]
	v_pk_mul_f32 v[14:15], v[28:29], v[16:17]
	v_mul_f32_e32 v2, v8, v9
	v_mul_f32_e32 v8, v10, v11
	v_mul_f32_e32 v9, v12, v13
	v_mul_f32_e32 v10, v14, v15
	v_cvt_pk_bf16_f32 v8, v2, v8
	v_cvt_pk_bf16_f32 v9, v9, v10
	global_store_dwordx2 v[0:1], v[8:9], off offset:1920
	global_load_dwordx2 v[8:9], v[18:19], off
	v_lshlrev_b32_e32 v10, 16, v66
	v_and_b32_e32 v12, 0xffff0000, v66
	v_lshlrev_b32_e32 v14, 16, v64
	v_and_b32_e32 v16, 0xffff0000, v64
	v_or_b32_e32 v18, 0x3c0, v32
	v_mov_b32_e32 v19, v33
	v_lshl_add_u64 v[18:19], v[4:5], 0, v[18:19]
	v_or_b32_e32 v32, 0x3e0, v32
	v_lshl_add_u64 v[4:5], v[4:5], 0, v[32:33]
	s_waitcnt vmcnt(0)
	v_lshlrev_b32_e32 v11, 16, v8
	v_and_b32_e32 v13, 0xffff0000, v8
	v_lshlrev_b32_e32 v15, 16, v9
	v_and_b32_e32 v17, 0xffff0000, v9
	v_mul_f32_e32 v2, 0xbfb8aa3b, v11
	v_mul_f32_e32 v8, 0xbfb8aa3b, v13
	v_mul_f32_e32 v9, 0xbfb8aa3b, v15
	v_mul_f32_e32 v23, 0xbfb8aa3b, v17
	v_exp_f32_e32 v2, v2
	v_exp_f32_e32 v8, v8
	v_exp_f32_e32 v9, v9
	v_exp_f32_e32 v23, v23
	v_add_f32_e32 v2, 1.0, v2
	v_add_f32_e32 v8, 1.0, v8
	v_add_f32_e32 v9, 1.0, v9
	v_add_f32_e32 v29, 1.0, v23
	v_rcp_f32_e32 v23, v2
	v_rcp_f32_e32 v25, v8
	v_rcp_f32_e32 v27, v9
	v_rcp_f32_e32 v29, v29
	v_pk_mul_f32 v[8:9], v[22:23], v[10:11]
	v_pk_mul_f32 v[10:11], v[24:25], v[12:13]
	v_pk_mul_f32 v[12:13], v[26:27], v[14:15]
	v_pk_mul_f32 v[14:15], v[28:29], v[16:17]
	v_mul_f32_e32 v2, v8, v9
	v_mul_f32_e32 v8, v10, v11
	v_mul_f32_e32 v9, v12, v13
	v_mul_f32_e32 v10, v14, v15
	v_cvt_pk_bf16_f32 v8, v2, v8
	v_cvt_pk_bf16_f32 v9, v9, v10
	global_store_dwordx2 v[0:1], v[8:9], off offset:1952
	global_load_dwordx2 v[8:9], v[18:19], off
	v_lshlrev_b32_e32 v10, 16, v21
	v_and_b32_e32 v12, 0xffff0000, v21
	v_lshlrev_b32_e32 v14, 16, v20
	v_and_b32_e32 v16, 0xffff0000, v20
	v_mov_b32_e32 v18, v3
	v_mov_b32_e32 v20, v3
	s_waitcnt vmcnt(0)
	v_lshlrev_b32_e32 v11, 16, v8
	v_and_b32_e32 v13, 0xffff0000, v8
	v_lshlrev_b32_e32 v15, 16, v9
	v_and_b32_e32 v17, 0xffff0000, v9
	v_mul_f32_e32 v2, 0xbfb8aa3b, v11
	v_mul_f32_e32 v8, 0xbfb8aa3b, v13
	v_mul_f32_e32 v9, 0xbfb8aa3b, v15
	v_mul_f32_e32 v19, 0xbfb8aa3b, v17
	v_exp_f32_e32 v2, v2
	v_exp_f32_e32 v8, v8
	v_exp_f32_e32 v9, v9
	v_exp_f32_e32 v19, v19
	v_add_f32_e32 v2, 1.0, v2
	v_add_f32_e32 v8, 1.0, v8
	v_add_f32_e32 v9, 1.0, v9
	v_add_f32_e32 v25, 1.0, v19
	v_rcp_f32_e32 v19, v2
	v_rcp_f32_e32 v21, v8
	v_rcp_f32_e32 v23, v9
	v_rcp_f32_e32 v25, v25
	v_pk_mul_f32 v[8:9], v[18:19], v[10:11]
	v_pk_mul_f32 v[10:11], v[20:21], v[12:13]
	v_pk_mul_f32 v[12:13], v[22:23], v[14:15]
	v_pk_mul_f32 v[14:15], v[24:25], v[16:17]
	v_mul_f32_e32 v2, v8, v9
	v_mul_f32_e32 v8, v10, v11
	v_mul_f32_e32 v9, v12, v13
	v_mul_f32_e32 v10, v14, v15
	v_cvt_pk_bf16_f32 v8, v2, v8
	v_cvt_pk_bf16_f32 v9, v9, v10
	global_store_dwordx2 v[0:1], v[8:9], off offset:1984
	global_load_dwordx2 v[4:5], v[4:5], off
	v_mov_b32_e32 v12, v3
	v_mov_b32_e32 v14, v3
	v_mov_b32_e32 v16, v3
	v_lshlrev_b32_e32 v2, 16, v7
	v_and_b32_e32 v8, 0xffff0000, v7
	v_lshlrev_b32_e32 v10, 16, v6
	v_and_b32_e32 v6, 0xffff0000, v6
	s_waitcnt vmcnt(0)
	v_lshlrev_b32_e32 v3, 16, v4
	v_and_b32_e32 v9, 0xffff0000, v4
	v_lshlrev_b32_e32 v11, 16, v5
	v_and_b32_e32 v7, 0xffff0000, v5
	v_mul_f32_e32 v4, 0xbfb8aa3b, v3
	v_mul_f32_e32 v5, 0xbfb8aa3b, v9
	v_mul_f32_e32 v13, 0xbfb8aa3b, v11
	v_mul_f32_e32 v15, 0xbfb8aa3b, v7
	v_exp_f32_e32 v4, v4
	v_exp_f32_e32 v5, v5
	v_exp_f32_e32 v13, v13
	v_exp_f32_e32 v15, v15
	v_add_f32_e32 v4, 1.0, v4
	v_add_f32_e32 v5, 1.0, v5
	v_add_f32_e32 v17, 1.0, v13
	v_add_f32_e32 v19, 1.0, v15
	v_rcp_f32_e32 v13, v4
	v_rcp_f32_e32 v15, v5
	v_rcp_f32_e32 v17, v17
	v_rcp_f32_e32 v19, v19
	v_pk_mul_f32 v[2:3], v[12:13], v[2:3]
	v_pk_mul_f32 v[4:5], v[14:15], v[8:9]
	v_pk_mul_f32 v[8:9], v[16:17], v[10:11]
	v_pk_mul_f32 v[6:7], v[18:19], v[6:7]
	v_mul_f32_e32 v2, v2, v3
	v_mul_f32_e32 v3, v4, v5
	v_mul_f32_e32 v4, v8, v9
	v_mul_f32_e32 v5, v6, v7
	v_cvt_pk_bf16_f32 v2, v2, v3
	v_cvt_pk_bf16_f32 v3, v4, v5
	global_store_dwordx2 v[0:1], v[2:3], off offset:2016
	s_cbranch_scc1 .LBB0_900

.LBB0_1054:
	v_mbcnt_lo_u32_b32 v1, -1, 0
	v_mbcnt_hi_u32_b32 v1, -1, v1
	s_add_i32 s47, s47, s34
	v_ashrrev_i32_e32 v3, 1, v1
	v_and_or_b32 v2, v1, 15, s47
	v_and_b32_e32 v3, -8, v3
	s_lshl_b32 s54, s10, 8
	v_add_u32_e32 v132, s35, v3
	v_ashrrev_i32_e32 v3, 31, v2
	s_ashr_i32 s55, s54, 31
	v_lshlrev_b64 v[134:135], 10, v[2:3]
	v_lshl_add_u64 v[140:141], v[134:135], 0, s[54:55]
	v_ashrrev_i32_e32 v133, 31, v132
	v_lshl_add_u64 v[134:135], v[140:141], 0, v[132:133]
	v_lshlrev_b64 v[142:143], 1, v[134:135]
	v_lshl_add_u64 v[134:135], s[20:21], 0, v[142:143]
	global_load_dwordx4 v[136:139], v[134:135], off
	v_add_u32_e32 v134, 0x80, v132
	v_ashrrev_i32_e32 v135, 31, v134
	v_lshl_add_u64 v[140:141], v[140:141], 0, v[134:135]
	v_lshl_add_u64 v[142:143], s[72:73], 0, v[142:143]
	v_lshlrev_b64 v[140:141], 1, v[140:141]
	v_lshl_add_u64 v[144:145], s[20:21], 0, v[140:141]
	v_cmp_gt_u32_e32 vcc, 16, v1
	v_lshl_add_u64 v[140:141], s[72:73], 0, v[140:141]
	s_lshl_b32 s6, s10, 2
	s_ashr_i32 s7, s6, 31
	s_waitcnt vmcnt(0)
	v_lshlrev_b32_e32 v146, 16, v136
	v_and_b32_e32 v147, 0xffff0000, v136
	v_lshlrev_b32_e32 v136, 16, v137
	v_and_b32_e32 v137, 0xffff0000, v137
	v_lshlrev_b32_e32 v148, 16, v138
	v_and_b32_e32 v149, 0xffff0000, v138
	v_lshlrev_b32_e32 v138, 16, v139
	v_and_b32_e32 v139, 0xffff0000, v139
	v_pk_fma_f32 v[130:131], v[136:137], s[44:45], v[130:131] op_sel_hi:[1,0,1]
	v_pk_fma_f32 v[128:129], v[146:147], s[44:45], v[128:129] op_sel_hi:[1,0,1]
	v_pk_fma_f32 v[136:137], v[138:139], s[44:45], v[126:127] op_sel_hi:[1,0,1]
	v_pk_fma_f32 v[138:139], v[148:149], s[44:45], v[124:125] op_sel_hi:[1,0,1]
	v_cvt_pk_bf16_f32 v124, v128, v129
	v_cvt_pk_bf16_f32 v125, v130, v131
	v_add_f32_e32 v1, v128, v129
	v_cvt_pk_bf16_f32 v126, v138, v139
	v_cvt_pk_bf16_f32 v127, v136, v137
	global_store_dwordx4 v[142:143], v[124:127], off
	global_load_dwordx4 v[124:127], v[144:145], off
	v_add_f32_e32 v142, v130, v131
	v_add_f32_e32 v143, v138, v139
	v_add_f32_e32 v144, v136, v137
	v_mul_f32_e32 v129, v129, v129
	v_mul_f32_e32 v131, v131, v131
	v_mul_f32_e32 v139, v139, v139
	v_mul_f32_e32 v137, v137, v137
	v_fmac_f32_e32 v129, v128, v128
	v_fmac_f32_e32 v131, v130, v130
	v_fmac_f32_e32 v139, v138, v138
	v_fmac_f32_e32 v137, v136, v136
	v_add_f32_e32 v128, v129, v131
	v_add_f32_e32 v129, v139, v137
	v_add_f32_e32 v136, v128, v129
	v_add_f32_e32 v1, v1, v142
	v_add_f32_e32 v142, v143, v144
	v_add_f32_e32 v1, v1, v142
	v_add_f32_e32 v1, 0, v1
	s_waitcnt vmcnt(0)
	v_lshlrev_b32_e32 v128, 16, v124
	v_and_b32_e32 v129, 0xffff0000, v124
	v_lshlrev_b32_e32 v124, 16, v125
	v_and_b32_e32 v125, 0xffff0000, v125
	v_lshlrev_b32_e32 v130, 16, v126
	v_and_b32_e32 v131, 0xffff0000, v126
	v_lshlrev_b32_e32 v126, 16, v127
	v_and_b32_e32 v127, 0xffff0000, v127
	v_pk_fma_f32 v[122:123], v[124:125], s[44:45], v[122:123] op_sel_hi:[1,0,1]
	v_pk_fma_f32 v[120:121], v[128:129], s[44:45], v[120:121] op_sel_hi:[1,0,1]
	v_pk_fma_f32 v[124:125], v[126:127], s[44:45], v[118:119] op_sel_hi:[1,0,1]
	v_pk_fma_f32 v[126:127], v[130:131], s[44:45], v[116:117] op_sel_hi:[1,0,1]
	v_cvt_pk_bf16_f32 v116, v120, v121
	v_cvt_pk_bf16_f32 v117, v122, v123
	v_add_f32_e32 v119, v120, v121
	v_cvt_pk_bf16_f32 v118, v126, v127
	v_add_f32_e32 v128, v122, v123
	v_add_f32_e32 v129, v126, v127
	v_add_f32_e32 v130, v124, v125
	v_mul_f32_e32 v121, v121, v121
	v_mul_f32_e32 v123, v123, v123
	v_mul_f32_e32 v127, v127, v127
	v_mul_f32_e32 v131, v125, v125
	v_add_f32_e32 v119, v119, v128
	v_add_f32_e32 v128, v129, v130
	v_fmac_f32_e32 v121, v120, v120
	v_fmac_f32_e32 v123, v122, v122
	v_fmac_f32_e32 v127, v126, v126
	v_fmac_f32_e32 v131, v124, v124
	v_add_f32_e32 v119, v119, v128
	v_add_f32_e32 v120, v121, v123
	v_add_f32_e32 v121, v127, v131
	v_add_f32_e32 v1, v1, v119
	v_add_f32_e32 v119, v120, v121
	v_add_f32_e32 v121, v136, v119
	v_cvt_pk_bf16_f32 v119, v124, v125
	global_store_dwordx4 v[140:141], v[116:119], off
	s_waitcnt lgkmcnt(1)
	s_nop 0
	v_mov_b32_e32 v120, v1
	s_nop 1
	v_permlane16_swap_b32_e32 v1, v120
	v_add_f32_e32 v116, v1, v120
	s_waitcnt lgkmcnt(0)
	v_mov_b32_e32 v122, v121
	s_nop 1
	v_permlane16_swap_b32_e32 v121, v122
	v_add_f32_e32 v117, v121, v122
	v_mov_b32_e32 v118, v116
	v_mov_b32_e32 v119, v117
	s_nop 0
	v_permlane32_swap_b32_e32 v116, v118
	v_permlane32_swap_b32_e32 v117, v119
	s_and_saveexec_b64 s[56:57], vcc
	s_cbranch_execz .LBB0_1056
	v_pk_add_f32 v[116:117], v[116:117], v[118:119]
	v_lshlrev_b64 v[118:119], 7, v[2:3]
	v_lshl_add_u64 v[118:119], s[36:37], 0, v[118:119]
	v_lshl_add_u64 v[118:119], s[6:7], 3, v[118:119]
	s_lshl_b32 s10, s31, 3
	v_lshl_add_u64 v[118:119], v[118:119], 0, s[10:11]
	global_store_dwordx2 v[118:119], v[116:117], off
.LBB0_1056:
	s_or_b64 exec, exec, s[56:57]
	v_or_b32_e32 v116, 16, v2
	v_ashrrev_i32_e32 v117, 31, v116
	v_lshlrev_b64 v[118:119], 10, v[116:117]
	v_lshl_add_u64 v[122:123], v[118:119], 0, s[54:55]
	v_lshl_add_u64 v[118:119], v[122:123], 0, v[132:133]
	v_lshlrev_b64 v[124:125], 1, v[118:119]
	v_lshl_add_u64 v[118:119], s[20:21], 0, v[124:125]
	global_load_dwordx4 v[118:121], v[118:119], off
	v_lshl_add_u64 v[122:123], v[122:123], 0, v[134:135]
	v_lshlrev_b64 v[122:123], 1, v[122:123]
	v_lshl_add_u64 v[124:125], s[72:73], 0, v[124:125]
	v_lshl_add_u64 v[126:127], s[20:21], 0, v[122:123]
	v_lshl_add_u64 v[122:123], s[72:73], 0, v[122:123]
	s_waitcnt vmcnt(0)
	v_lshlrev_b32_e32 v128, 16, v118
	v_and_b32_e32 v129, 0xffff0000, v118
	v_lshlrev_b32_e32 v118, 16, v119
	v_and_b32_e32 v119, 0xffff0000, v119
	v_lshlrev_b32_e32 v130, 16, v120
	v_and_b32_e32 v131, 0xffff0000, v120
	v_lshlrev_b32_e32 v120, 16, v121
	v_and_b32_e32 v121, 0xffff0000, v121
	v_pk_fma_f32 v[114:115], v[118:119], s[44:45], v[114:115] op_sel_hi:[1,0,1]
	v_pk_fma_f32 v[112:113], v[128:129], s[44:45], v[112:113] op_sel_hi:[1,0,1]
	v_pk_fma_f32 v[118:119], v[120:121], s[44:45], v[110:111] op_sel_hi:[1,0,1]
	v_pk_fma_f32 v[120:121], v[130:131], s[44:45], v[108:109] op_sel_hi:[1,0,1]
	v_cvt_pk_bf16_f32 v108, v112, v113
	v_cvt_pk_bf16_f32 v109, v114, v115
	v_add_f32_e32 v1, v112, v113
	v_cvt_pk_bf16_f32 v110, v120, v121
	v_cvt_pk_bf16_f32 v111, v118, v119
	global_store_dwordx4 v[124:125], v[108:111], off
	global_load_dwordx4 v[108:111], v[126:127], off
	v_add_f32_e32 v3, v114, v115
	v_add_f32_e32 v124, v120, v121
	v_add_f32_e32 v125, v118, v119
	v_mul_f32_e32 v113, v113, v113
	v_mul_f32_e32 v115, v115, v115
	v_mul_f32_e32 v121, v121, v121
	v_mul_f32_e32 v119, v119, v119
	v_add_f32_e32 v1, v1, v3
	v_add_f32_e32 v3, v124, v125
	v_fmac_f32_e32 v113, v112, v112
	v_fmac_f32_e32 v115, v114, v114
	v_fmac_f32_e32 v121, v120, v120
	v_fmac_f32_e32 v119, v118, v118
	v_add_f32_e32 v1, v1, v3
	v_add_f32_e32 v3, v113, v115
	v_add_f32_e32 v112, v121, v119
	v_add_f32_e32 v3, v3, v112
	v_add_f32_e32 v1, 0, v1
	s_waitcnt vmcnt(0)
	v_lshlrev_b32_e32 v112, 16, v108
	v_and_b32_e32 v113, 0xffff0000, v108
	v_lshlrev_b32_e32 v108, 16, v109
	v_and_b32_e32 v109, 0xffff0000, v109
	v_lshlrev_b32_e32 v114, 16, v110
	v_and_b32_e32 v115, 0xffff0000, v110
	v_lshlrev_b32_e32 v110, 16, v111
	v_and_b32_e32 v111, 0xffff0000, v111
	v_pk_fma_f32 v[106:107], v[108:109], s[44:45], v[106:107] op_sel_hi:[1,0,1]
	v_pk_fma_f32 v[104:105], v[112:113], s[44:45], v[104:105] op_sel_hi:[1,0,1]
	v_pk_fma_f32 v[108:109], v[110:111], s[44:45], v[102:103] op_sel_hi:[1,0,1]
	v_pk_fma_f32 v[110:111], v[114:115], s[44:45], v[100:101] op_sel_hi:[1,0,1]
	v_cvt_pk_bf16_f32 v100, v104, v105
	v_cvt_pk_bf16_f32 v101, v106, v107
	v_add_f32_e32 v103, v104, v105
	v_cvt_pk_bf16_f32 v102, v110, v111
	v_add_f32_e32 v112, v106, v107
	v_add_f32_e32 v113, v110, v111
	v_add_f32_e32 v114, v108, v109
	v_mul_f32_e32 v105, v105, v105
	v_mul_f32_e32 v107, v107, v107
	v_mul_f32_e32 v111, v111, v111
	v_mul_f32_e32 v115, v109, v109
	v_add_f32_e32 v103, v103, v112
	v_add_f32_e32 v112, v113, v114
	v_fmac_f32_e32 v105, v104, v104
	v_fmac_f32_e32 v107, v106, v106
	v_fmac_f32_e32 v111, v110, v110
	v_fmac_f32_e32 v115, v108, v108
	v_add_f32_e32 v103, v103, v112
	v_add_f32_e32 v104, v105, v107
	v_add_f32_e32 v105, v111, v115
	v_add_f32_e32 v1, v1, v103
	v_add_f32_e32 v103, v104, v105
	v_add_f32_e32 v3, v3, v103
	v_cvt_pk_bf16_f32 v103, v108, v109
	global_store_dwordx4 v[122:123], v[100:103], off
	s_waitcnt lgkmcnt(1)
	s_nop 0
	v_mov_b32_e32 v104, v1
	s_nop 1
	v_permlane16_swap_b32_e32 v1, v104
	v_add_f32_e32 v100, v1, v104
	s_waitcnt lgkmcnt(0)
	v_mov_b32_e32 v105, v3
	s_nop 1
	v_permlane16_swap_b32_e32 v3, v105
	v_add_f32_e32 v101, v3, v105
	v_mov_b32_e32 v102, v100
	v_mov_b32_e32 v103, v101
	s_nop 0
	v_permlane32_swap_b32_e32 v100, v102
	v_permlane32_swap_b32_e32 v101, v103
	s_and_saveexec_b64 s[56:57], vcc
	s_cbranch_execz .LBB0_1058
	v_pk_add_f32 v[100:101], v[100:101], v[102:103]
	v_lshlrev_b64 v[102:103], 7, v[116:117]
	v_lshl_add_u64 v[102:103], s[36:37], 0, v[102:103]
	v_lshl_add_u64 v[102:103], s[6:7], 3, v[102:103]
	s_lshl_b32 s10, s31, 3
	v_lshl_add_u64 v[102:103], v[102:103], 0, s[10:11]
	global_store_dwordx2 v[102:103], v[100:101], off
.LBB0_1058:
	s_or_b64 exec, exec, s[56:57]
	v_or_b32_e32 v100, 32, v2
	v_ashrrev_i32_e32 v101, 31, v100
	v_lshlrev_b64 v[102:103], 10, v[100:101]
	v_lshl_add_u64 v[106:107], v[102:103], 0, s[54:55]
	v_lshl_add_u64 v[102:103], v[106:107], 0, v[132:133]
	v_lshlrev_b64 v[108:109], 1, v[102:103]
	v_lshl_add_u64 v[102:103], s[20:21], 0, v[108:109]
	global_load_dwordx4 v[102:105], v[102:103], off
	v_lshl_add_u64 v[106:107], v[106:107], 0, v[134:135]
	v_lshlrev_b64 v[106:107], 1, v[106:107]
	v_lshl_add_u64 v[108:109], s[72:73], 0, v[108:109]
	v_lshl_add_u64 v[110:111], s[20:21], 0, v[106:107]
	v_lshl_add_u64 v[106:107], s[72:73], 0, v[106:107]
	s_waitcnt vmcnt(0)
	v_lshlrev_b32_e32 v112, 16, v102
	v_and_b32_e32 v113, 0xffff0000, v102
	v_lshlrev_b32_e32 v102, 16, v103
	v_and_b32_e32 v103, 0xffff0000, v103
	v_lshlrev_b32_e32 v114, 16, v104
	v_and_b32_e32 v115, 0xffff0000, v104
	v_lshlrev_b32_e32 v104, 16, v105
	v_and_b32_e32 v105, 0xffff0000, v105
	v_pk_fma_f32 v[98:99], v[102:103], s[44:45], v[98:99] op_sel_hi:[1,0,1]
	v_pk_fma_f32 v[96:97], v[112:113], s[44:45], v[96:97] op_sel_hi:[1,0,1]
	v_pk_fma_f32 v[102:103], v[104:105], s[44:45], v[94:95] op_sel_hi:[1,0,1]
	v_pk_fma_f32 v[104:105], v[114:115], s[44:45], v[92:93] op_sel_hi:[1,0,1]
	v_cvt_pk_bf16_f32 v92, v96, v97
	v_cvt_pk_bf16_f32 v93, v98, v99
	v_add_f32_e32 v1, v96, v97
	v_cvt_pk_bf16_f32 v94, v104, v105
	v_cvt_pk_bf16_f32 v95, v102, v103
	global_store_dwordx4 v[108:109], v[92:95], off
	global_load_dwordx4 v[92:95], v[110:111], off
	v_add_f32_e32 v3, v98, v99
	v_add_f32_e32 v108, v104, v105
	v_add_f32_e32 v109, v102, v103
	v_mul_f32_e32 v97, v97, v97
	v_mul_f32_e32 v99, v99, v99
	v_mul_f32_e32 v105, v105, v105
	v_mul_f32_e32 v103, v103, v103
	v_add_f32_e32 v1, v1, v3
	v_add_f32_e32 v3, v108, v109
	v_fmac_f32_e32 v97, v96, v96
	v_fmac_f32_e32 v99, v98, v98
	v_fmac_f32_e32 v105, v104, v104
	v_fmac_f32_e32 v103, v102, v102
	v_add_f32_e32 v1, v1, v3
	v_add_f32_e32 v3, v97, v99
	v_add_f32_e32 v96, v105, v103
	v_add_f32_e32 v3, v3, v96
	v_add_f32_e32 v1, 0, v1
	s_waitcnt vmcnt(0)
	v_lshlrev_b32_e32 v96, 16, v92
	v_and_b32_e32 v97, 0xffff0000, v92
	v_lshlrev_b32_e32 v92, 16, v93
	v_and_b32_e32 v93, 0xffff0000, v93
	v_lshlrev_b32_e32 v98, 16, v94
	v_and_b32_e32 v99, 0xffff0000, v94
	v_lshlrev_b32_e32 v94, 16, v95
	v_and_b32_e32 v95, 0xffff0000, v95
	v_pk_fma_f32 v[90:91], v[92:93], s[44:45], v[90:91] op_sel_hi:[1,0,1]
	v_pk_fma_f32 v[88:89], v[96:97], s[44:45], v[88:89] op_sel_hi:[1,0,1]
	v_pk_fma_f32 v[92:93], v[94:95], s[44:45], v[86:87] op_sel_hi:[1,0,1]
	v_pk_fma_f32 v[94:95], v[98:99], s[44:45], v[84:85] op_sel_hi:[1,0,1]
	v_cvt_pk_bf16_f32 v84, v88, v89
	v_cvt_pk_bf16_f32 v85, v90, v91
	v_add_f32_e32 v87, v88, v89
	v_cvt_pk_bf16_f32 v86, v94, v95
	v_add_f32_e32 v96, v90, v91
	v_add_f32_e32 v97, v94, v95
	v_add_f32_e32 v98, v92, v93
	v_mul_f32_e32 v89, v89, v89
	v_mul_f32_e32 v91, v91, v91
	v_mul_f32_e32 v95, v95, v95
	v_mul_f32_e32 v99, v93, v93
	v_add_f32_e32 v87, v87, v96
	v_add_f32_e32 v96, v97, v98
	v_fmac_f32_e32 v89, v88, v88
	v_fmac_f32_e32 v91, v90, v90
	v_fmac_f32_e32 v95, v94, v94
	v_fmac_f32_e32 v99, v92, v92
	v_add_f32_e32 v87, v87, v96
	v_add_f32_e32 v88, v89, v91
	v_add_f32_e32 v89, v95, v99
	v_add_f32_e32 v1, v1, v87
	v_add_f32_e32 v87, v88, v89
	v_add_f32_e32 v3, v3, v87
	v_cvt_pk_bf16_f32 v87, v92, v93
	global_store_dwordx4 v[106:107], v[84:87], off
	s_waitcnt lgkmcnt(1)
	s_nop 0
	v_mov_b32_e32 v88, v1
	s_nop 1
	v_permlane16_swap_b32_e32 v1, v88
	v_add_f32_e32 v84, v1, v88
	s_waitcnt lgkmcnt(0)
	v_mov_b32_e32 v89, v3
	s_nop 1
	v_permlane16_swap_b32_e32 v3, v89
	v_add_f32_e32 v85, v3, v89
	v_mov_b32_e32 v86, v84
	v_mov_b32_e32 v87, v85
	s_nop 0
	v_permlane32_swap_b32_e32 v84, v86
	v_permlane32_swap_b32_e32 v85, v87
	s_and_saveexec_b64 s[56:57], vcc
	s_cbranch_execz .LBB0_1060
	v_pk_add_f32 v[84:85], v[84:85], v[86:87]
	v_lshlrev_b64 v[86:87], 7, v[100:101]
	v_lshl_add_u64 v[86:87], s[36:37], 0, v[86:87]
	v_lshl_add_u64 v[86:87], s[6:7], 3, v[86:87]
	s_lshl_b32 s10, s31, 3
	v_lshl_add_u64 v[86:87], v[86:87], 0, s[10:11]
	global_store_dwordx2 v[86:87], v[84:85], off
.LBB0_1060:
	s_or_b64 exec, exec, s[56:57]
	v_or_b32_e32 v84, 48, v2
	v_ashrrev_i32_e32 v85, 31, v84
	v_lshlrev_b64 v[86:87], 10, v[84:85]
	v_lshl_add_u64 v[90:91], v[86:87], 0, s[54:55]
	v_lshl_add_u64 v[86:87], v[90:91], 0, v[132:133]
	v_lshlrev_b64 v[92:93], 1, v[86:87]
	v_lshl_add_u64 v[86:87], s[20:21], 0, v[92:93]
	global_load_dwordx4 v[86:89], v[86:87], off
	v_lshl_add_u64 v[90:91], v[90:91], 0, v[134:135]
	v_lshlrev_b64 v[90:91], 1, v[90:91]
	v_lshl_add_u64 v[92:93], s[72:73], 0, v[92:93]
	v_lshl_add_u64 v[94:95], s[20:21], 0, v[90:91]
	v_lshl_add_u64 v[90:91], s[72:73], 0, v[90:91]
	s_waitcnt vmcnt(0)
	v_lshlrev_b32_e32 v96, 16, v86
	v_and_b32_e32 v97, 0xffff0000, v86
	v_lshlrev_b32_e32 v86, 16, v87
	v_and_b32_e32 v87, 0xffff0000, v87
	v_lshlrev_b32_e32 v98, 16, v88
	v_and_b32_e32 v99, 0xffff0000, v88
	v_lshlrev_b32_e32 v88, 16, v89
	v_and_b32_e32 v89, 0xffff0000, v89
	v_pk_fma_f32 v[82:83], v[86:87], s[44:45], v[82:83] op_sel_hi:[1,0,1]
	v_pk_fma_f32 v[80:81], v[96:97], s[44:45], v[80:81] op_sel_hi:[1,0,1]
	v_pk_fma_f32 v[86:87], v[88:89], s[44:45], v[78:79] op_sel_hi:[1,0,1]
	v_pk_fma_f32 v[88:89], v[98:99], s[44:45], v[76:77] op_sel_hi:[1,0,1]
	v_cvt_pk_bf16_f32 v76, v80, v81
	v_cvt_pk_bf16_f32 v77, v82, v83
	v_add_f32_e32 v1, v80, v81
	v_cvt_pk_bf16_f32 v78, v88, v89
	v_cvt_pk_bf16_f32 v79, v86, v87
	global_store_dwordx4 v[92:93], v[76:79], off
	global_load_dwordx4 v[76:79], v[94:95], off
	v_add_f32_e32 v3, v82, v83
	v_add_f32_e32 v92, v88, v89
	v_add_f32_e32 v93, v86, v87
	v_mul_f32_e32 v81, v81, v81
	v_mul_f32_e32 v83, v83, v83
	v_mul_f32_e32 v89, v89, v89
	v_mul_f32_e32 v87, v87, v87
	v_add_f32_e32 v1, v1, v3
	v_add_f32_e32 v3, v92, v93
	v_fmac_f32_e32 v81, v80, v80
	v_fmac_f32_e32 v83, v82, v82
	v_fmac_f32_e32 v89, v88, v88
	v_fmac_f32_e32 v87, v86, v86
	v_add_f32_e32 v1, v1, v3
	v_add_f32_e32 v3, v81, v83
	v_add_f32_e32 v80, v89, v87
	v_add_f32_e32 v3, v3, v80
	v_add_f32_e32 v1, 0, v1
	s_waitcnt vmcnt(0)
	v_lshlrev_b32_e32 v80, 16, v76
	v_and_b32_e32 v81, 0xffff0000, v76
	v_lshlrev_b32_e32 v76, 16, v77
	v_and_b32_e32 v77, 0xffff0000, v77
	v_lshlrev_b32_e32 v82, 16, v78
	v_and_b32_e32 v83, 0xffff0000, v78
	v_lshlrev_b32_e32 v78, 16, v79
	v_and_b32_e32 v79, 0xffff0000, v79
	v_pk_fma_f32 v[74:75], v[76:77], s[44:45], v[74:75] op_sel_hi:[1,0,1]
	v_pk_fma_f32 v[72:73], v[80:81], s[44:45], v[72:73] op_sel_hi:[1,0,1]
	v_pk_fma_f32 v[76:77], v[78:79], s[44:45], v[70:71] op_sel_hi:[1,0,1]
	v_pk_fma_f32 v[78:79], v[82:83], s[44:45], v[68:69] op_sel_hi:[1,0,1]
	v_cvt_pk_bf16_f32 v68, v72, v73
	v_cvt_pk_bf16_f32 v69, v74, v75
	v_add_f32_e32 v71, v72, v73
	v_cvt_pk_bf16_f32 v70, v78, v79
	v_add_f32_e32 v80, v74, v75
	v_add_f32_e32 v81, v78, v79
	v_add_f32_e32 v82, v76, v77
	v_mul_f32_e32 v73, v73, v73
	v_mul_f32_e32 v75, v75, v75
	v_mul_f32_e32 v79, v79, v79
	v_mul_f32_e32 v83, v77, v77
	v_add_f32_e32 v71, v71, v80
	v_add_f32_e32 v80, v81, v82
	v_fmac_f32_e32 v73, v72, v72
	v_fmac_f32_e32 v75, v74, v74
	v_fmac_f32_e32 v79, v78, v78
	v_fmac_f32_e32 v83, v76, v76
	v_add_f32_e32 v71, v71, v80
	v_add_f32_e32 v72, v73, v75
	v_add_f32_e32 v73, v79, v83
	v_add_f32_e32 v1, v1, v71
	v_add_f32_e32 v71, v72, v73
	v_add_f32_e32 v3, v3, v71
	v_cvt_pk_bf16_f32 v71, v76, v77
	global_store_dwordx4 v[90:91], v[68:71], off
	s_waitcnt lgkmcnt(1)
	s_nop 0
	v_mov_b32_e32 v72, v1
	s_nop 1
	v_permlane16_swap_b32_e32 v1, v72
	v_add_f32_e32 v68, v1, v72
	s_waitcnt lgkmcnt(0)
	v_mov_b32_e32 v73, v3
	s_nop 1
	v_permlane16_swap_b32_e32 v3, v73
	v_add_f32_e32 v69, v3, v73
	v_mov_b32_e32 v70, v68
	v_mov_b32_e32 v71, v69
	s_nop 0
	v_permlane32_swap_b32_e32 v68, v70
	v_permlane32_swap_b32_e32 v69, v71
	s_and_saveexec_b64 s[56:57], vcc
	s_cbranch_execz .LBB0_1062
	v_pk_add_f32 v[68:69], v[68:69], v[70:71]
	v_lshlrev_b64 v[70:71], 7, v[84:85]
	v_lshl_add_u64 v[70:71], s[36:37], 0, v[70:71]
	v_lshl_add_u64 v[70:71], s[6:7], 3, v[70:71]
	s_lshl_b32 s10, s31, 3
	v_lshl_add_u64 v[70:71], v[70:71], 0, s[10:11]
	global_store_dwordx2 v[70:71], v[68:69], off
.LBB0_1062:
	s_or_b64 exec, exec, s[56:57]
	v_add_u32_e32 v68, 0x80, v2
	v_ashrrev_i32_e32 v69, 31, v68
	v_lshlrev_b64 v[70:71], 10, v[68:69]
	v_lshl_add_u64 v[74:75], v[70:71], 0, s[54:55]
	v_lshl_add_u64 v[70:71], v[74:75], 0, v[132:133]
	v_lshlrev_b64 v[76:77], 1, v[70:71]
	v_lshl_add_u64 v[70:71], s[20:21], 0, v[76:77]
	global_load_dwordx4 v[70:73], v[70:71], off
	v_lshl_add_u64 v[74:75], v[74:75], 0, v[134:135]
	v_lshlrev_b64 v[74:75], 1, v[74:75]
	v_lshl_add_u64 v[76:77], s[72:73], 0, v[76:77]
	v_lshl_add_u64 v[78:79], s[20:21], 0, v[74:75]
	v_lshl_add_u64 v[74:75], s[72:73], 0, v[74:75]
	s_waitcnt vmcnt(0)
	v_lshlrev_b32_e32 v80, 16, v70
	v_and_b32_e32 v81, 0xffff0000, v70
	v_lshlrev_b32_e32 v70, 16, v71
	v_and_b32_e32 v71, 0xffff0000, v71
	v_lshlrev_b32_e32 v82, 16, v72
	v_and_b32_e32 v83, 0xffff0000, v72
	v_lshlrev_b32_e32 v72, 16, v73
	v_and_b32_e32 v73, 0xffff0000, v73
	v_pk_fma_f32 v[66:67], v[70:71], s[44:45], v[66:67] op_sel_hi:[1,0,1]
	v_pk_fma_f32 v[64:65], v[80:81], s[44:45], v[64:65] op_sel_hi:[1,0,1]
	v_pk_fma_f32 v[70:71], v[72:73], s[44:45], v[62:63] op_sel_hi:[1,0,1]
	v_pk_fma_f32 v[72:73], v[82:83], s[44:45], v[60:61] op_sel_hi:[1,0,1]
	v_cvt_pk_bf16_f32 v60, v64, v65
	v_cvt_pk_bf16_f32 v61, v66, v67
	v_add_f32_e32 v1, v64, v65
	v_cvt_pk_bf16_f32 v62, v72, v73
	v_cvt_pk_bf16_f32 v63, v70, v71
	global_store_dwordx4 v[76:77], v[60:63], off
	global_load_dwordx4 v[60:63], v[78:79], off
	v_add_f32_e32 v3, v66, v67
	v_add_f32_e32 v76, v72, v73
	v_add_f32_e32 v77, v70, v71
	v_mul_f32_e32 v65, v65, v65
	v_mul_f32_e32 v67, v67, v67
	v_mul_f32_e32 v73, v73, v73
	v_mul_f32_e32 v71, v71, v71
	v_add_f32_e32 v1, v1, v3
	v_add_f32_e32 v3, v76, v77
	v_fmac_f32_e32 v65, v64, v64
	v_fmac_f32_e32 v67, v66, v66
	v_fmac_f32_e32 v73, v72, v72
	v_fmac_f32_e32 v71, v70, v70
	v_add_f32_e32 v1, v1, v3
	v_add_f32_e32 v3, v65, v67
	v_add_f32_e32 v64, v73, v71
	v_add_f32_e32 v3, v3, v64
	v_add_f32_e32 v1, 0, v1
	s_waitcnt vmcnt(0)
	v_lshlrev_b32_e32 v64, 16, v60
	v_and_b32_e32 v65, 0xffff0000, v60
	v_lshlrev_b32_e32 v60, 16, v61
	v_and_b32_e32 v61, 0xffff0000, v61
	v_lshlrev_b32_e32 v66, 16, v62
	v_and_b32_e32 v67, 0xffff0000, v62
	v_lshlrev_b32_e32 v62, 16, v63
	v_and_b32_e32 v63, 0xffff0000, v63
	v_pk_fma_f32 v[58:59], v[60:61], s[44:45], v[58:59] op_sel_hi:[1,0,1]
	v_pk_fma_f32 v[56:57], v[64:65], s[44:45], v[56:57] op_sel_hi:[1,0,1]
	v_pk_fma_f32 v[60:61], v[62:63], s[44:45], v[54:55] op_sel_hi:[1,0,1]
	v_pk_fma_f32 v[62:63], v[66:67], s[44:45], v[52:53] op_sel_hi:[1,0,1]
	v_cvt_pk_bf16_f32 v52, v56, v57
	v_cvt_pk_bf16_f32 v53, v58, v59
	v_add_f32_e32 v55, v56, v57
	v_cvt_pk_bf16_f32 v54, v62, v63
	v_add_f32_e32 v64, v58, v59
	v_add_f32_e32 v65, v62, v63
	v_add_f32_e32 v66, v60, v61
	v_mul_f32_e32 v57, v57, v57
	v_mul_f32_e32 v59, v59, v59
	v_mul_f32_e32 v63, v63, v63
	v_mul_f32_e32 v67, v61, v61
	v_add_f32_e32 v55, v55, v64
	v_add_f32_e32 v64, v65, v66
	v_fmac_f32_e32 v57, v56, v56
	v_fmac_f32_e32 v59, v58, v58
	v_fmac_f32_e32 v63, v62, v62
	v_fmac_f32_e32 v67, v60, v60
	v_add_f32_e32 v55, v55, v64
	v_add_f32_e32 v56, v57, v59
	v_add_f32_e32 v57, v63, v67
	v_add_f32_e32 v1, v1, v55
	v_add_f32_e32 v55, v56, v57
	v_add_f32_e32 v3, v3, v55
	v_cvt_pk_bf16_f32 v55, v60, v61
	global_store_dwordx4 v[74:75], v[52:55], off
	s_waitcnt lgkmcnt(1)
	s_nop 0
	v_mov_b32_e32 v56, v1
	s_nop 1
	v_permlane16_swap_b32_e32 v1, v56
	v_add_f32_e32 v52, v1, v56
	s_waitcnt lgkmcnt(0)
	v_mov_b32_e32 v57, v3
	s_nop 1
	v_permlane16_swap_b32_e32 v3, v57
	v_add_f32_e32 v53, v3, v57
	v_mov_b32_e32 v54, v52
	v_mov_b32_e32 v55, v53
	s_nop 0
	v_permlane32_swap_b32_e32 v52, v54
	v_permlane32_swap_b32_e32 v53, v55
	s_and_saveexec_b64 s[56:57], vcc
	s_cbranch_execz .LBB0_1064
	v_pk_add_f32 v[52:53], v[52:53], v[54:55]
	v_lshlrev_b64 v[54:55], 7, v[68:69]
	v_lshl_add_u64 v[54:55], s[36:37], 0, v[54:55]
	v_lshl_add_u64 v[54:55], s[6:7], 3, v[54:55]
	s_lshl_b32 s10, s31, 3
	v_lshl_add_u64 v[54:55], v[54:55], 0, s[10:11]
	global_store_dwordx2 v[54:55], v[52:53], off
.LBB0_1064:
	s_or_b64 exec, exec, s[56:57]
	v_add_u32_e32 v52, 0x90, v2
	v_ashrrev_i32_e32 v53, 31, v52
	v_lshlrev_b64 v[54:55], 10, v[52:53]
	v_lshl_add_u64 v[58:59], v[54:55], 0, s[54:55]
	v_lshl_add_u64 v[54:55], v[58:59], 0, v[132:133]
	v_lshlrev_b64 v[60:61], 1, v[54:55]
	v_lshl_add_u64 v[54:55], s[20:21], 0, v[60:61]
	global_load_dwordx4 v[54:57], v[54:55], off
	v_lshl_add_u64 v[58:59], v[58:59], 0, v[134:135]
	v_lshlrev_b64 v[58:59], 1, v[58:59]
	v_lshl_add_u64 v[60:61], s[72:73], 0, v[60:61]
	v_lshl_add_u64 v[62:63], s[20:21], 0, v[58:59]
	v_lshl_add_u64 v[58:59], s[72:73], 0, v[58:59]
	s_waitcnt vmcnt(0)
	v_lshlrev_b32_e32 v64, 16, v54
	v_and_b32_e32 v65, 0xffff0000, v54
	v_lshlrev_b32_e32 v54, 16, v55
	v_and_b32_e32 v55, 0xffff0000, v55
	v_lshlrev_b32_e32 v66, 16, v56
	v_and_b32_e32 v67, 0xffff0000, v56
	v_lshlrev_b32_e32 v56, 16, v57
	v_and_b32_e32 v57, 0xffff0000, v57
	v_pk_fma_f32 v[50:51], v[54:55], s[44:45], v[50:51] op_sel_hi:[1,0,1]
	v_pk_fma_f32 v[48:49], v[64:65], s[44:45], v[48:49] op_sel_hi:[1,0,1]
	v_pk_fma_f32 v[54:55], v[56:57], s[44:45], v[46:47] op_sel_hi:[1,0,1]
	v_pk_fma_f32 v[56:57], v[66:67], s[44:45], v[44:45] op_sel_hi:[1,0,1]
	v_cvt_pk_bf16_f32 v44, v48, v49
	v_cvt_pk_bf16_f32 v45, v50, v51
	v_add_f32_e32 v1, v48, v49
	v_cvt_pk_bf16_f32 v46, v56, v57
	v_cvt_pk_bf16_f32 v47, v54, v55
	global_store_dwordx4 v[60:61], v[44:47], off
	global_load_dwordx4 v[44:47], v[62:63], off
	v_add_f32_e32 v3, v50, v51
	v_add_f32_e32 v60, v56, v57
	v_add_f32_e32 v61, v54, v55
	v_mul_f32_e32 v49, v49, v49
	v_mul_f32_e32 v51, v51, v51
	v_mul_f32_e32 v57, v57, v57
	v_mul_f32_e32 v55, v55, v55
	v_add_f32_e32 v1, v1, v3
	v_add_f32_e32 v3, v60, v61
	v_fmac_f32_e32 v49, v48, v48
	v_fmac_f32_e32 v51, v50, v50
	v_fmac_f32_e32 v57, v56, v56
	v_fmac_f32_e32 v55, v54, v54
	v_add_f32_e32 v1, v1, v3
	v_add_f32_e32 v3, v49, v51
	v_add_f32_e32 v48, v57, v55
	v_add_f32_e32 v3, v3, v48
	v_add_f32_e32 v1, 0, v1
	s_waitcnt vmcnt(0)
	v_lshlrev_b32_e32 v48, 16, v44
	v_and_b32_e32 v49, 0xffff0000, v44
	v_lshlrev_b32_e32 v44, 16, v45
	v_and_b32_e32 v45, 0xffff0000, v45
	v_lshlrev_b32_e32 v50, 16, v46
	v_and_b32_e32 v51, 0xffff0000, v46
	v_lshlrev_b32_e32 v46, 16, v47
	v_and_b32_e32 v47, 0xffff0000, v47
	v_pk_fma_f32 v[42:43], v[44:45], s[44:45], v[42:43] op_sel_hi:[1,0,1]
	v_pk_fma_f32 v[40:41], v[48:49], s[44:45], v[40:41] op_sel_hi:[1,0,1]
	v_pk_fma_f32 v[44:45], v[46:47], s[44:45], v[38:39] op_sel_hi:[1,0,1]
	v_pk_fma_f32 v[46:47], v[50:51], s[44:45], v[36:37] op_sel_hi:[1,0,1]
	v_cvt_pk_bf16_f32 v36, v40, v41
	v_cvt_pk_bf16_f32 v37, v42, v43
	v_add_f32_e32 v39, v40, v41
	v_cvt_pk_bf16_f32 v38, v46, v47
	v_add_f32_e32 v48, v42, v43
	v_add_f32_e32 v49, v46, v47
	v_add_f32_e32 v50, v44, v45
	v_mul_f32_e32 v41, v41, v41
	v_mul_f32_e32 v43, v43, v43
	v_mul_f32_e32 v47, v47, v47
	v_mul_f32_e32 v51, v45, v45
	v_add_f32_e32 v39, v39, v48
	v_add_f32_e32 v48, v49, v50
	v_fmac_f32_e32 v41, v40, v40
	v_fmac_f32_e32 v43, v42, v42
	v_fmac_f32_e32 v47, v46, v46
	v_fmac_f32_e32 v51, v44, v44
	v_add_f32_e32 v39, v39, v48
	v_add_f32_e32 v40, v41, v43
	v_add_f32_e32 v41, v47, v51
	v_add_f32_e32 v1, v1, v39
	v_add_f32_e32 v39, v40, v41
	v_add_f32_e32 v3, v3, v39
	v_cvt_pk_bf16_f32 v39, v44, v45
	global_store_dwordx4 v[58:59], v[36:39], off
	s_waitcnt lgkmcnt(1)
	s_nop 0
	v_mov_b32_e32 v40, v1
	s_nop 1
	v_permlane16_swap_b32_e32 v1, v40
	v_add_f32_e32 v36, v1, v40
	s_waitcnt lgkmcnt(0)
	v_mov_b32_e32 v41, v3
	s_nop 1
	v_permlane16_swap_b32_e32 v3, v41
	v_add_f32_e32 v37, v3, v41
	v_mov_b32_e32 v38, v36
	v_mov_b32_e32 v39, v37
	s_nop 0
	v_permlane32_swap_b32_e32 v36, v38
	v_permlane32_swap_b32_e32 v37, v39
	s_and_saveexec_b64 s[56:57], vcc
	s_cbranch_execz .LBB0_1066
	v_pk_add_f32 v[36:37], v[36:37], v[38:39]
	v_lshlrev_b64 v[38:39], 7, v[52:53]
	v_lshl_add_u64 v[38:39], s[36:37], 0, v[38:39]
	v_lshl_add_u64 v[38:39], s[6:7], 3, v[38:39]
	s_lshl_b32 s10, s31, 3
	v_lshl_add_u64 v[38:39], v[38:39], 0, s[10:11]
	global_store_dwordx2 v[38:39], v[36:37], off
.LBB0_1066:
	s_or_b64 exec, exec, s[56:57]
	v_add_u32_e32 v36, 0xa0, v2
	v_ashrrev_i32_e32 v37, 31, v36
	v_lshlrev_b64 v[38:39], 10, v[36:37]
	v_lshl_add_u64 v[42:43], v[38:39], 0, s[54:55]
	v_lshl_add_u64 v[38:39], v[42:43], 0, v[132:133]
	v_lshlrev_b64 v[44:45], 1, v[38:39]
	v_lshl_add_u64 v[38:39], s[20:21], 0, v[44:45]
	global_load_dwordx4 v[38:41], v[38:39], off
	v_lshl_add_u64 v[42:43], v[42:43], 0, v[134:135]
	v_lshlrev_b64 v[42:43], 1, v[42:43]
	v_lshl_add_u64 v[44:45], s[72:73], 0, v[44:45]
	v_lshl_add_u64 v[46:47], s[20:21], 0, v[42:43]
	v_lshl_add_u64 v[42:43], s[72:73], 0, v[42:43]
	s_waitcnt vmcnt(0)
	v_lshlrev_b32_e32 v48, 16, v38
	v_and_b32_e32 v49, 0xffff0000, v38
	v_lshlrev_b32_e32 v38, 16, v39
	v_and_b32_e32 v39, 0xffff0000, v39
	v_lshlrev_b32_e32 v50, 16, v40
	v_and_b32_e32 v51, 0xffff0000, v40
	v_lshlrev_b32_e32 v40, 16, v41
	v_and_b32_e32 v41, 0xffff0000, v41
	v_pk_fma_f32 v[34:35], v[38:39], s[44:45], v[34:35] op_sel_hi:[1,0,1]
	v_pk_fma_f32 v[32:33], v[48:49], s[44:45], v[32:33] op_sel_hi:[1,0,1]
	v_pk_fma_f32 v[38:39], v[40:41], s[44:45], v[30:31] op_sel_hi:[1,0,1]
	v_pk_fma_f32 v[40:41], v[50:51], s[44:45], v[28:29] op_sel_hi:[1,0,1]
	v_cvt_pk_bf16_f32 v28, v32, v33
	v_cvt_pk_bf16_f32 v29, v34, v35
	v_add_f32_e32 v1, v32, v33
	v_cvt_pk_bf16_f32 v30, v40, v41
	v_cvt_pk_bf16_f32 v31, v38, v39
	global_store_dwordx4 v[44:45], v[28:31], off
	global_load_dwordx4 v[28:31], v[46:47], off
	v_add_f32_e32 v3, v34, v35
	v_add_f32_e32 v44, v40, v41
	v_add_f32_e32 v45, v38, v39
	v_mul_f32_e32 v33, v33, v33
	v_mul_f32_e32 v35, v35, v35
	v_mul_f32_e32 v41, v41, v41
	v_mul_f32_e32 v39, v39, v39
	v_add_f32_e32 v1, v1, v3
	v_add_f32_e32 v3, v44, v45
	v_fmac_f32_e32 v33, v32, v32
	v_fmac_f32_e32 v35, v34, v34
	v_fmac_f32_e32 v41, v40, v40
	v_fmac_f32_e32 v39, v38, v38
	v_add_f32_e32 v1, v1, v3
	v_add_f32_e32 v3, v33, v35
	v_add_f32_e32 v32, v41, v39
	v_add_f32_e32 v3, v3, v32
	v_add_f32_e32 v1, 0, v1
	s_waitcnt vmcnt(0)
	v_lshlrev_b32_e32 v32, 16, v28
	v_and_b32_e32 v33, 0xffff0000, v28
	v_lshlrev_b32_e32 v28, 16, v29
	v_and_b32_e32 v29, 0xffff0000, v29
	v_lshlrev_b32_e32 v34, 16, v30
	v_and_b32_e32 v35, 0xffff0000, v30
	v_lshlrev_b32_e32 v30, 16, v31
	v_and_b32_e32 v31, 0xffff0000, v31
	v_pk_fma_f32 v[26:27], v[28:29], s[44:45], v[26:27] op_sel_hi:[1,0,1]
	v_pk_fma_f32 v[24:25], v[32:33], s[44:45], v[24:25] op_sel_hi:[1,0,1]
	v_pk_fma_f32 v[28:29], v[30:31], s[44:45], v[22:23] op_sel_hi:[1,0,1]
	v_pk_fma_f32 v[30:31], v[34:35], s[44:45], v[20:21] op_sel_hi:[1,0,1]
	v_cvt_pk_bf16_f32 v20, v24, v25
	v_cvt_pk_bf16_f32 v21, v26, v27
	v_add_f32_e32 v23, v24, v25
	v_cvt_pk_bf16_f32 v22, v30, v31
	v_add_f32_e32 v32, v26, v27
	v_add_f32_e32 v33, v30, v31
	v_add_f32_e32 v34, v28, v29
	v_mul_f32_e32 v25, v25, v25
	v_mul_f32_e32 v27, v27, v27
	v_mul_f32_e32 v31, v31, v31
	v_mul_f32_e32 v35, v29, v29
	v_add_f32_e32 v23, v23, v32
	v_add_f32_e32 v32, v33, v34
	v_fmac_f32_e32 v25, v24, v24
	v_fmac_f32_e32 v27, v26, v26
	v_fmac_f32_e32 v31, v30, v30
	v_fmac_f32_e32 v35, v28, v28
	v_add_f32_e32 v23, v23, v32
	v_add_f32_e32 v24, v25, v27
	v_add_f32_e32 v25, v31, v35
	v_add_f32_e32 v1, v1, v23
	v_add_f32_e32 v23, v24, v25
	v_add_f32_e32 v3, v3, v23
	v_cvt_pk_bf16_f32 v23, v28, v29
	global_store_dwordx4 v[42:43], v[20:23], off
	s_waitcnt lgkmcnt(1)
	s_nop 0
	v_mov_b32_e32 v24, v1
	s_nop 1
	v_permlane16_swap_b32_e32 v1, v24
	v_add_f32_e32 v20, v1, v24
	s_waitcnt lgkmcnt(0)
	v_mov_b32_e32 v25, v3
	s_nop 1
	v_permlane16_swap_b32_e32 v3, v25
	v_add_f32_e32 v21, v3, v25
	v_mov_b32_e32 v22, v20
	v_mov_b32_e32 v23, v21
	s_nop 0
	v_permlane32_swap_b32_e32 v20, v22
	v_permlane32_swap_b32_e32 v21, v23
	s_and_saveexec_b64 s[56:57], vcc
	s_cbranch_execz .LBB0_1068
	v_pk_add_f32 v[20:21], v[20:21], v[22:23]
	v_lshlrev_b64 v[22:23], 7, v[36:37]
	v_lshl_add_u64 v[22:23], s[36:37], 0, v[22:23]
	v_lshl_add_u64 v[22:23], s[6:7], 3, v[22:23]
	s_lshl_b32 s10, s31, 3
	v_lshl_add_u64 v[22:23], v[22:23], 0, s[10:11]
	global_store_dwordx2 v[22:23], v[20:21], off
.LBB0_1068:
	s_or_b64 exec, exec, s[56:57]
	v_add_u32_e32 v2, 0xb0, v2
	v_ashrrev_i32_e32 v3, 31, v2
	v_lshlrev_b64 v[20:21], 10, v[2:3]
	v_lshl_add_u64 v[24:25], v[20:21], 0, s[54:55]
	v_lshl_add_u64 v[20:21], v[24:25], 0, v[132:133]
	v_lshlrev_b64 v[26:27], 1, v[20:21]
	v_lshl_add_u64 v[20:21], s[20:21], 0, v[26:27]
	global_load_dwordx4 v[20:23], v[20:21], off
	v_lshl_add_u64 v[24:25], v[24:25], 0, v[134:135]
	v_lshlrev_b64 v[24:25], 1, v[24:25]
	v_lshl_add_u64 v[26:27], s[72:73], 0, v[26:27]
	v_lshl_add_u64 v[28:29], s[20:21], 0, v[24:25]
	v_lshl_add_u64 v[24:25], s[72:73], 0, v[24:25]
	s_waitcnt vmcnt(0)
	v_lshlrev_b32_e32 v30, 16, v20
	v_and_b32_e32 v31, 0xffff0000, v20
	v_lshlrev_b32_e32 v20, 16, v21
	v_and_b32_e32 v21, 0xffff0000, v21
	v_lshlrev_b32_e32 v32, 16, v22
	v_and_b32_e32 v33, 0xffff0000, v22
	v_lshlrev_b32_e32 v22, 16, v23
	v_and_b32_e32 v23, 0xffff0000, v23
	v_pk_fma_f32 v[18:19], v[20:21], s[44:45], v[18:19] op_sel_hi:[1,0,1]
	v_pk_fma_f32 v[16:17], v[30:31], s[44:45], v[16:17] op_sel_hi:[1,0,1]
	v_pk_fma_f32 v[20:21], v[22:23], s[44:45], v[14:15] op_sel_hi:[1,0,1]
	v_pk_fma_f32 v[22:23], v[32:33], s[44:45], v[12:13] op_sel_hi:[1,0,1]
	v_cvt_pk_bf16_f32 v12, v16, v17
	v_cvt_pk_bf16_f32 v13, v18, v19
	v_add_f32_e32 v1, v16, v17
	v_cvt_pk_bf16_f32 v14, v22, v23
	v_cvt_pk_bf16_f32 v15, v20, v21
	global_store_dwordx4 v[26:27], v[12:15], off
	global_load_dwordx4 v[12:15], v[28:29], off
	v_add_f32_e32 v26, v18, v19
	v_add_f32_e32 v27, v22, v23
	v_add_f32_e32 v28, v20, v21
	v_mul_f32_e32 v17, v17, v17
	v_mul_f32_e32 v19, v19, v19
	v_mul_f32_e32 v23, v23, v23
	v_mul_f32_e32 v21, v21, v21
	v_fmac_f32_e32 v17, v16, v16
	v_fmac_f32_e32 v19, v18, v18
	v_fmac_f32_e32 v23, v22, v22
	v_fmac_f32_e32 v21, v20, v20
	v_add_f32_e32 v16, v17, v19
	v_add_f32_e32 v17, v23, v21
	v_add_f32_e32 v20, v16, v17
	v_add_f32_e32 v1, v1, v26
	v_add_f32_e32 v26, v27, v28
	v_add_f32_e32 v1, v1, v26
	v_add_f32_e32 v1, 0, v1
	s_waitcnt vmcnt(0)
	v_lshlrev_b32_e32 v16, 16, v12
	v_and_b32_e32 v17, 0xffff0000, v12
	v_lshlrev_b32_e32 v12, 16, v13
	v_and_b32_e32 v13, 0xffff0000, v13
	v_lshlrev_b32_e32 v18, 16, v14
	v_and_b32_e32 v19, 0xffff0000, v14
	v_lshlrev_b32_e32 v14, 16, v15
	v_and_b32_e32 v15, 0xffff0000, v15
	v_pk_fma_f32 v[10:11], v[12:13], s[44:45], v[10:11] op_sel_hi:[1,0,1]
	v_pk_fma_f32 v[8:9], v[16:17], s[44:45], v[8:9] op_sel_hi:[1,0,1]
	v_pk_fma_f32 v[12:13], v[14:15], s[44:45], v[6:7] op_sel_hi:[1,0,1]
	v_pk_fma_f32 v[14:15], v[18:19], s[44:45], v[4:5] op_sel_hi:[1,0,1]
	v_cvt_pk_bf16_f32 v4, v8, v9
	v_cvt_pk_bf16_f32 v5, v10, v11
	v_add_f32_e32 v7, v8, v9
	v_cvt_pk_bf16_f32 v6, v14, v15
	v_add_f32_e32 v16, v10, v11
	v_add_f32_e32 v17, v14, v15
	v_add_f32_e32 v18, v12, v13
	v_mul_f32_e32 v9, v9, v9
	v_mul_f32_e32 v11, v11, v11
	v_mul_f32_e32 v15, v15, v15
	v_mul_f32_e32 v19, v13, v13
	v_add_f32_e32 v7, v7, v16
	v_add_f32_e32 v16, v17, v18
	v_fmac_f32_e32 v9, v8, v8
	v_fmac_f32_e32 v11, v10, v10
	v_fmac_f32_e32 v15, v14, v14
	v_fmac_f32_e32 v19, v12, v12
	v_add_f32_e32 v7, v7, v16
	v_add_f32_e32 v8, v9, v11
	v_add_f32_e32 v9, v15, v19
	v_add_f32_e32 v1, v1, v7
	v_add_f32_e32 v7, v8, v9
	v_add_f32_e32 v9, v20, v7
	ds_swizzle_b32 v10, v9 offset:swizzle(SWAP,16)
	v_cvt_pk_bf16_f32 v7, v12, v13
	global_store_dwordx4 v[24:25], v[4:7], off
	s_waitcnt lgkmcnt(1)
	s_nop 0
	v_mov_b32_e32 v8, v1
	s_nop 1
	v_permlane16_swap_b32_e32 v1, v8
	v_add_f32_e32 v4, v1, v8
	s_waitcnt lgkmcnt(0)
	v_add_f32_e32 v5, v9, v10
	v_mov_b32_e32 v6, v4
	v_mov_b32_e32 v7, v5
	s_nop 0
	v_permlane32_swap_b32_e32 v4, v6
	v_permlane32_swap_b32_e32 v5, v7
	s_and_saveexec_b64 s[54:55], vcc
	s_cbranch_execz .LBB0_1070
	v_lshlrev_b64 v[2:3], 7, v[2:3]
	v_lshl_add_u64 v[2:3], s[36:37], 0, v[2:3]
	v_lshl_add_u64 v[2:3], s[6:7], 3, v[2:3]
	s_lshl_b32 s10, s31, 3
	v_pk_add_f32 v[4:5], v[4:5], v[6:7]
	v_lshl_add_u64 v[2:3], v[2:3], 0, s[10:11]
	global_store_dwordx2 v[2:3], v[4:5], off
